# loop-edge rotation: LDS read-base computation moved from the K-loop head (after the barrier) to the tail in 7 pipelined gemm K-loops
# baseline (speedup 1.0000x reference)
; #define A256_LOADH(kt_, hf_) { a0 = la.ld1(kt_, (hf_) * 4 + 0, tid); a1 = la.ld1(kt_, (hf_) * 4 + 1, tid); a2 = la.ld1(kt_, (hf_) * 4 + 2, tid); a3 = la.ld1(kt_, (hf_) * 4 + 3, tid); }
; #define ZERO_ACC8(a) { _Pragma("unroll") for (int i_ = 0; i_ < 8; i_++) _Pragma("unroll") for (int r_ = 0; r_ < 16; r_++) a[i_][r_] = 0.f; }
; template <bool swap, class LA>
; DI void gemm256_ws(const LA& la, const bf16_t* Wt, const int KS, const int nk, bf16_t* smem, f32x16 (&acc)[8]) {
;     ...
;   A256_LOADH(0, 0) A256_STH(smem, 0)
;   A256_LOADH(0, 1) A256_STH(smem, 1)
;   W256_LD(0, 0, w00, w10) W256_LD(0, 1, w01, w11) W256_LD(0, 2, w02, w12) W256_LD(0, 3, w03, w13)
;   __syncthreads();
;   const int aoff = (tbk * 128 + l32) * LDT + h * 8;
; DI void ph_out(const Params& P, int layer, bf16_t* smem) {
;     ...
;   for (int it = 0;; it++) {
;     int mt, nt; if (!tile_sched256(bid, it, 8, 8, mt, nt)) break;
;     const int m0 = mt * 256, n0 = nt * 128;
;     __syncthreads();
;     f32x16 acc[8]; ZERO_ACC8(acc)
;     LoadTile256 la{cat + (size_t)(2 * mt) * 16 * 8192, 16 * 8192};
;     gemm256_ws<true>(la, W + (size_t)n0 * 1024, 64, 16, smem, acc);
.LBB0_29:
	s_ashr_i32 s3, s2, 31
	s_lshr_b32 s3, s3, 24
	s_add_i32 s3, s2, s3
	s_ashr_i32 s6, s3, 8
	s_and_b32 s3, s3, 0xffffff00
	s_sub_i32 s2, s2, s3
	s_ashr_i32 s3, s2, 31
	s_lshr_b32 s3, s3, 29
	s_add_i32 s3, s2, s3
	s_ashr_i32 s17, s3, 3
	s_sub_i32 s3, s6, s17
	s_add_i32 s17, s17, s14
	s_lshl_b32 s16, s3, 3
	s_lshl_b32 s6, s17, 1
	s_add_i32 s16, s16, s2
	s_ashr_i32 s7, s6, 31
	s_lshl_b32 s2, s16, 7
	s_lshl_b64 s[6:7], s[6:7], 18
	v_mov_b32_e32 v0, v234
	s_barrier
	s_add_u32 s8, s84, s6
	s_addc_u32 s9, s85, s7
	v_lshlrev_b32_e32 v2, 3, v0
	s_ashr_i32 s3, s2, 31
	v_add_u32_e32 v6, 0x800, v2
	s_lshl_b64 s[6:7], s[2:3], 11
	v_readlane_b32 s10, v255, 25
	v_ashrrev_i32_e32 v3, 31, v2
	v_ashrrev_i32_e32 v7, 31, v6
	v_readlane_b32 s11, v255, 26
	s_add_u32 s6, s10, s6
	v_lshlrev_b64 v[176:177], 1, v[2:3]
	v_lshlrev_b64 v[178:179], 1, v[6:7]
	v_add_u32_e32 v6, 0x1000, v2
	v_add_u32_e32 v2, 0x1800, v2
	s_addc_u32 s7, s11, s7
	v_ashrrev_i32_e32 v7, 31, v6
	v_ashrrev_i32_e32 v3, 31, v2
	v_lshlrev_b64 v[180:181], 1, v[6:7]
	v_lshlrev_b64 v[182:183], 1, v[2:3]
	s_add_u32 s10, s8, 0x40000
	v_lshl_add_u64 v[4:5], s[8:9], 0, v[176:177]
	v_lshl_add_u64 v[8:9], s[8:9], 0, v[178:179]
	v_lshl_add_u64 v[12:13], s[8:9], 0, v[180:181]
	v_lshl_add_u64 v[2:3], s[8:9], 0, v[182:183]
	s_addc_u32 s11, s9, 0
	v_ashrrev_i32_e32 v36, 6, v0
	global_load_dwordx4 v[4:7], v[4:5], off
	s_nop 0
	global_load_dwordx4 v[8:11], v[8:9], off
	s_nop 0
	global_load_dwordx4 v[12:15], v[12:13], off
	s_nop 0
	global_load_dwordx4 v[16:19], v[2:3], off
	v_lshl_add_u64 v[2:3], s[10:11], 0, v[176:177]
	v_lshl_add_u64 v[24:25], s[10:11], 0, v[178:179]
	v_lshl_add_u64 v[28:29], s[10:11], 0, v[180:181]
	v_lshl_add_u64 v[32:33], s[10:11], 0, v[182:183]
	v_lshlrev_b32_e32 v37, 4, v0
	v_and_b32_e32 v36, -2, v36
	global_load_dwordx4 v[20:23], v[2:3], off
	s_nop 0
	global_load_dwordx4 v[24:27], v[24:25], off
	s_nop 0
	global_load_dwordx4 v[28:31], v[28:29], off
	s_nop 0
	global_load_dwordx4 v[32:35], v[32:33], off
	v_and_b32_e32 v3, 31, v0
	v_lshrrev_b32_e32 v39, 3, v0
	v_lshlrev_b32_e32 v40, 1, v0
	v_lshrrev_b32_e32 v41, 1, v0
	v_and_b32_e32 v0, 0x3f0, v37
	v_and_b32_e32 v38, 0x70, v37
	v_ashrrev_i32_e32 v37, 31, v36
	v_lshlrev_b64 v[36:37], 16, v[36:37]
	v_lshl_add_u64 v[36:37], s[6:7], 0, v[36:37]
	v_lshl_add_u64 v[186:187], v[36:37], 0, v[0:1]
	s_mov_b64 s[6:7], 0x10000
	v_lshl_add_u64 v[188:189], v[186:187], 0, s[6:7]
	v_add_co_u32_e64 v36, s[6:7], s94, v186
	s_movk_i32 s18, 0x80
	s_nop 0
	v_addc_co_u32_e64 v37, s[6:7], 0, v187, s[6:7]
	global_load_dwordx4 v[154:157], v[36:37], off
	global_load_dwordx4 v[158:161], v[186:187], off
	global_load_dwordx4 v[146:149], v[36:37], off offset:1024
	global_load_dwordx4 v[150:153], v[186:187], off offset:1024
	global_load_dwordx4 v[142:145], v[36:37], off offset:2048
	global_load_dwordx4 v[138:141], v[186:187], off offset:2048
	global_load_dwordx4 v[130:133], v[36:37], off offset:3072
	global_load_dwordx4 v[134:137], v[186:187], off offset:3072
	v_mov_b32_e32 v2, 0
	v_and_or_b32 v3, v40, s18, v3
	v_and_b32_e32 v40, 16, v41
	v_mad_u64_u32 v[184:185], s[18:19], v39, s0, v[38:39]
	v_mad_u32_u24 v169, v3, s0, v40
	s_mov_b32 s6, 0
	v_mov_b32_e32 v3, v2
	v_mov_b32_e32 v50, v2
	v_mov_b32_e32 v51, v2
	v_mov_b32_e32 v52, v2
	v_mov_b32_e32 v53, v2
	v_mov_b32_e32 v54, v2
	v_mov_b32_e32 v55, v2
	v_mov_b32_e32 v56, v2
	v_mov_b32_e32 v57, v2
	v_mov_b32_e32 v58, v2
	v_mov_b32_e32 v59, v2
	v_mov_b32_e32 v60, v2
	v_mov_b32_e32 v61, v2
	v_mov_b32_e32 v62, v2
	v_mov_b32_e32 v63, v2
	v_mov_b32_e32 v64, v2
	v_mov_b32_e32 v65, v2
	v_mov_b32_e32 v82, v2
	s_waitcnt vmcnt(15)
	ds_write_b128 v184, v[4:7]
	s_waitcnt vmcnt(14)
	ds_write_b128 v184, v[8:11] offset:4608
	s_waitcnt vmcnt(13)
	ds_write_b128 v184, v[12:15] offset:9216
	s_waitcnt vmcnt(12)
	ds_write_b128 v184, v[16:19] offset:13824
	s_waitcnt vmcnt(11)
	ds_write_b128 v184, v[20:23] offset:18432
	s_waitcnt vmcnt(10)
	ds_write_b128 v184, v[24:27] offset:23040
	s_waitcnt vmcnt(9)
	ds_write_b128 v184, v[28:31] offset:27648
	s_waitcnt vmcnt(8)
	ds_write_b128 v184, v[32:35] offset:32256
	v_mov_b32_e32 v4, v2
	v_mov_b32_e32 v5, v2
	v_mov_b32_e32 v6, v2
	v_mov_b32_e32 v7, v2
	v_mov_b32_e32 v8, v2
	v_mov_b32_e32 v9, v2
	v_mov_b32_e32 v10, v2
	v_mov_b32_e32 v11, v2
	v_mov_b32_e32 v12, v2
	v_mov_b32_e32 v13, v2
	v_mov_b32_e32 v14, v2
	v_mov_b32_e32 v15, v2
	v_mov_b32_e32 v16, v2
	v_mov_b32_e32 v17, v2
	v_mov_b32_e32 v18, v2
	v_mov_b32_e32 v19, v2
	v_mov_b32_e32 v20, v2
	v_mov_b32_e32 v21, v2
	v_mov_b32_e32 v22, v2
	v_mov_b32_e32 v23, v2
	v_mov_b32_e32 v24, v2
	v_mov_b32_e32 v25, v2
	v_mov_b32_e32 v26, v2
	v_mov_b32_e32 v27, v2
	v_mov_b32_e32 v28, v2
	v_mov_b32_e32 v29, v2
	v_mov_b32_e32 v30, v2
	v_mov_b32_e32 v31, v2
	v_mov_b32_e32 v32, v2
	v_mov_b32_e32 v33, v2
	v_mov_b32_e32 v83, v2
	v_mov_b32_e32 v84, v2
	v_mov_b32_e32 v85, v2
	v_mov_b32_e32 v86, v2
	v_mov_b32_e32 v87, v2
	v_mov_b32_e32 v88, v2
	v_mov_b32_e32 v89, v2
	v_mov_b32_e32 v90, v2
	v_mov_b32_e32 v91, v2
	v_mov_b32_e32 v92, v2
	v_mov_b32_e32 v93, v2
	v_mov_b32_e32 v94, v2
	v_mov_b32_e32 v95, v2
	v_mov_b32_e32 v96, v2
	v_mov_b32_e32 v97, v2
	v_mov_b32_e32 v34, v2
	v_mov_b32_e32 v35, v2
	v_mov_b32_e32 v36, v2
	v_mov_b32_e32 v37, v2
	v_mov_b32_e32 v38, v2
	v_mov_b32_e32 v39, v2
	v_mov_b32_e32 v40, v2
	v_mov_b32_e32 v41, v2
	v_mov_b32_e32 v42, v2
	v_mov_b32_e32 v43, v2
	v_mov_b32_e32 v44, v2
	v_mov_b32_e32 v45, v2
	v_mov_b32_e32 v46, v2
	v_mov_b32_e32 v47, v2
	v_mov_b32_e32 v48, v2
	v_mov_b32_e32 v49, v2
	v_mov_b32_e32 v66, v2
	v_mov_b32_e32 v67, v2
	v_mov_b32_e32 v68, v2
	v_mov_b32_e32 v69, v2
	v_mov_b32_e32 v70, v2
	v_mov_b32_e32 v71, v2
	v_mov_b32_e32 v72, v2
	v_mov_b32_e32 v73, v2
	v_mov_b32_e32 v74, v2
	v_mov_b32_e32 v75, v2
	v_mov_b32_e32 v76, v2
	v_mov_b32_e32 v77, v2
	v_mov_b32_e32 v78, v2
	v_mov_b32_e32 v79, v2
	v_mov_b32_e32 v80, v2
	v_mov_b32_e32 v81, v2
	v_mov_b32_e32 v98, v2
	v_mov_b32_e32 v99, v2
	v_mov_b32_e32 v100, v2
	v_mov_b32_e32 v101, v2
	v_mov_b32_e32 v102, v2
	v_mov_b32_e32 v103, v2
	v_mov_b32_e32 v104, v2
	v_mov_b32_e32 v105, v2
	v_mov_b32_e32 v106, v2
	v_mov_b32_e32 v107, v2
	v_mov_b32_e32 v108, v2
	v_mov_b32_e32 v109, v2
	v_mov_b32_e32 v110, v2
	v_mov_b32_e32 v111, v2
	v_mov_b32_e32 v112, v2
	v_mov_b32_e32 v113, v2
	v_mov_b32_e32 v114, v2
	v_mov_b32_e32 v115, v2
	v_mov_b32_e32 v116, v2
	v_mov_b32_e32 v117, v2
	v_mov_b32_e32 v118, v2
	v_mov_b32_e32 v119, v2
	v_mov_b32_e32 v120, v2
	v_mov_b32_e32 v121, v2
	v_mov_b32_e32 v122, v2
	v_mov_b32_e32 v123, v2
	v_mov_b32_e32 v124, v2
	v_mov_b32_e32 v125, v2
	v_mov_b32_e32 v126, v2
	v_mov_b32_e32 v127, v2
	v_mov_b32_e32 v128, v2
	v_mov_b32_e32 v129, v2
	s_waitcnt lgkmcnt(0)
	s_barrier
; #define A256_LOADH(kt_, hf_) { a0 = la.ld1(kt_, (hf_) * 4 + 0, tid); a1 = la.ld1(kt_, (hf_) * 4 + 1, tid); a2 = la.ld1(kt_, (hf_) * 4 + 2, tid); a3 = la.ld1(kt_, (hf_) * 4 + 3, tid); }
; template <bool swap, class LA>
; DI void gemm256_ws(const LA& la, const bf16_t* Wt, const int KS, const int nk, bf16_t* smem, f32x16 (&acc)[8]) {
;     ...
;   for (int kt = 0; kt < nk; kt++) {
;     const int cur = kt & 1; const int kn = (kt + 1 < nk) ? kt + 1 : last;
;     const bf16_t* sp = smem + cur * ATILE_E + aoff;
;     bf16_t* nxt = smem + (cur ^ 1) * ATILE_E;
;     A256_LOADH(kn, 0)
;     MMA256(0, w00, w10) W256_LD(kn, 0, w00, w10)
;     MMA256(1, w01, w11) W256_LD(kn, 1, w01, w11)
;     A256_STH(nxt, 0)
;     A256_LOADH(kn, 1)
;     MMA256(2, w02, w12) W256_LD(kn, 2, w02, w12)
;     MMA256(3, w03, w13) W256_LD(kn, 3, w03, w13)
;     A256_STH(nxt, 1)
;     __syncthreads();
;   }
	s_lshl_b32 s36, 1, 14
	s_add_u32 s18, s8, s36
	s_addc_u32 s19, s9, 0
	v_lshl_add_u64 v[206:207], s[18:19], 0, v[176:177]
	v_lshl_add_u64 v[210:211], s[18:19], 0, v[178:179]
	v_lshl_add_u64 v[214:215], s[18:19], 0, v[180:181]
	v_lshl_add_u64 v[218:219], s[18:19], 0, v[182:183]
	global_load_dwordx4 v[206:209], v[206:207], off
	global_load_dwordx4 v[210:213], v[210:211], off
	global_load_dwordx4 v[214:217], v[214:215], off
	global_load_dwordx4 v[218:221], v[218:219], off
	s_add_u32 s18, s10, s36
	s_addc_u32 s19, s11, 0
	v_lshl_add_u64 v[222:223], s[18:19], 0, v[176:177]
	v_lshl_add_u64 v[226:227], s[18:19], 0, v[178:179]
	v_lshl_add_u64 v[230:231], s[18:19], 0, v[180:181]
	v_lshl_add_u64 v[246:247], s[18:19], 0, v[182:183]
	global_load_dwordx4 v[222:225], v[222:223], off
	global_load_dwordx4 v[226:229], v[226:227], off
	global_load_dwordx4 v[230:233], v[230:231], off
	global_load_dwordx4 v[246:249], v[246:247], off
	s_and_b32 s7, s6, 1
	s_mul_i32 s18, s7, 0x9000
	v_add_u32_e32 v0, s18, v169
.LBB0_30:
	ds_read_b128 v[190:193], v0
	ds_read_b128 v[194:197], v0 offset:4608
	ds_read_b128 v[198:201], v0 offset:9216
	ds_read_b128 v[202:205], v0 offset:13824
	s_and_b32 s7, s6, 1
	s_add_i32 s6, s6, 1
	s_min_u32 s29, s6, 15
	s_xor_b32 s7, s7, 1
	s_mul_i32 s7, s7, 0x9000
	v_add_u32_e32 v171, s7, v184
	s_lshl_b32 s90, s29, 12
	s_add_i32 s29, s6, 1
	s_min_u32 s29, s29, 15
	s_lshl_b32 s36, s29, 14
	s_waitcnt vmcnt(14) lgkmcnt(3)
	v_mfma_f32_32x32x16_bf16 v[82:97], v[154:157], v[190:193], v[82:97]
	v_mfma_f32_32x32x16_bf16 v[114:129], v[158:161], v[190:193], v[114:129]
	ds_read_b128 v[190:193], v0 offset:32
	s_waitcnt lgkmcnt(3)
	v_mfma_f32_32x32x16_bf16 v[50:65], v[154:157], v[194:197], v[50:65]
	v_mfma_f32_32x32x16_bf16 v[98:113], v[158:161], v[194:197], v[98:113]
	ds_read_b128 v[194:197], v0 offset:4640
	s_waitcnt lgkmcnt(3)
	v_mfma_f32_32x32x16_bf16 v[18:33], v[154:157], v[198:201], v[18:33]
	v_mfma_f32_32x32x16_bf16 v[66:81], v[158:161], v[198:201], v[66:81]
	ds_read_b128 v[198:201], v0 offset:9248
	s_waitcnt lgkmcnt(3)
	v_mfma_f32_32x32x16_bf16 v[2:17], v[154:157], v[202:205], v[2:17]
	v_mfma_f32_32x32x16_bf16 v[34:49], v[158:161], v[202:205], v[34:49]
	ds_read_b128 v[202:205], v0 offset:13856
	v_lshl_add_u64 v[154:155], v[188:189], 0, s[90:91]
	global_load_dwordx4 v[154:157], v[154:155], off
	v_lshl_add_u64 v[158:159], v[186:187], 0, s[90:91]
	global_load_dwordx4 v[158:161], v[158:159], off
	s_waitcnt vmcnt(14) lgkmcnt(3)
	v_mfma_f32_32x32x16_bf16 v[82:97], v[146:149], v[190:193], v[82:97]
	v_mfma_f32_32x32x16_bf16 v[114:129], v[150:153], v[190:193], v[114:129]
	ds_read_b128 v[190:193], v0 offset:64
	s_waitcnt lgkmcnt(3)
	v_mfma_f32_32x32x16_bf16 v[50:65], v[146:149], v[194:197], v[50:65]
	v_mfma_f32_32x32x16_bf16 v[98:113], v[150:153], v[194:197], v[98:113]
	ds_read_b128 v[194:197], v0 offset:4672
	s_waitcnt lgkmcnt(3)
	v_mfma_f32_32x32x16_bf16 v[18:33], v[146:149], v[198:201], v[18:33]
	v_mfma_f32_32x32x16_bf16 v[66:81], v[150:153], v[198:201], v[66:81]
	ds_read_b128 v[198:201], v0 offset:9280
	s_waitcnt lgkmcnt(3)
	v_mfma_f32_32x32x16_bf16 v[2:17], v[146:149], v[202:205], v[2:17]
	v_mfma_f32_32x32x16_bf16 v[34:49], v[150:153], v[202:205], v[34:49]
	ds_read_b128 v[202:205], v0 offset:13888
	v_lshl_add_u64 v[146:147], v[188:189], 0, s[90:91]
	global_load_dwordx4 v[146:149], v[146:147], off offset:1024
	v_lshl_add_u64 v[150:151], v[186:187], 0, s[90:91]
	global_load_dwordx4 v[150:153], v[150:151], off offset:1024
	s_waitcnt vmcnt(8)
	ds_write_b128 v171, v[206:209]
	ds_write_b128 v171, v[210:213] offset:4608
	ds_write_b128 v171, v[214:217] offset:9216
	ds_write_b128 v171, v[218:221] offset:13824
	s_add_u32 s18, s8, s36
	s_addc_u32 s19, s9, 0
	v_lshl_add_u64 v[206:207], s[18:19], 0, v[176:177]
	v_lshl_add_u64 v[210:211], s[18:19], 0, v[178:179]
	v_lshl_add_u64 v[214:215], s[18:19], 0, v[180:181]
	v_lshl_add_u64 v[218:219], s[18:19], 0, v[182:183]
	global_load_dwordx4 v[206:209], v[206:207], off
	global_load_dwordx4 v[210:213], v[210:211], off
	global_load_dwordx4 v[214:217], v[214:215], off
	global_load_dwordx4 v[218:221], v[218:219], off
	s_waitcnt lgkmcnt(7)
	v_mfma_f32_32x32x16_bf16 v[82:97], v[142:145], v[190:193], v[82:97]
	v_mfma_f32_32x32x16_bf16 v[114:129], v[138:141], v[190:193], v[114:129]
	ds_read_b128 v[190:193], v0 offset:96
	s_waitcnt lgkmcnt(7)
	v_mfma_f32_32x32x16_bf16 v[50:65], v[142:145], v[194:197], v[50:65]
	v_mfma_f32_32x32x16_bf16 v[98:113], v[138:141], v[194:197], v[98:113]
	ds_read_b128 v[194:197], v0 offset:4704
	s_waitcnt lgkmcnt(7)
	v_mfma_f32_32x32x16_bf16 v[18:33], v[142:145], v[198:201], v[18:33]
	v_mfma_f32_32x32x16_bf16 v[66:81], v[138:141], v[198:201], v[66:81]
	ds_read_b128 v[198:201], v0 offset:9312
	s_waitcnt lgkmcnt(7)
	v_mfma_f32_32x32x16_bf16 v[2:17], v[142:145], v[202:205], v[2:17]
	v_mfma_f32_32x32x16_bf16 v[34:49], v[138:141], v[202:205], v[34:49]
	ds_read_b128 v[202:205], v0 offset:13920
	v_lshl_add_u64 v[142:143], v[188:189], 0, s[90:91]
	global_load_dwordx4 v[142:145], v[142:143], off offset:2048
	v_lshl_add_u64 v[138:139], v[186:187], 0, s[90:91]
	global_load_dwordx4 v[138:141], v[138:139], off offset:2048
	s_waitcnt lgkmcnt(3)
	v_mfma_f32_32x32x16_bf16 v[82:97], v[130:133], v[190:193], v[82:97]
	v_mfma_f32_32x32x16_bf16 v[114:129], v[134:137], v[190:193], v[114:129]
	s_waitcnt lgkmcnt(2)
	v_mfma_f32_32x32x16_bf16 v[50:65], v[130:133], v[194:197], v[50:65]
	v_mfma_f32_32x32x16_bf16 v[98:113], v[134:137], v[194:197], v[98:113]
	s_waitcnt lgkmcnt(1)
	v_mfma_f32_32x32x16_bf16 v[18:33], v[130:133], v[198:201], v[18:33]
	v_mfma_f32_32x32x16_bf16 v[66:81], v[134:137], v[198:201], v[66:81]
	s_waitcnt lgkmcnt(0)
	v_mfma_f32_32x32x16_bf16 v[2:17], v[130:133], v[202:205], v[2:17]
	v_mfma_f32_32x32x16_bf16 v[34:49], v[134:137], v[202:205], v[34:49]
	v_lshl_add_u64 v[130:131], v[188:189], 0, s[90:91]
	global_load_dwordx4 v[130:133], v[130:131], off offset:3072
	v_lshl_add_u64 v[134:135], v[186:187], 0, s[90:91]
	global_load_dwordx4 v[134:137], v[134:135], off offset:3072
	s_waitcnt vmcnt(12)
	ds_write_b128 v171, v[222:225] offset:18432
	ds_write_b128 v171, v[226:229] offset:23040
	ds_write_b128 v171, v[230:233] offset:27648
	ds_write_b128 v171, v[246:249] offset:32256
	s_add_u32 s18, s10, s36
	s_addc_u32 s19, s11, 0
	v_lshl_add_u64 v[222:223], s[18:19], 0, v[176:177]
	v_lshl_add_u64 v[226:227], s[18:19], 0, v[178:179]
	v_lshl_add_u64 v[230:231], s[18:19], 0, v[180:181]
	v_lshl_add_u64 v[246:247], s[18:19], 0, v[182:183]
	global_load_dwordx4 v[222:225], v[222:223], off
	global_load_dwordx4 v[226:229], v[226:227], off
	global_load_dwordx4 v[230:233], v[230:231], off
	global_load_dwordx4 v[246:249], v[246:247], off
	s_and_b32 s7, s6, 1
	s_mul_i32 s7, s7, 0x9000
	v_add_u32_e32 v0, s7, v169
	s_cmp_lg_u32 s6, 16
	s_waitcnt lgkmcnt(0)
	s_barrier
; #define SW_FOR_TOK(j) _Pragma("unroll") for (int j = 0; j < 4; j++)
; #define SW_FOR_FEAT(i, rq) _Pragma("unroll") for (int i = 0; i < 2; i++) _Pragma("unroll") for (int rq = 0; rq < 4; rq++)
; DI void ph_out(const Params& P, int layer, bf16_t* smem) {
;     ...
;     SW_FOR_TOK(j) {
;       const int tl = wn * 128 + j * 32 + l32; const size_t tg = (size_t)m0 + tl;
;       float sq = 0.f;
;       SW_FOR_FEAT(i, rq) {
;         const int c = n0 + wm * 64 + i * 32 + 8 * rq + 4 * h;
;         const float a0 = SWV(i, j, 4 * rq), a1 = SWV(i, j, 4 * rq + 1), a2 = SWV(i, j, 4 * rq + 2), a3 = SWV(i, j, 4 * rq + 3);
;         sq += a0 * a0 + a1 * a1 + a2 * a2 + a3 * a3; (void)c;
;       }
;       sq += __shfl_xor(sq, 32);
;       if (h == 0) ss[tg * 16 + nt * 2 + wm] = sq;
;     }
	s_cbranch_scc1 .LBB0_30
	s_waitcnt vmcnt(0)
	s_waitcnt vmcnt(0)
	v_mul_f32_e32 v130, v115, v115
	v_mul_f32_e32 v131, v119, v119
	v_fmac_f32_e32 v130, v114, v114
	v_fmac_f32_e32 v131, v118, v118
	v_fmac_f32_e32 v130, v116, v116
	v_fmac_f32_e32 v131, v120, v120
	v_fmac_f32_e32 v130, v117, v117
	v_fmac_f32_e32 v131, v121, v121
	v_add_f32_e32 v130, v130, v131
	v_mul_f32_e32 v131, v123, v123
	v_fmac_f32_e32 v131, v122, v122
	v_fmac_f32_e32 v131, v124, v124
	v_fmac_f32_e32 v131, v125, v125
	v_add_f32_e32 v130, v131, v130
	v_mul_f32_e32 v131, v127, v127
	v_fmac_f32_e32 v131, v126, v126
	v_fmac_f32_e32 v131, v128, v128
	v_fmac_f32_e32 v131, v129, v129
	v_add_f32_e32 v130, v131, v130
	v_mul_f32_e32 v131, v83, v83
	v_fmac_f32_e32 v131, v82, v82
	v_fmac_f32_e32 v131, v84, v84
	v_fmac_f32_e32 v131, v85, v85
	v_add_f32_e32 v130, v130, v131
	v_mul_f32_e32 v131, v87, v87
	v_fmac_f32_e32 v131, v86, v86
	v_fmac_f32_e32 v131, v88, v88
	v_fmac_f32_e32 v131, v89, v89
	v_add_f32_e32 v130, v131, v130
	v_mul_f32_e32 v131, v91, v91
	v_fmac_f32_e32 v131, v90, v90
	v_fmac_f32_e32 v131, v92, v92
	v_fmac_f32_e32 v131, v93, v93
	v_add_f32_e32 v130, v131, v130
	v_mul_f32_e32 v131, v95, v95
	v_fmac_f32_e32 v131, v94, v94
	v_cmp_lt_i32_e64 s[6:7], v236, v237
	v_fmac_f32_e32 v131, v96, v96
	v_fmac_f32_e32 v131, v97, v97
	v_cndmask_b32_e64 v0, v238, v236, s[6:7]
	v_lshlrev_b32_e32 v0, 2, v0
	v_add_f32_e32 v132, v131, v130
	ds_bpermute_b32 v133, v0, v132
	s_lshl_b32 s6, s16, 1
	s_lshl_b32 s8, s17, 8
	s_ashr_i32 s7, s6, 31
	s_ashr_i32 s9, s8, 31
	v_lshl_add_u64 v[130:131], s[6:7], 2, v[164:165]
	s_and_saveexec_b64 s[6:7], vcc
	s_cbranch_execz .LBB0_33
	s_waitcnt lgkmcnt(0)
	v_add_f32_e32 v134, v132, v133
	v_mov_b32_e32 v133, s9
	v_or_b32_e32 v132, s8, v162
	v_lshlrev_b64 v[132:133], 6, v[132:133]
	v_lshl_add_u64 v[132:133], v[130:131], 0, v[132:133]
	global_store_dword v[132:133], v134, off

; DI void ph_in_o(const Params& P, int g, bf16_t* smem, float* s_rs) {
;     ...
;   for (int it = 0;; it++) {
;     int mt, nt; if (!tile_sched256(bid, it, 20, 10, mt, nt)) break;
;     const int m0 = mt * 256, n0 = nt * 128;
;     __syncthreads();
;     {
;       const float4* pp = (const float4*)(ssx + (size_t)(m0 + tid) * 16);
;       float4 a = pp[0], b = pp[1], c = pp[2], d = pp[3];
.LBB0_181:
	s_lshl_b32 s86, s29, 8
	v_add_u32_e32 v2, s86, v169
	v_ashrrev_i32_e32 v3, 31, v2
	v_readlane_b32 s2, v253, 45
	v_lshlrev_b64 v[2:3], 6, v[2:3]
	v_readlane_b32 s3, v253, 46
	s_barrier
	s_nop 0
	v_lshl_add_u64 v[14:15], s[2:3], 0, v[2:3]
	global_load_dwordx4 v[220:223], v[14:15], off offset:48
	global_load_dwordx4 v[224:227], v[14:15], off offset:32
	global_load_dwordx4 v[228:231], v[14:15], off offset:16
	s_nop 0
	global_load_dwordx4 v[212:215], v[14:15], off
	s_mov_b32 s2, 0x800000
	s_lshl_b32 s12, s6, 7
	v_readlane_b32 s8, v253, 47
	v_readlane_b32 s9, v253, 48


; DI void ph_in_o(const Params& P, int g, bf16_t* smem, float* s_rs) {
;     ...
;     LoadTile256 la{x2b + (size_t)(2 * mt) * 16 * 8192, 16 * 8192};
	s_lshl_b32 s2, s29, 1
	s_ashr_i32 s3, s2, 31
	s_lshl_b64 s[14:15], s[2:3], 18

; DI void ph_in_o(const Params& P, int g, bf16_t* smem, float* s_rs) {
;     ...
;     LoadTile256 la{x2b + (size_t)(2 * mt) * 16 * 8192, 16 * 8192};
	s_add_u32 s10, s82, s14

; DI void ph_in_o(const Params& P, int g, bf16_t* smem, float* s_rs) {
;     ...
;     LoadTile256 la{x2b + (size_t)(2 * mt) * 16 * 8192, 16 * 8192};
;     const bool isY = (nt >= 8 && nt < 16);
	s_addc_u32 s11, s83, s15
	s_and_b32 s18, s6, -8

; DI void ph_in_o(const Params& P, int g, bf16_t* smem, float* s_rs) {
;     ...
;     const bool isY = (nt >= 8 && nt < 16);
;     gemm256(la, W + (size_t)n0 * 1024, 64, 16, smem, acc, !isY);
	s_cmp_lg_u32 s18, 8
	s_cselect_b64 s[2:3], -1, 0
	s_ashr_i32 s13, s12, 31
	s_lshl_b64 s[16:17], s[12:13], 11
	s_add_u32 s8, s8, s16

; DI void ph_in_o(const Params& P, int g, bf16_t* smem, float* s_rs) {
;     ...
;     gemm256(la, W + (size_t)n0 * 1024, 64, 16, smem, acc, !isY);
	s_addc_u32 s9, s9, s17


; DI void ph_in_o(const Params& P, int g, bf16_t* smem, float* s_rs) {
;     ...
;     const bool isY = (nt >= 8 && nt < 16);
;     gemm256(la, W + (size_t)n0 * 1024, 64, 16, smem, acc, !isY);
;     if (isY) {
	s_cmp_eq_u32 s18, 8
	s_mov_b64 s[18:19], -1

; #define A256_LOADH(kt_, hf_) { a0 = la.ld1(kt_, (hf_) * 4 + 0, tid); a1 = la.ld1(kt_, (hf_) * 4 + 1, tid); a2 = la.ld1(kt_, (hf_) * 4 + 2, tid); a3 = la.ld1(kt_, (hf_) * 4 + 3, tid); }
; #define ZERO_ACC8(a) { _Pragma("unroll") for (int i_ = 0; i_ < 8; i_++) _Pragma("unroll") for (int r_ = 0; r_ < 16; r_++) a[i_][r_] = 0.f; }
; template <bool swap, class LA>
; DI void gemm256_ws(const LA& la, const bf16_t* Wt, const int KS, const int nk, bf16_t* smem, f32x16 (&acc)[8]) {
;     ...
;   A256_LOADH(0, 0) A256_STH(smem, 0)
;   A256_LOADH(0, 1) A256_STH(smem, 1)
;   W256_LD(0, 0, w00, w10) W256_LD(0, 1, w01, w11) W256_LD(0, 2, w02, w12) W256_LD(0, 3, w03, w13)
;   __syncthreads();
;   const int aoff = (tbk * 128 + l32) * LDT + h * 8;
; DI void ph_in_o(const Params& P, int g, bf16_t* smem, float* s_rs) {
;     ...
;     {
;       const float4* pp = (const float4*)(ssx + (size_t)(m0 + tid) * 16);
;       float4 a = pp[0], b = pp[1], c = pp[2], d = pp[3];
;       float s = a.x + a.y + a.z + a.w + b.x + b.y + b.z + b.w + c.x + c.y + c.z + c.w + d.x + d.y + d.z + d.w;
;       s_rs[tid] = rsqrtf(s * (1.f / 1024.f) + EPS);
;     }
;     f32x16 acc[8]; ZERO_ACC8(acc)
;     LoadTile256 la{x2b + (size_t)(2 * mt) * 16 * 8192, 16 * 8192};
;     const bool isY = (nt >= 8 && nt < 16);
;     gemm256(la, W + (size_t)n0 * 1024, 64, 16, smem, acc, !isY);
	s_cbranch_scc1 .LBB0_194
	v_mov_b32_e32 v0, v234
	s_add_u32 s18, s10, 0x40000
	v_lshlrev_b32_e32 v2, 3, v0
	v_ashrrev_i32_e32 v3, 31, v2
	v_ashrrev_i32_e32 v48, 6, v0
	v_lshlrev_b64 v[196:197], 1, v[2:3]
	v_add_u32_e32 v6, 0x800, v2
	v_add_u32_e32 v8, 0x1000, v2
	v_add_u32_e32 v2, 0x1800, v2
	v_lshlrev_b32_e32 v49, 4, v0
	v_and_b32_e32 v48, -2, v48
	v_ashrrev_i32_e32 v3, 31, v2
	v_and_b32_e32 v15, 31, v0
	v_lshrrev_b32_e32 v51, 3, v0
	v_lshlrev_b32_e32 v52, 1, v0
	v_lshrrev_b32_e32 v53, 1, v0
	v_and_b32_e32 v0, 0x3f0, v49
	v_and_b32_e32 v50, 0x70, v49
	v_ashrrev_i32_e32 v49, 31, v48
	v_ashrrev_i32_e32 v7, 31, v6
	v_ashrrev_i32_e32 v9, 31, v8
	v_lshlrev_b64 v[202:203], 1, v[2:3]
	v_lshlrev_b64 v[48:49], 16, v[48:49]
	v_lshl_add_u64 v[4:5], s[10:11], 0, v[196:197]
	v_lshlrev_b64 v[198:199], 1, v[6:7]
	v_lshlrev_b64 v[200:201], 1, v[8:9]
	v_lshl_add_u64 v[2:3], s[10:11], 0, v[202:203]
	s_addc_u32 s19, s11, 0
	v_lshl_add_u64 v[48:49], s[8:9], 0, v[48:49]
	v_lshl_add_u64 v[6:7], s[10:11], 0, v[198:199]
	v_lshl_add_u64 v[8:9], s[10:11], 0, v[200:201]
	global_load_dwordx4 v[16:19], v[4:5], off
	global_load_dwordx4 v[20:23], v[6:7], off
	global_load_dwordx4 v[24:27], v[8:9], off
	global_load_dwordx4 v[28:31], v[2:3], off
	v_lshl_add_u64 v[2:3], s[18:19], 0, v[196:197]
	v_lshl_add_u64 v[206:207], v[48:49], 0, v[0:1]
	global_load_dwordx4 v[32:35], v[2:3], off
	v_lshl_add_u64 v[2:3], s[18:19], 0, v[198:199]
	v_add_co_u32_e32 v48, vcc, s94, v206
	v_lshl_add_u64 v[4:5], s[18:19], 0, v[200:201]
	v_lshl_add_u64 v[6:7], s[18:19], 0, v[202:203]
	global_load_dwordx4 v[36:39], v[2:3], off
	global_load_dwordx4 v[40:43], v[4:5], off
	global_load_dwordx4 v[44:47], v[6:7], off
	v_addc_co_u32_e32 v49, vcc, 0, v207, vcc
	global_load_dwordx4 v[154:157], v[48:49], off
	global_load_dwordx4 v[158:161], v[206:207], off
	global_load_dwordx4 v[146:149], v[48:49], off offset:1024
	global_load_dwordx4 v[150:153], v[206:207], off offset:1024
	global_load_dwordx4 v[142:145], v[48:49], off offset:2048
	global_load_dwordx4 v[138:141], v[206:207], off offset:2048
	global_load_dwordx4 v[130:133], v[48:49], off offset:3072
	global_load_dwordx4 v[134:137], v[206:207], off offset:3072
	s_movk_i32 s36, 0x80
	v_and_or_b32 v15, v52, s36, v15
	v_mad_u64_u32 v[204:205], s[36:37], v51, s0, v[50:51]
	v_mov_b32_e32 v2, 0
	v_and_b32_e32 v52, 16, v53
	s_mov_b64 s[36:37], 0x10000
	s_mov_b32 s13, 0
	v_mov_b32_e32 v3, v2
	v_mov_b32_e32 v4, v2
	v_mov_b32_e32 v5, v2
	v_mov_b32_e32 v6, v2
	v_mov_b32_e32 v7, v2
	v_mov_b32_e32 v8, v2
	v_mov_b32_e32 v9, v2
	v_mov_b32_e32 v10, v2
	v_mov_b32_e32 v11, v2
	v_mov_b32_e32 v12, v2
	v_mov_b32_e32 v13, v2
	v_mov_b32_e32 v14, v2
	v_mad_u32_u24 v195, v15, s0, v52
	v_lshl_add_u64 v[208:209], v[206:207], 0, s[36:37]
	v_mov_b32_e32 v15, v2
	v_mov_b32_e32 v48, v2
	v_mov_b32_e32 v49, v2
	v_mov_b32_e32 v82, v2
	v_mov_b32_e32 v83, v2
	v_mov_b32_e32 v84, v2
	v_mov_b32_e32 v85, v2
	v_mov_b32_e32 v86, v2
	v_mov_b32_e32 v87, v2
	v_mov_b32_e32 v88, v2
	v_mov_b32_e32 v89, v2
	v_mov_b32_e32 v90, v2
	v_mov_b32_e32 v91, v2
	v_mov_b32_e32 v92, v2
	v_mov_b32_e32 v93, v2
	v_mov_b32_e32 v94, v2
	v_mov_b32_e32 v95, v2
	v_mov_b32_e32 v96, v2
	v_mov_b32_e32 v97, v2
	v_mov_b32_e32 v50, v2
	v_mov_b32_e32 v51, v2
	v_mov_b32_e32 v52, v2
	s_waitcnt vmcnt(16)
	v_add_f32_e32 v232, v212, v213
	v_add_f32_e32 v232, v232, v214
	v_add_f32_e32 v232, v232, v215
	v_add_f32_e32 v232, v232, v228
	v_add_f32_e32 v232, v232, v229
	v_add_f32_e32 v232, v232, v230
	v_add_f32_e32 v232, v232, v231
	v_add_f32_e32 v232, v232, v224
	v_add_f32_e32 v232, v232, v225
	v_add_f32_e32 v232, v232, v226
	v_add_f32_e32 v232, v232, v227
	v_add_f32_e32 v232, v232, v220
	v_add_f32_e32 v232, v232, v221
	v_add_f32_e32 v232, v232, v222
	v_add_f32_e32 v232, v232, v223
	v_fmamk_f32 v232, v232, 0x3a800000, v235
	v_cmp_gt_f32_e32 vcc, 0x800000, v232
	v_mul_f32_e32 v233, 0x4b800000, v232
	s_nop 1
	v_cndmask_b32_e32 v232, v232, v233, vcc
	v_rsq_f32_e32 v232, v232
	v_lshl_add_u32 v212, v169, 2, v244
	v_mul_f32_e32 v233, 0x45800000, v232
	v_cndmask_b32_e32 v232, v232, v233, vcc
	ds_write_b32 v212, v232
	s_waitcnt vmcnt(15)
	ds_write_b128 v204, v[16:19]
	s_waitcnt vmcnt(11)
	ds_write_b128 v204, v[32:35] offset:18432
	ds_write_b128 v204, v[20:23] offset:4608
	ds_write_b128 v204, v[24:27] offset:9216
	ds_write_b128 v204, v[28:31] offset:13824
	s_waitcnt vmcnt(10)
	ds_write_b128 v204, v[36:39] offset:23040
	s_waitcnt vmcnt(9)
	ds_write_b128 v204, v[40:43] offset:27648
	s_waitcnt vmcnt(8)
	ds_write_b128 v204, v[44:47] offset:32256
	v_mov_b32_e32 v16, v2
	v_mov_b32_e32 v17, v2
	v_mov_b32_e32 v34, v2
	v_mov_b32_e32 v35, v2
	v_mov_b32_e32 v36, v2
	v_mov_b32_e32 v37, v2
	v_mov_b32_e32 v38, v2
	v_mov_b32_e32 v39, v2
	v_mov_b32_e32 v40, v2
	v_mov_b32_e32 v41, v2
	v_mov_b32_e32 v42, v2
	v_mov_b32_e32 v43, v2
	v_mov_b32_e32 v44, v2
	v_mov_b32_e32 v45, v2
	v_mov_b32_e32 v46, v2
	v_mov_b32_e32 v47, v2
	v_mov_b32_e32 v18, v2
	v_mov_b32_e32 v19, v2
	v_mov_b32_e32 v20, v2
	v_mov_b32_e32 v21, v2
	v_mov_b32_e32 v22, v2
	v_mov_b32_e32 v23, v2
	v_mov_b32_e32 v24, v2
	v_mov_b32_e32 v25, v2
	v_mov_b32_e32 v26, v2
	v_mov_b32_e32 v27, v2
	v_mov_b32_e32 v28, v2
	v_mov_b32_e32 v29, v2
	v_mov_b32_e32 v30, v2
	v_mov_b32_e32 v31, v2
	v_mov_b32_e32 v32, v2
	v_mov_b32_e32 v33, v2
	v_mov_b32_e32 v53, v2
	v_mov_b32_e32 v54, v2
	v_mov_b32_e32 v55, v2
	v_mov_b32_e32 v56, v2
	v_mov_b32_e32 v57, v2
	v_mov_b32_e32 v58, v2
	v_mov_b32_e32 v59, v2
	v_mov_b32_e32 v60, v2
	v_mov_b32_e32 v61, v2
	v_mov_b32_e32 v62, v2
	v_mov_b32_e32 v63, v2
	v_mov_b32_e32 v64, v2
	v_mov_b32_e32 v65, v2
	v_mov_b32_e32 v98, v2
	v_mov_b32_e32 v99, v2
	v_mov_b32_e32 v100, v2
	v_mov_b32_e32 v101, v2
	v_mov_b32_e32 v102, v2
	v_mov_b32_e32 v103, v2
	v_mov_b32_e32 v104, v2
	v_mov_b32_e32 v105, v2
	v_mov_b32_e32 v106, v2
	v_mov_b32_e32 v107, v2
	v_mov_b32_e32 v108, v2
	v_mov_b32_e32 v109, v2
	v_mov_b32_e32 v110, v2
	v_mov_b32_e32 v111, v2
	v_mov_b32_e32 v112, v2
	v_mov_b32_e32 v113, v2
	v_mov_b32_e32 v66, v2
	v_mov_b32_e32 v67, v2
	v_mov_b32_e32 v68, v2
	v_mov_b32_e32 v69, v2
	v_mov_b32_e32 v70, v2
	v_mov_b32_e32 v71, v2
	v_mov_b32_e32 v72, v2
	v_mov_b32_e32 v73, v2
	v_mov_b32_e32 v74, v2
	v_mov_b32_e32 v75, v2
	v_mov_b32_e32 v76, v2
	v_mov_b32_e32 v77, v2
	v_mov_b32_e32 v78, v2
	v_mov_b32_e32 v79, v2
	v_mov_b32_e32 v80, v2
	v_mov_b32_e32 v81, v2
	v_mov_b32_e32 v114, v2
	v_mov_b32_e32 v115, v2
	v_mov_b32_e32 v116, v2
	v_mov_b32_e32 v117, v2
	v_mov_b32_e32 v118, v2
	v_mov_b32_e32 v119, v2
	v_mov_b32_e32 v120, v2
	v_mov_b32_e32 v121, v2
	v_mov_b32_e32 v122, v2
	v_mov_b32_e32 v123, v2
	v_mov_b32_e32 v124, v2
	v_mov_b32_e32 v125, v2
	v_mov_b32_e32 v126, v2
	v_mov_b32_e32 v127, v2
	v_mov_b32_e32 v128, v2
	v_mov_b32_e32 v129, v2
	s_waitcnt lgkmcnt(0)
	s_barrier
	s_and_b32 s36, s13, 1
	s_mul_i32 s37, s36, 0x9000
	v_add_u32_e32 v0, s37, v195
; #define A256_LOADH(kt_, hf_) { a0 = la.ld1(kt_, (hf_) * 4 + 0, tid); a1 = la.ld1(kt_, (hf_) * 4 + 1, tid); a2 = la.ld1(kt_, (hf_) * 4 + 2, tid); a3 = la.ld1(kt_, (hf_) * 4 + 3, tid); }
; template <bool swap, class LA>
; DI void gemm256_ws(const LA& la, const bf16_t* Wt, const int KS, const int nk, bf16_t* smem, f32x16 (&acc)[8]) {
;     ...
;   for (int kt = 0; kt < nk; kt++) {
;     const int cur = kt & 1; const int kn = (kt + 1 < nk) ? kt + 1 : last;
;     const bf16_t* sp = smem + cur * ATILE_E + aoff;
;     bf16_t* nxt = smem + (cur ^ 1) * ATILE_E;
;     A256_LOADH(kn, 0)
;     MMA256(0, w00, w10) W256_LD(kn, 0, w00, w10)
;     MMA256(1, w01, w11) W256_LD(kn, 1, w01, w11)
;     A256_STH(nxt, 0)
;     A256_LOADH(kn, 1)
;     MMA256(2, w02, w12) W256_LD(kn, 2, w02, w12)
;     MMA256(3, w03, w13) W256_LD(kn, 3, w03, w13)
;     A256_STH(nxt, 1)
;     __syncthreads();
;   }
.LBB0_183:
	ds_read_b128 v[210:213], v0
	ds_read_b128 v[214:217], v0 offset:4608
	ds_read_b128 v[220:223], v0 offset:9216
	s_and_b32 s36, s13, 1
	s_add_i32 s13, s13, 1
	s_min_u32 s38, s13, 15
	s_xor_b32 s36, s36, 1
	s_mul_i32 s37, s36, 0x9000
	v_add_u32_e32 v205, s37, v204
	s_lshl_b32 s39, s38, 14
	s_lshl_b32 s90, s38, 12
	s_add_u32 s36, s10, s39
	s_addc_u32 s37, s11, 0
	v_lshl_add_u64 v[224:225], s[36:37], 0, v[196:197]
	s_add_u32 s36, s36, 0x1000
	s_addc_u32 s37, s37, 0
	v_lshl_add_u64 v[228:229], s[36:37], 0, v[196:197]
	s_add_u32 s36, s36, 0x1000
	s_addc_u32 s37, s37, 0
	v_lshl_add_u64 v[246:247], s[36:37], 0, v[196:197]
	s_add_u32 s36, s36, 0x1000
	s_addc_u32 s37, s37, 0
	v_lshl_add_u64 v[198:199], s[36:37], 0, v[196:197]
	global_load_dwordx4 v[224:227], v[224:225], off
	global_load_dwordx4 v[228:231], v[228:229], off
	global_load_dwordx4 v[246:249], v[246:247], off
	global_load_dwordx4 v[198:201], v[198:199], off
	s_waitcnt vmcnt(10) lgkmcnt(2)
	v_mfma_f32_32x32x16_bf16 v[82:97], v[154:157], v[210:213], v[82:97]
	v_mfma_f32_32x32x16_bf16 v[114:129], v[158:161], v[210:213], v[114:129]
	ds_read_b128 v[210:213], v0 offset:13824
	s_waitcnt lgkmcnt(2)
	v_mfma_f32_32x32x16_bf16 v[18:33], v[154:157], v[214:217], v[18:33]
	v_mfma_f32_32x32x16_bf16 v[66:81], v[158:161], v[214:217], v[66:81]
	ds_read_b128 v[214:217], v0 offset:32
	s_waitcnt lgkmcnt(2)
	v_mfma_f32_32x32x16_bf16 v[34:49], v[154:157], v[220:223], v[34:49]
	v_mfma_f32_32x32x16_bf16 v[98:113], v[158:161], v[220:223], v[98:113]
	ds_read_b128 v[220:223], v0 offset:4640
	s_waitcnt lgkmcnt(2)
	v_mfma_f32_32x32x16_bf16 v[2:17], v[154:157], v[210:213], v[2:17]
	v_mfma_f32_32x32x16_bf16 v[50:65], v[158:161], v[210:213], v[50:65]
	ds_read_b128 v[210:213], v0 offset:9248
	v_lshl_add_u64 v[154:155], v[208:209], 0, s[90:91]
	global_load_dwordx4 v[154:157], v[154:155], off
	v_lshl_add_u64 v[158:159], v[206:207], 0, s[90:91]
	global_load_dwordx4 v[158:161], v[158:159], off
	s_waitcnt vmcnt(10) lgkmcnt(2)
	v_mfma_f32_32x32x16_bf16 v[82:97], v[146:149], v[214:217], v[82:97]
	v_mfma_f32_32x32x16_bf16 v[114:129], v[150:153], v[214:217], v[114:129]
	ds_read_b128 v[214:217], v0 offset:13856
	s_waitcnt lgkmcnt(2)
	v_mfma_f32_32x32x16_bf16 v[18:33], v[146:149], v[220:223], v[18:33]
	v_mfma_f32_32x32x16_bf16 v[66:81], v[150:153], v[220:223], v[66:81]
	ds_read_b128 v[220:223], v0 offset:64
	s_waitcnt lgkmcnt(2)
	v_mfma_f32_32x32x16_bf16 v[34:49], v[146:149], v[210:213], v[34:49]
	v_mfma_f32_32x32x16_bf16 v[98:113], v[150:153], v[210:213], v[98:113]
	ds_read_b128 v[210:213], v0 offset:4672
	s_waitcnt lgkmcnt(2)
	v_mfma_f32_32x32x16_bf16 v[2:17], v[146:149], v[214:217], v[2:17]
	v_mfma_f32_32x32x16_bf16 v[50:65], v[150:153], v[214:217], v[50:65]
	ds_read_b128 v[214:217], v0 offset:9280
	v_lshl_add_u64 v[146:147], v[208:209], 0, s[90:91]
	global_load_dwordx4 v[146:149], v[146:147], off offset:1024
	v_lshl_add_u64 v[150:151], v[206:207], 0, s[90:91]
	global_load_dwordx4 v[150:153], v[150:151], off offset:1024
	s_waitcnt vmcnt(4)
	ds_write_b128 v205, v[224:227]
	ds_write_b128 v205, v[228:231] offset:4608
	ds_write_b128 v205, v[246:249] offset:9216
	ds_write_b128 v205, v[198:201] offset:13824
	s_add_u32 s36, s18, s39
	s_addc_u32 s37, s19, 0
	v_lshl_add_u64 v[224:225], s[36:37], 0, v[196:197]
	s_add_u32 s36, s36, 0x1000
	s_addc_u32 s37, s37, 0
	v_lshl_add_u64 v[228:229], s[36:37], 0, v[196:197]
	s_add_u32 s36, s36, 0x1000
	s_addc_u32 s37, s37, 0
	v_lshl_add_u64 v[246:247], s[36:37], 0, v[196:197]
	s_add_u32 s36, s36, 0x1000
	s_addc_u32 s37, s37, 0
	v_lshl_add_u64 v[198:199], s[36:37], 0, v[196:197]
	global_load_dwordx4 v[224:227], v[224:225], off
	global_load_dwordx4 v[228:231], v[228:229], off
	global_load_dwordx4 v[246:249], v[246:247], off
	global_load_dwordx4 v[198:201], v[198:199], off
	s_waitcnt lgkmcnt(6)
	v_mfma_f32_32x32x16_bf16 v[82:97], v[142:145], v[220:223], v[82:97]
	v_mfma_f32_32x32x16_bf16 v[114:129], v[138:141], v[220:223], v[114:129]
	ds_read_b128 v[220:223], v0 offset:13888
	s_waitcnt lgkmcnt(6)
	v_mfma_f32_32x32x16_bf16 v[18:33], v[142:145], v[210:213], v[18:33]
	v_mfma_f32_32x32x16_bf16 v[66:81], v[138:141], v[210:213], v[66:81]
	ds_read_b128 v[210:213], v0 offset:96
	s_waitcnt lgkmcnt(6)
	v_mfma_f32_32x32x16_bf16 v[34:49], v[142:145], v[214:217], v[34:49]
	v_mfma_f32_32x32x16_bf16 v[98:113], v[138:141], v[214:217], v[98:113]
	ds_read_b128 v[214:217], v0 offset:4704
	s_waitcnt lgkmcnt(2)
	v_mfma_f32_32x32x16_bf16 v[2:17], v[142:145], v[220:223], v[2:17]
	v_mfma_f32_32x32x16_bf16 v[50:65], v[138:141], v[220:223], v[50:65]
	ds_read_b128 v[220:223], v0 offset:9312
	v_lshl_add_u64 v[142:143], v[208:209], 0, s[90:91]
	global_load_dwordx4 v[142:145], v[142:143], off offset:2048
	v_lshl_add_u64 v[138:139], v[206:207], 0, s[90:91]
	global_load_dwordx4 v[138:141], v[138:139], off offset:2048
	s_waitcnt lgkmcnt(2)
	v_mfma_f32_32x32x16_bf16 v[82:97], v[130:133], v[210:213], v[82:97]
	v_mfma_f32_32x32x16_bf16 v[114:129], v[134:137], v[210:213], v[114:129]
	ds_read_b128 v[210:213], v0 offset:13920
	s_waitcnt lgkmcnt(2)
	v_mfma_f32_32x32x16_bf16 v[18:33], v[130:133], v[214:217], v[18:33]
	v_mfma_f32_32x32x16_bf16 v[66:81], v[134:137], v[214:217], v[66:81]
	s_waitcnt lgkmcnt(1)
	v_mfma_f32_32x32x16_bf16 v[34:49], v[130:133], v[220:223], v[34:49]
	v_mfma_f32_32x32x16_bf16 v[98:113], v[134:137], v[220:223], v[98:113]
	s_waitcnt lgkmcnt(0)
	v_mfma_f32_32x32x16_bf16 v[2:17], v[130:133], v[210:213], v[2:17]
	v_mfma_f32_32x32x16_bf16 v[50:65], v[134:137], v[210:213], v[50:65]
	v_lshl_add_u64 v[130:131], v[208:209], 0, s[90:91]
	global_load_dwordx4 v[130:133], v[130:131], off offset:3072
	v_lshl_add_u64 v[134:135], v[206:207], 0, s[90:91]
	global_load_dwordx4 v[134:137], v[134:135], off offset:3072
	s_waitcnt vmcnt(4)
	ds_write_b128 v205, v[224:227] offset:18432
	ds_write_b128 v205, v[228:231] offset:23040
	ds_write_b128 v205, v[246:249] offset:27648
	ds_write_b128 v205, v[198:201] offset:32256
	s_and_b32 s36, s13, 1
	s_mul_i32 s36, s36, 0x9000
	v_add_u32_e32 v0, s36, v195
	s_cmp_eq_u32 s13, 16
	s_waitcnt lgkmcnt(0)
	s_barrier
	s_cbranch_scc0 .LBB0_183
	s_waitcnt vmcnt(0)

; #define A256_LOADH(kt_, hf_) { a0 = la.ld1(kt_, (hf_) * 4 + 0, tid); a1 = la.ld1(kt_, (hf_) * 4 + 1, tid); a2 = la.ld1(kt_, (hf_) * 4 + 2, tid); a3 = la.ld1(kt_, (hf_) * 4 + 3, tid); }
; template <bool swap, class LA>
; DI void gemm256_ws(const LA& la, const bf16_t* Wt, const int KS, const int nk, bf16_t* smem, f32x16 (&acc)[8]) {
;     ...
;   A256_LOADH(0, 0) A256_STH(smem, 0)
;   A256_LOADH(0, 1) A256_STH(smem, 1)
;   W256_LD(0, 0, w00, w10) W256_LD(0, 1, w01, w11) W256_LD(0, 2, w02, w12) W256_LD(0, 3, w03, w13)
;   __syncthreads();
;   const int aoff = (tbk * 128 + l32) * LDT + h * 8;
; DI void ph_in_o(const Params& P, int g, bf16_t* smem, float* s_rs) {
;     ...
;     LoadTile256 la{x2b + (size_t)(2 * mt) * 16 * 8192, 16 * 8192};
;     const bool isY = (nt >= 8 && nt < 16);
;     gemm256(la, W + (size_t)n0 * 1024, 64, 16, smem, acc, !isY);
.LBB0_194:
	s_and_b64 vcc, exec, s[18:19]
	s_cbranch_vccz .LBB0_185
	v_mov_b32_e32 v0, v234
	s_add_u32 s18, s10, 0x40000
	v_lshlrev_b32_e32 v2, 3, v0
	v_ashrrev_i32_e32 v3, 31, v2
	v_lshlrev_b64 v[196:197], 1, v[2:3]
	v_add_u32_e32 v6, 0x800, v2
	v_add_u32_e32 v8, 0x1000, v2
	v_add_u32_e32 v2, 0x1800, v2
	v_lshlrev_b32_e32 v42, 11, v0
	v_ashrrev_i32_e32 v3, 31, v2
	v_lshlrev_b32_e32 v44, 4, v0
	v_lshrrev_b32_e32 v45, 3, v0
	v_and_b32_e32 v47, 0xfffff9f, v0
	v_lshrrev_b32_e32 v46, 1, v0
	v_and_b32_e32 v50, 63, v0
	v_and_b32_e32 v0, 0x20000, v42
	v_ashrrev_i32_e32 v7, 31, v6
	v_ashrrev_i32_e32 v9, 31, v8
	v_lshlrev_b64 v[202:203], 1, v[2:3]
	v_mov_b32_e32 v43, v1
	v_and_b32_e32 v42, 0x3f0, v44
	v_and_b32_e32 v44, 0x70, v44
	v_lshl_add_u64 v[48:49], s[8:9], 0, v[0:1]
	v_lshl_add_u64 v[4:5], s[10:11], 0, v[196:197]
	v_lshlrev_b64 v[198:199], 1, v[6:7]
	v_lshlrev_b64 v[200:201], 1, v[8:9]
	v_lshl_add_u64 v[2:3], s[10:11], 0, v[202:203]
	s_addc_u32 s19, s11, 0
	v_mad_u64_u32 v[204:205], s[8:9], v45, s0, v[44:45]
	v_lshl_add_u64 v[44:45], v[0:1], 0, s[16:17]
	v_lshlrev_b32_e32 v0, 4, v50
	v_lshl_add_u64 v[42:43], v[48:49], 0, v[42:43]
	v_lshl_add_u64 v[6:7], s[10:11], 0, v[198:199]
	v_lshl_add_u64 v[8:9], s[10:11], 0, v[200:201]
	global_load_dwordx4 v[10:13], v[4:5], off
	global_load_dwordx4 v[14:17], v[6:7], off
	global_load_dwordx4 v[18:21], v[8:9], off
	global_load_dwordx4 v[22:25], v[2:3], off
	v_lshl_add_u64 v[2:3], s[18:19], 0, v[196:197]
	v_lshl_add_u64 v[208:209], v[44:45], 0, v[0:1]
	v_add_co_u32_e32 v44, vcc, s94, v42
	global_load_dwordx4 v[26:29], v[2:3], off
	v_lshl_add_u64 v[2:3], s[18:19], 0, v[198:199]
	v_addc_co_u32_e32 v45, vcc, 0, v43, vcc
	v_lshl_add_u64 v[4:5], s[18:19], 0, v[200:201]
	v_lshl_add_u64 v[6:7], s[18:19], 0, v[202:203]
	global_load_dwordx4 v[30:33], v[2:3], off
	global_load_dwordx4 v[34:37], v[4:5], off
	global_load_dwordx4 v[38:41], v[6:7], off
	global_load_dwordx4 v[154:157], v[42:43], off
	global_load_dwordx4 v[158:161], v[44:45], off
	global_load_dwordx4 v[150:153], v[42:43], off offset:1024
	global_load_dwordx4 v[146:149], v[44:45], off offset:1024
	global_load_dwordx4 v[138:141], v[42:43], off offset:2048
	global_load_dwordx4 v[142:145], v[44:45], off offset:2048
	global_load_dwordx4 v[134:137], v[42:43], off offset:3072
	global_load_dwordx4 v[130:133], v[44:45], off offset:3072
	v_mov_b32_e32 v232, v42
	v_mov_b32_e32 v233, v43
	v_mov_b32_e32 v2, 0
	v_and_b32_e32 v46, 16, v46
	v_mov_b32_e32 v219, 0x12000
	s_mov_b32 s13, 0
	v_mov_b32_e32 v3, v2
	v_mov_b32_e32 v4, v2
	v_mov_b32_e32 v5, v2
	v_mov_b32_e32 v6, v2
	v_mov_b32_e32 v7, v2
	v_mov_b32_e32 v8, v2
	v_mov_b32_e32 v9, v2
	v_mad_u64_u32 v[206:207], s[8:9], v47, s0, v[46:47]


; #define A256_LOADH(kt_, hf_) { a0 = la.ld1(kt_, (hf_) * 4 + 0, tid); a1 = la.ld1(kt_, (hf_) * 4 + 1, tid); a2 = la.ld1(kt_, (hf_) * 4 + 2, tid); a3 = la.ld1(kt_, (hf_) * 4 + 3, tid); }
; template <bool swap, class LA>
; DI void gemm256_ws(const LA& la, const bf16_t* Wt, const int KS, const int nk, bf16_t* smem, f32x16 (&acc)[8]) {
;     ...
;   A256_LOADH(0, 0) A256_STH(smem, 0)
;   A256_LOADH(0, 1) A256_STH(smem, 1)
;   W256_LD(0, 0, w00, w10) W256_LD(0, 1, w01, w11) W256_LD(0, 2, w02, w12) W256_LD(0, 3, w03, w13)
;   __syncthreads();
;   const int aoff = (tbk * 128 + l32) * LDT + h * 8;
;   for (int kt = 0; kt < nk; kt++) {
;     const int cur = kt & 1; const int kn = (kt + 1 < nk) ? kt + 1 : last;
;     const bf16_t* sp = smem + cur * ATILE_E + aoff;
;     bf16_t* nxt = smem + (cur ^ 1) * ATILE_E;
;     A256_LOADH(kn, 0)
;     MMA256(0, w00, w10) W256_LD(kn, 0, w00, w10)
;     MMA256(1, w01, w11) W256_LD(kn, 1, w01, w11)
;     A256_STH(nxt, 0)
;     A256_LOADH(kn, 1)
;     MMA256(2, w02, w12) W256_LD(kn, 2, w02, w12)
;     MMA256(3, w03, w13) W256_LD(kn, 3, w03, w13)
;     A256_STH(nxt, 1)
;     __syncthreads();
;   }
; DI void ph_in_o(const Params& P, int g, bf16_t* smem, float* s_rs) {
;     ...
;     {
;       const float4* pp = (const float4*)(ssx + (size_t)(m0 + tid) * 16);
;       float4 a = pp[0], b = pp[1], c = pp[2], d = pp[3];
;       float s = a.x + a.y + a.z + a.w + b.x + b.y + b.z + b.w + c.x + c.y + c.z + c.w + d.x + d.y + d.z + d.w;
;       s_rs[tid] = rsqrtf(s * (1.f / 1024.f) + EPS);
	v_mov_b32_e32 v42, v2
	v_mov_b32_e32 v43, v2
	v_mov_b32_e32 v44, v2
	v_mov_b32_e32 v45, v2
	v_mov_b32_e32 v46, v2
	v_mov_b32_e32 v47, v2
	v_mov_b32_e32 v48, v2
	v_mov_b32_e32 v49, v2
	v_mov_b32_e32 v82, v2
	v_mov_b32_e32 v83, v2
	v_mov_b32_e32 v84, v2
	v_mov_b32_e32 v85, v2
	v_mov_b32_e32 v86, v2
	v_mov_b32_e32 v87, v2
	v_mov_b32_e32 v88, v2
	v_mov_b32_e32 v89, v2
	v_mov_b32_e32 v90, v2
	v_mov_b32_e32 v91, v2
	v_mov_b32_e32 v92, v2
	v_mov_b32_e32 v93, v2
	v_mov_b32_e32 v94, v2
	v_mov_b32_e32 v95, v2
	s_waitcnt vmcnt(16)
	v_add_f32_e32 v216, v212, v213
	v_add_f32_e32 v216, v216, v214
	v_add_f32_e32 v216, v216, v215
	v_add_f32_e32 v216, v216, v228
	v_add_f32_e32 v216, v216, v229
	v_add_f32_e32 v216, v216, v230
	v_add_f32_e32 v216, v216, v231
	v_add_f32_e32 v216, v216, v224
	v_add_f32_e32 v216, v216, v225
	v_add_f32_e32 v216, v216, v226
	v_add_f32_e32 v216, v216, v227
	v_add_f32_e32 v216, v216, v220
	v_add_f32_e32 v216, v216, v221
	v_add_f32_e32 v216, v216, v222
	v_add_f32_e32 v216, v216, v223
	v_fmamk_f32 v216, v216, 0x3a800000, v235
	v_cmp_gt_f32_e32 vcc, 0x800000, v216
	v_mul_f32_e32 v217, 0x4b800000, v216
	s_nop 1
	v_cndmask_b32_e32 v216, v216, v217, vcc
	v_rsq_f32_e32 v216, v216
	v_lshl_add_u32 v212, v169, 2, v244
	v_mul_f32_e32 v217, 0x45800000, v216
	v_cndmask_b32_e32 v216, v216, v217, vcc
	ds_write_b32 v212, v216
	s_waitcnt vmcnt(15)
	ds_write_b128 v204, v[10:13]
	s_waitcnt vmcnt(11)
	ds_write_b128 v204, v[26:29] offset:18432
	ds_write_b128 v204, v[14:17] offset:4608
	ds_write_b128 v204, v[18:21] offset:9216
	ds_write_b128 v204, v[22:25] offset:13824
	s_waitcnt vmcnt(10)
	ds_write_b128 v204, v[30:33] offset:23040
	s_waitcnt vmcnt(9)
	ds_write_b128 v204, v[34:37] offset:27648
	s_waitcnt vmcnt(8)
	ds_write_b128 v204, v[38:41] offset:32256
	v_mov_b32_e32 v10, v2
	v_mov_b32_e32 v11, v2
	v_mov_b32_e32 v12, v2
	v_mov_b32_e32 v13, v2
	v_mov_b32_e32 v14, v2
	v_mov_b32_e32 v15, v2
	v_mov_b32_e32 v16, v2
	v_mov_b32_e32 v17, v2
	v_mov_b32_e32 v34, v2
	v_mov_b32_e32 v35, v2
	v_mov_b32_e32 v36, v2
	v_mov_b32_e32 v37, v2
	v_mov_b32_e32 v38, v2
	v_mov_b32_e32 v39, v2
	v_mov_b32_e32 v40, v2
	v_mov_b32_e32 v41, v2
	v_mov_b32_e32 v18, v2
	v_mov_b32_e32 v19, v2
	v_mov_b32_e32 v20, v2
	v_mov_b32_e32 v21, v2
	v_mov_b32_e32 v22, v2
	v_mov_b32_e32 v23, v2
	v_mov_b32_e32 v24, v2
	v_mov_b32_e32 v25, v2
	v_mov_b32_e32 v26, v2
	v_mov_b32_e32 v27, v2
	v_mov_b32_e32 v28, v2
	v_mov_b32_e32 v29, v2
	v_mov_b32_e32 v30, v2
	v_mov_b32_e32 v31, v2
	v_mov_b32_e32 v32, v2
	v_mov_b32_e32 v33, v2
	v_mov_b32_e32 v96, v2
	v_mov_b32_e32 v97, v2
	v_mov_b32_e32 v50, v2
	v_mov_b32_e32 v51, v2
	v_mov_b32_e32 v52, v2
	v_mov_b32_e32 v53, v2
	v_mov_b32_e32 v54, v2
	v_mov_b32_e32 v55, v2
	v_mov_b32_e32 v56, v2
	v_mov_b32_e32 v57, v2
	v_mov_b32_e32 v58, v2
	v_mov_b32_e32 v59, v2
	v_mov_b32_e32 v60, v2
	v_mov_b32_e32 v61, v2
	v_mov_b32_e32 v62, v2
	v_mov_b32_e32 v63, v2
	v_mov_b32_e32 v64, v2
	v_mov_b32_e32 v65, v2
	v_mov_b32_e32 v98, v2
	v_mov_b32_e32 v99, v2
	v_mov_b32_e32 v100, v2
	v_mov_b32_e32 v101, v2
	v_mov_b32_e32 v102, v2
	v_mov_b32_e32 v103, v2
	v_mov_b32_e32 v104, v2
	v_mov_b32_e32 v105, v2
	v_mov_b32_e32 v106, v2
	v_mov_b32_e32 v107, v2
	v_mov_b32_e32 v108, v2
	v_mov_b32_e32 v109, v2
	v_mov_b32_e32 v110, v2
	v_mov_b32_e32 v111, v2
	v_mov_b32_e32 v112, v2
	v_mov_b32_e32 v113, v2
	v_mov_b32_e32 v66, v2
	v_mov_b32_e32 v67, v2
	v_mov_b32_e32 v68, v2
	v_mov_b32_e32 v69, v2
	v_mov_b32_e32 v70, v2
	v_mov_b32_e32 v71, v2
	v_mov_b32_e32 v72, v2
	v_mov_b32_e32 v73, v2
	v_mov_b32_e32 v74, v2
	v_mov_b32_e32 v75, v2
	v_mov_b32_e32 v76, v2
	v_mov_b32_e32 v77, v2
	v_mov_b32_e32 v78, v2
	v_mov_b32_e32 v79, v2
	v_mov_b32_e32 v80, v2
	v_mov_b32_e32 v81, v2
	v_mov_b32_e32 v114, v2
	v_mov_b32_e32 v115, v2
	v_mov_b32_e32 v116, v2
	v_mov_b32_e32 v117, v2
	v_mov_b32_e32 v118, v2
	v_mov_b32_e32 v119, v2
	v_mov_b32_e32 v120, v2
	v_mov_b32_e32 v121, v2
	v_mov_b32_e32 v122, v2
	v_mov_b32_e32 v123, v2
	v_mov_b32_e32 v124, v2
	v_mov_b32_e32 v125, v2
	v_mov_b32_e32 v126, v2
	v_mov_b32_e32 v127, v2
	v_mov_b32_e32 v128, v2
	v_mov_b32_e32 v129, v2
	s_waitcnt lgkmcnt(0)
	s_barrier
	s_and_b32 s36, s13, 1
	s_mul_i32 s37, s36, 0x9000
	v_add_u32_e32 v0, s37, v206
.LBB0_196:
	ds_read_b128 v[220:223], v0
	ds_read_b128 v[224:227], v0 offset:4608
	ds_read_b128 v[228:231], v0 offset:9216
	s_and_b32 s36, s13, 1
	s_add_i32 s13, s13, 1
	s_min_u32 s38, s13, 15
	s_xor_b32 s36, s36, 1
	s_mul_i32 s37, s36, 0x9000
	v_add_u32_e32 v195, s37, v204
	s_lshl_b32 s39, s38, 14
	s_lshl_b32 s90, s38, 12
	s_add_u32 s8, s90, 0x10000
	s_mov_b32 s9, 0
	s_add_u32 s36, s10, s39
	s_addc_u32 s37, s11, 0
	v_lshl_add_u64 v[208:209], s[36:37], 0, v[196:197]
	v_lshl_add_u64 v[212:213], s[36:37], 0, v[198:199]
	v_lshl_add_u64 v[244:245], s[36:37], 0, v[200:201]
	v_lshl_add_u64 v[248:249], s[36:37], 0, v[202:203]
	global_load_dwordx4 v[208:211], v[208:209], off
	global_load_dwordx4 v[212:215], v[212:213], off
	global_load_dwordx4 v[244:247], v[244:245], off
	global_load_dwordx4 v[248:251], v[248:249], off
	s_waitcnt vmcnt(10) lgkmcnt(2)
	v_mfma_f32_32x32x16_bf16 v[114:129], v[220:223], v[154:157], v[114:129]
	v_mfma_f32_32x32x16_bf16 v[66:81], v[220:223], v[158:161], v[66:81]
	ds_read_b128 v[220:223], v0 offset:13824
	s_waitcnt lgkmcnt(2)
	v_mfma_f32_32x32x16_bf16 v[98:113], v[224:227], v[154:157], v[98:113]
	v_mfma_f32_32x32x16_bf16 v[50:65], v[224:227], v[158:161], v[50:65]
	ds_read_b128 v[224:227], v0 offset:32
	s_waitcnt lgkmcnt(2)
	v_mfma_f32_32x32x16_bf16 v[82:97], v[228:231], v[154:157], v[82:97]
	v_mfma_f32_32x32x16_bf16 v[18:33], v[228:231], v[158:161], v[18:33]
	ds_read_b128 v[228:231], v0 offset:4640
	s_waitcnt lgkmcnt(2)
; #define A256_LOADH(kt_, hf_) { a0 = la.ld1(kt_, (hf_) * 4 + 0, tid); a1 = la.ld1(kt_, (hf_) * 4 + 1, tid); a2 = la.ld1(kt_, (hf_) * 4 + 2, tid); a3 = la.ld1(kt_, (hf_) * 4 + 3, tid); }
; template <bool swap, class LA>
; DI void gemm256_ws(const LA& la, const bf16_t* Wt, const int KS, const int nk, bf16_t* smem, f32x16 (&acc)[8]) {
;     ...
;   for (int kt = 0; kt < nk; kt++) {
;     const int cur = kt & 1; const int kn = (kt + 1 < nk) ? kt + 1 : last;
;     const bf16_t* sp = smem + cur * ATILE_E + aoff;
;     bf16_t* nxt = smem + (cur ^ 1) * ATILE_E;
;     A256_LOADH(kn, 0)
;     MMA256(0, w00, w10) W256_LD(kn, 0, w00, w10)
;     MMA256(1, w01, w11) W256_LD(kn, 1, w01, w11)
;     A256_STH(nxt, 0)
;     A256_LOADH(kn, 1)
;     MMA256(2, w02, w12) W256_LD(kn, 2, w02, w12)
;     MMA256(3, w03, w13) W256_LD(kn, 3, w03, w13)
;     A256_STH(nxt, 1)
;     __syncthreads();
;   }
	v_mfma_f32_32x32x16_bf16 v[34:49], v[220:223], v[154:157], v[34:49]
	v_mfma_f32_32x32x16_bf16 v[2:17], v[220:223], v[158:161], v[2:17]
	ds_read_b128 v[220:223], v0 offset:9248
	v_lshl_add_u64 v[154:155], v[232:233], 0, s[90:91]
	global_load_dwordx4 v[154:157], v[154:155], off
	v_lshl_add_u64 v[158:159], v[232:233], 0, s[8:9]
	global_load_dwordx4 v[158:161], v[158:159], off
	s_waitcnt vmcnt(10) lgkmcnt(2)
	v_mfma_f32_32x32x16_bf16 v[114:129], v[224:227], v[150:153], v[114:129]
	v_mfma_f32_32x32x16_bf16 v[66:81], v[224:227], v[146:149], v[66:81]
	ds_read_b128 v[224:227], v0 offset:13856
	s_waitcnt lgkmcnt(2)
	v_mfma_f32_32x32x16_bf16 v[98:113], v[228:231], v[150:153], v[98:113]
	v_mfma_f32_32x32x16_bf16 v[50:65], v[228:231], v[146:149], v[50:65]
	ds_read_b128 v[228:231], v0 offset:64
	s_waitcnt lgkmcnt(2)
	v_mfma_f32_32x32x16_bf16 v[82:97], v[220:223], v[150:153], v[82:97]
	v_mfma_f32_32x32x16_bf16 v[18:33], v[220:223], v[146:149], v[18:33]
	ds_read_b128 v[220:223], v0 offset:4672
	s_waitcnt lgkmcnt(2)
	v_mfma_f32_32x32x16_bf16 v[34:49], v[224:227], v[150:153], v[34:49]
	v_mfma_f32_32x32x16_bf16 v[2:17], v[224:227], v[146:149], v[2:17]
	ds_read_b128 v[224:227], v0 offset:9280
	v_lshl_add_u64 v[150:151], v[232:233], 0, s[90:91]
	global_load_dwordx4 v[150:153], v[150:151], off offset:1024
	v_lshl_add_u64 v[146:147], v[232:233], 0, s[8:9]
	global_load_dwordx4 v[146:149], v[146:147], off offset:1024
	s_waitcnt vmcnt(4)
	ds_write_b128 v195, v[208:211]
	ds_write_b128 v195, v[212:215] offset:4608
	ds_write_b128 v195, v[244:247] offset:9216
	ds_write_b128 v195, v[248:251] offset:13824
	s_add_u32 s36, s18, s39
	s_addc_u32 s37, s19, 0
	v_lshl_add_u64 v[208:209], s[36:37], 0, v[196:197]
	v_lshl_add_u64 v[212:213], s[36:37], 0, v[198:199]
	v_lshl_add_u64 v[244:245], s[36:37], 0, v[200:201]
	v_lshl_add_u64 v[248:249], s[36:37], 0, v[202:203]
	global_load_dwordx4 v[208:211], v[208:209], off
	global_load_dwordx4 v[212:215], v[212:213], off
	global_load_dwordx4 v[244:247], v[244:245], off
	global_load_dwordx4 v[248:251], v[248:249], off
	s_waitcnt lgkmcnt(6)
	v_mfma_f32_32x32x16_bf16 v[114:129], v[228:231], v[138:141], v[114:129]
	v_mfma_f32_32x32x16_bf16 v[66:81], v[228:231], v[142:145], v[66:81]
	ds_read_b128 v[228:231], v0 offset:13888
	s_waitcnt lgkmcnt(6)
	v_mfma_f32_32x32x16_bf16 v[98:113], v[220:223], v[138:141], v[98:113]
	v_mfma_f32_32x32x16_bf16 v[50:65], v[220:223], v[142:145], v[50:65]
	ds_read_b128 v[220:223], v0 offset:96
	s_waitcnt lgkmcnt(6)
	v_mfma_f32_32x32x16_bf16 v[82:97], v[224:227], v[138:141], v[82:97]
	v_mfma_f32_32x32x16_bf16 v[18:33], v[224:227], v[142:145], v[18:33]
	ds_read_b128 v[224:227], v0 offset:4704
	s_waitcnt lgkmcnt(2)
	v_mfma_f32_32x32x16_bf16 v[34:49], v[228:231], v[138:141], v[34:49]
	v_mfma_f32_32x32x16_bf16 v[2:17], v[228:231], v[142:145], v[2:17]
	ds_read_b128 v[228:231], v0 offset:9312
	v_lshl_add_u64 v[138:139], v[232:233], 0, s[90:91]
	global_load_dwordx4 v[138:141], v[138:139], off offset:2048
	v_lshl_add_u64 v[142:143], v[232:233], 0, s[8:9]
	global_load_dwordx4 v[142:145], v[142:143], off offset:2048
	s_waitcnt lgkmcnt(2)
	v_mfma_f32_32x32x16_bf16 v[114:129], v[220:223], v[134:137], v[114:129]
	v_mfma_f32_32x32x16_bf16 v[66:81], v[220:223], v[130:133], v[66:81]
	ds_read_b128 v[220:223], v0 offset:13920
	s_waitcnt lgkmcnt(2)
	v_mfma_f32_32x32x16_bf16 v[98:113], v[224:227], v[134:137], v[98:113]
	v_mfma_f32_32x32x16_bf16 v[50:65], v[224:227], v[130:133], v[50:65]
	s_waitcnt lgkmcnt(1)
	v_mfma_f32_32x32x16_bf16 v[82:97], v[228:231], v[134:137], v[82:97]
	v_mfma_f32_32x32x16_bf16 v[18:33], v[228:231], v[130:133], v[18:33]
	s_waitcnt lgkmcnt(0)
	v_mfma_f32_32x32x16_bf16 v[34:49], v[220:223], v[134:137], v[34:49]
	v_mfma_f32_32x32x16_bf16 v[2:17], v[220:223], v[130:133], v[2:17]
	v_lshl_add_u64 v[134:135], v[232:233], 0, s[90:91]
	global_load_dwordx4 v[134:137], v[134:135], off offset:3072
	v_lshl_add_u64 v[130:131], v[232:233], 0, s[8:9]
	global_load_dwordx4 v[130:133], v[130:131], off offset:3072
	s_waitcnt vmcnt(4)
	ds_write_b128 v195, v[208:211] offset:18432
	ds_write_b128 v195, v[212:215] offset:23040
	ds_write_b128 v195, v[244:247] offset:27648
	ds_write_b128 v195, v[248:251] offset:32256
	s_and_b32 s36, s13, 1
	s_mul_i32 s36, s36, 0x9000
	v_add_u32_e32 v0, s36, v206
	s_cmp_lg_u32 s13, 15
	s_waitcnt lgkmcnt(0)
	s_barrier
	s_cbranch_scc1 .LBB0_196
; #define A256_LOADH(kt_, hf_) { a0 = la.ld1(kt_, (hf_) * 4 + 0, tid); a1 = la.ld1(kt_, (hf_) * 4 + 1, tid); a2 = la.ld1(kt_, (hf_) * 4 + 2, tid); a3 = la.ld1(kt_, (hf_) * 4 + 3, tid); }
; template <bool swap, class LA>
; DI void gemm256_ws(const LA& la, const bf16_t* Wt, const int KS, const int nk, bf16_t* smem, f32x16 (&acc)[8]) {
;     ...
;   for (int kt = 0; kt < nk; kt++) {
;     const int cur = kt & 1; const int kn = (kt + 1 < nk) ? kt + 1 : last;
;     const bf16_t* sp = smem + cur * ATILE_E + aoff;
;     bf16_t* nxt = smem + (cur ^ 1) * ATILE_E;
;     A256_LOADH(kn, 0)
;     MMA256(0, w00, w10) W256_LD(kn, 0, w00, w10)
;     MMA256(1, w01, w11) W256_LD(kn, 1, w01, w11)
;     A256_STH(nxt, 0)
;     A256_LOADH(kn, 1)
;     MMA256(2, w02, w12) W256_LD(kn, 2, w02, w12)
;     MMA256(3, w03, w13) W256_LD(kn, 3, w03, w13)
;     A256_STH(nxt, 1)
;     __syncthreads();
;   }
	s_waitcnt vmcnt(0)
	ds_read_b128 v[208:211], v206 offset:36864
	s_add_u32 s8, s10, 0x3c000
	s_addc_u32 s9, s11, 0
	v_lshl_add_u64 v[212:213], s[8:9], 0, v[202:203]
	v_xor_b32_e32 v240, 2, v238
	v_xor_b32_e32 v241, 1, v238
	v_mov_b32_e32 v244, v219
	s_waitcnt vmcnt(6) lgkmcnt(0)
	v_mfma_f32_32x32x16_bf16 v[114:129], v[208:211], v[154:157], v[114:129]
	v_mfma_f32_32x32x16_bf16 v[66:81], v[208:211], v[158:161], v[66:81]
	ds_read_b128 v[208:211], v206 offset:41472
	s_waitcnt lgkmcnt(0)
	v_mfma_f32_32x32x16_bf16 v[98:113], v[208:211], v[154:157], v[98:113]
	v_mfma_f32_32x32x16_bf16 v[50:65], v[208:211], v[158:161], v[50:65]
	ds_read_b128 v[208:211], v206 offset:46080
	s_waitcnt lgkmcnt(0)
	v_mfma_f32_32x32x16_bf16 v[82:97], v[208:211], v[154:157], v[82:97]
	v_mfma_f32_32x32x16_bf16 v[18:33], v[208:211], v[158:161], v[18:33]
	ds_read_b128 v[208:211], v206 offset:50688
	s_waitcnt lgkmcnt(0)
	v_mfma_f32_32x32x16_bf16 v[34:49], v[208:211], v[154:157], v[34:49]
	ds_read_b128 v[154:157], v206 offset:36896
	s_waitcnt vmcnt(5) lgkmcnt(0)
	v_mfma_f32_32x32x16_bf16 v[114:129], v[154:157], v[150:153], v[114:129]
	s_waitcnt vmcnt(4)
	v_mfma_f32_32x32x16_bf16 v[66:81], v[154:157], v[146:149], v[66:81]
	ds_read_b128 v[154:157], v206 offset:41504
	s_waitcnt lgkmcnt(0)
	v_mfma_f32_32x32x16_bf16 v[98:113], v[154:157], v[150:153], v[98:113]
	v_mfma_f32_32x32x16_bf16 v[50:65], v[154:157], v[146:149], v[50:65]
	ds_read_b128 v[154:157], v206 offset:46112
	s_waitcnt lgkmcnt(0)
	v_mfma_f32_32x32x16_bf16 v[82:97], v[154:157], v[150:153], v[82:97]
	v_mfma_f32_32x32x16_bf16 v[18:33], v[154:157], v[146:149], v[18:33]
	ds_read_b128 v[154:157], v206 offset:50720
	v_mfma_f32_32x32x16_bf16 v[2:17], v[208:211], v[158:161], v[2:17]
	v_lshl_add_u64 v[158:159], s[8:9], 0, v[196:197]
	v_lshl_add_u64 v[160:161], s[8:9], 0, v[198:199]
	v_lshl_add_u64 v[208:209], s[8:9], 0, v[200:201]
	s_add_u32 s8, s10, 0x7c000
	s_addc_u32 s9, s11, 0
	s_waitcnt lgkmcnt(0)
	v_mfma_f32_32x32x16_bf16 v[34:49], v[154:157], v[150:153], v[34:49]
	global_load_dwordx4 v[150:153], v[158:159], off
	s_nop 0
	global_load_dwordx4 v[158:161], v[160:161], off
	s_nop 0
	global_load_dwordx4 v[208:211], v[208:209], off
	s_nop 0
	global_load_dwordx4 v[212:215], v[212:213], off
	s_waitcnt vmcnt(3)
	ds_write_b128 v204, v[150:153]
	s_waitcnt vmcnt(2)
	ds_write_b128 v204, v[158:161] offset:4608
	s_waitcnt vmcnt(1)
	ds_write_b128 v204, v[208:211] offset:9216
	s_waitcnt vmcnt(0)
	ds_write_b128 v204, v[212:215] offset:13824
	v_mfma_f32_32x32x16_bf16 v[2:17], v[154:157], v[146:149], v[2:17]
	ds_read_b128 v[146:149], v206 offset:36928
	v_lshl_add_u64 v[150:151], s[8:9], 0, v[200:201]
	v_lshl_add_u64 v[154:155], s[8:9], 0, v[202:203]
	s_waitcnt lgkmcnt(0)
	v_mfma_f32_32x32x16_bf16 v[114:129], v[146:149], v[138:141], v[114:129]
	v_mfma_f32_32x32x16_bf16 v[66:81], v[146:149], v[142:145], v[66:81]
	ds_read_b128 v[146:149], v206 offset:41536
	s_waitcnt lgkmcnt(0)
	v_mfma_f32_32x32x16_bf16 v[98:113], v[146:149], v[138:141], v[98:113]
	v_mfma_f32_32x32x16_bf16 v[50:65], v[146:149], v[142:145], v[50:65]
	ds_read_b128 v[146:149], v206 offset:46144
	s_waitcnt lgkmcnt(0)
	v_mfma_f32_32x32x16_bf16 v[82:97], v[146:149], v[138:141], v[82:97]
	v_mfma_f32_32x32x16_bf16 v[18:33], v[146:149], v[142:145], v[18:33]
	ds_read_b128 v[146:149], v206 offset:50752
	s_waitcnt lgkmcnt(0)
	v_mfma_f32_32x32x16_bf16 v[34:49], v[146:149], v[138:141], v[34:49]
	ds_read_b128 v[138:141], v206 offset:36960
	s_waitcnt lgkmcnt(0)
	v_mfma_f32_32x32x16_bf16 v[114:129], v[138:141], v[134:137], v[114:129]
	v_mfma_f32_32x32x16_bf16 v[66:81], v[138:141], v[130:133], v[66:81]
	ds_read_b128 v[138:141], v206 offset:41568
	v_mfma_f32_32x32x16_bf16 v[2:17], v[146:149], v[142:145], v[2:17]
	v_lshl_add_u64 v[142:143], s[8:9], 0, v[196:197]
	v_lshl_add_u64 v[146:147], s[8:9], 0, v[198:199]
	s_waitcnt lgkmcnt(0)
	v_mfma_f32_32x32x16_bf16 v[98:113], v[138:141], v[134:137], v[98:113]
	v_mfma_f32_32x32x16_bf16 v[50:65], v[138:141], v[130:133], v[50:65]
	ds_read_b128 v[138:141], v206 offset:46176
	global_load_dwordx4 v[142:145], v[142:143], off
	s_nop 0
	global_load_dwordx4 v[146:149], v[146:147], off
	s_nop 0
	global_load_dwordx4 v[150:153], v[150:151], off
	s_nop 0
	global_load_dwordx4 v[154:157], v[154:155], off
	s_waitcnt lgkmcnt(0)
	v_mfma_f32_32x32x16_bf16 v[82:97], v[138:141], v[134:137], v[82:97]
	v_mfma_f32_32x32x16_bf16 v[18:33], v[138:141], v[130:133], v[18:33]
	ds_read_b128 v[138:141], v206 offset:50784
	s_waitcnt vmcnt(3)
	ds_write_b128 v204, v[142:145] offset:18432
	s_waitcnt vmcnt(2)
	ds_write_b128 v204, v[146:149] offset:23040
	s_waitcnt vmcnt(1)
	ds_write_b128 v204, v[150:153] offset:27648
	s_waitcnt vmcnt(0)
	ds_write_b128 v204, v[154:157] offset:32256
	s_waitcnt lgkmcnt(4)
	v_mfma_f32_32x32x16_bf16 v[34:49], v[138:141], v[134:137], v[34:49]
	s_waitcnt lgkmcnt(0)
	s_barrier
	v_mfma_f32_32x32x16_bf16 v[2:17], v[138:141], v[130:133], v[2:17]
	s_mov_b64 s[8:9], -1
	s_and_b64 vcc, exec, s[2:3]
	s_cbranch_vccnz .LBB0_186

; DI size_t tix(size_t t, int f, int KT) { return ((t >> 7) * KT + (f >> 6)) * 8192 + (t & 127) * 64 + (f & 63); }
; DI void rows_out_tiled(const bf16_t* smem, bf16_t* buf, size_t t0, int f0, int KT, int tid) {
; #pragma unroll 8
;   for (int k = 0; k < 16; k++) { const int c = tid + 256 * k; const int ch = c & 7, row = (c >> 3) & 255, fh = c >> 11;
;     *(uint4*)(buf + tix(t0 + row, f0 + fh * 64 + ch * 8, KT)) = *(const uint4*)(smem + row * EPLD + fh * 64 + ch * 8); }
; }
.LBB0_234:
	v_add_u32_e32 v14, s10, v163
	v_ashrrev_i32_e32 v0, 5, v14
	v_lshlrev_b32_e32 v6, 1, v0
	v_and_b32_e32 v6, 0xffffff80, v6
	v_add_u32_e32 v0, s8, v0
	v_add_u32_e32 v8, v175, v6
	v_ashrrev_i32_e32 v6, 6, v0
	v_ashrrev_i32_e32 v7, 31, v6
	v_lshl_add_u64 v[6:7], v[2:3], 0, v[6:7]
	v_lshlrev_b64 v[6:7], 14, v[6:7]
	v_lshl_add_u64 v[10:11], v[4:5], 0, v[6:7]
	ds_read_b128 v[6:9], v8
	v_add_u32_e32 v0, 0x100, v14
	v_mov_b32_e32 v169, v1
	s_addk_i32 s10, 0x800
	s_cmpk_lg_i32 s10, 0x1000
	s_waitcnt lgkmcnt(0)
	global_store_dwordx4 v[10:11], v[6:9], off
	s_nop 1
	v_bfe_u32 v6, v0, 3, 8
	v_ashrrev_i32_e32 v0, 5, v0
	v_lshlrev_b32_e32 v8, 1, v0
	v_mul_u32_u24_e32 v7, 0x110, v6
	v_and_b32_e32 v8, 0xffffff80, v8
	v_add3_u32 v15, v7, v8, v168
	v_or_b32_e32 v6, s18, v6
	v_mov_b32_e32 v7, s19
	v_add_u32_e32 v0, s8, v0
	v_lshrrev_b64 v[8:9], 3, v[6:7]
	v_ashrrev_i32_e32 v10, 6, v0
	v_and_b32_e32 v9, 0x3ffff, v9
	v_and_b32_e32 v8, -16, v8
	v_ashrrev_i32_e32 v11, 31, v10
	v_lshl_add_u64 v[8:9], v[8:9], 0, v[10:11]
	v_lshlrev_b64 v[8:9], 14, v[8:9]
	v_lshlrev_b32_e32 v0, 7, v6
	v_lshl_add_u64 v[8:9], s[82:83], 0, v[8:9]
	v_and_b32_e32 v0, 0x3f80, v0
	v_lshl_add_u64 v[8:9], v[8:9], 0, v[0:1]
	v_lshl_add_u64 v[12:13], v[8:9], 0, v[168:169]
	ds_read_b128 v[8:11], v15
	v_add_u32_e32 v0, 0x200, v14
	v_bfe_u32 v6, v0, 3, 8
	v_ashrrev_i32_e32 v0, 5, v0
	s_waitcnt lgkmcnt(0)
	global_store_dwordx4 v[12:13], v[8:11], off
	s_nop 1
	v_lshlrev_b32_e32 v9, 1, v0
	v_mul_u32_u24_e32 v8, 0x110, v6
	v_and_b32_e32 v9, 0xffffff80, v9
	v_or_b32_e32 v6, s18, v6
	v_add_u32_e32 v0, s8, v0
	v_add3_u32 v15, v8, v9, v168
	v_lshrrev_b64 v[8:9], 3, v[6:7]
	v_ashrrev_i32_e32 v10, 6, v0
	v_and_b32_e32 v9, 0x3ffff, v9
	v_and_b32_e32 v8, -16, v8
	v_ashrrev_i32_e32 v11, 31, v10
	v_lshl_add_u64 v[8:9], v[8:9], 0, v[10:11]
	v_lshlrev_b64 v[8:9], 14, v[8:9]
	v_lshlrev_b32_e32 v0, 7, v6
	v_lshl_add_u64 v[8:9], s[82:83], 0, v[8:9]
	v_and_b32_e32 v0, 0x3f80, v0
	v_lshl_add_u64 v[8:9], v[8:9], 0, v[0:1]
	v_lshl_add_u64 v[12:13], v[8:9], 0, v[168:169]
	ds_read_b128 v[8:11], v15
	v_add_u32_e32 v0, 0x300, v14
	v_bfe_u32 v6, v0, 3, 8
	v_ashrrev_i32_e32 v0, 5, v0
	s_waitcnt lgkmcnt(0)
	global_store_dwordx4 v[12:13], v[8:11], off
	s_nop 1
	v_lshlrev_b32_e32 v9, 1, v0
	v_mul_u32_u24_e32 v8, 0x110, v6
	v_and_b32_e32 v9, 0xffffff80, v9
	v_or_b32_e32 v6, s18, v6
	v_add_u32_e32 v0, s8, v0
	v_add3_u32 v15, v8, v9, v168
	v_lshrrev_b64 v[8:9], 3, v[6:7]
	v_ashrrev_i32_e32 v10, 6, v0
	v_and_b32_e32 v9, 0x3ffff, v9
	v_and_b32_e32 v8, -16, v8
	v_ashrrev_i32_e32 v11, 31, v10
	v_lshl_add_u64 v[8:9], v[8:9], 0, v[10:11]
	v_lshlrev_b64 v[8:9], 14, v[8:9]
	v_lshlrev_b32_e32 v0, 7, v6
	v_lshl_add_u64 v[8:9], s[82:83], 0, v[8:9]
	v_and_b32_e32 v0, 0x3f80, v0
	v_lshl_add_u64 v[8:9], v[8:9], 0, v[0:1]
	v_lshl_add_u64 v[12:13], v[8:9], 0, v[168:169]
	ds_read_b128 v[8:11], v15
	v_add_u32_e32 v0, 0x400, v14
	v_bfe_u32 v6, v0, 3, 8
	v_ashrrev_i32_e32 v0, 5, v0
	s_waitcnt lgkmcnt(0)
	global_store_dwordx4 v[12:13], v[8:11], off
	s_nop 1
	v_lshlrev_b32_e32 v9, 1, v0
	v_mul_u32_u24_e32 v8, 0x110, v6
	v_and_b32_e32 v9, 0xffffff80, v9
	v_or_b32_e32 v6, s18, v6
	v_add_u32_e32 v0, s8, v0
	v_add3_u32 v15, v8, v9, v168
	v_lshrrev_b64 v[8:9], 3, v[6:7]
	v_ashrrev_i32_e32 v10, 6, v0
	v_and_b32_e32 v9, 0x3ffff, v9
	v_and_b32_e32 v8, -16, v8
	v_ashrrev_i32_e32 v11, 31, v10
	v_lshl_add_u64 v[8:9], v[8:9], 0, v[10:11]
	v_lshlrev_b64 v[8:9], 14, v[8:9]
	v_lshlrev_b32_e32 v0, 7, v6
	v_lshl_add_u64 v[8:9], s[82:83], 0, v[8:9]
	v_and_b32_e32 v0, 0x3f80, v0
	v_lshl_add_u64 v[8:9], v[8:9], 0, v[0:1]
	v_lshl_add_u64 v[12:13], v[8:9], 0, v[168:169]
	ds_read_b128 v[8:11], v15
	v_add_u32_e32 v0, 0x500, v14
	v_bfe_u32 v6, v0, 3, 8
	v_ashrrev_i32_e32 v0, 5, v0
	s_waitcnt lgkmcnt(0)
	global_store_dwordx4 v[12:13], v[8:11], off
	s_nop 1
	v_lshlrev_b32_e32 v9, 1, v0
	v_mul_u32_u24_e32 v8, 0x110, v6
	v_and_b32_e32 v9, 0xffffff80, v9
	v_or_b32_e32 v6, s18, v6
	v_add_u32_e32 v0, s8, v0
	v_add3_u32 v15, v8, v9, v168
	v_lshrrev_b64 v[8:9], 3, v[6:7]
	v_ashrrev_i32_e32 v10, 6, v0
	v_and_b32_e32 v9, 0x3ffff, v9
	v_and_b32_e32 v8, -16, v8
	v_ashrrev_i32_e32 v11, 31, v10
	v_lshl_add_u64 v[8:9], v[8:9], 0, v[10:11]
	v_lshlrev_b64 v[8:9], 14, v[8:9]
	v_lshlrev_b32_e32 v0, 7, v6
	v_lshl_add_u64 v[8:9], s[82:83], 0, v[8:9]
	v_and_b32_e32 v0, 0x3f80, v0
	v_lshl_add_u64 v[8:9], v[8:9], 0, v[0:1]
	v_lshl_add_u64 v[12:13], v[8:9], 0, v[168:169]
	ds_read_b128 v[8:11], v15
	v_add_u32_e32 v0, 0x600, v14
	v_bfe_u32 v6, v0, 3, 8
	v_ashrrev_i32_e32 v0, 5, v0
	s_waitcnt lgkmcnt(0)
	global_store_dwordx4 v[12:13], v[8:11], off
	s_nop 1
	v_lshlrev_b32_e32 v9, 1, v0
	v_mul_u32_u24_e32 v8, 0x110, v6
	v_and_b32_e32 v9, 0xffffff80, v9
	v_or_b32_e32 v6, s18, v6
	v_add_u32_e32 v0, s8, v0
	v_add3_u32 v15, v8, v9, v168
	v_lshrrev_b64 v[8:9], 3, v[6:7]
	v_ashrrev_i32_e32 v10, 6, v0
	v_and_b32_e32 v9, 0x3ffff, v9
	v_and_b32_e32 v8, -16, v8
	v_ashrrev_i32_e32 v11, 31, v10
	v_lshl_add_u64 v[8:9], v[8:9], 0, v[10:11]
	v_lshlrev_b64 v[8:9], 14, v[8:9]
	v_lshlrev_b32_e32 v0, 7, v6
	v_lshl_add_u64 v[8:9], s[82:83], 0, v[8:9]
	v_and_b32_e32 v0, 0x3f80, v0
	v_lshl_add_u64 v[8:9], v[8:9], 0, v[0:1]
	v_lshl_add_u64 v[12:13], v[8:9], 0, v[168:169]
	ds_read_b128 v[8:11], v15
	v_add_u32_e32 v0, 0x700, v14
	v_bfe_u32 v6, v0, 3, 8
	v_ashrrev_i32_e32 v0, 5, v0
	s_waitcnt lgkmcnt(0)
	global_store_dwordx4 v[12:13], v[8:11], off
	s_nop 1
	v_lshlrev_b32_e32 v9, 1, v0
	v_mul_u32_u24_e32 v8, 0x110, v6
	v_and_b32_e32 v9, 0xffffff80, v9
	v_or_b32_e32 v6, s18, v6
	v_add_u32_e32 v0, s8, v0
	v_add3_u32 v12, v8, v9, v168
	v_lshrrev_b64 v[8:9], 3, v[6:7]
	v_ashrrev_i32_e32 v10, 6, v0
	v_and_b32_e32 v9, 0x3ffff, v9
	v_and_b32_e32 v8, -16, v8
	v_ashrrev_i32_e32 v11, 31, v10
	v_lshl_add_u64 v[8:9], v[8:9], 0, v[10:11]
	v_lshlrev_b64 v[8:9], 14, v[8:9]
	v_lshlrev_b32_e32 v0, 7, v6
	v_lshl_add_u64 v[8:9], s[82:83], 0, v[8:9]
	v_and_b32_e32 v0, 0x3f80, v0
	v_lshl_add_u64 v[6:7], v[8:9], 0, v[0:1]
	v_lshl_add_u64 v[10:11], v[6:7], 0, v[168:169]
	ds_read_b128 v[6:9], v12
	s_waitcnt lgkmcnt(0)
	global_store_dwordx4 v[10:11], v[6:9], off
	s_cbranch_scc1 .LBB0_234
; #define A256_LOADH(kt_, hf_) { a0 = la.ld1(kt_, (hf_) * 4 + 0, tid); a1 = la.ld1(kt_, (hf_) * 4 + 1, tid); a2 = la.ld1(kt_, (hf_) * 4 + 2, tid); a3 = la.ld1(kt_, (hf_) * 4 + 3, tid); }
; #define ZERO_ACC8(a) { _Pragma("unroll") for (int i_ = 0; i_ < 8; i_++) _Pragma("unroll") for (int r_ = 0; r_ < 16; r_++) a[i_][r_] = 0.f; }
; template <bool swap, class LA>
; DI void gemm256_ws(const LA& la, const bf16_t* Wt, const int KS, const int nk, bf16_t* smem, f32x16 (&acc)[8]) {
;     ...
;   A256_LOADH(0, 0) A256_STH(smem, 0)
;   A256_LOADH(0, 1) A256_STH(smem, 1)
;   W256_LD(0, 0, w00, w10) W256_LD(0, 1, w01, w11) W256_LD(0, 2, w02, w12) W256_LD(0, 3, w03, w13)
;   __syncthreads();
;   const int aoff = (tbk * 128 + l32) * LDT + h * 8;
; DI void ph_ple(const Params& P, int g, int layer, bf16_t* smem) {
;     ...
;     ZERO_ACC8(acc)
;     { LoadTile256 la{x1b + (size_t)(2 * mt) * 16 * 8192, 16 * 8192}; gemm256_ws<true>(la, Wg + (size_t)n0 * 1024, 64, 16, smem, acc); }
	s_lshl_b64 s[2:3], s[2:3], 18
	v_mov_b32_e32 v0, v234
	s_barrier
	s_add_u32 s2, s78, s2
	s_addc_u32 s3, s79, s3
	v_lshlrev_b32_e32 v2, 3, v0
	s_lshl_b64 s[10:11], s[8:9], 11
	v_readlane_b32 s12, v253, 49
	v_ashrrev_i32_e32 v3, 31, v2
	v_readlane_b32 s13, v253, 50
	s_add_u32 s12, s12, s10
	v_lshlrev_b64 v[176:177], 1, v[2:3]
	v_add_u32_e32 v6, 0x800, v2
	v_add_u32_e32 v8, 0x1000, v2
	v_add_u32_e32 v2, 0x1800, v2
	s_addc_u32 s13, s13, s11
	v_ashrrev_i32_e32 v7, 31, v6
	v_ashrrev_i32_e32 v9, 31, v8
	v_ashrrev_i32_e32 v3, 31, v2
	v_lshlrev_b64 v[178:179], 1, v[6:7]
	v_lshlrev_b64 v[180:181], 1, v[8:9]
	v_lshlrev_b64 v[182:183], 1, v[2:3]
	s_add_u32 s10, s2, 0x40000
	v_lshl_add_u64 v[4:5], s[2:3], 0, v[176:177]
	v_lshl_add_u64 v[6:7], s[2:3], 0, v[178:179]
	v_lshl_add_u64 v[16:17], s[2:3], 0, v[180:181]
	v_lshl_add_u64 v[2:3], s[2:3], 0, v[182:183]
	s_addc_u32 s11, s3, 0
	v_ashrrev_i32_e32 v40, 6, v0
	global_load_dwordx4 v[8:11], v[4:5], off
	global_load_dwordx4 v[12:15], v[6:7], off
	s_nop 0
	global_load_dwordx4 v[16:19], v[16:17], off
	s_nop 0
	global_load_dwordx4 v[20:23], v[2:3], off
	v_lshl_add_u64 v[2:3], s[10:11], 0, v[176:177]
	v_lshl_add_u64 v[6:7], s[10:11], 0, v[180:181]
	v_lshl_add_u64 v[36:37], s[10:11], 0, v[182:183]
	v_lshlrev_b32_e32 v41, 4, v0
	v_and_b32_e32 v40, -2, v40
	v_lshl_add_u64 v[4:5], s[10:11], 0, v[178:179]
	global_load_dwordx4 v[24:27], v[2:3], off
	global_load_dwordx4 v[28:31], v[4:5], off
	global_load_dwordx4 v[32:35], v[6:7], off
	s_nop 0
	global_load_dwordx4 v[36:39], v[36:37], off
	v_and_b32_e32 v7, 31, v0
	v_lshrrev_b32_e32 v43, 3, v0
	v_lshlrev_b32_e32 v44, 1, v0
	v_lshrrev_b32_e32 v45, 1, v0
	v_and_b32_e32 v0, 0x3f0, v41
	v_and_b32_e32 v42, 0x70, v41
	v_ashrrev_i32_e32 v41, 31, v40
	v_lshlrev_b64 v[40:41], 16, v[40:41]
	v_lshl_add_u64 v[40:41], s[12:13], 0, v[40:41]
	v_lshl_add_u64 v[186:187], v[40:41], 0, v[0:1]
	v_add_co_u32_e32 v40, vcc, s94, v186
	s_movk_i32 s36, 0x80
	s_nop 0
	v_addc_co_u32_e32 v41, vcc, 0, v187, vcc
	global_load_dwordx4 v[154:157], v[40:41], off
	global_load_dwordx4 v[158:161], v[186:187], off
	global_load_dwordx4 v[146:149], v[40:41], off offset:1024
	global_load_dwordx4 v[150:153], v[186:187], off offset:1024
	global_load_dwordx4 v[142:145], v[40:41], off offset:2048
	global_load_dwordx4 v[138:141], v[186:187], off offset:2048
	global_load_dwordx4 v[130:133], v[40:41], off offset:3072
	global_load_dwordx4 v[134:137], v[186:187], off offset:3072
	v_mov_b32_e32 v2, 0
	v_and_or_b32 v7, v44, s36, v7
	v_and_b32_e32 v44, 16, v45
	v_mad_u64_u32 v[184:185], s[36:37], v43, s0, v[42:43]
	s_mov_b64 s[12:13], 0x10000
	s_mov_b32 s9, 0
	v_mov_b32_e32 v3, v2
	v_mov_b32_e32 v4, v2
	v_mov_b32_e32 v5, v2
	v_mov_b32_e32 v6, v2
	v_mad_u32_u24 v169, v7, s0, v44
	v_lshl_add_u64 v[188:189], v[186:187], 0, s[12:13]
	v_mov_b32_e32 v7, v2
	v_mov_b32_e32 v40, v2
	v_mov_b32_e32 v41, v2
	v_mov_b32_e32 v42, v2
	v_mov_b32_e32 v43, v2
	v_mov_b32_e32 v44, v2
	v_mov_b32_e32 v45, v2
	v_mov_b32_e32 v46, v2
	v_mov_b32_e32 v47, v2
	v_mov_b32_e32 v48, v2
	v_mov_b32_e32 v49, v2
	v_mov_b32_e32 v66, v2
	v_mov_b32_e32 v67, v2
	v_mov_b32_e32 v68, v2
	v_mov_b32_e32 v69, v2
	v_mov_b32_e32 v70, v2
	v_mov_b32_e32 v71, v2
	v_mov_b32_e32 v72, v2
	v_mov_b32_e32 v73, v2
	s_waitcnt vmcnt(15)
	ds_write_b128 v184, v[8:11]
	s_waitcnt vmcnt(14)
	ds_write_b128 v184, v[12:15] offset:4608
	s_waitcnt vmcnt(13)
	ds_write_b128 v184, v[16:19] offset:9216
	s_waitcnt vmcnt(12)
	ds_write_b128 v184, v[20:23] offset:13824
	s_waitcnt vmcnt(11)
	ds_write_b128 v184, v[24:27] offset:18432
	s_waitcnt vmcnt(10)
	ds_write_b128 v184, v[28:31] offset:23040
	s_waitcnt vmcnt(9)
	ds_write_b128 v184, v[32:35] offset:27648
	s_waitcnt vmcnt(8)
	ds_write_b128 v184, v[36:39] offset:32256
	v_mov_b32_e32 v8, v2
	v_mov_b32_e32 v9, v2
	v_mov_b32_e32 v10, v2
	v_mov_b32_e32 v11, v2
	v_mov_b32_e32 v12, v2
	v_mov_b32_e32 v13, v2
	v_mov_b32_e32 v14, v2
	v_mov_b32_e32 v15, v2
	v_mov_b32_e32 v16, v2
	v_mov_b32_e32 v17, v2
	v_mov_b32_e32 v34, v2
	v_mov_b32_e32 v35, v2
	v_mov_b32_e32 v36, v2
	v_mov_b32_e32 v37, v2
	v_mov_b32_e32 v38, v2
	v_mov_b32_e32 v39, v2
	v_mov_b32_e32 v74, v2
	v_mov_b32_e32 v75, v2
	v_mov_b32_e32 v76, v2
	v_mov_b32_e32 v77, v2
	v_mov_b32_e32 v78, v2
	v_mov_b32_e32 v79, v2
	v_mov_b32_e32 v80, v2
	v_mov_b32_e32 v81, v2
	v_mov_b32_e32 v98, v2
	v_mov_b32_e32 v99, v2
	v_mov_b32_e32 v100, v2
	v_mov_b32_e32 v101, v2
	v_mov_b32_e32 v102, v2
	v_mov_b32_e32 v103, v2
	v_mov_b32_e32 v104, v2
	v_mov_b32_e32 v105, v2
	v_mov_b32_e32 v106, v2
	v_mov_b32_e32 v107, v2
	v_mov_b32_e32 v108, v2
	v_mov_b32_e32 v109, v2
	v_mov_b32_e32 v110, v2
	v_mov_b32_e32 v111, v2
	v_mov_b32_e32 v112, v2
	v_mov_b32_e32 v113, v2
	v_mov_b32_e32 v18, v2
	v_mov_b32_e32 v19, v2
	v_mov_b32_e32 v20, v2
	v_mov_b32_e32 v21, v2
	v_mov_b32_e32 v22, v2
	v_mov_b32_e32 v23, v2
	v_mov_b32_e32 v24, v2
	v_mov_b32_e32 v25, v2
	v_mov_b32_e32 v26, v2
	v_mov_b32_e32 v27, v2
	v_mov_b32_e32 v28, v2
	v_mov_b32_e32 v29, v2
	v_mov_b32_e32 v30, v2
	v_mov_b32_e32 v31, v2
	v_mov_b32_e32 v32, v2
	v_mov_b32_e32 v33, v2
	v_mov_b32_e32 v50, v2
	v_mov_b32_e32 v51, v2
	v_mov_b32_e32 v52, v2
	v_mov_b32_e32 v53, v2
	v_mov_b32_e32 v54, v2
	v_mov_b32_e32 v55, v2
	v_mov_b32_e32 v56, v2
	v_mov_b32_e32 v57, v2
	v_mov_b32_e32 v58, v2
	v_mov_b32_e32 v59, v2
	v_mov_b32_e32 v60, v2
	v_mov_b32_e32 v61, v2
	v_mov_b32_e32 v62, v2
	v_mov_b32_e32 v63, v2
	v_mov_b32_e32 v64, v2
	v_mov_b32_e32 v65, v2
	v_mov_b32_e32 v82, v2
	v_mov_b32_e32 v83, v2
	v_mov_b32_e32 v84, v2
	v_mov_b32_e32 v85, v2
	v_mov_b32_e32 v86, v2
	v_mov_b32_e32 v87, v2
	v_mov_b32_e32 v88, v2
	v_mov_b32_e32 v89, v2
	v_mov_b32_e32 v90, v2
	v_mov_b32_e32 v91, v2
	v_mov_b32_e32 v92, v2
	v_mov_b32_e32 v93, v2
	v_mov_b32_e32 v94, v2
	v_mov_b32_e32 v95, v2
	v_mov_b32_e32 v96, v2
	v_mov_b32_e32 v97, v2
	v_mov_b32_e32 v114, v2
	v_mov_b32_e32 v115, v2
	v_mov_b32_e32 v116, v2
	v_mov_b32_e32 v117, v2
	v_mov_b32_e32 v118, v2
	v_mov_b32_e32 v119, v2
	v_mov_b32_e32 v120, v2
	v_mov_b32_e32 v121, v2
	v_mov_b32_e32 v122, v2
	v_mov_b32_e32 v123, v2
	v_mov_b32_e32 v124, v2
	v_mov_b32_e32 v125, v2
	v_mov_b32_e32 v126, v2
	v_mov_b32_e32 v127, v2
	v_mov_b32_e32 v128, v2
	v_mov_b32_e32 v129, v2
	s_waitcnt lgkmcnt(0)
	s_barrier
; #define A256_LOADH(kt_, hf_) { a0 = la.ld1(kt_, (hf_) * 4 + 0, tid); a1 = la.ld1(kt_, (hf_) * 4 + 1, tid); a2 = la.ld1(kt_, (hf_) * 4 + 2, tid); a3 = la.ld1(kt_, (hf_) * 4 + 3, tid); }
; template <bool swap, class LA>
; DI void gemm256_ws(const LA& la, const bf16_t* Wt, const int KS, const int nk, bf16_t* smem, f32x16 (&acc)[8]) {
;     ...
;   for (int kt = 0; kt < nk; kt++) {
;     const int cur = kt & 1; const int kn = (kt + 1 < nk) ? kt + 1 : last;
;     const bf16_t* sp = smem + cur * ATILE_E + aoff;
;     bf16_t* nxt = smem + (cur ^ 1) * ATILE_E;
;     A256_LOADH(kn, 0)
;     MMA256(0, w00, w10) W256_LD(kn, 0, w00, w10)
;     MMA256(1, w01, w11) W256_LD(kn, 1, w01, w11)
;     A256_STH(nxt, 0)
;     A256_LOADH(kn, 1)
;     MMA256(2, w02, w12) W256_LD(kn, 2, w02, w12)
;     MMA256(3, w03, w13) W256_LD(kn, 3, w03, w13)
	s_lshl_b32 s37, 1, 14
	s_add_u32 s12, s2, s37
	s_addc_u32 s13, s3, 0
	v_lshl_add_u64 v[206:207], s[12:13], 0, v[176:177]
	s_add_u32 s12, s12, 0x1000
	s_addc_u32 s13, s13, 0
	v_lshl_add_u64 v[210:211], s[12:13], 0, v[176:177]
	s_add_u32 s12, s12, 0x1000
	s_addc_u32 s13, s13, 0
	v_lshl_add_u64 v[216:217], s[12:13], 0, v[176:177]
	s_add_u32 s12, s12, 0x1000
	s_addc_u32 s13, s13, 0
	v_lshl_add_u64 v[220:221], s[12:13], 0, v[176:177]
	global_load_dwordx4 v[206:209], v[206:207], off
	global_load_dwordx4 v[210:213], v[210:211], off
	global_load_dwordx4 v[216:219], v[216:217], off
	global_load_dwordx4 v[220:223], v[220:221], off
	s_add_u32 s12, s10, s37
	s_addc_u32 s13, s11, 0
	v_lshl_add_u64 v[224:225], s[12:13], 0, v[176:177]
	s_add_u32 s12, s12, 0x1000
	s_addc_u32 s13, s13, 0
	v_lshl_add_u64 v[228:229], s[12:13], 0, v[176:177]
	s_add_u32 s12, s12, 0x1000
	s_addc_u32 s13, s13, 0
	v_lshl_add_u64 v[246:247], s[12:13], 0, v[176:177]
	s_add_u32 s12, s12, 0x1000
	s_addc_u32 s13, s13, 0
	v_lshl_add_u64 v[178:179], s[12:13], 0, v[176:177]
	global_load_dwordx4 v[224:227], v[224:225], off
	global_load_dwordx4 v[228:231], v[228:229], off
	global_load_dwordx4 v[246:249], v[246:247], off
	global_load_dwordx4 v[178:181], v[178:179], off
	s_and_b32 s12, s9, 1
	s_mul_i32 s13, s12, 0x9000
	v_add_u32_e32 v0, s13, v169
.LBB0_236:
	ds_read_b128 v[194:197], v0
	ds_read_b128 v[198:201], v0 offset:4608
	ds_read_b128 v[202:205], v0 offset:9216
	s_and_b32 s12, s9, 1
	s_add_i32 s9, s9, 1
	s_min_u32 s36, s9, 15
	s_xor_b32 s12, s12, 1
	s_mul_i32 s13, s12, 0x9000
	v_add_u32_e32 v185, s13, v184
	s_lshl_b32 s90, s36, 12
	s_add_i32 s36, s9, 1
	s_min_u32 s36, s36, 15
	s_lshl_b32 s37, s36, 14
	s_waitcnt vmcnt(14) lgkmcnt(2)
	v_mfma_f32_32x32x16_bf16 v[98:113], v[154:157], v[194:197], v[98:113]
	v_mfma_f32_32x32x16_bf16 v[114:129], v[158:161], v[194:197], v[114:129]
	ds_read_b128 v[194:197], v0 offset:13824
	s_waitcnt lgkmcnt(2)
	v_mfma_f32_32x32x16_bf16 v[66:81], v[154:157], v[198:201], v[66:81]
	v_mfma_f32_32x32x16_bf16 v[82:97], v[158:161], v[198:201], v[82:97]
	ds_read_b128 v[198:201], v0 offset:32
	s_waitcnt lgkmcnt(2)
	v_mfma_f32_32x32x16_bf16 v[34:49], v[154:157], v[202:205], v[34:49]
	v_mfma_f32_32x32x16_bf16 v[50:65], v[158:161], v[202:205], v[50:65]
	ds_read_b128 v[202:205], v0 offset:4640
	s_waitcnt lgkmcnt(2)
	v_mfma_f32_32x32x16_bf16 v[2:17], v[154:157], v[194:197], v[2:17]
	v_mfma_f32_32x32x16_bf16 v[18:33], v[158:161], v[194:197], v[18:33]
	ds_read_b128 v[194:197], v0 offset:9248
	v_lshl_add_u64 v[154:155], v[188:189], 0, s[90:91]
	global_load_dwordx4 v[154:157], v[154:155], off
	v_lshl_add_u64 v[158:159], v[186:187], 0, s[90:91]
	global_load_dwordx4 v[158:161], v[158:159], off
	s_waitcnt vmcnt(14) lgkmcnt(2)
	v_mfma_f32_32x32x16_bf16 v[98:113], v[146:149], v[198:201], v[98:113]
	v_mfma_f32_32x32x16_bf16 v[114:129], v[150:153], v[198:201], v[114:129]
	ds_read_b128 v[198:201], v0 offset:13856
	s_waitcnt lgkmcnt(2)
	v_mfma_f32_32x32x16_bf16 v[66:81], v[146:149], v[202:205], v[66:81]
	v_mfma_f32_32x32x16_bf16 v[82:97], v[150:153], v[202:205], v[82:97]
	ds_read_b128 v[202:205], v0 offset:64
	s_waitcnt lgkmcnt(2)
	v_mfma_f32_32x32x16_bf16 v[34:49], v[146:149], v[194:197], v[34:49]
	v_mfma_f32_32x32x16_bf16 v[50:65], v[150:153], v[194:197], v[50:65]
	ds_read_b128 v[194:197], v0 offset:4672
	s_waitcnt lgkmcnt(2)
	v_mfma_f32_32x32x16_bf16 v[2:17], v[146:149], v[198:201], v[2:17]
	v_mfma_f32_32x32x16_bf16 v[18:33], v[150:153], v[198:201], v[18:33]
	ds_read_b128 v[198:201], v0 offset:9280
	v_lshl_add_u64 v[146:147], v[188:189], 0, s[90:91]
	global_load_dwordx4 v[146:149], v[146:147], off offset:1024
	v_lshl_add_u64 v[150:151], v[186:187], 0, s[90:91]
	global_load_dwordx4 v[150:153], v[150:151], off offset:1024
	s_waitcnt vmcnt(8)
	ds_write_b128 v185, v[206:209]
	ds_write_b128 v185, v[210:213] offset:4608
	ds_write_b128 v185, v[216:219] offset:9216
	ds_write_b128 v185, v[220:223] offset:13824
	s_add_u32 s12, s2, s37
	s_addc_u32 s13, s3, 0
	v_lshl_add_u64 v[206:207], s[12:13], 0, v[176:177]
	s_add_u32 s12, s12, 0x1000
	s_addc_u32 s13, s13, 0
	v_lshl_add_u64 v[210:211], s[12:13], 0, v[176:177]
	s_add_u32 s12, s12, 0x1000
	s_addc_u32 s13, s13, 0
	v_lshl_add_u64 v[216:217], s[12:13], 0, v[176:177]
	s_add_u32 s12, s12, 0x1000
	s_addc_u32 s13, s13, 0
	v_lshl_add_u64 v[220:221], s[12:13], 0, v[176:177]
	global_load_dwordx4 v[206:209], v[206:207], off
	global_load_dwordx4 v[210:213], v[210:211], off
	global_load_dwordx4 v[216:219], v[216:217], off
	global_load_dwordx4 v[220:223], v[220:221], off
	s_waitcnt lgkmcnt(6)
	v_mfma_f32_32x32x16_bf16 v[98:113], v[142:145], v[202:205], v[98:113]
	v_mfma_f32_32x32x16_bf16 v[114:129], v[138:141], v[202:205], v[114:129]
	ds_read_b128 v[202:205], v0 offset:13888
	s_waitcnt lgkmcnt(6)
	v_mfma_f32_32x32x16_bf16 v[66:81], v[142:145], v[194:197], v[66:81]
	v_mfma_f32_32x32x16_bf16 v[82:97], v[138:141], v[194:197], v[82:97]
	ds_read_b128 v[194:197], v0 offset:96
	s_waitcnt lgkmcnt(6)
	v_mfma_f32_32x32x16_bf16 v[34:49], v[142:145], v[198:201], v[34:49]
	v_mfma_f32_32x32x16_bf16 v[50:65], v[138:141], v[198:201], v[50:65]
	ds_read_b128 v[198:201], v0 offset:4704
	s_waitcnt lgkmcnt(2)
	v_mfma_f32_32x32x16_bf16 v[2:17], v[142:145], v[202:205], v[2:17]
	v_mfma_f32_32x32x16_bf16 v[18:33], v[138:141], v[202:205], v[18:33]
	ds_read_b128 v[202:205], v0 offset:9312
	v_lshl_add_u64 v[142:143], v[188:189], 0, s[90:91]
	global_load_dwordx4 v[142:145], v[142:143], off offset:2048
	v_lshl_add_u64 v[138:139], v[186:187], 0, s[90:91]
	global_load_dwordx4 v[138:141], v[138:139], off offset:2048
	s_waitcnt lgkmcnt(2)
; DI unsigned pk2(float a, float b) { f32v2 v = {a, b}; return __builtin_bit_cast(unsigned, __builtin_convertvector(v, bf16v2)); }
; DI float sigmoidf_(float v) { return 1.f / (1.f + __expf(-v)); }
; #define A256_LOADH(kt_, hf_) { a0 = la.ld1(kt_, (hf_) * 4 + 0, tid); a1 = la.ld1(kt_, (hf_) * 4 + 1, tid); a2 = la.ld1(kt_, (hf_) * 4 + 2, tid); a3 = la.ld1(kt_, (hf_) * 4 + 3, tid); }
; #define SW_FOR_TOK(j) _Pragma("unroll") for (int j = 0; j < 4; j++)
; #define SW_FOR_FEAT(i, rq) _Pragma("unroll") for (int i = 0; i < 2; i++) _Pragma("unroll") for (int rq = 0; rq < 4; rq++)
; template <bool swap, class LA>
; DI void gemm256_ws(const LA& la, const bf16_t* Wt, const int KS, const int nk, bf16_t* smem, f32x16 (&acc)[8]) {
;     ...
;     MMA256(1, w01, w11) W256_LD(kn, 1, w01, w11)
;     A256_STH(nxt, 0)
;     A256_LOADH(kn, 1)
;     MMA256(2, w02, w12) W256_LD(kn, 2, w02, w12)
;     MMA256(3, w03, w13) W256_LD(kn, 3, w03, w13)
;     A256_STH(nxt, 1)
;     __syncthreads();
; DI void ph_ple(const Params& P, int g, int layer, bf16_t* smem) {
;     ...
;     SW_FOR_TOK(j) { const int tl_ = wn * 128 + j * 32 + l32;
;       SW_FOR_FEAT(i, rq) { const int c_ = wm * 64 + i * 32 + 8 * rq + 4 * h;
;         *(uint2*)(smem + tl_ * EPLD + c_) = make_uint2(pk2(sigmoidf_(SWV(i, j, 4 * rq)), sigmoidf_(SWV(i, j, 4 * rq + 1))), pk2(sigmoidf_(SWV(i, j, 4 * rq + 2)), sigmoidf_(SWV(i, j, 4 * rq + 3)))); } }
	v_mfma_f32_32x32x16_bf16 v[98:113], v[130:133], v[194:197], v[98:113]
	v_mfma_f32_32x32x16_bf16 v[114:129], v[134:137], v[194:197], v[114:129]
	ds_read_b128 v[194:197], v0 offset:13920
	s_waitcnt lgkmcnt(2)
	v_mfma_f32_32x32x16_bf16 v[66:81], v[130:133], v[198:201], v[66:81]
	v_mfma_f32_32x32x16_bf16 v[82:97], v[134:137], v[198:201], v[82:97]
	s_waitcnt lgkmcnt(1)
	v_mfma_f32_32x32x16_bf16 v[34:49], v[130:133], v[202:205], v[34:49]
	v_mfma_f32_32x32x16_bf16 v[50:65], v[134:137], v[202:205], v[50:65]
	s_waitcnt lgkmcnt(0)
	v_mfma_f32_32x32x16_bf16 v[2:17], v[130:133], v[194:197], v[2:17]
	v_mfma_f32_32x32x16_bf16 v[18:33], v[134:137], v[194:197], v[18:33]
	v_lshl_add_u64 v[130:131], v[188:189], 0, s[90:91]
	global_load_dwordx4 v[130:133], v[130:131], off offset:3072
	v_lshl_add_u64 v[134:135], v[186:187], 0, s[90:91]
	global_load_dwordx4 v[134:137], v[134:135], off offset:3072
	s_waitcnt vmcnt(12)
	ds_write_b128 v185, v[224:227] offset:18432
	ds_write_b128 v185, v[228:231] offset:23040
	ds_write_b128 v185, v[246:249] offset:27648
	ds_write_b128 v185, v[178:181] offset:32256
	s_add_u32 s12, s10, s37
	s_addc_u32 s13, s11, 0
	v_lshl_add_u64 v[224:225], s[12:13], 0, v[176:177]
	s_add_u32 s12, s12, 0x1000
	s_addc_u32 s13, s13, 0
	v_lshl_add_u64 v[228:229], s[12:13], 0, v[176:177]
	s_add_u32 s12, s12, 0x1000
	s_addc_u32 s13, s13, 0
	v_lshl_add_u64 v[246:247], s[12:13], 0, v[176:177]
	s_add_u32 s12, s12, 0x1000
	s_addc_u32 s13, s13, 0
	v_lshl_add_u64 v[178:179], s[12:13], 0, v[176:177]
	global_load_dwordx4 v[224:227], v[224:225], off
	global_load_dwordx4 v[228:231], v[228:229], off
	global_load_dwordx4 v[246:249], v[246:247], off
	global_load_dwordx4 v[178:181], v[178:179], off
	s_and_b32 s12, s9, 1
	s_mul_i32 s12, s12, 0x9000
	v_add_u32_e32 v0, s12, v169
	s_cmp_lg_u32 s9, 16
	s_waitcnt lgkmcnt(0)
	s_barrier
	s_cbranch_scc1 .LBB0_236
	s_waitcnt vmcnt(0)
	v_mul_f32_e32 v0, 0xbfb8aa3b, v114
	v_exp_f32_e32 v114, v0
	v_mul_f32_e32 v0, 0xbfb8aa3b, v115
	v_exp_f32_e32 v115, v0
	v_readlane_b32 s10, v253, 45
	v_readlane_b32 s11, v253, 46
	s_mov_b32 s9, 0
	v_pk_add_f32 v[114:115], v[114:115], 1.0 op_sel_hi:[1,0]
	s_nop 0
	v_div_scale_f32 v0, s[2:3], v115, v115, 1.0
	s_waitcnt vmcnt(0)
	v_rcp_f32_e32 v130, v0
	s_nop 0
	v_fma_f32 v131, -v0, v130, 1.0
	v_fmac_f32_e32 v130, v131, v130
	v_div_scale_f32 v131, vcc, 1.0, v115, 1.0
	v_mul_f32_e32 v132, v131, v130
	v_fma_f32 v133, -v0, v132, v131
	v_fmac_f32_e32 v132, v133, v130
	v_fma_f32 v0, -v0, v132, v131
	v_div_fmas_f32 v0, v0, v130, v132
	v_div_fixup_f32 v0, v0, v115, 1.0
	v_div_scale_f32 v115, s[2:3], v114, v114, 1.0
	v_rcp_f32_e32 v130, v115
	s_nop 0
	v_fma_f32 v131, -v115, v130, 1.0
	v_fmac_f32_e32 v130, v131, v130
	v_div_scale_f32 v131, vcc, 1.0, v114, 1.0
	v_mul_f32_e32 v132, v131, v130
	v_fma_f32 v133, -v115, v132, v131
	v_fmac_f32_e32 v132, v133, v130
	v_fma_f32 v115, -v115, v132, v131
	v_div_fmas_f32 v115, v115, v130, v132
	v_div_fixup_f32 v114, v115, v114, 1.0
	v_cvt_pk_bf16_f32 v114, v114, v0
	v_mul_f32_e32 v0, 0xbfb8aa3b, v116
	v_exp_f32_e32 v116, v0
	v_mul_f32_e32 v0, 0xbfb8aa3b, v117
	v_exp_f32_e32 v117, v0
	s_nop 0
	v_pk_add_f32 v[116:117], v[116:117], 1.0 op_sel_hi:[1,0]
	s_nop 0
	v_div_scale_f32 v0, s[2:3], v117, v117, 1.0
	v_rcp_f32_e32 v115, v0
	s_nop 0
	v_fma_f32 v130, -v0, v115, 1.0
	v_fmac_f32_e32 v115, v130, v115
	v_div_scale_f32 v130, vcc, 1.0, v117, 1.0
	v_mul_f32_e32 v131, v130, v115
	v_fma_f32 v132, -v0, v131, v130
	v_fmac_f32_e32 v131, v132, v115
	v_fma_f32 v0, -v0, v131, v130
	v_div_fmas_f32 v0, v0, v115, v131
	v_div_scale_f32 v115, s[2:3], v116, v116, 1.0
	v_div_fixup_f32 v0, v0, v117, 1.0
	v_rcp_f32_e32 v117, v115
	s_nop 0
	v_fma_f32 v130, -v115, v117, 1.0
	v_fmac_f32_e32 v117, v130, v117
	v_div_scale_f32 v130, vcc, 1.0, v116, 1.0
	v_mul_f32_e32 v131, v130, v117
	v_fma_f32 v132, -v115, v131, v130
	v_fmac_f32_e32 v131, v132, v117
	v_fma_f32 v115, -v115, v131, v130
	v_div_fmas_f32 v115, v115, v117, v131
	v_div_fixup_f32 v115, v115, v116, 1.0
	v_cvt_pk_bf16_f32 v115, v115, v0
	v_mul_f32_e32 v0, 0xbfb8aa3b, v118
	v_exp_f32_e32 v116, v0
	v_mul_f32_e32 v0, 0xbfb8aa3b, v119
	v_exp_f32_e32 v117, v0
	s_nop 0
	v_pk_add_f32 v[116:117], v[116:117], 1.0 op_sel_hi:[1,0]
	s_nop 0
	v_div_scale_f32 v0, s[2:3], v117, v117, 1.0
	v_rcp_f32_e32 v118, v0
	s_nop 0
	v_fma_f32 v119, -v0, v118, 1.0
	v_fmac_f32_e32 v118, v119, v118
	v_div_scale_f32 v119, vcc, 1.0, v117, 1.0
	v_mul_f32_e32 v130, v119, v118
	v_fma_f32 v131, -v0, v130, v119
	v_fmac_f32_e32 v130, v131, v118
	v_fma_f32 v0, -v0, v130, v119
	v_div_fmas_f32 v0, v0, v118, v130
	v_div_fixup_f32 v0, v0, v117, 1.0
	v_div_scale_f32 v117, s[2:3], v116, v116, 1.0
	v_rcp_f32_e32 v118, v117
	s_nop 0
	v_fma_f32 v119, -v117, v118, 1.0
	v_fmac_f32_e32 v118, v119, v118
	v_div_scale_f32 v119, vcc, 1.0, v116, 1.0
	v_mul_f32_e32 v130, v119, v118
	v_fma_f32 v131, -v117, v130, v119
	v_fmac_f32_e32 v130, v131, v118
	v_fma_f32 v117, -v117, v130, v119
	v_div_fmas_f32 v117, v117, v118, v130
	v_div_fixup_f32 v116, v117, v116, 1.0
	v_cvt_pk_bf16_f32 v116, v116, v0
	v_mul_f32_e32 v0, 0xbfb8aa3b, v120
	v_exp_f32_e32 v118, v0
	v_mul_f32_e32 v0, 0xbfb8aa3b, v121
	v_exp_f32_e32 v119, v0
	s_nop 0
	v_pk_add_f32 v[118:119], v[118:119], 1.0 op_sel_hi:[1,0]
	s_nop 0
	v_div_scale_f32 v0, s[2:3], v119, v119, 1.0
	v_rcp_f32_e32 v117, v0
	s_nop 0
	v_fma_f32 v120, -v0, v117, 1.0
	v_fmac_f32_e32 v117, v120, v117
	v_div_scale_f32 v120, vcc, 1.0, v119, 1.0
	v_mul_f32_e32 v121, v120, v117
	v_fma_f32 v130, -v0, v121, v120
	v_fmac_f32_e32 v121, v130, v117
	v_fma_f32 v0, -v0, v121, v120
	v_div_fmas_f32 v0, v0, v117, v121
	v_div_scale_f32 v117, s[2:3], v118, v118, 1.0
	v_div_fixup_f32 v0, v0, v119, 1.0
; DI unsigned pk2(float a, float b) { f32v2 v = {a, b}; return __builtin_bit_cast(unsigned, __builtin_convertvector(v, bf16v2)); }
; DI float sigmoidf_(float v) { return 1.f / (1.f + __expf(-v)); }
; #define SW_FOR_TOK(j) _Pragma("unroll") for (int j = 0; j < 4; j++)
; #define SW_FOR_FEAT(i, rq) _Pragma("unroll") for (int i = 0; i < 2; i++) _Pragma("unroll") for (int rq = 0; rq < 4; rq++)
; DI void ph_ple(const Params& P, int g, int layer, bf16_t* smem) {
;     ...
;     SW_FOR_TOK(j) { const int tl_ = wn * 128 + j * 32 + l32;
;       SW_FOR_FEAT(i, rq) { const int c_ = wm * 64 + i * 32 + 8 * rq + 4 * h;
;         *(uint2*)(smem + tl_ * EPLD + c_) = make_uint2(pk2(sigmoidf_(SWV(i, j, 4 * rq)), sigmoidf_(SWV(i, j, 4 * rq + 1))), pk2(sigmoidf_(SWV(i, j, 4 * rq + 2)), sigmoidf_(SWV(i, j, 4 * rq + 3)))); } }
	v_rcp_f32_e32 v119, v117
	s_nop 0
	v_fma_f32 v120, -v117, v119, 1.0
	v_fmac_f32_e32 v119, v120, v119
	v_div_scale_f32 v120, vcc, 1.0, v118, 1.0
	v_mul_f32_e32 v121, v120, v119
	v_fma_f32 v130, -v117, v121, v120
	v_fmac_f32_e32 v121, v130, v119
	v_fma_f32 v117, -v117, v121, v120
	v_div_fmas_f32 v117, v117, v119, v121
	v_div_fixup_f32 v117, v117, v118, 1.0
	v_cvt_pk_bf16_f32 v117, v117, v0
	v_mul_f32_e32 v0, 0xbfb8aa3b, v122
	ds_write2_b64 v165, v[114:115], v[116:117] offset1:2
	v_exp_f32_e32 v114, v0
	v_mul_f32_e32 v0, 0xbfb8aa3b, v123
	v_exp_f32_e32 v115, v0
	s_nop 0
	v_pk_add_f32 v[114:115], v[114:115], 1.0 op_sel_hi:[1,0]
	s_nop 0
	v_div_scale_f32 v0, s[2:3], v115, v115, 1.0
	v_rcp_f32_e32 v116, v0
	s_nop 0
	v_fma_f32 v117, -v0, v116, 1.0
	v_fmac_f32_e32 v116, v117, v116
	v_div_scale_f32 v117, vcc, 1.0, v115, 1.0
	v_mul_f32_e32 v118, v117, v116
	v_fma_f32 v119, -v0, v118, v117
	v_fmac_f32_e32 v118, v119, v116
	v_fma_f32 v0, -v0, v118, v117
	v_div_fmas_f32 v0, v0, v116, v118
	v_div_fixup_f32 v0, v0, v115, 1.0
	v_div_scale_f32 v115, s[2:3], v114, v114, 1.0
	v_rcp_f32_e32 v116, v115
	s_nop 0
	v_fma_f32 v117, -v115, v116, 1.0
	v_fmac_f32_e32 v116, v117, v116
	v_div_scale_f32 v117, vcc, 1.0, v114, 1.0
	v_mul_f32_e32 v118, v117, v116
	v_fma_f32 v119, -v115, v118, v117
	v_fmac_f32_e32 v118, v119, v116
	v_fma_f32 v115, -v115, v118, v117
	v_div_fmas_f32 v115, v115, v116, v118
	v_div_fixup_f32 v114, v115, v114, 1.0
	v_cvt_pk_bf16_f32 v114, v114, v0
	v_mul_f32_e32 v0, 0xbfb8aa3b, v124
	v_exp_f32_e32 v116, v0
	v_mul_f32_e32 v0, 0xbfb8aa3b, v125
	v_exp_f32_e32 v117, v0
	s_nop 0
	v_pk_add_f32 v[116:117], v[116:117], 1.0 op_sel_hi:[1,0]
	s_nop 0
	v_div_scale_f32 v0, s[2:3], v117, v117, 1.0
	v_rcp_f32_e32 v115, v0
	s_nop 0
	v_fma_f32 v118, -v0, v115, 1.0
	v_fmac_f32_e32 v115, v118, v115
	v_div_scale_f32 v118, vcc, 1.0, v117, 1.0
	v_mul_f32_e32 v119, v118, v115
	v_fma_f32 v120, -v0, v119, v118
	v_fmac_f32_e32 v119, v120, v115
	v_fma_f32 v0, -v0, v119, v118
	v_div_fmas_f32 v0, v0, v115, v119
	v_div_scale_f32 v115, s[2:3], v116, v116, 1.0
	v_div_fixup_f32 v0, v0, v117, 1.0
	v_rcp_f32_e32 v117, v115
	s_nop 0
	v_fma_f32 v118, -v115, v117, 1.0
	v_fmac_f32_e32 v117, v118, v117
	v_div_scale_f32 v118, vcc, 1.0, v116, 1.0
	v_mul_f32_e32 v119, v118, v117
	v_fma_f32 v120, -v115, v119, v118
	v_fmac_f32_e32 v119, v120, v117
	v_fma_f32 v115, -v115, v119, v118
	v_div_fmas_f32 v115, v115, v117, v119
	v_div_fixup_f32 v115, v115, v116, 1.0
	v_cvt_pk_bf16_f32 v115, v115, v0
	v_mul_f32_e32 v0, 0xbfb8aa3b, v126
	v_exp_f32_e32 v116, v0
	v_mul_f32_e32 v0, 0xbfb8aa3b, v127
	v_exp_f32_e32 v117, v0
	s_nop 0
	v_pk_add_f32 v[116:117], v[116:117], 1.0 op_sel_hi:[1,0]
	s_nop 0
	v_div_scale_f32 v0, s[2:3], v117, v117, 1.0
	v_rcp_f32_e32 v118, v0
	s_nop 0
	v_fma_f32 v119, -v0, v118, 1.0
	v_fmac_f32_e32 v118, v119, v118
	v_div_scale_f32 v119, vcc, 1.0, v117, 1.0
	v_mul_f32_e32 v120, v119, v118
	v_fma_f32 v121, -v0, v120, v119
	v_fmac_f32_e32 v120, v121, v118
	v_fma_f32 v0, -v0, v120, v119
	v_div_fmas_f32 v0, v0, v118, v120
	v_div_fixup_f32 v0, v0, v117, 1.0
	v_div_scale_f32 v117, s[2:3], v116, v116, 1.0
	v_rcp_f32_e32 v118, v117
	s_nop 0
	v_fma_f32 v119, -v117, v118, 1.0
	v_fmac_f32_e32 v118, v119, v118
	v_div_scale_f32 v119, vcc, 1.0, v116, 1.0
	v_mul_f32_e32 v120, v119, v118
	v_fma_f32 v121, -v117, v120, v119
	v_fmac_f32_e32 v120, v121, v118
	v_fma_f32 v117, -v117, v120, v119
	v_div_fmas_f32 v117, v117, v118, v120
	v_div_fixup_f32 v116, v117, v116, 1.0
	v_cvt_pk_bf16_f32 v116, v116, v0
	v_mul_f32_e32 v0, 0xbfb8aa3b, v128
	v_exp_f32_e32 v118, v0
	v_mul_f32_e32 v0, 0xbfb8aa3b, v129
	v_exp_f32_e32 v119, v0
	s_nop 0
	v_pk_add_f32 v[118:119], v[118:119], 1.0 op_sel_hi:[1,0]
	s_nop 0
	v_div_scale_f32 v0, s[2:3], v119, v119, 1.0
	v_rcp_f32_e32 v117, v0
	s_nop 0
	v_fma_f32 v120, -v0, v117, 1.0
	v_fmac_f32_e32 v117, v120, v117
	v_div_scale_f32 v120, vcc, 1.0, v119, 1.0
	v_mul_f32_e32 v121, v120, v117
	v_fma_f32 v122, -v0, v121, v120
	v_fmac_f32_e32 v121, v122, v117
	v_fma_f32 v0, -v0, v121, v120
	v_div_fmas_f32 v0, v0, v117, v121
	v_div_scale_f32 v117, s[2:3], v118, v118, 1.0
	v_div_fixup_f32 v0, v0, v119, 1.0
	v_rcp_f32_e32 v119, v117
	s_nop 0
	v_fma_f32 v120, -v117, v119, 1.0
	v_fmac_f32_e32 v119, v120, v119
	v_div_scale_f32 v120, vcc, 1.0, v118, 1.0
	v_mul_f32_e32 v121, v120, v119
	v_fma_f32 v122, -v117, v121, v120
	v_fmac_f32_e32 v121, v122, v119
	v_fma_f32 v117, -v117, v121, v120
	v_div_fmas_f32 v117, v117, v119, v121
	v_div_fixup_f32 v117, v117, v118, 1.0
	v_cvt_pk_bf16_f32 v117, v117, v0
	v_mul_f32_e32 v0, 0xbfb8aa3b, v98
	v_exp_f32_e32 v98, v0
	v_mul_f32_e32 v0, 0xbfb8aa3b, v99
	v_exp_f32_e32 v99, v0
	ds_write2_b64 v165, v[114:115], v[116:117] offset0:4 offset1:6
	v_pk_add_f32 v[98:99], v[98:99], 1.0 op_sel_hi:[1,0]
	s_nop 0
	v_div_scale_f32 v0, s[2:3], v99, v99, 1.0
	v_rcp_f32_e32 v114, v0
	s_nop 0
	v_fma_f32 v115, -v0, v114, 1.0
	v_fmac_f32_e32 v114, v115, v114
	v_div_scale_f32 v115, vcc, 1.0, v99, 1.0
	v_mul_f32_e32 v116, v115, v114
	v_fma_f32 v117, -v0, v116, v115
	v_fmac_f32_e32 v116, v117, v114
	v_fma_f32 v0, -v0, v116, v115
	v_div_fmas_f32 v0, v0, v114, v116
	v_div_fixup_f32 v0, v0, v99, 1.0
	v_div_scale_f32 v99, s[2:3], v98, v98, 1.0
	v_rcp_f32_e32 v114, v99
	s_nop 0
	v_fma_f32 v115, -v99, v114, 1.0
	v_fmac_f32_e32 v114, v115, v114
	v_div_scale_f32 v115, vcc, 1.0, v98, 1.0
	v_mul_f32_e32 v116, v115, v114
	v_fma_f32 v117, -v99, v116, v115
	v_fmac_f32_e32 v116, v117, v114
	v_fma_f32 v99, -v99, v116, v115
	v_div_fmas_f32 v99, v99, v114, v116
	v_div_fixup_f32 v98, v99, v98, 1.0
	v_cvt_pk_bf16_f32 v98, v98, v0
	v_mul_f32_e32 v0, 0xbfb8aa3b, v100
	v_exp_f32_e32 v100, v0
; DI unsigned pk2(float a, float b) { f32v2 v = {a, b}; return __builtin_bit_cast(unsigned, __builtin_convertvector(v, bf16v2)); }
; DI float sigmoidf_(float v) { return 1.f / (1.f + __expf(-v)); }
; #define SW_FOR_TOK(j) _Pragma("unroll") for (int j = 0; j < 4; j++)
; #define SW_FOR_FEAT(i, rq) _Pragma("unroll") for (int i = 0; i < 2; i++) _Pragma("unroll") for (int rq = 0; rq < 4; rq++)
; DI void ph_ple(const Params& P, int g, int layer, bf16_t* smem) {
;     ...
;     SW_FOR_TOK(j) { const int tl_ = wn * 128 + j * 32 + l32;
;       SW_FOR_FEAT(i, rq) { const int c_ = wm * 64 + i * 32 + 8 * rq + 4 * h;
;         *(uint2*)(smem + tl_ * EPLD + c_) = make_uint2(pk2(sigmoidf_(SWV(i, j, 4 * rq)), sigmoidf_(SWV(i, j, 4 * rq + 1))), pk2(sigmoidf_(SWV(i, j, 4 * rq + 2)), sigmoidf_(SWV(i, j, 4 * rq + 3)))); } }
	v_mul_f32_e32 v0, 0xbfb8aa3b, v101
	v_exp_f32_e32 v101, v0
	s_nop 0
	v_pk_add_f32 v[100:101], v[100:101], 1.0 op_sel_hi:[1,0]
	s_nop 0
	v_div_scale_f32 v0, s[2:3], v101, v101, 1.0
	v_rcp_f32_e32 v99, v0
	s_nop 0
	v_fma_f32 v114, -v0, v99, 1.0
	v_fmac_f32_e32 v99, v114, v99
	v_div_scale_f32 v114, vcc, 1.0, v101, 1.0
	v_mul_f32_e32 v115, v114, v99
	v_fma_f32 v116, -v0, v115, v114
	v_fmac_f32_e32 v115, v116, v99
	v_fma_f32 v0, -v0, v115, v114
	v_div_fmas_f32 v0, v0, v99, v115
	v_div_scale_f32 v99, s[2:3], v100, v100, 1.0
	v_div_fixup_f32 v0, v0, v101, 1.0
	v_rcp_f32_e32 v101, v99
	s_nop 0
	v_fma_f32 v114, -v99, v101, 1.0
	v_fmac_f32_e32 v101, v114, v101
	v_div_scale_f32 v114, vcc, 1.0, v100, 1.0
	v_mul_f32_e32 v115, v114, v101
	v_fma_f32 v116, -v99, v115, v114
	v_fmac_f32_e32 v115, v116, v101
	v_fma_f32 v99, -v99, v115, v114
	v_div_fmas_f32 v99, v99, v101, v115
	v_div_fixup_f32 v99, v99, v100, 1.0
	v_cvt_pk_bf16_f32 v99, v99, v0
	v_mul_f32_e32 v0, 0xbfb8aa3b, v102
	v_exp_f32_e32 v100, v0
	v_mul_f32_e32 v0, 0xbfb8aa3b, v103
	v_exp_f32_e32 v101, v0
	s_nop 0
	v_pk_add_f32 v[100:101], v[100:101], 1.0 op_sel_hi:[1,0]
	s_nop 0
	v_div_scale_f32 v0, s[2:3], v101, v101, 1.0
	v_rcp_f32_e32 v102, v0
	s_nop 0
	v_fma_f32 v103, -v0, v102, 1.0
	v_fmac_f32_e32 v102, v103, v102
	v_div_scale_f32 v103, vcc, 1.0, v101, 1.0
	v_mul_f32_e32 v114, v103, v102
	v_fma_f32 v115, -v0, v114, v103
	v_fmac_f32_e32 v114, v115, v102
	v_fma_f32 v0, -v0, v114, v103
	v_div_fmas_f32 v0, v0, v102, v114
	v_div_fixup_f32 v0, v0, v101, 1.0
	v_div_scale_f32 v101, s[2:3], v100, v100, 1.0
	v_rcp_f32_e32 v102, v101
	s_nop 0
	v_fma_f32 v103, -v101, v102, 1.0
	v_fmac_f32_e32 v102, v103, v102
	v_div_scale_f32 v103, vcc, 1.0, v100, 1.0
	v_mul_f32_e32 v114, v103, v102
	v_fma_f32 v115, -v101, v114, v103
	v_fmac_f32_e32 v114, v115, v102
	v_fma_f32 v101, -v101, v114, v103
	v_div_fmas_f32 v101, v101, v102, v114
	v_div_fixup_f32 v100, v101, v100, 1.0
	v_cvt_pk_bf16_f32 v100, v100, v0
	v_mul_f32_e32 v0, 0xbfb8aa3b, v104
	v_exp_f32_e32 v102, v0
	v_mul_f32_e32 v0, 0xbfb8aa3b, v105
	v_exp_f32_e32 v103, v0
	s_nop 0
	v_pk_add_f32 v[102:103], v[102:103], 1.0 op_sel_hi:[1,0]
	s_nop 0
	v_div_scale_f32 v0, s[2:3], v103, v103, 1.0
	v_rcp_f32_e32 v101, v0
	s_nop 0
	v_fma_f32 v104, -v0, v101, 1.0
	v_fmac_f32_e32 v101, v104, v101
	v_div_scale_f32 v104, vcc, 1.0, v103, 1.0
	v_mul_f32_e32 v105, v104, v101
	v_fma_f32 v114, -v0, v105, v104
	v_fmac_f32_e32 v105, v114, v101
	v_fma_f32 v0, -v0, v105, v104
	v_div_fmas_f32 v0, v0, v101, v105
	v_div_scale_f32 v101, s[2:3], v102, v102, 1.0
	v_div_fixup_f32 v0, v0, v103, 1.0
	v_rcp_f32_e32 v103, v101
	s_nop 0
	v_fma_f32 v104, -v101, v103, 1.0
	v_fmac_f32_e32 v103, v104, v103
	v_div_scale_f32 v104, vcc, 1.0, v102, 1.0
	v_mul_f32_e32 v105, v104, v103
	v_fma_f32 v114, -v101, v105, v104
	v_fmac_f32_e32 v105, v114, v103
	v_fma_f32 v101, -v101, v105, v104
	v_div_fmas_f32 v101, v101, v103, v105
	v_div_fixup_f32 v101, v101, v102, 1.0
	v_cvt_pk_bf16_f32 v101, v101, v0
	v_mul_f32_e32 v0, 0xbfb8aa3b, v106
	ds_write2_b64 v165, v[98:99], v[100:101] offset0:8 offset1:10
	v_exp_f32_e32 v98, v0
	v_mul_f32_e32 v0, 0xbfb8aa3b, v107
	v_exp_f32_e32 v99, v0
	s_nop 0
	v_pk_add_f32 v[98:99], v[98:99], 1.0 op_sel_hi:[1,0]
	s_nop 0
	v_div_scale_f32 v0, s[2:3], v99, v99, 1.0
	v_rcp_f32_e32 v100, v0
	s_nop 0
	v_fma_f32 v101, -v0, v100, 1.0
	v_fmac_f32_e32 v100, v101, v100
	v_div_scale_f32 v101, vcc, 1.0, v99, 1.0
	v_mul_f32_e32 v102, v101, v100
	v_fma_f32 v103, -v0, v102, v101
	v_fmac_f32_e32 v102, v103, v100
	v_fma_f32 v0, -v0, v102, v101
	v_div_fmas_f32 v0, v0, v100, v102
	v_div_fixup_f32 v0, v0, v99, 1.0
	v_div_scale_f32 v99, s[2:3], v98, v98, 1.0
	v_rcp_f32_e32 v100, v99
	s_nop 0
	v_fma_f32 v101, -v99, v100, 1.0
	v_fmac_f32_e32 v100, v101, v100
	v_div_scale_f32 v101, vcc, 1.0, v98, 1.0
	v_mul_f32_e32 v102, v101, v100
	v_fma_f32 v103, -v99, v102, v101
	v_fmac_f32_e32 v102, v103, v100
	v_fma_f32 v99, -v99, v102, v101
	v_div_fmas_f32 v99, v99, v100, v102
	v_div_fixup_f32 v98, v99, v98, 1.0
	v_cvt_pk_bf16_f32 v98, v98, v0
	v_mul_f32_e32 v0, 0xbfb8aa3b, v108
	v_exp_f32_e32 v100, v0
	v_mul_f32_e32 v0, 0xbfb8aa3b, v109
	v_exp_f32_e32 v101, v0
	s_nop 0
	v_pk_add_f32 v[100:101], v[100:101], 1.0 op_sel_hi:[1,0]
	s_nop 0
	v_div_scale_f32 v0, s[2:3], v101, v101, 1.0
	v_rcp_f32_e32 v99, v0
	s_nop 0
	v_fma_f32 v102, -v0, v99, 1.0
	v_fmac_f32_e32 v99, v102, v99
	v_div_scale_f32 v102, vcc, 1.0, v101, 1.0
	v_mul_f32_e32 v103, v102, v99
	v_fma_f32 v104, -v0, v103, v102
	v_fmac_f32_e32 v103, v104, v99
	v_fma_f32 v0, -v0, v103, v102
	v_div_fmas_f32 v0, v0, v99, v103
	v_div_scale_f32 v99, s[2:3], v100, v100, 1.0
	v_div_fixup_f32 v0, v0, v101, 1.0
	v_rcp_f32_e32 v101, v99
	s_nop 0
	v_fma_f32 v102, -v99, v101, 1.0
	v_fmac_f32_e32 v101, v102, v101
	v_div_scale_f32 v102, vcc, 1.0, v100, 1.0
	v_mul_f32_e32 v103, v102, v101
	v_fma_f32 v104, -v99, v103, v102
	v_fmac_f32_e32 v103, v104, v101
	v_fma_f32 v99, -v99, v103, v102
	v_div_fmas_f32 v99, v99, v101, v103
	v_div_fixup_f32 v99, v99, v100, 1.0
	v_cvt_pk_bf16_f32 v99, v99, v0
	v_mul_f32_e32 v0, 0xbfb8aa3b, v110
	v_exp_f32_e32 v100, v0
	v_mul_f32_e32 v0, 0xbfb8aa3b, v111
	v_exp_f32_e32 v101, v0
	s_nop 0
	v_pk_add_f32 v[100:101], v[100:101], 1.0 op_sel_hi:[1,0]
	s_nop 0
	v_div_scale_f32 v0, s[2:3], v101, v101, 1.0
	v_rcp_f32_e32 v102, v0
	s_nop 0
	v_fma_f32 v103, -v0, v102, 1.0
	v_fmac_f32_e32 v102, v103, v102
	v_div_scale_f32 v103, vcc, 1.0, v101, 1.0
	v_mul_f32_e32 v104, v103, v102
	v_fma_f32 v105, -v0, v104, v103
	v_fmac_f32_e32 v104, v105, v102
	v_fma_f32 v0, -v0, v104, v103
	v_div_fmas_f32 v0, v0, v102, v104
	v_div_fixup_f32 v0, v0, v101, 1.0
; DI unsigned pk2(float a, float b) { f32v2 v = {a, b}; return __builtin_bit_cast(unsigned, __builtin_convertvector(v, bf16v2)); }
; DI float sigmoidf_(float v) { return 1.f / (1.f + __expf(-v)); }
; #define SW_FOR_TOK(j) _Pragma("unroll") for (int j = 0; j < 4; j++)
; #define SW_FOR_FEAT(i, rq) _Pragma("unroll") for (int i = 0; i < 2; i++) _Pragma("unroll") for (int rq = 0; rq < 4; rq++)
; DI void ph_ple(const Params& P, int g, int layer, bf16_t* smem) {
;     ...
;     SW_FOR_TOK(j) { const int tl_ = wn * 128 + j * 32 + l32;
;       SW_FOR_FEAT(i, rq) { const int c_ = wm * 64 + i * 32 + 8 * rq + 4 * h;
;         *(uint2*)(smem + tl_ * EPLD + c_) = make_uint2(pk2(sigmoidf_(SWV(i, j, 4 * rq)), sigmoidf_(SWV(i, j, 4 * rq + 1))), pk2(sigmoidf_(SWV(i, j, 4 * rq + 2)), sigmoidf_(SWV(i, j, 4 * rq + 3)))); } }
	v_div_scale_f32 v101, s[2:3], v100, v100, 1.0
	v_rcp_f32_e32 v102, v101
	s_nop 0
	v_fma_f32 v103, -v101, v102, 1.0
	v_fmac_f32_e32 v102, v103, v102
	v_div_scale_f32 v103, vcc, 1.0, v100, 1.0
	v_mul_f32_e32 v104, v103, v102
	v_fma_f32 v105, -v101, v104, v103
	v_fmac_f32_e32 v104, v105, v102
	v_fma_f32 v101, -v101, v104, v103
	v_div_fmas_f32 v101, v101, v102, v104
	v_div_fixup_f32 v100, v101, v100, 1.0
	v_cvt_pk_bf16_f32 v100, v100, v0
	v_mul_f32_e32 v0, 0xbfb8aa3b, v112
	v_exp_f32_e32 v102, v0
	v_mul_f32_e32 v0, 0xbfb8aa3b, v113
	v_exp_f32_e32 v103, v0
	s_nop 0
	v_pk_add_f32 v[102:103], v[102:103], 1.0 op_sel_hi:[1,0]
	s_nop 0
	v_div_scale_f32 v0, s[2:3], v103, v103, 1.0
	v_rcp_f32_e32 v101, v0
	s_nop 0
	v_fma_f32 v104, -v0, v101, 1.0
	v_fmac_f32_e32 v101, v104, v101
	v_div_scale_f32 v104, vcc, 1.0, v103, 1.0
	v_mul_f32_e32 v105, v104, v101
	v_fma_f32 v106, -v0, v105, v104
	v_fmac_f32_e32 v105, v106, v101
	v_fma_f32 v0, -v0, v105, v104
	v_div_fmas_f32 v0, v0, v101, v105
	v_div_scale_f32 v101, s[2:3], v102, v102, 1.0
	v_div_fixup_f32 v0, v0, v103, 1.0
	v_rcp_f32_e32 v103, v101
	s_nop 0
	v_fma_f32 v104, -v101, v103, 1.0
	v_fmac_f32_e32 v103, v104, v103
	v_div_scale_f32 v104, vcc, 1.0, v102, 1.0
	v_mul_f32_e32 v105, v104, v103
	v_fma_f32 v106, -v101, v105, v104
	v_fmac_f32_e32 v105, v106, v103
	v_fma_f32 v101, -v101, v105, v104
	v_div_fmas_f32 v101, v101, v103, v105
	v_div_fixup_f32 v101, v101, v102, 1.0
	v_cvt_pk_bf16_f32 v101, v101, v0
	v_mul_f32_e32 v0, 0xbfb8aa3b, v82
	v_exp_f32_e32 v82, v0
	v_mul_f32_e32 v0, 0xbfb8aa3b, v83
	v_exp_f32_e32 v83, v0
	ds_write2_b64 v165, v[98:99], v[100:101] offset0:12 offset1:14
	v_pk_add_f32 v[82:83], v[82:83], 1.0 op_sel_hi:[1,0]
	s_nop 0
	v_div_scale_f32 v0, s[2:3], v83, v83, 1.0
	v_rcp_f32_e32 v98, v0
	s_nop 0
	v_fma_f32 v99, -v0, v98, 1.0
	v_fmac_f32_e32 v98, v99, v98
	v_div_scale_f32 v99, vcc, 1.0, v83, 1.0
	v_mul_f32_e32 v100, v99, v98
	v_fma_f32 v101, -v0, v100, v99
	v_fmac_f32_e32 v100, v101, v98
	v_fma_f32 v0, -v0, v100, v99
	v_div_fmas_f32 v0, v0, v98, v100
	v_div_fixup_f32 v0, v0, v83, 1.0
	v_div_scale_f32 v83, s[2:3], v82, v82, 1.0
	v_rcp_f32_e32 v98, v83
	s_nop 0
	v_fma_f32 v99, -v83, v98, 1.0
	v_fmac_f32_e32 v98, v99, v98
	v_div_scale_f32 v99, vcc, 1.0, v82, 1.0
	v_mul_f32_e32 v100, v99, v98
	v_fma_f32 v101, -v83, v100, v99
	v_fmac_f32_e32 v100, v101, v98
	v_fma_f32 v83, -v83, v100, v99
	v_div_fmas_f32 v83, v83, v98, v100
	v_div_fixup_f32 v82, v83, v82, 1.0
	v_cvt_pk_bf16_f32 v82, v82, v0
	v_mul_f32_e32 v0, 0xbfb8aa3b, v84
	v_exp_f32_e32 v84, v0
	v_mul_f32_e32 v0, 0xbfb8aa3b, v85
	v_exp_f32_e32 v85, v0
	s_nop 0
	v_pk_add_f32 v[84:85], v[84:85], 1.0 op_sel_hi:[1,0]
	s_nop 0
	v_div_scale_f32 v0, s[2:3], v85, v85, 1.0
	v_rcp_f32_e32 v83, v0
	s_nop 0
	v_fma_f32 v98, -v0, v83, 1.0
	v_fmac_f32_e32 v83, v98, v83
	v_div_scale_f32 v98, vcc, 1.0, v85, 1.0
	v_mul_f32_e32 v99, v98, v83
	v_fma_f32 v100, -v0, v99, v98
	v_fmac_f32_e32 v99, v100, v83
	v_fma_f32 v0, -v0, v99, v98
	v_div_fmas_f32 v0, v0, v83, v99
	v_div_scale_f32 v83, s[2:3], v84, v84, 1.0
	v_div_fixup_f32 v0, v0, v85, 1.0
	v_rcp_f32_e32 v85, v83
	s_nop 0
	v_fma_f32 v98, -v83, v85, 1.0
	v_fmac_f32_e32 v85, v98, v85
	v_div_scale_f32 v98, vcc, 1.0, v84, 1.0
	v_mul_f32_e32 v99, v98, v85
	v_fma_f32 v100, -v83, v99, v98
	v_fmac_f32_e32 v99, v100, v85
	v_fma_f32 v83, -v83, v99, v98
	v_div_fmas_f32 v83, v83, v85, v99
	v_div_fixup_f32 v83, v83, v84, 1.0
	v_cvt_pk_bf16_f32 v83, v83, v0
	v_mul_f32_e32 v0, 0xbfb8aa3b, v86
	v_exp_f32_e32 v84, v0
	v_mul_f32_e32 v0, 0xbfb8aa3b, v87
	v_exp_f32_e32 v85, v0
	s_nop 0
	v_pk_add_f32 v[84:85], v[84:85], 1.0 op_sel_hi:[1,0]
	s_nop 0
	v_div_scale_f32 v0, s[2:3], v85, v85, 1.0
	v_rcp_f32_e32 v86, v0
	s_nop 0
	v_fma_f32 v87, -v0, v86, 1.0
	v_fmac_f32_e32 v86, v87, v86
	v_div_scale_f32 v87, vcc, 1.0, v85, 1.0
	v_mul_f32_e32 v98, v87, v86
	v_fma_f32 v99, -v0, v98, v87
	v_fmac_f32_e32 v98, v99, v86
	v_fma_f32 v0, -v0, v98, v87
	v_div_fmas_f32 v0, v0, v86, v98
	v_div_fixup_f32 v0, v0, v85, 1.0
	v_div_scale_f32 v85, s[2:3], v84, v84, 1.0
	v_rcp_f32_e32 v86, v85
	s_nop 0
	v_fma_f32 v87, -v85, v86, 1.0
	v_fmac_f32_e32 v86, v87, v86
	v_div_scale_f32 v87, vcc, 1.0, v84, 1.0
	v_mul_f32_e32 v98, v87, v86
	v_fma_f32 v99, -v85, v98, v87
	v_fmac_f32_e32 v98, v99, v86
	v_fma_f32 v85, -v85, v98, v87
	v_div_fmas_f32 v85, v85, v86, v98
	v_div_fixup_f32 v84, v85, v84, 1.0
	v_cvt_pk_bf16_f32 v84, v84, v0
	v_mul_f32_e32 v0, 0xbfb8aa3b, v88
	v_exp_f32_e32 v86, v0
	v_mul_f32_e32 v0, 0xbfb8aa3b, v89
	v_exp_f32_e32 v87, v0
	s_nop 0
	v_pk_add_f32 v[86:87], v[86:87], 1.0 op_sel_hi:[1,0]
	s_nop 0
	v_div_scale_f32 v0, s[2:3], v87, v87, 1.0
	v_rcp_f32_e32 v85, v0
	s_nop 0
	v_fma_f32 v88, -v0, v85, 1.0
	v_fmac_f32_e32 v85, v88, v85
	v_div_scale_f32 v88, vcc, 1.0, v87, 1.0
	v_mul_f32_e32 v89, v88, v85
	v_fma_f32 v98, -v0, v89, v88
	v_fmac_f32_e32 v89, v98, v85
	v_fma_f32 v0, -v0, v89, v88
	v_div_fmas_f32 v0, v0, v85, v89
	v_div_scale_f32 v85, s[2:3], v86, v86, 1.0
	v_div_fixup_f32 v0, v0, v87, 1.0
	v_rcp_f32_e32 v87, v85
	s_nop 0
	v_fma_f32 v88, -v85, v87, 1.0
	v_fmac_f32_e32 v87, v88, v87
	v_div_scale_f32 v88, vcc, 1.0, v86, 1.0
	v_mul_f32_e32 v89, v88, v87
	v_fma_f32 v98, -v85, v89, v88
	v_fmac_f32_e32 v89, v98, v87
	v_fma_f32 v85, -v85, v89, v88
	v_div_fmas_f32 v85, v85, v87, v89
	v_div_fixup_f32 v85, v85, v86, 1.0
	v_cvt_pk_bf16_f32 v85, v85, v0
	v_mul_f32_e32 v0, 0xbfb8aa3b, v90
	ds_write2_b64 v193, v[82:83], v[84:85] offset0:64 offset1:66
	v_exp_f32_e32 v82, v0
	v_mul_f32_e32 v0, 0xbfb8aa3b, v91
	v_exp_f32_e32 v83, v0
	s_nop 0
	v_pk_add_f32 v[82:83], v[82:83], 1.0 op_sel_hi:[1,0]
	s_nop 0
	v_div_scale_f32 v0, s[2:3], v83, v83, 1.0
; DI unsigned pk2(float a, float b) { f32v2 v = {a, b}; return __builtin_bit_cast(unsigned, __builtin_convertvector(v, bf16v2)); }
; DI float sigmoidf_(float v) { return 1.f / (1.f + __expf(-v)); }
; #define SW_FOR_TOK(j) _Pragma("unroll") for (int j = 0; j < 4; j++)
; #define SW_FOR_FEAT(i, rq) _Pragma("unroll") for (int i = 0; i < 2; i++) _Pragma("unroll") for (int rq = 0; rq < 4; rq++)
; DI void ph_ple(const Params& P, int g, int layer, bf16_t* smem) {
;     ...
;     SW_FOR_TOK(j) { const int tl_ = wn * 128 + j * 32 + l32;
;       SW_FOR_FEAT(i, rq) { const int c_ = wm * 64 + i * 32 + 8 * rq + 4 * h;
;         *(uint2*)(smem + tl_ * EPLD + c_) = make_uint2(pk2(sigmoidf_(SWV(i, j, 4 * rq)), sigmoidf_(SWV(i, j, 4 * rq + 1))), pk2(sigmoidf_(SWV(i, j, 4 * rq + 2)), sigmoidf_(SWV(i, j, 4 * rq + 3)))); } }
	v_rcp_f32_e32 v84, v0
	s_nop 0
	v_fma_f32 v85, -v0, v84, 1.0
	v_fmac_f32_e32 v84, v85, v84
	v_div_scale_f32 v85, vcc, 1.0, v83, 1.0
	v_mul_f32_e32 v86, v85, v84
	v_fma_f32 v87, -v0, v86, v85
	v_fmac_f32_e32 v86, v87, v84
	v_fma_f32 v0, -v0, v86, v85
	v_div_fmas_f32 v0, v0, v84, v86
	v_div_fixup_f32 v0, v0, v83, 1.0
	v_div_scale_f32 v83, s[2:3], v82, v82, 1.0
	v_rcp_f32_e32 v84, v83
	s_nop 0
	v_fma_f32 v85, -v83, v84, 1.0
	v_fmac_f32_e32 v84, v85, v84
	v_div_scale_f32 v85, vcc, 1.0, v82, 1.0
	v_mul_f32_e32 v86, v85, v84
	v_fma_f32 v87, -v83, v86, v85
	v_fmac_f32_e32 v86, v87, v84
	v_fma_f32 v83, -v83, v86, v85
	v_div_fmas_f32 v83, v83, v84, v86
	v_div_fixup_f32 v82, v83, v82, 1.0
	v_cvt_pk_bf16_f32 v82, v82, v0
	v_mul_f32_e32 v0, 0xbfb8aa3b, v92
	v_exp_f32_e32 v84, v0
	v_mul_f32_e32 v0, 0xbfb8aa3b, v93
	v_exp_f32_e32 v85, v0
	s_nop 0
	v_pk_add_f32 v[84:85], v[84:85], 1.0 op_sel_hi:[1,0]
	s_nop 0
	v_div_scale_f32 v0, s[2:3], v85, v85, 1.0
	v_rcp_f32_e32 v83, v0
	s_nop 0
	v_fma_f32 v86, -v0, v83, 1.0
	v_fmac_f32_e32 v83, v86, v83
	v_div_scale_f32 v86, vcc, 1.0, v85, 1.0
	v_mul_f32_e32 v87, v86, v83
	v_fma_f32 v88, -v0, v87, v86
	v_fmac_f32_e32 v87, v88, v83
	v_fma_f32 v0, -v0, v87, v86
	v_div_fmas_f32 v0, v0, v83, v87
	v_div_scale_f32 v83, s[2:3], v84, v84, 1.0
	v_div_fixup_f32 v0, v0, v85, 1.0
	v_rcp_f32_e32 v85, v83
	s_nop 0
	v_fma_f32 v86, -v83, v85, 1.0
	v_fmac_f32_e32 v85, v86, v85
	v_div_scale_f32 v86, vcc, 1.0, v84, 1.0
	v_mul_f32_e32 v87, v86, v85
	v_fma_f32 v88, -v83, v87, v86
	v_fmac_f32_e32 v87, v88, v85
	v_fma_f32 v83, -v83, v87, v86
	v_div_fmas_f32 v83, v83, v85, v87
	v_div_fixup_f32 v83, v83, v84, 1.0
	v_cvt_pk_bf16_f32 v83, v83, v0
	v_mul_f32_e32 v0, 0xbfb8aa3b, v94
	v_exp_f32_e32 v84, v0
	v_mul_f32_e32 v0, 0xbfb8aa3b, v95
	v_exp_f32_e32 v85, v0
	s_nop 0
	v_pk_add_f32 v[84:85], v[84:85], 1.0 op_sel_hi:[1,0]
	s_nop 0
	v_div_scale_f32 v0, s[2:3], v85, v85, 1.0
	v_rcp_f32_e32 v86, v0
	s_nop 0
	v_fma_f32 v87, -v0, v86, 1.0
	v_fmac_f32_e32 v86, v87, v86
	v_div_scale_f32 v87, vcc, 1.0, v85, 1.0
	v_mul_f32_e32 v88, v87, v86
	v_fma_f32 v89, -v0, v88, v87
	v_fmac_f32_e32 v88, v89, v86
	v_fma_f32 v0, -v0, v88, v87
	v_div_fmas_f32 v0, v0, v86, v88
	v_div_fixup_f32 v0, v0, v85, 1.0
	v_div_scale_f32 v85, s[2:3], v84, v84, 1.0
	v_rcp_f32_e32 v86, v85
	s_nop 0
	v_fma_f32 v87, -v85, v86, 1.0
	v_fmac_f32_e32 v86, v87, v86
	v_div_scale_f32 v87, vcc, 1.0, v84, 1.0
	v_mul_f32_e32 v88, v87, v86
	v_fma_f32 v89, -v85, v88, v87
	v_fmac_f32_e32 v88, v89, v86
	v_fma_f32 v85, -v85, v88, v87
	v_div_fmas_f32 v85, v85, v86, v88
	v_div_fixup_f32 v84, v85, v84, 1.0
	v_cvt_pk_bf16_f32 v84, v84, v0
	v_mul_f32_e32 v0, 0xbfb8aa3b, v96
	v_exp_f32_e32 v86, v0
	v_mul_f32_e32 v0, 0xbfb8aa3b, v97
	v_exp_f32_e32 v87, v0
	s_nop 0
	v_pk_add_f32 v[86:87], v[86:87], 1.0 op_sel_hi:[1,0]
	s_nop 0
	v_div_scale_f32 v0, s[2:3], v87, v87, 1.0
	v_rcp_f32_e32 v85, v0
	s_nop 0
	v_fma_f32 v88, -v0, v85, 1.0
	v_fmac_f32_e32 v85, v88, v85
	v_div_scale_f32 v88, vcc, 1.0, v87, 1.0
	v_mul_f32_e32 v89, v88, v85
	v_fma_f32 v90, -v0, v89, v88
	v_fmac_f32_e32 v89, v90, v85
	v_fma_f32 v0, -v0, v89, v88
	v_div_fmas_f32 v0, v0, v85, v89
	v_div_scale_f32 v85, s[2:3], v86, v86, 1.0
	v_div_fixup_f32 v0, v0, v87, 1.0
	v_rcp_f32_e32 v87, v85
	s_nop 0
	v_fma_f32 v88, -v85, v87, 1.0
	v_fmac_f32_e32 v87, v88, v87
	v_div_scale_f32 v88, vcc, 1.0, v86, 1.0
	v_mul_f32_e32 v89, v88, v87
	v_fma_f32 v90, -v85, v89, v88
	v_fmac_f32_e32 v89, v90, v87
	v_fma_f32 v85, -v85, v89, v88
	v_div_fmas_f32 v85, v85, v87, v89
	v_div_fixup_f32 v85, v85, v86, 1.0
	v_cvt_pk_bf16_f32 v85, v85, v0
	v_mul_f32_e32 v0, 0xbfb8aa3b, v66
	v_exp_f32_e32 v66, v0
	v_mul_f32_e32 v0, 0xbfb8aa3b, v67
	v_exp_f32_e32 v67, v0
	ds_write2_b64 v193, v[82:83], v[84:85] offset0:68 offset1:70
	v_pk_add_f32 v[66:67], v[66:67], 1.0 op_sel_hi:[1,0]
	s_nop 0
	v_div_scale_f32 v0, s[2:3], v67, v67, 1.0
	v_rcp_f32_e32 v82, v0
	s_nop 0
	v_fma_f32 v83, -v0, v82, 1.0
	v_fmac_f32_e32 v82, v83, v82
	v_div_scale_f32 v83, vcc, 1.0, v67, 1.0
	v_mul_f32_e32 v84, v83, v82
	v_fma_f32 v85, -v0, v84, v83
	v_fmac_f32_e32 v84, v85, v82
	v_fma_f32 v0, -v0, v84, v83
	v_div_fmas_f32 v0, v0, v82, v84
	v_div_fixup_f32 v0, v0, v67, 1.0
	v_div_scale_f32 v67, s[2:3], v66, v66, 1.0
	v_rcp_f32_e32 v82, v67
	s_nop 0
	v_fma_f32 v83, -v67, v82, 1.0
	v_fmac_f32_e32 v82, v83, v82
	v_div_scale_f32 v83, vcc, 1.0, v66, 1.0
	v_mul_f32_e32 v84, v83, v82
	v_fma_f32 v85, -v67, v84, v83
	v_fmac_f32_e32 v84, v85, v82
	v_fma_f32 v67, -v67, v84, v83
	v_div_fmas_f32 v67, v67, v82, v84
	v_div_fixup_f32 v66, v67, v66, 1.0
	v_cvt_pk_bf16_f32 v66, v66, v0
	v_mul_f32_e32 v0, 0xbfb8aa3b, v68
	v_exp_f32_e32 v68, v0
	v_mul_f32_e32 v0, 0xbfb8aa3b, v69
	v_exp_f32_e32 v69, v0
	s_nop 0
	v_pk_add_f32 v[68:69], v[68:69], 1.0 op_sel_hi:[1,0]
	s_nop 0
	v_div_scale_f32 v0, s[2:3], v69, v69, 1.0
	v_rcp_f32_e32 v67, v0
	s_nop 0
	v_fma_f32 v82, -v0, v67, 1.0
	v_fmac_f32_e32 v67, v82, v67
	v_div_scale_f32 v82, vcc, 1.0, v69, 1.0
	v_mul_f32_e32 v83, v82, v67
	v_fma_f32 v84, -v0, v83, v82
	v_fmac_f32_e32 v83, v84, v67
	v_fma_f32 v0, -v0, v83, v82
	v_div_fmas_f32 v0, v0, v67, v83
	v_div_scale_f32 v67, s[2:3], v68, v68, 1.0
	v_div_fixup_f32 v0, v0, v69, 1.0
	v_rcp_f32_e32 v69, v67
	s_nop 0
	v_fma_f32 v82, -v67, v69, 1.0
	v_fmac_f32_e32 v69, v82, v69
	v_div_scale_f32 v82, vcc, 1.0, v68, 1.0
	v_mul_f32_e32 v83, v82, v69
	v_fma_f32 v84, -v67, v83, v82
	v_fmac_f32_e32 v83, v84, v69
	v_fma_f32 v67, -v67, v83, v82
	v_div_fmas_f32 v67, v67, v69, v83
	v_div_fixup_f32 v67, v67, v68, 1.0
	v_cvt_pk_bf16_f32 v67, v67, v0
	v_mul_f32_e32 v0, 0xbfb8aa3b, v70
	v_exp_f32_e32 v68, v0
	v_mul_f32_e32 v0, 0xbfb8aa3b, v71
	v_exp_f32_e32 v69, v0
; DI unsigned pk2(float a, float b) { f32v2 v = {a, b}; return __builtin_bit_cast(unsigned, __builtin_convertvector(v, bf16v2)); }
; DI float sigmoidf_(float v) { return 1.f / (1.f + __expf(-v)); }
; #define SW_FOR_TOK(j) _Pragma("unroll") for (int j = 0; j < 4; j++)
; #define SW_FOR_FEAT(i, rq) _Pragma("unroll") for (int i = 0; i < 2; i++) _Pragma("unroll") for (int rq = 0; rq < 4; rq++)
; DI void ph_ple(const Params& P, int g, int layer, bf16_t* smem) {
;     ...
;     SW_FOR_TOK(j) { const int tl_ = wn * 128 + j * 32 + l32;
;       SW_FOR_FEAT(i, rq) { const int c_ = wm * 64 + i * 32 + 8 * rq + 4 * h;
;         *(uint2*)(smem + tl_ * EPLD + c_) = make_uint2(pk2(sigmoidf_(SWV(i, j, 4 * rq)), sigmoidf_(SWV(i, j, 4 * rq + 1))), pk2(sigmoidf_(SWV(i, j, 4 * rq + 2)), sigmoidf_(SWV(i, j, 4 * rq + 3)))); } }
	s_nop 0
	v_pk_add_f32 v[68:69], v[68:69], 1.0 op_sel_hi:[1,0]
	s_nop 0
	v_div_scale_f32 v0, s[2:3], v69, v69, 1.0
	v_rcp_f32_e32 v70, v0
	s_nop 0
	v_fma_f32 v71, -v0, v70, 1.0
	v_fmac_f32_e32 v70, v71, v70
	v_div_scale_f32 v71, vcc, 1.0, v69, 1.0
	v_mul_f32_e32 v82, v71, v70
	v_fma_f32 v83, -v0, v82, v71
	v_fmac_f32_e32 v82, v83, v70
	v_fma_f32 v0, -v0, v82, v71
	v_div_fmas_f32 v0, v0, v70, v82
	v_div_fixup_f32 v0, v0, v69, 1.0
	v_div_scale_f32 v69, s[2:3], v68, v68, 1.0
	v_rcp_f32_e32 v70, v69
	s_nop 0
	v_fma_f32 v71, -v69, v70, 1.0
	v_fmac_f32_e32 v70, v71, v70
	v_div_scale_f32 v71, vcc, 1.0, v68, 1.0
	v_mul_f32_e32 v82, v71, v70
	v_fma_f32 v83, -v69, v82, v71
	v_fmac_f32_e32 v82, v83, v70
	v_fma_f32 v69, -v69, v82, v71
	v_div_fmas_f32 v69, v69, v70, v82
	v_div_fixup_f32 v68, v69, v68, 1.0
	v_cvt_pk_bf16_f32 v68, v68, v0
	v_mul_f32_e32 v0, 0xbfb8aa3b, v72
	v_exp_f32_e32 v70, v0
	v_mul_f32_e32 v0, 0xbfb8aa3b, v73
	v_exp_f32_e32 v71, v0
	s_nop 0
	v_pk_add_f32 v[70:71], v[70:71], 1.0 op_sel_hi:[1,0]
	s_nop 0
	v_div_scale_f32 v0, s[2:3], v71, v71, 1.0
	v_rcp_f32_e32 v69, v0
	s_nop 0
	v_fma_f32 v72, -v0, v69, 1.0
	v_fmac_f32_e32 v69, v72, v69
	v_div_scale_f32 v72, vcc, 1.0, v71, 1.0
	v_mul_f32_e32 v73, v72, v69
	v_fma_f32 v82, -v0, v73, v72
	v_fmac_f32_e32 v73, v82, v69
	v_fma_f32 v0, -v0, v73, v72
	v_div_fmas_f32 v0, v0, v69, v73
	v_div_scale_f32 v69, s[2:3], v70, v70, 1.0
	v_div_fixup_f32 v0, v0, v71, 1.0
	v_rcp_f32_e32 v71, v69
	s_nop 0
	v_fma_f32 v72, -v69, v71, 1.0
	v_fmac_f32_e32 v71, v72, v71
	v_div_scale_f32 v72, vcc, 1.0, v70, 1.0
	v_mul_f32_e32 v73, v72, v71
	v_fma_f32 v82, -v69, v73, v72
	v_fmac_f32_e32 v73, v82, v71
	v_fma_f32 v69, -v69, v73, v72
	v_div_fmas_f32 v69, v69, v71, v73
	v_div_fixup_f32 v69, v69, v70, 1.0
	v_cvt_pk_bf16_f32 v69, v69, v0
	v_mul_f32_e32 v0, 0xbfb8aa3b, v74
	ds_write2_b64 v193, v[66:67], v[68:69] offset0:72 offset1:74
	v_exp_f32_e32 v66, v0
	v_mul_f32_e32 v0, 0xbfb8aa3b, v75
	v_exp_f32_e32 v67, v0
	s_nop 0
	v_pk_add_f32 v[66:67], v[66:67], 1.0 op_sel_hi:[1,0]
	s_nop 0
	v_div_scale_f32 v0, s[2:3], v67, v67, 1.0
	v_rcp_f32_e32 v68, v0
	s_nop 0
	v_fma_f32 v69, -v0, v68, 1.0
	v_fmac_f32_e32 v68, v69, v68
	v_div_scale_f32 v69, vcc, 1.0, v67, 1.0
	v_mul_f32_e32 v70, v69, v68
	v_fma_f32 v71, -v0, v70, v69
	v_fmac_f32_e32 v70, v71, v68
	v_fma_f32 v0, -v0, v70, v69
	v_div_fmas_f32 v0, v0, v68, v70
	v_div_fixup_f32 v0, v0, v67, 1.0
	v_div_scale_f32 v67, s[2:3], v66, v66, 1.0
	v_rcp_f32_e32 v68, v67
	s_nop 0
	v_fma_f32 v69, -v67, v68, 1.0
	v_fmac_f32_e32 v68, v69, v68
	v_div_scale_f32 v69, vcc, 1.0, v66, 1.0
	v_mul_f32_e32 v70, v69, v68
	v_fma_f32 v71, -v67, v70, v69
	v_fmac_f32_e32 v70, v71, v68
	v_fma_f32 v67, -v67, v70, v69
	v_div_fmas_f32 v67, v67, v68, v70
	v_div_fixup_f32 v66, v67, v66, 1.0
	v_cvt_pk_bf16_f32 v66, v66, v0
	v_mul_f32_e32 v0, 0xbfb8aa3b, v76
	v_exp_f32_e32 v68, v0
	v_mul_f32_e32 v0, 0xbfb8aa3b, v77
	v_exp_f32_e32 v69, v0
	s_nop 0
	v_pk_add_f32 v[68:69], v[68:69], 1.0 op_sel_hi:[1,0]
	s_nop 0
	v_div_scale_f32 v0, s[2:3], v69, v69, 1.0
	v_rcp_f32_e32 v67, v0
	s_nop 0
	v_fma_f32 v70, -v0, v67, 1.0
	v_fmac_f32_e32 v67, v70, v67
	v_div_scale_f32 v70, vcc, 1.0, v69, 1.0
	v_mul_f32_e32 v71, v70, v67
	v_fma_f32 v72, -v0, v71, v70
	v_fmac_f32_e32 v71, v72, v67
	v_fma_f32 v0, -v0, v71, v70
	v_div_fmas_f32 v0, v0, v67, v71
	v_div_scale_f32 v67, s[2:3], v68, v68, 1.0
	v_div_fixup_f32 v0, v0, v69, 1.0
	v_rcp_f32_e32 v69, v67
	s_nop 0
	v_fma_f32 v70, -v67, v69, 1.0
	v_fmac_f32_e32 v69, v70, v69
	v_div_scale_f32 v70, vcc, 1.0, v68, 1.0
	v_mul_f32_e32 v71, v70, v69
	v_fma_f32 v72, -v67, v71, v70
	v_fmac_f32_e32 v71, v72, v69
	v_fma_f32 v67, -v67, v71, v70
	v_div_fmas_f32 v67, v67, v69, v71
	v_div_fixup_f32 v67, v67, v68, 1.0
	v_cvt_pk_bf16_f32 v67, v67, v0
	v_mul_f32_e32 v0, 0xbfb8aa3b, v78
	v_exp_f32_e32 v68, v0
	v_mul_f32_e32 v0, 0xbfb8aa3b, v79
	v_exp_f32_e32 v69, v0
	s_nop 0
	v_pk_add_f32 v[68:69], v[68:69], 1.0 op_sel_hi:[1,0]
	s_nop 0
	v_div_scale_f32 v0, s[2:3], v69, v69, 1.0
	v_rcp_f32_e32 v70, v0
	s_nop 0
	v_fma_f32 v71, -v0, v70, 1.0
	v_fmac_f32_e32 v70, v71, v70
	v_div_scale_f32 v71, vcc, 1.0, v69, 1.0
	v_mul_f32_e32 v72, v71, v70
	v_fma_f32 v73, -v0, v72, v71
	v_fmac_f32_e32 v72, v73, v70
	v_fma_f32 v0, -v0, v72, v71
	v_div_fmas_f32 v0, v0, v70, v72
	v_div_fixup_f32 v0, v0, v69, 1.0
	v_div_scale_f32 v69, s[2:3], v68, v68, 1.0
	v_rcp_f32_e32 v70, v69
	s_nop 0
	v_fma_f32 v71, -v69, v70, 1.0
	v_fmac_f32_e32 v70, v71, v70
	v_div_scale_f32 v71, vcc, 1.0, v68, 1.0
	v_mul_f32_e32 v72, v71, v70
	v_fma_f32 v73, -v69, v72, v71
	v_fmac_f32_e32 v72, v73, v70
	v_fma_f32 v69, -v69, v72, v71
	v_div_fmas_f32 v69, v69, v70, v72
	v_div_fixup_f32 v68, v69, v68, 1.0
	v_cvt_pk_bf16_f32 v68, v68, v0
	v_mul_f32_e32 v0, 0xbfb8aa3b, v80
	v_exp_f32_e32 v70, v0
	v_mul_f32_e32 v0, 0xbfb8aa3b, v81
	v_exp_f32_e32 v71, v0
	s_nop 0
	v_pk_add_f32 v[70:71], v[70:71], 1.0 op_sel_hi:[1,0]
	s_nop 0
	v_div_scale_f32 v0, s[2:3], v71, v71, 1.0
	v_rcp_f32_e32 v69, v0
	s_nop 0
	v_fma_f32 v72, -v0, v69, 1.0
	v_fmac_f32_e32 v69, v72, v69
	v_div_scale_f32 v72, vcc, 1.0, v71, 1.0
	v_mul_f32_e32 v73, v72, v69
	v_fma_f32 v74, -v0, v73, v72
	v_fmac_f32_e32 v73, v74, v69
	v_fma_f32 v0, -v0, v73, v72
	v_div_fmas_f32 v0, v0, v69, v73
	v_div_scale_f32 v69, s[2:3], v70, v70, 1.0
	v_div_fixup_f32 v0, v0, v71, 1.0
	v_rcp_f32_e32 v71, v69
	s_nop 0
	v_fma_f32 v72, -v69, v71, 1.0
	v_fmac_f32_e32 v71, v72, v71
	v_div_scale_f32 v72, vcc, 1.0, v70, 1.0
	v_mul_f32_e32 v73, v72, v71
	v_fma_f32 v74, -v69, v73, v72
	v_fmac_f32_e32 v73, v74, v71
	v_fma_f32 v69, -v69, v73, v72
	v_div_fmas_f32 v69, v69, v71, v73
	v_div_fixup_f32 v69, v69, v70, 1.0
; DI unsigned pk2(float a, float b) { f32v2 v = {a, b}; return __builtin_bit_cast(unsigned, __builtin_convertvector(v, bf16v2)); }
; DI float sigmoidf_(float v) { return 1.f / (1.f + __expf(-v)); }
; #define SW_FOR_TOK(j) _Pragma("unroll") for (int j = 0; j < 4; j++)
; #define SW_FOR_FEAT(i, rq) _Pragma("unroll") for (int i = 0; i < 2; i++) _Pragma("unroll") for (int rq = 0; rq < 4; rq++)
; DI void ph_ple(const Params& P, int g, int layer, bf16_t* smem) {
;     ...
;     SW_FOR_TOK(j) { const int tl_ = wn * 128 + j * 32 + l32;
;       SW_FOR_FEAT(i, rq) { const int c_ = wm * 64 + i * 32 + 8 * rq + 4 * h;
;         *(uint2*)(smem + tl_ * EPLD + c_) = make_uint2(pk2(sigmoidf_(SWV(i, j, 4 * rq)), sigmoidf_(SWV(i, j, 4 * rq + 1))), pk2(sigmoidf_(SWV(i, j, 4 * rq + 2)), sigmoidf_(SWV(i, j, 4 * rq + 3)))); } }
	v_cvt_pk_bf16_f32 v69, v69, v0
	v_mul_f32_e32 v0, 0xbfb8aa3b, v50
	v_exp_f32_e32 v50, v0
	v_mul_f32_e32 v0, 0xbfb8aa3b, v51
	v_exp_f32_e32 v51, v0
	ds_write2_b64 v193, v[66:67], v[68:69] offset0:76 offset1:78
	v_pk_add_f32 v[50:51], v[50:51], 1.0 op_sel_hi:[1,0]
	s_nop 0
	v_div_scale_f32 v0, s[2:3], v51, v51, 1.0
	v_rcp_f32_e32 v66, v0
	s_nop 0
	v_fma_f32 v67, -v0, v66, 1.0
	v_fmac_f32_e32 v66, v67, v66
	v_div_scale_f32 v67, vcc, 1.0, v51, 1.0
	v_mul_f32_e32 v68, v67, v66
	v_fma_f32 v69, -v0, v68, v67
	v_fmac_f32_e32 v68, v69, v66
	v_fma_f32 v0, -v0, v68, v67
	v_div_fmas_f32 v0, v0, v66, v68
	v_div_fixup_f32 v0, v0, v51, 1.0
	v_div_scale_f32 v51, s[2:3], v50, v50, 1.0
	v_rcp_f32_e32 v66, v51
	s_nop 0
	v_fma_f32 v67, -v51, v66, 1.0
	v_fmac_f32_e32 v66, v67, v66
	v_div_scale_f32 v67, vcc, 1.0, v50, 1.0
	v_mul_f32_e32 v68, v67, v66
	v_fma_f32 v69, -v51, v68, v67
	v_fmac_f32_e32 v68, v69, v66
	v_fma_f32 v51, -v51, v68, v67
	v_div_fmas_f32 v51, v51, v66, v68
	v_div_fixup_f32 v50, v51, v50, 1.0
	v_cvt_pk_bf16_f32 v50, v50, v0
	v_mul_f32_e32 v0, 0xbfb8aa3b, v52
	v_exp_f32_e32 v52, v0
	v_mul_f32_e32 v0, 0xbfb8aa3b, v53
	v_exp_f32_e32 v53, v0
	s_nop 0
	v_pk_add_f32 v[52:53], v[52:53], 1.0 op_sel_hi:[1,0]
	s_nop 0
	v_div_scale_f32 v0, s[2:3], v53, v53, 1.0
	v_rcp_f32_e32 v51, v0
	s_nop 0
	v_fma_f32 v66, -v0, v51, 1.0
	v_fmac_f32_e32 v51, v66, v51
	v_div_scale_f32 v66, vcc, 1.0, v53, 1.0
	v_mul_f32_e32 v67, v66, v51
	v_fma_f32 v68, -v0, v67, v66
	v_fmac_f32_e32 v67, v68, v51
	v_fma_f32 v0, -v0, v67, v66
	v_div_fmas_f32 v0, v0, v51, v67
	v_div_scale_f32 v51, s[2:3], v52, v52, 1.0
	v_div_fixup_f32 v0, v0, v53, 1.0
	v_rcp_f32_e32 v53, v51
	s_nop 0
	v_fma_f32 v66, -v51, v53, 1.0
	v_fmac_f32_e32 v53, v66, v53
	v_div_scale_f32 v66, vcc, 1.0, v52, 1.0
	v_mul_f32_e32 v67, v66, v53
	v_fma_f32 v68, -v51, v67, v66
	v_fmac_f32_e32 v67, v68, v53
	v_fma_f32 v51, -v51, v67, v66
	v_div_fmas_f32 v51, v51, v53, v67
	v_div_fixup_f32 v51, v51, v52, 1.0
	v_cvt_pk_bf16_f32 v51, v51, v0
	v_mul_f32_e32 v0, 0xbfb8aa3b, v54
	v_exp_f32_e32 v52, v0
	v_mul_f32_e32 v0, 0xbfb8aa3b, v55
	v_exp_f32_e32 v53, v0
	s_nop 0
	v_pk_add_f32 v[52:53], v[52:53], 1.0 op_sel_hi:[1,0]
	s_nop 0
	v_div_scale_f32 v0, s[2:3], v53, v53, 1.0
	v_rcp_f32_e32 v54, v0
	s_nop 0
	v_fma_f32 v55, -v0, v54, 1.0
	v_fmac_f32_e32 v54, v55, v54
	v_div_scale_f32 v55, vcc, 1.0, v53, 1.0
	v_mul_f32_e32 v66, v55, v54
	v_fma_f32 v67, -v0, v66, v55
	v_fmac_f32_e32 v66, v67, v54
	v_fma_f32 v0, -v0, v66, v55
	v_div_fmas_f32 v0, v0, v54, v66
	v_div_fixup_f32 v0, v0, v53, 1.0
	v_div_scale_f32 v53, s[2:3], v52, v52, 1.0
	v_rcp_f32_e32 v54, v53
	s_nop 0
	v_fma_f32 v55, -v53, v54, 1.0
	v_fmac_f32_e32 v54, v55, v54
	v_div_scale_f32 v55, vcc, 1.0, v52, 1.0
	v_mul_f32_e32 v66, v55, v54
	v_fma_f32 v67, -v53, v66, v55
	v_fmac_f32_e32 v66, v67, v54
	v_fma_f32 v53, -v53, v66, v55
	v_div_fmas_f32 v53, v53, v54, v66
	v_div_fixup_f32 v52, v53, v52, 1.0
	v_cvt_pk_bf16_f32 v52, v52, v0
	v_mul_f32_e32 v0, 0xbfb8aa3b, v56
	v_exp_f32_e32 v54, v0
	v_mul_f32_e32 v0, 0xbfb8aa3b, v57
	v_exp_f32_e32 v55, v0
	s_nop 0
	v_pk_add_f32 v[54:55], v[54:55], 1.0 op_sel_hi:[1,0]
	s_nop 0
	v_div_scale_f32 v0, s[2:3], v55, v55, 1.0
	v_rcp_f32_e32 v53, v0
	s_nop 0
	v_fma_f32 v56, -v0, v53, 1.0
	v_fmac_f32_e32 v53, v56, v53
	v_div_scale_f32 v56, vcc, 1.0, v55, 1.0
	v_mul_f32_e32 v57, v56, v53
	v_fma_f32 v66, -v0, v57, v56
	v_fmac_f32_e32 v57, v66, v53
	v_fma_f32 v0, -v0, v57, v56
	v_div_fmas_f32 v0, v0, v53, v57
	v_div_scale_f32 v53, s[2:3], v54, v54, 1.0
	v_div_fixup_f32 v0, v0, v55, 1.0
	v_rcp_f32_e32 v55, v53
	s_nop 0
	v_fma_f32 v56, -v53, v55, 1.0
	v_fmac_f32_e32 v55, v56, v55
	v_div_scale_f32 v56, vcc, 1.0, v54, 1.0
	v_mul_f32_e32 v57, v56, v55
	v_fma_f32 v66, -v53, v57, v56
	v_fmac_f32_e32 v57, v66, v55
	v_fma_f32 v53, -v53, v57, v56
	v_div_fmas_f32 v53, v53, v55, v57
	v_div_fixup_f32 v53, v53, v54, 1.0
	v_cvt_pk_bf16_f32 v53, v53, v0
	v_mul_f32_e32 v0, 0xbfb8aa3b, v58
	ds_write2_b64 v192, v[50:51], v[52:53] offset0:128 offset1:130
	v_exp_f32_e32 v50, v0
	v_mul_f32_e32 v0, 0xbfb8aa3b, v59
	v_exp_f32_e32 v51, v0
	s_nop 0
	v_pk_add_f32 v[50:51], v[50:51], 1.0 op_sel_hi:[1,0]
	s_nop 0
	v_div_scale_f32 v0, s[2:3], v51, v51, 1.0
	v_rcp_f32_e32 v52, v0
	s_nop 0
	v_fma_f32 v53, -v0, v52, 1.0
	v_fmac_f32_e32 v52, v53, v52
	v_div_scale_f32 v53, vcc, 1.0, v51, 1.0
	v_mul_f32_e32 v54, v53, v52
	v_fma_f32 v55, -v0, v54, v53
	v_fmac_f32_e32 v54, v55, v52
	v_fma_f32 v0, -v0, v54, v53
	v_div_fmas_f32 v0, v0, v52, v54
	v_div_fixup_f32 v0, v0, v51, 1.0
	v_div_scale_f32 v51, s[2:3], v50, v50, 1.0
	v_rcp_f32_e32 v52, v51
	s_nop 0
	v_fma_f32 v53, -v51, v52, 1.0
	v_fmac_f32_e32 v52, v53, v52
	v_div_scale_f32 v53, vcc, 1.0, v50, 1.0
	v_mul_f32_e32 v54, v53, v52
	v_fma_f32 v55, -v51, v54, v53
	v_fmac_f32_e32 v54, v55, v52
	v_fma_f32 v51, -v51, v54, v53
	v_div_fmas_f32 v51, v51, v52, v54
	v_div_fixup_f32 v50, v51, v50, 1.0
	v_cvt_pk_bf16_f32 v50, v50, v0
	v_mul_f32_e32 v0, 0xbfb8aa3b, v60
	v_exp_f32_e32 v52, v0
	v_mul_f32_e32 v0, 0xbfb8aa3b, v61
	v_exp_f32_e32 v53, v0
	s_nop 0
	v_pk_add_f32 v[52:53], v[52:53], 1.0 op_sel_hi:[1,0]
	s_nop 0
	v_div_scale_f32 v0, s[2:3], v53, v53, 1.0
	v_rcp_f32_e32 v51, v0
	s_nop 0
	v_fma_f32 v54, -v0, v51, 1.0
	v_fmac_f32_e32 v51, v54, v51
	v_div_scale_f32 v54, vcc, 1.0, v53, 1.0
	v_mul_f32_e32 v55, v54, v51
	v_fma_f32 v56, -v0, v55, v54
	v_fmac_f32_e32 v55, v56, v51
	v_fma_f32 v0, -v0, v55, v54
	v_div_fmas_f32 v0, v0, v51, v55
	v_div_scale_f32 v51, s[2:3], v52, v52, 1.0
	v_div_fixup_f32 v0, v0, v53, 1.0
	v_rcp_f32_e32 v53, v51
	s_nop 0
	v_fma_f32 v54, -v51, v53, 1.0
	v_fmac_f32_e32 v53, v54, v53
	v_div_scale_f32 v54, vcc, 1.0, v52, 1.0
; DI unsigned pk2(float a, float b) { f32v2 v = {a, b}; return __builtin_bit_cast(unsigned, __builtin_convertvector(v, bf16v2)); }
; DI float sigmoidf_(float v) { return 1.f / (1.f + __expf(-v)); }
; #define SW_FOR_TOK(j) _Pragma("unroll") for (int j = 0; j < 4; j++)
; #define SW_FOR_FEAT(i, rq) _Pragma("unroll") for (int i = 0; i < 2; i++) _Pragma("unroll") for (int rq = 0; rq < 4; rq++)
; DI void ph_ple(const Params& P, int g, int layer, bf16_t* smem) {
;     ...
;     SW_FOR_TOK(j) { const int tl_ = wn * 128 + j * 32 + l32;
;       SW_FOR_FEAT(i, rq) { const int c_ = wm * 64 + i * 32 + 8 * rq + 4 * h;
;         *(uint2*)(smem + tl_ * EPLD + c_) = make_uint2(pk2(sigmoidf_(SWV(i, j, 4 * rq)), sigmoidf_(SWV(i, j, 4 * rq + 1))), pk2(sigmoidf_(SWV(i, j, 4 * rq + 2)), sigmoidf_(SWV(i, j, 4 * rq + 3)))); } }
	v_mul_f32_e32 v55, v54, v53
	v_fma_f32 v56, -v51, v55, v54
	v_fmac_f32_e32 v55, v56, v53
	v_fma_f32 v51, -v51, v55, v54
	v_div_fmas_f32 v51, v51, v53, v55
	v_div_fixup_f32 v51, v51, v52, 1.0
	v_cvt_pk_bf16_f32 v51, v51, v0
	v_mul_f32_e32 v0, 0xbfb8aa3b, v62
	v_exp_f32_e32 v52, v0
	v_mul_f32_e32 v0, 0xbfb8aa3b, v63
	v_exp_f32_e32 v53, v0
	s_nop 0
	v_pk_add_f32 v[52:53], v[52:53], 1.0 op_sel_hi:[1,0]
	s_nop 0
	v_div_scale_f32 v0, s[2:3], v53, v53, 1.0
	v_rcp_f32_e32 v54, v0
	s_nop 0
	v_fma_f32 v55, -v0, v54, 1.0
	v_fmac_f32_e32 v54, v55, v54
	v_div_scale_f32 v55, vcc, 1.0, v53, 1.0
	v_mul_f32_e32 v56, v55, v54
	v_fma_f32 v57, -v0, v56, v55
	v_fmac_f32_e32 v56, v57, v54
	v_fma_f32 v0, -v0, v56, v55
	v_div_fmas_f32 v0, v0, v54, v56
	v_div_fixup_f32 v0, v0, v53, 1.0
	v_div_scale_f32 v53, s[2:3], v52, v52, 1.0
	v_rcp_f32_e32 v54, v53
	s_nop 0
	v_fma_f32 v55, -v53, v54, 1.0
	v_fmac_f32_e32 v54, v55, v54
	v_div_scale_f32 v55, vcc, 1.0, v52, 1.0
	v_mul_f32_e32 v56, v55, v54
	v_fma_f32 v57, -v53, v56, v55
	v_fmac_f32_e32 v56, v57, v54
	v_fma_f32 v53, -v53, v56, v55
	v_div_fmas_f32 v53, v53, v54, v56
	v_div_fixup_f32 v52, v53, v52, 1.0
	v_cvt_pk_bf16_f32 v52, v52, v0
	v_mul_f32_e32 v0, 0xbfb8aa3b, v64
	v_exp_f32_e32 v54, v0
	v_mul_f32_e32 v0, 0xbfb8aa3b, v65
	v_exp_f32_e32 v55, v0
	s_nop 0
	v_pk_add_f32 v[54:55], v[54:55], 1.0 op_sel_hi:[1,0]
	s_nop 0
	v_div_scale_f32 v0, s[2:3], v55, v55, 1.0
	v_rcp_f32_e32 v53, v0
	s_nop 0
	v_fma_f32 v56, -v0, v53, 1.0
	v_fmac_f32_e32 v53, v56, v53
	v_div_scale_f32 v56, vcc, 1.0, v55, 1.0
	v_mul_f32_e32 v57, v56, v53
	v_fma_f32 v58, -v0, v57, v56
	v_fmac_f32_e32 v57, v58, v53
	v_fma_f32 v0, -v0, v57, v56
	v_div_fmas_f32 v0, v0, v53, v57
	v_div_scale_f32 v53, s[2:3], v54, v54, 1.0
	v_div_fixup_f32 v0, v0, v55, 1.0
	v_rcp_f32_e32 v55, v53
	s_nop 0
	v_fma_f32 v56, -v53, v55, 1.0
	v_fmac_f32_e32 v55, v56, v55
	v_div_scale_f32 v56, vcc, 1.0, v54, 1.0
	v_mul_f32_e32 v57, v56, v55
	v_fma_f32 v58, -v53, v57, v56
	v_fmac_f32_e32 v57, v58, v55
	v_fma_f32 v53, -v53, v57, v56
	v_div_fmas_f32 v53, v53, v55, v57
	v_div_fixup_f32 v53, v53, v54, 1.0
	v_cvt_pk_bf16_f32 v53, v53, v0
	v_mul_f32_e32 v0, 0xbfb8aa3b, v34
	v_exp_f32_e32 v34, v0
	v_mul_f32_e32 v0, 0xbfb8aa3b, v35
	v_exp_f32_e32 v35, v0
	ds_write2_b64 v192, v[50:51], v[52:53] offset0:132 offset1:134
	v_pk_add_f32 v[34:35], v[34:35], 1.0 op_sel_hi:[1,0]
	s_nop 0
	v_div_scale_f32 v0, s[2:3], v35, v35, 1.0
	v_rcp_f32_e32 v50, v0
	s_nop 0
	v_fma_f32 v51, -v0, v50, 1.0
	v_fmac_f32_e32 v50, v51, v50
	v_div_scale_f32 v51, vcc, 1.0, v35, 1.0
	v_mul_f32_e32 v52, v51, v50
	v_fma_f32 v53, -v0, v52, v51
	v_fmac_f32_e32 v52, v53, v50
	v_fma_f32 v0, -v0, v52, v51
	v_div_fmas_f32 v0, v0, v50, v52
	v_div_fixup_f32 v0, v0, v35, 1.0
	v_div_scale_f32 v35, s[2:3], v34, v34, 1.0
	v_rcp_f32_e32 v50, v35
	s_nop 0
	v_fma_f32 v51, -v35, v50, 1.0
	v_fmac_f32_e32 v50, v51, v50
	v_div_scale_f32 v51, vcc, 1.0, v34, 1.0
	v_mul_f32_e32 v52, v51, v50
	v_fma_f32 v53, -v35, v52, v51
	v_fmac_f32_e32 v52, v53, v50
	v_fma_f32 v35, -v35, v52, v51
	v_div_fmas_f32 v35, v35, v50, v52
	v_div_fixup_f32 v34, v35, v34, 1.0
	v_cvt_pk_bf16_f32 v34, v34, v0
	v_mul_f32_e32 v0, 0xbfb8aa3b, v36
	v_exp_f32_e32 v36, v0
	v_mul_f32_e32 v0, 0xbfb8aa3b, v37
	v_exp_f32_e32 v37, v0
	s_nop 0
	v_pk_add_f32 v[36:37], v[36:37], 1.0 op_sel_hi:[1,0]
	s_nop 0
	v_div_scale_f32 v0, s[2:3], v37, v37, 1.0
	v_rcp_f32_e32 v35, v0
	s_nop 0
	v_fma_f32 v50, -v0, v35, 1.0
	v_fmac_f32_e32 v35, v50, v35
	v_div_scale_f32 v50, vcc, 1.0, v37, 1.0
	v_mul_f32_e32 v51, v50, v35
	v_fma_f32 v52, -v0, v51, v50
	v_fmac_f32_e32 v51, v52, v35
	v_fma_f32 v0, -v0, v51, v50
	v_div_fmas_f32 v0, v0, v35, v51
	v_div_scale_f32 v35, s[2:3], v36, v36, 1.0
	v_div_fixup_f32 v0, v0, v37, 1.0
	v_rcp_f32_e32 v37, v35
	s_nop 0
	v_fma_f32 v50, -v35, v37, 1.0
	v_fmac_f32_e32 v37, v50, v37
	v_div_scale_f32 v50, vcc, 1.0, v36, 1.0
	v_mul_f32_e32 v51, v50, v37
	v_fma_f32 v52, -v35, v51, v50
	v_fmac_f32_e32 v51, v52, v37
	v_fma_f32 v35, -v35, v51, v50
	v_div_fmas_f32 v35, v35, v37, v51
	v_div_fixup_f32 v35, v35, v36, 1.0
	v_cvt_pk_bf16_f32 v35, v35, v0
	v_mul_f32_e32 v0, 0xbfb8aa3b, v38
	v_exp_f32_e32 v36, v0
	v_mul_f32_e32 v0, 0xbfb8aa3b, v39
	v_exp_f32_e32 v37, v0
	s_nop 0
	v_pk_add_f32 v[36:37], v[36:37], 1.0 op_sel_hi:[1,0]
	s_nop 0
	v_div_scale_f32 v0, s[2:3], v37, v37, 1.0
	v_rcp_f32_e32 v38, v0
	s_nop 0
	v_fma_f32 v39, -v0, v38, 1.0
	v_fmac_f32_e32 v38, v39, v38
	v_div_scale_f32 v39, vcc, 1.0, v37, 1.0
	v_mul_f32_e32 v50, v39, v38
	v_fma_f32 v51, -v0, v50, v39
	v_fmac_f32_e32 v50, v51, v38
	v_fma_f32 v0, -v0, v50, v39
	v_div_fmas_f32 v0, v0, v38, v50
	v_div_fixup_f32 v0, v0, v37, 1.0
	v_div_scale_f32 v37, s[2:3], v36, v36, 1.0
	v_rcp_f32_e32 v38, v37
	s_nop 0
	v_fma_f32 v39, -v37, v38, 1.0
	v_fmac_f32_e32 v38, v39, v38
	v_div_scale_f32 v39, vcc, 1.0, v36, 1.0
	v_mul_f32_e32 v50, v39, v38
	v_fma_f32 v51, -v37, v50, v39
	v_fmac_f32_e32 v50, v51, v38
	v_fma_f32 v37, -v37, v50, v39
	v_div_fmas_f32 v37, v37, v38, v50
	v_div_fixup_f32 v36, v37, v36, 1.0
	v_cvt_pk_bf16_f32 v36, v36, v0
	v_mul_f32_e32 v0, 0xbfb8aa3b, v40
	v_exp_f32_e32 v38, v0
	v_mul_f32_e32 v0, 0xbfb8aa3b, v41
	v_exp_f32_e32 v39, v0
	s_nop 0
	v_pk_add_f32 v[38:39], v[38:39], 1.0 op_sel_hi:[1,0]
	s_nop 0
	v_div_scale_f32 v0, s[2:3], v39, v39, 1.0
	v_rcp_f32_e32 v37, v0
	s_nop 0
	v_fma_f32 v40, -v0, v37, 1.0
	v_fmac_f32_e32 v37, v40, v37
	v_div_scale_f32 v40, vcc, 1.0, v39, 1.0
	v_mul_f32_e32 v41, v40, v37
	v_fma_f32 v50, -v0, v41, v40
	v_fmac_f32_e32 v41, v50, v37
	v_fma_f32 v0, -v0, v41, v40
	v_div_fmas_f32 v0, v0, v37, v41
	v_div_scale_f32 v37, s[2:3], v38, v38, 1.0
	v_div_fixup_f32 v0, v0, v39, 1.0
; DI unsigned pk2(float a, float b) { f32v2 v = {a, b}; return __builtin_bit_cast(unsigned, __builtin_convertvector(v, bf16v2)); }
; DI float sigmoidf_(float v) { return 1.f / (1.f + __expf(-v)); }
; #define SW_FOR_TOK(j) _Pragma("unroll") for (int j = 0; j < 4; j++)
; #define SW_FOR_FEAT(i, rq) _Pragma("unroll") for (int i = 0; i < 2; i++) _Pragma("unroll") for (int rq = 0; rq < 4; rq++)
; DI void ph_ple(const Params& P, int g, int layer, bf16_t* smem) {
;     ...
;     SW_FOR_TOK(j) { const int tl_ = wn * 128 + j * 32 + l32;
;       SW_FOR_FEAT(i, rq) { const int c_ = wm * 64 + i * 32 + 8 * rq + 4 * h;
;         *(uint2*)(smem + tl_ * EPLD + c_) = make_uint2(pk2(sigmoidf_(SWV(i, j, 4 * rq)), sigmoidf_(SWV(i, j, 4 * rq + 1))), pk2(sigmoidf_(SWV(i, j, 4 * rq + 2)), sigmoidf_(SWV(i, j, 4 * rq + 3)))); } }
	v_rcp_f32_e32 v39, v37
	s_nop 0
	v_fma_f32 v40, -v37, v39, 1.0
	v_fmac_f32_e32 v39, v40, v39
	v_div_scale_f32 v40, vcc, 1.0, v38, 1.0
	v_mul_f32_e32 v41, v40, v39
	v_fma_f32 v50, -v37, v41, v40
	v_fmac_f32_e32 v41, v50, v39
	v_fma_f32 v37, -v37, v41, v40
	v_div_fmas_f32 v37, v37, v39, v41
	v_div_fixup_f32 v37, v37, v38, 1.0
	v_cvt_pk_bf16_f32 v37, v37, v0
	v_mul_f32_e32 v0, 0xbfb8aa3b, v42
	ds_write2_b64 v192, v[34:35], v[36:37] offset0:136 offset1:138
	v_exp_f32_e32 v34, v0
	v_mul_f32_e32 v0, 0xbfb8aa3b, v43
	v_exp_f32_e32 v35, v0
	s_nop 0
	v_pk_add_f32 v[34:35], v[34:35], 1.0 op_sel_hi:[1,0]
	s_nop 0
	v_div_scale_f32 v0, s[2:3], v35, v35, 1.0
	v_rcp_f32_e32 v36, v0
	s_nop 0
	v_fma_f32 v37, -v0, v36, 1.0
	v_fmac_f32_e32 v36, v37, v36
	v_div_scale_f32 v37, vcc, 1.0, v35, 1.0
	v_mul_f32_e32 v38, v37, v36
	v_fma_f32 v39, -v0, v38, v37
	v_fmac_f32_e32 v38, v39, v36
	v_fma_f32 v0, -v0, v38, v37
	v_div_fmas_f32 v0, v0, v36, v38
	v_div_fixup_f32 v0, v0, v35, 1.0
	v_div_scale_f32 v35, s[2:3], v34, v34, 1.0
	v_rcp_f32_e32 v36, v35
	s_nop 0
	v_fma_f32 v37, -v35, v36, 1.0
	v_fmac_f32_e32 v36, v37, v36
	v_div_scale_f32 v37, vcc, 1.0, v34, 1.0
	v_mul_f32_e32 v38, v37, v36
	v_fma_f32 v39, -v35, v38, v37
	v_fmac_f32_e32 v38, v39, v36
	v_fma_f32 v35, -v35, v38, v37
	v_div_fmas_f32 v35, v35, v36, v38
	v_div_fixup_f32 v34, v35, v34, 1.0
	v_cvt_pk_bf16_f32 v34, v34, v0
	v_mul_f32_e32 v0, 0xbfb8aa3b, v44
	v_exp_f32_e32 v36, v0
	v_mul_f32_e32 v0, 0xbfb8aa3b, v45
	v_exp_f32_e32 v37, v0
	s_nop 0
	v_pk_add_f32 v[36:37], v[36:37], 1.0 op_sel_hi:[1,0]
	s_nop 0
	v_div_scale_f32 v0, s[2:3], v37, v37, 1.0
	v_rcp_f32_e32 v35, v0
	s_nop 0
	v_fma_f32 v38, -v0, v35, 1.0
	v_fmac_f32_e32 v35, v38, v35
	v_div_scale_f32 v38, vcc, 1.0, v37, 1.0
	v_mul_f32_e32 v39, v38, v35
	v_fma_f32 v40, -v0, v39, v38
	v_fmac_f32_e32 v39, v40, v35
	v_fma_f32 v0, -v0, v39, v38
	v_div_fmas_f32 v0, v0, v35, v39
	v_div_scale_f32 v35, s[2:3], v36, v36, 1.0
	v_div_fixup_f32 v0, v0, v37, 1.0
	v_rcp_f32_e32 v37, v35
	s_nop 0
	v_fma_f32 v38, -v35, v37, 1.0
	v_fmac_f32_e32 v37, v38, v37
	v_div_scale_f32 v38, vcc, 1.0, v36, 1.0
	v_mul_f32_e32 v39, v38, v37
	v_fma_f32 v40, -v35, v39, v38
	v_fmac_f32_e32 v39, v40, v37
	v_fma_f32 v35, -v35, v39, v38
	v_div_fmas_f32 v35, v35, v37, v39
	v_div_fixup_f32 v35, v35, v36, 1.0
	v_cvt_pk_bf16_f32 v35, v35, v0
	v_mul_f32_e32 v0, 0xbfb8aa3b, v46
	v_exp_f32_e32 v36, v0
	v_mul_f32_e32 v0, 0xbfb8aa3b, v47
	v_exp_f32_e32 v37, v0
	s_nop 0
	v_pk_add_f32 v[36:37], v[36:37], 1.0 op_sel_hi:[1,0]
	s_nop 0
	v_div_scale_f32 v0, s[2:3], v37, v37, 1.0
	v_rcp_f32_e32 v38, v0
	s_nop 0
	v_fma_f32 v39, -v0, v38, 1.0
	v_fmac_f32_e32 v38, v39, v38
	v_div_scale_f32 v39, vcc, 1.0, v37, 1.0
	v_mul_f32_e32 v40, v39, v38
	v_fma_f32 v41, -v0, v40, v39
	v_fmac_f32_e32 v40, v41, v38
	v_fma_f32 v0, -v0, v40, v39
	v_div_fmas_f32 v0, v0, v38, v40
	v_div_fixup_f32 v0, v0, v37, 1.0
	v_div_scale_f32 v37, s[2:3], v36, v36, 1.0
	v_rcp_f32_e32 v38, v37
	s_nop 0
	v_fma_f32 v39, -v37, v38, 1.0
	v_fmac_f32_e32 v38, v39, v38
	v_div_scale_f32 v39, vcc, 1.0, v36, 1.0
	v_mul_f32_e32 v40, v39, v38
	v_fma_f32 v41, -v37, v40, v39
	v_fmac_f32_e32 v40, v41, v38
	v_fma_f32 v37, -v37, v40, v39
	v_div_fmas_f32 v37, v37, v38, v40
	v_div_fixup_f32 v36, v37, v36, 1.0
	v_cvt_pk_bf16_f32 v36, v36, v0
	v_mul_f32_e32 v0, 0xbfb8aa3b, v48
	v_exp_f32_e32 v38, v0
	v_mul_f32_e32 v0, 0xbfb8aa3b, v49
	v_exp_f32_e32 v39, v0
	s_nop 0
	v_pk_add_f32 v[38:39], v[38:39], 1.0 op_sel_hi:[1,0]
	s_nop 0
	v_div_scale_f32 v0, s[2:3], v39, v39, 1.0
	v_rcp_f32_e32 v37, v0
	s_nop 0
	v_fma_f32 v40, -v0, v37, 1.0
	v_fmac_f32_e32 v37, v40, v37
	v_div_scale_f32 v40, vcc, 1.0, v39, 1.0
	v_mul_f32_e32 v41, v40, v37
	v_fma_f32 v42, -v0, v41, v40
	v_fmac_f32_e32 v41, v42, v37
	v_fma_f32 v0, -v0, v41, v40
	v_div_fmas_f32 v0, v0, v37, v41
	v_div_scale_f32 v37, s[2:3], v38, v38, 1.0
	v_div_fixup_f32 v0, v0, v39, 1.0
	v_rcp_f32_e32 v39, v37
	s_nop 0
	v_fma_f32 v40, -v37, v39, 1.0
	v_fmac_f32_e32 v39, v40, v39
	v_div_scale_f32 v40, vcc, 1.0, v38, 1.0
	v_mul_f32_e32 v41, v40, v39
	v_fma_f32 v42, -v37, v41, v40
	v_fmac_f32_e32 v41, v42, v39
	v_fma_f32 v37, -v37, v41, v40
	v_div_fmas_f32 v37, v37, v39, v41
	v_div_fixup_f32 v37, v37, v38, 1.0
	v_cvt_pk_bf16_f32 v37, v37, v0
	v_mul_f32_e32 v0, 0xbfb8aa3b, v18
	v_exp_f32_e32 v18, v0
	v_mul_f32_e32 v0, 0xbfb8aa3b, v19
	v_exp_f32_e32 v19, v0
	ds_write2_b64 v192, v[34:35], v[36:37] offset0:140 offset1:142
	v_pk_add_f32 v[18:19], v[18:19], 1.0 op_sel_hi:[1,0]
	s_nop 0
	v_div_scale_f32 v0, s[2:3], v19, v19, 1.0
	v_rcp_f32_e32 v34, v0
	s_nop 0
	v_fma_f32 v35, -v0, v34, 1.0
	v_fmac_f32_e32 v34, v35, v34
	v_div_scale_f32 v35, vcc, 1.0, v19, 1.0
	v_mul_f32_e32 v36, v35, v34
	v_fma_f32 v37, -v0, v36, v35
	v_fmac_f32_e32 v36, v37, v34
	v_fma_f32 v0, -v0, v36, v35
	v_div_fmas_f32 v0, v0, v34, v36
	v_div_fixup_f32 v0, v0, v19, 1.0
	v_div_scale_f32 v19, s[2:3], v18, v18, 1.0
	v_rcp_f32_e32 v34, v19
	s_nop 0
	v_fma_f32 v35, -v19, v34, 1.0
	v_fmac_f32_e32 v34, v35, v34
	v_div_scale_f32 v35, vcc, 1.0, v18, 1.0
	v_mul_f32_e32 v36, v35, v34
	v_fma_f32 v37, -v19, v36, v35
	v_fmac_f32_e32 v36, v37, v34
	v_fma_f32 v19, -v19, v36, v35
	v_div_fmas_f32 v19, v19, v34, v36
	v_div_fixup_f32 v18, v19, v18, 1.0
	v_cvt_pk_bf16_f32 v18, v18, v0
	v_mul_f32_e32 v0, 0xbfb8aa3b, v20
	v_exp_f32_e32 v20, v0
	v_mul_f32_e32 v0, 0xbfb8aa3b, v21
	v_exp_f32_e32 v21, v0
	s_nop 0
	v_pk_add_f32 v[20:21], v[20:21], 1.0 op_sel_hi:[1,0]
	s_nop 0
	v_div_scale_f32 v0, s[2:3], v21, v21, 1.0
	v_rcp_f32_e32 v19, v0
	s_nop 0
	v_fma_f32 v34, -v0, v19, 1.0
	v_fmac_f32_e32 v19, v34, v19
	v_div_scale_f32 v34, vcc, 1.0, v21, 1.0
	v_mul_f32_e32 v35, v34, v19
; DI unsigned pk2(float a, float b) { f32v2 v = {a, b}; return __builtin_bit_cast(unsigned, __builtin_convertvector(v, bf16v2)); }
; DI float sigmoidf_(float v) { return 1.f / (1.f + __expf(-v)); }
; #define SW_FOR_TOK(j) _Pragma("unroll") for (int j = 0; j < 4; j++)
; #define SW_FOR_FEAT(i, rq) _Pragma("unroll") for (int i = 0; i < 2; i++) _Pragma("unroll") for (int rq = 0; rq < 4; rq++)
; DI void ph_ple(const Params& P, int g, int layer, bf16_t* smem) {
;     ...
;     SW_FOR_TOK(j) { const int tl_ = wn * 128 + j * 32 + l32;
;       SW_FOR_FEAT(i, rq) { const int c_ = wm * 64 + i * 32 + 8 * rq + 4 * h;
;         *(uint2*)(smem + tl_ * EPLD + c_) = make_uint2(pk2(sigmoidf_(SWV(i, j, 4 * rq)), sigmoidf_(SWV(i, j, 4 * rq + 1))), pk2(sigmoidf_(SWV(i, j, 4 * rq + 2)), sigmoidf_(SWV(i, j, 4 * rq + 3)))); } }
	v_fma_f32 v36, -v0, v35, v34
	v_fmac_f32_e32 v35, v36, v19
	v_fma_f32 v0, -v0, v35, v34
	v_div_fmas_f32 v0, v0, v19, v35
	v_div_scale_f32 v19, s[2:3], v20, v20, 1.0
	v_div_fixup_f32 v0, v0, v21, 1.0
	v_rcp_f32_e32 v21, v19
	s_nop 0
	v_fma_f32 v34, -v19, v21, 1.0
	v_fmac_f32_e32 v21, v34, v21
	v_div_scale_f32 v34, vcc, 1.0, v20, 1.0
	v_mul_f32_e32 v35, v34, v21
	v_fma_f32 v36, -v19, v35, v34
	v_fmac_f32_e32 v35, v36, v21
	v_fma_f32 v19, -v19, v35, v34
	v_div_fmas_f32 v19, v19, v21, v35
	v_div_fixup_f32 v19, v19, v20, 1.0
	v_cvt_pk_bf16_f32 v19, v19, v0
	v_mul_f32_e32 v0, 0xbfb8aa3b, v22
	v_exp_f32_e32 v20, v0
	v_mul_f32_e32 v0, 0xbfb8aa3b, v23
	v_exp_f32_e32 v21, v0
	s_nop 0
	v_pk_add_f32 v[20:21], v[20:21], 1.0 op_sel_hi:[1,0]
	s_nop 0
	v_div_scale_f32 v0, s[2:3], v21, v21, 1.0
	v_rcp_f32_e32 v22, v0
	s_nop 0
	v_fma_f32 v23, -v0, v22, 1.0
	v_fmac_f32_e32 v22, v23, v22
	v_div_scale_f32 v23, vcc, 1.0, v21, 1.0
	v_mul_f32_e32 v34, v23, v22
	v_fma_f32 v35, -v0, v34, v23
	v_fmac_f32_e32 v34, v35, v22
	v_fma_f32 v0, -v0, v34, v23
	v_div_fmas_f32 v0, v0, v22, v34
	v_div_fixup_f32 v0, v0, v21, 1.0
	v_div_scale_f32 v21, s[2:3], v20, v20, 1.0
	v_rcp_f32_e32 v22, v21
	s_nop 0
	v_fma_f32 v23, -v21, v22, 1.0
	v_fmac_f32_e32 v22, v23, v22
	v_div_scale_f32 v23, vcc, 1.0, v20, 1.0
	v_mul_f32_e32 v34, v23, v22
	v_fma_f32 v35, -v21, v34, v23
	v_fmac_f32_e32 v34, v35, v22
	v_fma_f32 v21, -v21, v34, v23
	v_div_fmas_f32 v21, v21, v22, v34
	v_div_fixup_f32 v20, v21, v20, 1.0
	v_cvt_pk_bf16_f32 v20, v20, v0
	v_mul_f32_e32 v0, 0xbfb8aa3b, v24
	v_exp_f32_e32 v22, v0
	v_mul_f32_e32 v0, 0xbfb8aa3b, v25
	v_exp_f32_e32 v23, v0
	s_nop 0
	v_pk_add_f32 v[22:23], v[22:23], 1.0 op_sel_hi:[1,0]
	s_nop 0
	v_div_scale_f32 v0, s[2:3], v23, v23, 1.0
	v_rcp_f32_e32 v21, v0
	s_nop 0
	v_fma_f32 v24, -v0, v21, 1.0
	v_fmac_f32_e32 v21, v24, v21
	v_div_scale_f32 v24, vcc, 1.0, v23, 1.0
	v_mul_f32_e32 v25, v24, v21
	v_fma_f32 v34, -v0, v25, v24
	v_fmac_f32_e32 v25, v34, v21
	v_fma_f32 v0, -v0, v25, v24
	v_div_fmas_f32 v0, v0, v21, v25
	v_div_scale_f32 v21, s[2:3], v22, v22, 1.0
	v_div_fixup_f32 v0, v0, v23, 1.0
	v_rcp_f32_e32 v23, v21
	s_nop 0
	v_fma_f32 v24, -v21, v23, 1.0
	v_fmac_f32_e32 v23, v24, v23
	v_div_scale_f32 v24, vcc, 1.0, v22, 1.0
	v_mul_f32_e32 v25, v24, v23
	v_fma_f32 v34, -v21, v25, v24
	v_fmac_f32_e32 v25, v34, v23
	v_fma_f32 v21, -v21, v25, v24
	v_div_fmas_f32 v21, v21, v23, v25
	v_div_fixup_f32 v21, v21, v22, 1.0
	v_cvt_pk_bf16_f32 v21, v21, v0
	v_mul_f32_e32 v0, 0xbfb8aa3b, v26
	ds_write2_b64 v191, v[18:19], v[20:21] offset0:192 offset1:194
	v_exp_f32_e32 v18, v0
	v_mul_f32_e32 v0, 0xbfb8aa3b, v27
	v_exp_f32_e32 v19, v0
	s_nop 0
	v_pk_add_f32 v[18:19], v[18:19], 1.0 op_sel_hi:[1,0]
	s_nop 0
	v_div_scale_f32 v0, s[2:3], v19, v19, 1.0
	v_rcp_f32_e32 v20, v0
	s_nop 0
	v_fma_f32 v21, -v0, v20, 1.0
	v_fmac_f32_e32 v20, v21, v20
	v_div_scale_f32 v21, vcc, 1.0, v19, 1.0
	v_mul_f32_e32 v22, v21, v20
	v_fma_f32 v23, -v0, v22, v21
	v_fmac_f32_e32 v22, v23, v20
	v_fma_f32 v0, -v0, v22, v21
	v_div_fmas_f32 v0, v0, v20, v22
	v_div_fixup_f32 v0, v0, v19, 1.0
	v_div_scale_f32 v19, s[2:3], v18, v18, 1.0
	v_rcp_f32_e32 v20, v19
	s_nop 0
	v_fma_f32 v21, -v19, v20, 1.0
	v_fmac_f32_e32 v20, v21, v20
	v_div_scale_f32 v21, vcc, 1.0, v18, 1.0
	v_mul_f32_e32 v22, v21, v20
	v_fma_f32 v23, -v19, v22, v21
	v_fmac_f32_e32 v22, v23, v20
	v_fma_f32 v19, -v19, v22, v21
	v_div_fmas_f32 v19, v19, v20, v22
	v_div_fixup_f32 v18, v19, v18, 1.0
	v_cvt_pk_bf16_f32 v18, v18, v0
	v_mul_f32_e32 v0, 0xbfb8aa3b, v28
	v_exp_f32_e32 v20, v0
	v_mul_f32_e32 v0, 0xbfb8aa3b, v29
	v_exp_f32_e32 v21, v0
	s_nop 0
	v_pk_add_f32 v[20:21], v[20:21], 1.0 op_sel_hi:[1,0]
	s_nop 0
	v_div_scale_f32 v0, s[2:3], v21, v21, 1.0
	v_rcp_f32_e32 v19, v0
	s_nop 0
	v_fma_f32 v22, -v0, v19, 1.0
	v_fmac_f32_e32 v19, v22, v19
	v_div_scale_f32 v22, vcc, 1.0, v21, 1.0
	v_mul_f32_e32 v23, v22, v19
	v_fma_f32 v24, -v0, v23, v22
	v_fmac_f32_e32 v23, v24, v19
	v_fma_f32 v0, -v0, v23, v22
	v_div_fmas_f32 v0, v0, v19, v23
	v_div_scale_f32 v19, s[2:3], v20, v20, 1.0
	v_div_fixup_f32 v0, v0, v21, 1.0
	v_rcp_f32_e32 v21, v19
	s_nop 0
	v_fma_f32 v22, -v19, v21, 1.0
	v_fmac_f32_e32 v21, v22, v21
	v_div_scale_f32 v22, vcc, 1.0, v20, 1.0
	v_mul_f32_e32 v23, v22, v21
	v_fma_f32 v24, -v19, v23, v22
	v_fmac_f32_e32 v23, v24, v21
	v_fma_f32 v19, -v19, v23, v22
	v_div_fmas_f32 v19, v19, v21, v23
	v_div_fixup_f32 v19, v19, v20, 1.0
	v_cvt_pk_bf16_f32 v19, v19, v0
	v_mul_f32_e32 v0, 0xbfb8aa3b, v30
	v_exp_f32_e32 v20, v0
	v_mul_f32_e32 v0, 0xbfb8aa3b, v31
	v_exp_f32_e32 v21, v0
	s_nop 0
	v_pk_add_f32 v[20:21], v[20:21], 1.0 op_sel_hi:[1,0]
	s_nop 0
	v_div_scale_f32 v0, s[2:3], v21, v21, 1.0
	v_rcp_f32_e32 v22, v0
	s_nop 0
	v_fma_f32 v23, -v0, v22, 1.0
	v_fmac_f32_e32 v22, v23, v22
	v_div_scale_f32 v23, vcc, 1.0, v21, 1.0
	v_mul_f32_e32 v24, v23, v22
	v_fma_f32 v25, -v0, v24, v23
	v_fmac_f32_e32 v24, v25, v22
	v_fma_f32 v0, -v0, v24, v23
	v_div_fmas_f32 v0, v0, v22, v24
	v_div_fixup_f32 v0, v0, v21, 1.0
	v_div_scale_f32 v21, s[2:3], v20, v20, 1.0
	v_rcp_f32_e32 v22, v21
	s_nop 0
	v_fma_f32 v23, -v21, v22, 1.0
	v_fmac_f32_e32 v22, v23, v22
	v_div_scale_f32 v23, vcc, 1.0, v20, 1.0
	v_mul_f32_e32 v24, v23, v22
	v_fma_f32 v25, -v21, v24, v23
	v_fmac_f32_e32 v24, v25, v22
	v_fma_f32 v21, -v21, v24, v23
	v_div_fmas_f32 v21, v21, v22, v24
	v_div_fixup_f32 v20, v21, v20, 1.0
	v_cvt_pk_bf16_f32 v20, v20, v0
	v_mul_f32_e32 v0, 0xbfb8aa3b, v32
	v_exp_f32_e32 v22, v0
	v_mul_f32_e32 v0, 0xbfb8aa3b, v33
	v_exp_f32_e32 v23, v0
	s_nop 0
	v_pk_add_f32 v[22:23], v[22:23], 1.0 op_sel_hi:[1,0]
	s_nop 0
	v_div_scale_f32 v0, s[2:3], v23, v23, 1.0
	v_rcp_f32_e32 v21, v0
; DI unsigned pk2(float a, float b) { f32v2 v = {a, b}; return __builtin_bit_cast(unsigned, __builtin_convertvector(v, bf16v2)); }
; DI float sigmoidf_(float v) { return 1.f / (1.f + __expf(-v)); }
; #define SW_FOR_TOK(j) _Pragma("unroll") for (int j = 0; j < 4; j++)
; #define SW_FOR_FEAT(i, rq) _Pragma("unroll") for (int i = 0; i < 2; i++) _Pragma("unroll") for (int rq = 0; rq < 4; rq++)
; DI void ph_ple(const Params& P, int g, int layer, bf16_t* smem) {
;     ...
;     SW_FOR_TOK(j) { const int tl_ = wn * 128 + j * 32 + l32;
;       SW_FOR_FEAT(i, rq) { const int c_ = wm * 64 + i * 32 + 8 * rq + 4 * h;
;         *(uint2*)(smem + tl_ * EPLD + c_) = make_uint2(pk2(sigmoidf_(SWV(i, j, 4 * rq)), sigmoidf_(SWV(i, j, 4 * rq + 1))), pk2(sigmoidf_(SWV(i, j, 4 * rq + 2)), sigmoidf_(SWV(i, j, 4 * rq + 3)))); } }
	s_nop 0
	v_fma_f32 v24, -v0, v21, 1.0
	v_fmac_f32_e32 v21, v24, v21
	v_div_scale_f32 v24, vcc, 1.0, v23, 1.0
	v_mul_f32_e32 v25, v24, v21
	v_fma_f32 v26, -v0, v25, v24
	v_fmac_f32_e32 v25, v26, v21
	v_fma_f32 v0, -v0, v25, v24
	v_div_fmas_f32 v0, v0, v21, v25
	v_div_scale_f32 v21, s[2:3], v22, v22, 1.0
	v_div_fixup_f32 v0, v0, v23, 1.0
	v_rcp_f32_e32 v23, v21
	s_nop 0
	v_fma_f32 v24, -v21, v23, 1.0
	v_fmac_f32_e32 v23, v24, v23
	v_div_scale_f32 v24, vcc, 1.0, v22, 1.0
	v_mul_f32_e32 v25, v24, v23
	v_fma_f32 v26, -v21, v25, v24
	v_fmac_f32_e32 v25, v26, v23
	v_fma_f32 v21, -v21, v25, v24
	v_div_fmas_f32 v21, v21, v23, v25
	v_div_fixup_f32 v21, v21, v22, 1.0
	v_cvt_pk_bf16_f32 v21, v21, v0
	v_mul_f32_e32 v0, 0xbfb8aa3b, v2
	v_exp_f32_e32 v2, v0
	v_mul_f32_e32 v0, 0xbfb8aa3b, v3
	v_exp_f32_e32 v3, v0
	ds_write2_b64 v191, v[18:19], v[20:21] offset0:196 offset1:198
	v_pk_add_f32 v[2:3], v[2:3], 1.0 op_sel_hi:[1,0]
	s_nop 0
	v_div_scale_f32 v0, s[2:3], v3, v3, 1.0
	v_rcp_f32_e32 v18, v0
	s_nop 0
	v_fma_f32 v19, -v0, v18, 1.0
	v_fmac_f32_e32 v18, v19, v18
	v_div_scale_f32 v19, vcc, 1.0, v3, 1.0
	v_mul_f32_e32 v20, v19, v18
	v_fma_f32 v21, -v0, v20, v19
	v_fmac_f32_e32 v20, v21, v18
	v_fma_f32 v0, -v0, v20, v19
	v_div_fmas_f32 v0, v0, v18, v20
	v_div_fixup_f32 v0, v0, v3, 1.0
	v_div_scale_f32 v3, s[2:3], v2, v2, 1.0
	v_rcp_f32_e32 v18, v3
	s_nop 0
	v_fma_f32 v19, -v3, v18, 1.0
	v_fmac_f32_e32 v18, v19, v18
	v_div_scale_f32 v19, vcc, 1.0, v2, 1.0
	v_mul_f32_e32 v20, v19, v18
	v_fma_f32 v21, -v3, v20, v19
	v_fmac_f32_e32 v20, v21, v18
	v_fma_f32 v3, -v3, v20, v19
	v_div_fmas_f32 v3, v3, v18, v20
	v_div_fixup_f32 v2, v3, v2, 1.0
	v_cvt_pk_bf16_f32 v2, v2, v0
	v_mul_f32_e32 v0, 0xbfb8aa3b, v4
	v_exp_f32_e32 v4, v0
	v_mul_f32_e32 v0, 0xbfb8aa3b, v5
	v_exp_f32_e32 v5, v0
	s_nop 0
	v_pk_add_f32 v[4:5], v[4:5], 1.0 op_sel_hi:[1,0]
	s_nop 0
	v_div_scale_f32 v0, s[2:3], v5, v5, 1.0
	v_rcp_f32_e32 v3, v0
	s_nop 0
	v_fma_f32 v18, -v0, v3, 1.0
	v_fmac_f32_e32 v3, v18, v3
	v_div_scale_f32 v18, vcc, 1.0, v5, 1.0
	v_mul_f32_e32 v19, v18, v3
	v_fma_f32 v20, -v0, v19, v18
	v_fmac_f32_e32 v19, v20, v3
	v_fma_f32 v0, -v0, v19, v18
	v_div_fmas_f32 v0, v0, v3, v19
	v_div_scale_f32 v3, s[2:3], v4, v4, 1.0
	v_div_fixup_f32 v0, v0, v5, 1.0
	v_rcp_f32_e32 v5, v3
	s_nop 0
	v_fma_f32 v18, -v3, v5, 1.0
	v_fmac_f32_e32 v5, v18, v5
	v_div_scale_f32 v18, vcc, 1.0, v4, 1.0
	v_mul_f32_e32 v19, v18, v5
	v_fma_f32 v20, -v3, v19, v18
	v_fmac_f32_e32 v19, v20, v5
	v_fma_f32 v3, -v3, v19, v18
	v_div_fmas_f32 v3, v3, v5, v19
	v_div_fixup_f32 v3, v3, v4, 1.0
	v_cvt_pk_bf16_f32 v3, v3, v0
	v_mul_f32_e32 v0, 0xbfb8aa3b, v6
	v_exp_f32_e32 v4, v0
	v_mul_f32_e32 v0, 0xbfb8aa3b, v7
	v_exp_f32_e32 v5, v0
	s_nop 0
	v_pk_add_f32 v[4:5], v[4:5], 1.0 op_sel_hi:[1,0]
	s_nop 0
	v_div_scale_f32 v0, s[2:3], v5, v5, 1.0
	v_rcp_f32_e32 v6, v0
	s_nop 0
	v_fma_f32 v7, -v0, v6, 1.0
	v_fmac_f32_e32 v6, v7, v6
	v_div_scale_f32 v7, vcc, 1.0, v5, 1.0
	v_mul_f32_e32 v18, v7, v6
	v_fma_f32 v19, -v0, v18, v7
	v_fmac_f32_e32 v18, v19, v6
	v_fma_f32 v0, -v0, v18, v7
	v_div_fmas_f32 v0, v0, v6, v18
	v_div_fixup_f32 v0, v0, v5, 1.0
	v_div_scale_f32 v5, s[2:3], v4, v4, 1.0
	v_rcp_f32_e32 v6, v5
	s_nop 0
	v_fma_f32 v7, -v5, v6, 1.0
	v_fmac_f32_e32 v6, v7, v6
	v_div_scale_f32 v7, vcc, 1.0, v4, 1.0
	v_mul_f32_e32 v18, v7, v6
	v_fma_f32 v19, -v5, v18, v7
	v_fmac_f32_e32 v18, v19, v6
	v_fma_f32 v5, -v5, v18, v7
	v_div_fmas_f32 v5, v5, v6, v18
	v_div_fixup_f32 v4, v5, v4, 1.0
	v_cvt_pk_bf16_f32 v4, v4, v0
	v_mul_f32_e32 v0, 0xbfb8aa3b, v8
	v_exp_f32_e32 v6, v0
	v_mul_f32_e32 v0, 0xbfb8aa3b, v9
	v_exp_f32_e32 v7, v0
	s_nop 0
	v_pk_add_f32 v[6:7], v[6:7], 1.0 op_sel_hi:[1,0]
	s_nop 0
	v_div_scale_f32 v0, s[2:3], v7, v7, 1.0
	v_rcp_f32_e32 v5, v0
	s_nop 0
	v_fma_f32 v8, -v0, v5, 1.0
	v_fmac_f32_e32 v5, v8, v5
	v_div_scale_f32 v8, vcc, 1.0, v7, 1.0
	v_mul_f32_e32 v9, v8, v5
	v_fma_f32 v18, -v0, v9, v8
	v_fmac_f32_e32 v9, v18, v5
	v_fma_f32 v0, -v0, v9, v8
	v_div_fmas_f32 v0, v0, v5, v9
	v_div_scale_f32 v5, s[2:3], v6, v6, 1.0
	v_div_fixup_f32 v0, v0, v7, 1.0
	v_rcp_f32_e32 v7, v5
	s_nop 0
	v_fma_f32 v8, -v5, v7, 1.0
	v_fmac_f32_e32 v7, v8, v7
	v_div_scale_f32 v8, vcc, 1.0, v6, 1.0
	v_mul_f32_e32 v9, v8, v7
	v_fma_f32 v18, -v5, v9, v8
	v_fmac_f32_e32 v9, v18, v7
	v_fma_f32 v5, -v5, v9, v8
	v_div_fmas_f32 v5, v5, v7, v9
	v_div_fixup_f32 v5, v5, v6, 1.0
; DI unsigned pk2(float a, float b) { f32v2 v = {a, b}; return __builtin_bit_cast(unsigned, __builtin_convertvector(v, bf16v2)); }
; DI float sigmoidf_(float v) { return 1.f / (1.f + __expf(-v)); }
; DI size_t tix(size_t t, int f, int KT) { return ((t >> 7) * KT + (f >> 6)) * 8192 + (t & 127) * 64 + (f & 63); }
; #define SW_FOR_TOK(j) _Pragma("unroll") for (int j = 0; j < 4; j++)
; #define SW_FOR_FEAT(i, rq) _Pragma("unroll") for (int i = 0; i < 2; i++) _Pragma("unroll") for (int rq = 0; rq < 4; rq++)
; DI void ph_ple(const Params& P, int g, int layer, bf16_t* smem) {
;     ...
;     SW_FOR_TOK(j) { const int tl_ = wn * 128 + j * 32 + l32;
;       SW_FOR_FEAT(i, rq) { const int c_ = wm * 64 + i * 32 + 8 * rq + 4 * h;
;         *(uint2*)(smem + tl_ * EPLD + c_) = make_uint2(pk2(sigmoidf_(SWV(i, j, 4 * rq)), sigmoidf_(SWV(i, j, 4 * rq + 1))), pk2(sigmoidf_(SWV(i, j, 4 * rq + 2)), sigmoidf_(SWV(i, j, 4 * rq + 3)))); } }
;     __syncthreads();
; #pragma unroll 8
;     for (int k = 0; k < 16; k++) {
;       const int c = tid + 256 * k; const int ch8 = c & 7, row = (c >> 3) & 255, fh = c >> 11;
;       const int f = fh * 64 + ch8 * 8; const size_t tg = (size_t)m0 + row;
;       const uint4 sg = *(const uint4*)(smem + row * EPLD + f);
;       bf16_t* ep = x2b + tix(tg, n0 + f, 16);
;       const uint4 eu = *(const uint4*)ep;
;       float* yp = y + tg * 1024 + n0 + f;
;       const uint4 xu = *(const uint4*)(x1b + tix(tg, n0 + f, 16));
	v_cvt_pk_bf16_f32 v5, v5, v0
	v_mul_f32_e32 v0, 0xbfb8aa3b, v10
	ds_write2_b64 v191, v[2:3], v[4:5] offset0:200 offset1:202
	v_exp_f32_e32 v2, v0
	v_mul_f32_e32 v0, 0xbfb8aa3b, v11
	v_exp_f32_e32 v3, v0
	s_nop 0
	v_pk_add_f32 v[2:3], v[2:3], 1.0 op_sel_hi:[1,0]
	s_nop 0
	v_div_scale_f32 v0, s[2:3], v3, v3, 1.0
	v_rcp_f32_e32 v4, v0
	s_nop 0
	v_fma_f32 v5, -v0, v4, 1.0
	v_fmac_f32_e32 v4, v5, v4
	v_div_scale_f32 v5, vcc, 1.0, v3, 1.0
	v_mul_f32_e32 v6, v5, v4
	v_fma_f32 v7, -v0, v6, v5
	v_fmac_f32_e32 v6, v7, v4
	v_fma_f32 v0, -v0, v6, v5
	v_div_fmas_f32 v0, v0, v4, v6
	v_div_fixup_f32 v0, v0, v3, 1.0
	v_div_scale_f32 v3, s[2:3], v2, v2, 1.0
	v_rcp_f32_e32 v4, v3
	s_nop 0
	v_fma_f32 v5, -v3, v4, 1.0
	v_fmac_f32_e32 v4, v5, v4
	v_div_scale_f32 v5, vcc, 1.0, v2, 1.0
	v_mul_f32_e32 v6, v5, v4
	v_fma_f32 v7, -v3, v6, v5
	v_fmac_f32_e32 v6, v7, v4
	v_fma_f32 v3, -v3, v6, v5
	v_div_fmas_f32 v3, v3, v4, v6
	v_div_fixup_f32 v2, v3, v2, 1.0
	v_cvt_pk_bf16_f32 v2, v2, v0
	v_mul_f32_e32 v0, 0xbfb8aa3b, v12
	v_exp_f32_e32 v4, v0
	v_mul_f32_e32 v0, 0xbfb8aa3b, v13
	v_exp_f32_e32 v5, v0
	s_nop 0
	v_pk_add_f32 v[4:5], v[4:5], 1.0 op_sel_hi:[1,0]
	s_nop 0
	v_div_scale_f32 v0, s[2:3], v5, v5, 1.0
	v_rcp_f32_e32 v3, v0
	s_nop 0
	v_fma_f32 v6, -v0, v3, 1.0
	v_fmac_f32_e32 v3, v6, v3
	v_div_scale_f32 v6, vcc, 1.0, v5, 1.0
	v_mul_f32_e32 v7, v6, v3
	v_fma_f32 v8, -v0, v7, v6
	v_fmac_f32_e32 v7, v8, v3
	v_fma_f32 v0, -v0, v7, v6
	v_div_fmas_f32 v0, v0, v3, v7
	v_div_scale_f32 v3, s[2:3], v4, v4, 1.0
	v_div_fixup_f32 v0, v0, v5, 1.0
	v_rcp_f32_e32 v5, v3
	s_nop 0
	v_fma_f32 v6, -v3, v5, 1.0
	v_fmac_f32_e32 v5, v6, v5
	v_div_scale_f32 v6, vcc, 1.0, v4, 1.0
	v_mul_f32_e32 v7, v6, v5
	v_fma_f32 v8, -v3, v7, v6
	v_fmac_f32_e32 v7, v8, v5
	v_fma_f32 v3, -v3, v7, v6
	v_div_fmas_f32 v3, v3, v5, v7
	v_div_fixup_f32 v3, v3, v4, 1.0
	v_cvt_pk_bf16_f32 v3, v3, v0
	v_mul_f32_e32 v0, 0xbfb8aa3b, v14
	v_exp_f32_e32 v4, v0
	v_mul_f32_e32 v0, 0xbfb8aa3b, v15
	v_exp_f32_e32 v5, v0
	s_nop 0
	v_pk_add_f32 v[4:5], v[4:5], 1.0 op_sel_hi:[1,0]
	s_nop 0
	v_div_scale_f32 v0, s[2:3], v5, v5, 1.0
	v_rcp_f32_e32 v6, v0
	s_nop 0
	v_fma_f32 v7, -v0, v6, 1.0
	v_fmac_f32_e32 v6, v7, v6
	v_div_scale_f32 v7, vcc, 1.0, v5, 1.0
	v_mul_f32_e32 v8, v7, v6
	v_fma_f32 v9, -v0, v8, v7
	v_fmac_f32_e32 v8, v9, v6
	v_fma_f32 v0, -v0, v8, v7
	v_div_fmas_f32 v0, v0, v6, v8
	v_div_fixup_f32 v0, v0, v5, 1.0
	v_div_scale_f32 v5, s[2:3], v4, v4, 1.0
	v_rcp_f32_e32 v6, v5
	s_nop 0
	v_fma_f32 v7, -v5, v6, 1.0
	v_fmac_f32_e32 v6, v7, v6
	v_div_scale_f32 v7, vcc, 1.0, v4, 1.0
	v_mul_f32_e32 v8, v7, v6
	v_fma_f32 v9, -v5, v8, v7
	v_fmac_f32_e32 v8, v9, v6
	v_fma_f32 v5, -v5, v8, v7
	v_div_fmas_f32 v5, v5, v6, v8
	v_div_fixup_f32 v4, v5, v4, 1.0
	v_cvt_pk_bf16_f32 v4, v4, v0
	v_mul_f32_e32 v0, 0xbfb8aa3b, v16
	v_exp_f32_e32 v6, v0
	v_mul_f32_e32 v0, 0xbfb8aa3b, v17
	v_exp_f32_e32 v7, v0
	s_nop 0
	v_pk_add_f32 v[6:7], v[6:7], 1.0 op_sel_hi:[1,0]
	s_nop 0
	v_div_scale_f32 v0, s[2:3], v7, v7, 1.0
	v_rcp_f32_e32 v5, v0
	s_nop 0
	v_fma_f32 v8, -v0, v5, 1.0
	v_fmac_f32_e32 v5, v8, v5
	v_div_scale_f32 v8, vcc, 1.0, v7, 1.0
	v_mul_f32_e32 v9, v8, v5
	v_fma_f32 v10, -v0, v9, v8
	v_fmac_f32_e32 v9, v10, v5
	v_fma_f32 v0, -v0, v9, v8
	v_div_fmas_f32 v0, v0, v5, v9
	v_div_scale_f32 v5, s[2:3], v6, v6, 1.0
	v_div_fixup_f32 v0, v0, v7, 1.0
	v_rcp_f32_e32 v7, v5
	s_lshl_b32 s2, s29, 1
	s_ashr_i32 s3, s2, 31
	s_lshl_b64 s[2:3], s[2:3], 2
	v_fma_f32 v8, -v5, v7, 1.0
	v_fmac_f32_e32 v7, v8, v7
	v_div_scale_f32 v8, vcc, 1.0, v6, 1.0
	v_mul_f32_e32 v9, v8, v7
	v_fma_f32 v10, -v5, v9, v8
	v_fmac_f32_e32 v9, v10, v7
	v_fma_f32 v5, -v5, v9, v8
	v_div_fmas_f32 v5, v5, v7, v9
	v_div_fixup_f32 v5, v5, v6, 1.0
	v_cmp_lt_i32_e32 vcc, v241, v237
	v_cvt_pk_bf16_f32 v5, v5, v0
	s_add_u32 s2, s10, s2
	v_cndmask_b32_e32 v0, v238, v241, vcc
	v_cmp_lt_i32_e32 vcc, v240, v237
	v_lshlrev_b32_e32 v10, 2, v0
	s_addc_u32 s3, s11, s3
	v_cndmask_b32_e32 v0, v238, v240, vcc
	v_cmp_lt_i32_e32 vcc, v252, v237
	v_lshlrev_b32_e32 v11, 2, v0
	ds_write2_b64 v191, v[2:3], v[4:5] offset0:204 offset1:206
	v_cndmask_b32_e32 v0, v238, v252, vcc
	v_lshlrev_b32_e32 v12, 2, v0
	v_and_b32_e32 v3, 0x7ffff, v171
	v_and_b32_e32 v2, -16, v170
	v_or_b32_e32 v0, v174, v162
	v_lshl_add_u64 v[4:5], s[2:3], 0, v[172:173]
	s_waitcnt lgkmcnt(0)
	s_barrier
	s_branch .LBB0_239

; #define A256_LOADH(kt_, hf_) { a0 = la.ld1(kt_, (hf_) * 4 + 0, tid); a1 = la.ld1(kt_, (hf_) * 4 + 1, tid); a2 = la.ld1(kt_, (hf_) * 4 + 2, tid); a3 = la.ld1(kt_, (hf_) * 4 + 3, tid); }
; #define ZERO_ACC8(a) { _Pragma("unroll") for (int i_ = 0; i_ < 8; i_++) _Pragma("unroll") for (int r_ = 0; r_ < 16; r_++) a[i_][r_] = 0.f; }
; template <bool swap, class LA>
; DI void gemm256_ws(const LA& la, const bf16_t* Wt, const int KS, const int nk, bf16_t* smem, f32x16 (&acc)[8]) {
;     ...
;   A256_LOADH(0, 0) A256_STH(smem, 0)
;   A256_LOADH(0, 1) A256_STH(smem, 1)
;   W256_LD(0, 0, w00, w10) W256_LD(0, 1, w01, w11) W256_LD(0, 2, w02, w12) W256_LD(0, 3, w03, w13)
;   __syncthreads();
;   const int aoff = (tbk * 128 + l32) * LDT + h * 8;
; DI void ph_out(const Params& P, int layer, bf16_t* smem) {
;     ...
;   for (int it = 0;; it++) {
;     int mt, nt; if (!tile_sched256(bid, it, 8, 8, mt, nt)) break;
;     const int m0 = mt * 256, n0 = nt * 128;
;     __syncthreads();
;     f32x16 acc[8]; ZERO_ACC8(acc)
;     LoadTile256 la{cat + (size_t)(2 * mt) * 16 * 8192, 16 * 8192};
;     gemm256_ws<true>(la, W + (size_t)n0 * 1024, 64, 16, smem, acc);
.LBB0_267:
	s_ashr_i32 s3, s2, 31
	s_lshr_b32 s3, s3, 24
	s_add_i32 s3, s2, s3
	s_ashr_i32 s6, s3, 8
	s_and_b32 s3, s3, 0xffffff00
	s_sub_i32 s2, s2, s3
	s_ashr_i32 s3, s2, 31
	s_lshr_b32 s3, s3, 29
	s_add_i32 s3, s2, s3
	s_ashr_i32 s17, s3, 3
	s_sub_i32 s3, s6, s17
	s_add_i32 s17, s17, s14
	s_lshl_b32 s16, s3, 3
	s_lshl_b32 s6, s17, 1
	s_add_i32 s16, s16, s2
	s_ashr_i32 s7, s6, 31
	s_lshl_b32 s2, s16, 7
	s_lshl_b64 s[6:7], s[6:7], 18
	v_mov_b32_e32 v0, v234
	s_barrier
	s_add_u32 s8, s84, s6
	s_addc_u32 s9, s85, s7
	v_lshlrev_b32_e32 v2, 3, v0
	s_ashr_i32 s3, s2, 31
	v_add_u32_e32 v6, 0x800, v2
	s_lshl_b64 s[6:7], s[2:3], 11
	v_readlane_b32 s10, v253, 53
	v_ashrrev_i32_e32 v3, 31, v2
	v_ashrrev_i32_e32 v7, 31, v6
	v_readlane_b32 s11, v253, 54
	s_add_u32 s6, s10, s6
	v_lshlrev_b64 v[176:177], 1, v[2:3]
	v_lshlrev_b64 v[178:179], 1, v[6:7]
	v_add_u32_e32 v6, 0x1000, v2
	v_add_u32_e32 v2, 0x1800, v2
	s_addc_u32 s7, s11, s7
	v_ashrrev_i32_e32 v7, 31, v6
	v_ashrrev_i32_e32 v3, 31, v2
	v_lshlrev_b64 v[180:181], 1, v[6:7]
	v_lshlrev_b64 v[182:183], 1, v[2:3]
	s_add_u32 s10, s8, 0x40000
	v_lshl_add_u64 v[4:5], s[8:9], 0, v[176:177]
	v_lshl_add_u64 v[8:9], s[8:9], 0, v[178:179]
	v_lshl_add_u64 v[12:13], s[8:9], 0, v[180:181]
	v_lshl_add_u64 v[2:3], s[8:9], 0, v[182:183]
	s_addc_u32 s11, s9, 0
	v_ashrrev_i32_e32 v36, 6, v0
	global_load_dwordx4 v[4:7], v[4:5], off
	s_nop 0
	global_load_dwordx4 v[8:11], v[8:9], off
	s_nop 0
	global_load_dwordx4 v[12:15], v[12:13], off
	s_nop 0
	global_load_dwordx4 v[16:19], v[2:3], off
	v_lshl_add_u64 v[2:3], s[10:11], 0, v[176:177]
	v_lshl_add_u64 v[24:25], s[10:11], 0, v[178:179]
	v_lshl_add_u64 v[28:29], s[10:11], 0, v[180:181]
	v_lshl_add_u64 v[32:33], s[10:11], 0, v[182:183]
	v_lshlrev_b32_e32 v37, 4, v0
	v_and_b32_e32 v36, -2, v36
	global_load_dwordx4 v[20:23], v[2:3], off
	s_nop 0
	global_load_dwordx4 v[24:27], v[24:25], off
	s_nop 0
	global_load_dwordx4 v[28:31], v[28:29], off
	s_nop 0
	global_load_dwordx4 v[32:35], v[32:33], off
	v_and_b32_e32 v3, 31, v0
	v_lshrrev_b32_e32 v39, 3, v0
	v_lshlrev_b32_e32 v40, 1, v0
	v_lshrrev_b32_e32 v41, 1, v0
	v_and_b32_e32 v0, 0x3f0, v37
	v_and_b32_e32 v38, 0x70, v37
	v_ashrrev_i32_e32 v37, 31, v36
	v_lshlrev_b64 v[36:37], 16, v[36:37]
	v_lshl_add_u64 v[36:37], s[6:7], 0, v[36:37]
	v_lshl_add_u64 v[186:187], v[36:37], 0, v[0:1]
	s_mov_b64 s[6:7], 0x10000
	v_lshl_add_u64 v[188:189], v[186:187], 0, s[6:7]
	v_add_co_u32_e64 v36, s[6:7], s94, v186
	s_movk_i32 s18, 0x80
	s_nop 0
	v_addc_co_u32_e64 v37, s[6:7], 0, v187, s[6:7]
	global_load_dwordx4 v[154:157], v[36:37], off
	global_load_dwordx4 v[158:161], v[186:187], off
	global_load_dwordx4 v[146:149], v[36:37], off offset:1024
	global_load_dwordx4 v[150:153], v[186:187], off offset:1024
	global_load_dwordx4 v[142:145], v[36:37], off offset:2048
	global_load_dwordx4 v[138:141], v[186:187], off offset:2048
	global_load_dwordx4 v[130:133], v[36:37], off offset:3072
	global_load_dwordx4 v[134:137], v[186:187], off offset:3072
	v_mov_b32_e32 v2, 0
	v_and_or_b32 v3, v40, s18, v3
	v_and_b32_e32 v40, 16, v41
	v_mad_u64_u32 v[184:185], s[18:19], v39, s0, v[38:39]
	v_mad_u32_u24 v169, v3, s0, v40
	s_mov_b32 s6, 0
	v_mov_b32_e32 v3, v2
	v_mov_b32_e32 v50, v2
	v_mov_b32_e32 v51, v2
	v_mov_b32_e32 v52, v2
	v_mov_b32_e32 v53, v2
	v_mov_b32_e32 v54, v2
	v_mov_b32_e32 v55, v2
	v_mov_b32_e32 v56, v2
	v_mov_b32_e32 v57, v2
	v_mov_b32_e32 v58, v2
	v_mov_b32_e32 v59, v2
	v_mov_b32_e32 v60, v2
	v_mov_b32_e32 v61, v2
	v_mov_b32_e32 v62, v2
	v_mov_b32_e32 v63, v2
	v_mov_b32_e32 v64, v2
	v_mov_b32_e32 v65, v2
	v_mov_b32_e32 v82, v2
	s_waitcnt vmcnt(15)
	ds_write_b128 v184, v[4:7]
	s_waitcnt vmcnt(14)
	ds_write_b128 v184, v[8:11] offset:4608
	s_waitcnt vmcnt(13)
	ds_write_b128 v184, v[12:15] offset:9216
	s_waitcnt vmcnt(12)
	ds_write_b128 v184, v[16:19] offset:13824
	s_waitcnt vmcnt(11)
	ds_write_b128 v184, v[20:23] offset:18432
	s_waitcnt vmcnt(10)
	ds_write_b128 v184, v[24:27] offset:23040
	s_waitcnt vmcnt(9)
	ds_write_b128 v184, v[28:31] offset:27648
	s_waitcnt vmcnt(8)
	ds_write_b128 v184, v[32:35] offset:32256
	v_mov_b32_e32 v4, v2
	v_mov_b32_e32 v5, v2
	v_mov_b32_e32 v6, v2
	v_mov_b32_e32 v7, v2
	v_mov_b32_e32 v8, v2
	v_mov_b32_e32 v9, v2
	v_mov_b32_e32 v10, v2
	v_mov_b32_e32 v11, v2
	v_mov_b32_e32 v12, v2
	v_mov_b32_e32 v13, v2
	v_mov_b32_e32 v14, v2
	v_mov_b32_e32 v15, v2
	v_mov_b32_e32 v16, v2
	v_mov_b32_e32 v17, v2
	v_mov_b32_e32 v18, v2
	v_mov_b32_e32 v19, v2
	v_mov_b32_e32 v20, v2
	v_mov_b32_e32 v21, v2
	v_mov_b32_e32 v22, v2
	v_mov_b32_e32 v23, v2
	v_mov_b32_e32 v24, v2
	v_mov_b32_e32 v25, v2
	v_mov_b32_e32 v26, v2
	v_mov_b32_e32 v27, v2
	v_mov_b32_e32 v28, v2
	v_mov_b32_e32 v29, v2
	v_mov_b32_e32 v30, v2
	v_mov_b32_e32 v31, v2
	v_mov_b32_e32 v32, v2
	v_mov_b32_e32 v33, v2
	v_mov_b32_e32 v83, v2
	v_mov_b32_e32 v84, v2
	v_mov_b32_e32 v85, v2
	v_mov_b32_e32 v86, v2
	v_mov_b32_e32 v87, v2
	v_mov_b32_e32 v88, v2
	v_mov_b32_e32 v89, v2
	v_mov_b32_e32 v90, v2
	v_mov_b32_e32 v91, v2
	v_mov_b32_e32 v92, v2
	v_mov_b32_e32 v93, v2
	v_mov_b32_e32 v94, v2
	v_mov_b32_e32 v95, v2
	v_mov_b32_e32 v96, v2
	v_mov_b32_e32 v97, v2
	v_mov_b32_e32 v34, v2
	v_mov_b32_e32 v35, v2
	v_mov_b32_e32 v36, v2
	v_mov_b32_e32 v37, v2
	v_mov_b32_e32 v38, v2
	v_mov_b32_e32 v39, v2
	v_mov_b32_e32 v40, v2
	v_mov_b32_e32 v41, v2
	v_mov_b32_e32 v42, v2
	v_mov_b32_e32 v43, v2
	v_mov_b32_e32 v44, v2
	v_mov_b32_e32 v45, v2
	v_mov_b32_e32 v46, v2
	v_mov_b32_e32 v47, v2
	v_mov_b32_e32 v48, v2
	v_mov_b32_e32 v49, v2
	v_mov_b32_e32 v66, v2
	v_mov_b32_e32 v67, v2
	v_mov_b32_e32 v68, v2
	v_mov_b32_e32 v69, v2
	v_mov_b32_e32 v70, v2
	v_mov_b32_e32 v71, v2
	v_mov_b32_e32 v72, v2
	v_mov_b32_e32 v73, v2
	v_mov_b32_e32 v74, v2
	v_mov_b32_e32 v75, v2
	v_mov_b32_e32 v76, v2
	v_mov_b32_e32 v77, v2
	v_mov_b32_e32 v78, v2
	v_mov_b32_e32 v79, v2
	v_mov_b32_e32 v80, v2
	v_mov_b32_e32 v81, v2
	v_mov_b32_e32 v98, v2
	v_mov_b32_e32 v99, v2
	v_mov_b32_e32 v100, v2
	v_mov_b32_e32 v101, v2
	v_mov_b32_e32 v102, v2
	v_mov_b32_e32 v103, v2
	v_mov_b32_e32 v104, v2
	v_mov_b32_e32 v105, v2
	v_mov_b32_e32 v106, v2
	v_mov_b32_e32 v107, v2
	v_mov_b32_e32 v108, v2
	v_mov_b32_e32 v109, v2
	v_mov_b32_e32 v110, v2
	v_mov_b32_e32 v111, v2
	v_mov_b32_e32 v112, v2
	v_mov_b32_e32 v113, v2
	v_mov_b32_e32 v114, v2
	v_mov_b32_e32 v115, v2
	v_mov_b32_e32 v116, v2
	v_mov_b32_e32 v117, v2
	v_mov_b32_e32 v118, v2
	v_mov_b32_e32 v119, v2
	v_mov_b32_e32 v120, v2
	v_mov_b32_e32 v121, v2
	v_mov_b32_e32 v122, v2
	v_mov_b32_e32 v123, v2
	v_mov_b32_e32 v124, v2
	v_mov_b32_e32 v125, v2
	v_mov_b32_e32 v126, v2
	v_mov_b32_e32 v127, v2
	v_mov_b32_e32 v128, v2
	v_mov_b32_e32 v129, v2
	s_waitcnt lgkmcnt(0)
	s_barrier
; #define A256_LOADH(kt_, hf_) { a0 = la.ld1(kt_, (hf_) * 4 + 0, tid); a1 = la.ld1(kt_, (hf_) * 4 + 1, tid); a2 = la.ld1(kt_, (hf_) * 4 + 2, tid); a3 = la.ld1(kt_, (hf_) * 4 + 3, tid); }
; template <bool swap, class LA>
; DI void gemm256_ws(const LA& la, const bf16_t* Wt, const int KS, const int nk, bf16_t* smem, f32x16 (&acc)[8]) {
;     ...
;   for (int kt = 0; kt < nk; kt++) {
;     const int cur = kt & 1; const int kn = (kt + 1 < nk) ? kt + 1 : last;
;     const bf16_t* sp = smem + cur * ATILE_E + aoff;
;     bf16_t* nxt = smem + (cur ^ 1) * ATILE_E;
;     A256_LOADH(kn, 0)
;     MMA256(0, w00, w10) W256_LD(kn, 0, w00, w10)
	s_lshl_b32 s36, 1, 14
	s_add_u32 s18, s8, s36
	s_addc_u32 s19, s9, 0
	v_lshl_add_u64 v[206:207], s[18:19], 0, v[176:177]
	v_lshl_add_u64 v[210:211], s[18:19], 0, v[178:179]
	v_lshl_add_u64 v[214:215], s[18:19], 0, v[180:181]
	v_lshl_add_u64 v[218:219], s[18:19], 0, v[182:183]
	global_load_dwordx4 v[206:209], v[206:207], off
	global_load_dwordx4 v[210:213], v[210:211], off
	global_load_dwordx4 v[214:217], v[214:215], off
	global_load_dwordx4 v[218:221], v[218:219], off
	s_add_u32 s18, s10, s36
	s_addc_u32 s19, s11, 0
	v_lshl_add_u64 v[222:223], s[18:19], 0, v[176:177]
	v_lshl_add_u64 v[226:227], s[18:19], 0, v[178:179]
	v_lshl_add_u64 v[230:231], s[18:19], 0, v[180:181]
	v_lshl_add_u64 v[246:247], s[18:19], 0, v[182:183]
	global_load_dwordx4 v[222:225], v[222:223], off
	global_load_dwordx4 v[226:229], v[226:227], off
	global_load_dwordx4 v[230:233], v[230:231], off
	global_load_dwordx4 v[246:249], v[246:247], off
	s_and_b32 s7, s6, 1
	s_mul_i32 s18, s7, 0x9000
	v_add_u32_e32 v0, s18, v169

; DI size_t tix(size_t t, int f, int KT) { return ((t >> 7) * KT + (f >> 6)) * 8192 + (t & 127) * 64 + (f & 63); }
; DI void rows_out_tiled(const bf16_t* smem, bf16_t* buf, size_t t0, int f0, int KT, int tid) {
; #pragma unroll 8
;   for (int k = 0; k < 16; k++) { const int c = tid + 256 * k; const int ch = c & 7, row = (c >> 3) & 255, fh = c >> 11;
;     *(uint4*)(buf + tix(t0 + row, f0 + fh * 64 + ch * 8, KT)) = *(const uint4*)(smem + row * EPLD + fh * 64 + ch * 8); }
; }
.LBB0_468:
	v_add_u32_e32 v16, s10, v163
	v_ashrrev_i32_e32 v0, 5, v16
	v_lshlrev_b32_e32 v6, 1, v0
	v_and_b32_e32 v6, 0xffffff80, v6
	v_add_u32_e32 v0, s8, v0
	v_add_u32_e32 v8, v188, v6
	v_ashrrev_i32_e32 v6, 6, v0
	v_ashrrev_i32_e32 v7, 31, v6
	v_lshl_add_u64 v[6:7], v[2:3], 0, v[6:7]
	v_lshlrev_b64 v[6:7], 14, v[6:7]
	v_lshl_add_u64 v[10:11], v[4:5], 0, v[6:7]
	ds_read_b128 v[6:9], v8
	v_add_u32_e32 v0, 0x100, v16
	v_mov_b32_e32 v13, s19
	s_addk_i32 s10, 0x800
	s_cmpk_lg_i32 s10, 0x1000
	s_waitcnt lgkmcnt(0)
	global_store_dwordx4 v[10:11], v[6:9], off
	v_lshlrev_b32_e32 v10, 1, v162
	v_mov_b32_e32 v11, v1
	v_bfe_u32 v6, v0, 3, 8
	v_ashrrev_i32_e32 v0, 5, v0
	v_lshlrev_b32_e32 v8, 1, v0
	v_mul_u32_u24_e32 v7, 0x110, v6
	v_and_b32_e32 v8, 0xffffff80, v8
	v_or_b32_e32 v12, s18, v6
	v_add_u32_e32 v0, s8, v0
	v_add3_u32 v17, v7, v8, v10
	v_lshrrev_b64 v[6:7], 3, v[12:13]
	v_ashrrev_i32_e32 v8, 6, v0
	v_and_b32_e32 v7, 0x3ffff, v7
	v_and_b32_e32 v6, -16, v6
	v_ashrrev_i32_e32 v9, 31, v8
	v_lshl_add_u64 v[6:7], v[6:7], 0, v[8:9]
	v_lshlrev_b64 v[6:7], 14, v[6:7]
	v_lshlrev_b32_e32 v0, 7, v12
	v_lshl_add_u64 v[6:7], s[82:83], 0, v[6:7]
	v_and_b32_e32 v0, 0x3f80, v0
	v_lshl_add_u64 v[6:7], v[6:7], 0, v[0:1]
	v_lshl_add_u64 v[14:15], v[6:7], 0, v[10:11]
	ds_read_b128 v[6:9], v17
	v_add_u32_e32 v0, 0x200, v16
	s_waitcnt lgkmcnt(0)
	global_store_dwordx4 v[14:15], v[6:9], off
	s_nop 1
	v_bfe_u32 v6, v0, 3, 8
	v_ashrrev_i32_e32 v0, 5, v0
	v_lshlrev_b32_e32 v8, 1, v0
	v_mul_u32_u24_e32 v7, 0x110, v6
	v_and_b32_e32 v8, 0xffffff80, v8
	v_or_b32_e32 v12, s18, v6
	v_add_u32_e32 v0, s8, v0
	v_add3_u32 v17, v7, v8, v10
	v_lshrrev_b64 v[6:7], 3, v[12:13]
	v_ashrrev_i32_e32 v8, 6, v0
	v_and_b32_e32 v7, 0x3ffff, v7
	v_and_b32_e32 v6, -16, v6
	v_ashrrev_i32_e32 v9, 31, v8
	v_lshl_add_u64 v[6:7], v[6:7], 0, v[8:9]
	v_lshlrev_b64 v[6:7], 14, v[6:7]
	v_lshlrev_b32_e32 v0, 7, v12
	v_lshl_add_u64 v[6:7], s[82:83], 0, v[6:7]
	v_and_b32_e32 v0, 0x3f80, v0
	v_lshl_add_u64 v[6:7], v[6:7], 0, v[0:1]
	v_lshl_add_u64 v[14:15], v[6:7], 0, v[10:11]
	ds_read_b128 v[6:9], v17
	v_add_u32_e32 v0, 0x300, v16
	s_waitcnt lgkmcnt(0)
	global_store_dwordx4 v[14:15], v[6:9], off
	s_nop 1
	v_bfe_u32 v6, v0, 3, 8
	v_ashrrev_i32_e32 v0, 5, v0
	v_lshlrev_b32_e32 v8, 1, v0
	v_mul_u32_u24_e32 v7, 0x110, v6
	v_and_b32_e32 v8, 0xffffff80, v8
	v_or_b32_e32 v12, s18, v6
	v_add_u32_e32 v0, s8, v0
	v_add3_u32 v17, v7, v8, v10
	v_lshrrev_b64 v[6:7], 3, v[12:13]
	v_ashrrev_i32_e32 v8, 6, v0
	v_and_b32_e32 v7, 0x3ffff, v7
	v_and_b32_e32 v6, -16, v6
	v_ashrrev_i32_e32 v9, 31, v8
	v_lshl_add_u64 v[6:7], v[6:7], 0, v[8:9]
	v_lshlrev_b64 v[6:7], 14, v[6:7]
	v_lshlrev_b32_e32 v0, 7, v12
	v_lshl_add_u64 v[6:7], s[82:83], 0, v[6:7]
	v_and_b32_e32 v0, 0x3f80, v0
	v_lshl_add_u64 v[6:7], v[6:7], 0, v[0:1]
	v_lshl_add_u64 v[14:15], v[6:7], 0, v[10:11]
	ds_read_b128 v[6:9], v17
	v_add_u32_e32 v0, 0x400, v16
	s_waitcnt lgkmcnt(0)
	global_store_dwordx4 v[14:15], v[6:9], off
	s_nop 1
	v_bfe_u32 v6, v0, 3, 8
	v_ashrrev_i32_e32 v0, 5, v0
	v_lshlrev_b32_e32 v8, 1, v0
	v_mul_u32_u24_e32 v7, 0x110, v6
	v_and_b32_e32 v8, 0xffffff80, v8
	v_or_b32_e32 v12, s18, v6
	v_add_u32_e32 v0, s8, v0
	v_add3_u32 v17, v7, v8, v10
	v_lshrrev_b64 v[6:7], 3, v[12:13]
	v_ashrrev_i32_e32 v8, 6, v0
	v_and_b32_e32 v7, 0x3ffff, v7
	v_and_b32_e32 v6, -16, v6
	v_ashrrev_i32_e32 v9, 31, v8
	v_lshl_add_u64 v[6:7], v[6:7], 0, v[8:9]
	v_lshlrev_b64 v[6:7], 14, v[6:7]
	v_lshlrev_b32_e32 v0, 7, v12
	v_lshl_add_u64 v[6:7], s[82:83], 0, v[6:7]
	v_and_b32_e32 v0, 0x3f80, v0
	v_lshl_add_u64 v[6:7], v[6:7], 0, v[0:1]
	v_lshl_add_u64 v[14:15], v[6:7], 0, v[10:11]
	ds_read_b128 v[6:9], v17
	v_add_u32_e32 v0, 0x500, v16
	s_waitcnt lgkmcnt(0)
	global_store_dwordx4 v[14:15], v[6:9], off
	s_nop 1
	v_bfe_u32 v6, v0, 3, 8
	v_ashrrev_i32_e32 v0, 5, v0
	v_lshlrev_b32_e32 v8, 1, v0
	v_mul_u32_u24_e32 v7, 0x110, v6
	v_and_b32_e32 v8, 0xffffff80, v8
	v_or_b32_e32 v12, s18, v6
	v_add_u32_e32 v0, s8, v0
	v_add3_u32 v17, v7, v8, v10
	v_lshrrev_b64 v[6:7], 3, v[12:13]
	v_ashrrev_i32_e32 v8, 6, v0
	v_and_b32_e32 v7, 0x3ffff, v7
	v_and_b32_e32 v6, -16, v6
	v_ashrrev_i32_e32 v9, 31, v8
	v_lshl_add_u64 v[6:7], v[6:7], 0, v[8:9]
	v_lshlrev_b64 v[6:7], 14, v[6:7]
	v_lshlrev_b32_e32 v0, 7, v12
	v_lshl_add_u64 v[6:7], s[82:83], 0, v[6:7]
	v_and_b32_e32 v0, 0x3f80, v0
	v_lshl_add_u64 v[6:7], v[6:7], 0, v[0:1]
	v_lshl_add_u64 v[14:15], v[6:7], 0, v[10:11]
	ds_read_b128 v[6:9], v17
	v_add_u32_e32 v0, 0x600, v16
	s_waitcnt lgkmcnt(0)
	global_store_dwordx4 v[14:15], v[6:9], off
	s_nop 1
	v_bfe_u32 v6, v0, 3, 8
	v_ashrrev_i32_e32 v0, 5, v0
	v_lshlrev_b32_e32 v8, 1, v0
	v_mul_u32_u24_e32 v7, 0x110, v6
	v_and_b32_e32 v8, 0xffffff80, v8
	v_or_b32_e32 v12, s18, v6
	v_add_u32_e32 v0, s8, v0
	v_add3_u32 v17, v7, v8, v10
	v_lshrrev_b64 v[6:7], 3, v[12:13]
	v_ashrrev_i32_e32 v8, 6, v0
	v_and_b32_e32 v7, 0x3ffff, v7
	v_and_b32_e32 v6, -16, v6
	v_ashrrev_i32_e32 v9, 31, v8
	v_lshl_add_u64 v[6:7], v[6:7], 0, v[8:9]
	v_lshlrev_b64 v[6:7], 14, v[6:7]
	v_lshlrev_b32_e32 v0, 7, v12
	v_lshl_add_u64 v[6:7], s[82:83], 0, v[6:7]
	v_and_b32_e32 v0, 0x3f80, v0
	v_lshl_add_u64 v[6:7], v[6:7], 0, v[0:1]
	v_lshl_add_u64 v[14:15], v[6:7], 0, v[10:11]
	ds_read_b128 v[6:9], v17
	v_add_u32_e32 v0, 0x700, v16
	s_waitcnt lgkmcnt(0)
	global_store_dwordx4 v[14:15], v[6:9], off
	s_nop 1
	v_bfe_u32 v6, v0, 3, 8
	v_ashrrev_i32_e32 v0, 5, v0
	v_lshlrev_b32_e32 v8, 1, v0
	v_mul_u32_u24_e32 v7, 0x110, v6
	v_and_b32_e32 v8, 0xffffff80, v8
	v_or_b32_e32 v12, s18, v6
	v_add_u32_e32 v0, s8, v0
	v_add3_u32 v14, v7, v8, v10
	v_lshrrev_b64 v[6:7], 3, v[12:13]
	v_ashrrev_i32_e32 v8, 6, v0
	v_and_b32_e32 v7, 0x3ffff, v7
	v_and_b32_e32 v6, -16, v6
	v_ashrrev_i32_e32 v9, 31, v8
	v_lshl_add_u64 v[6:7], v[6:7], 0, v[8:9]
	v_lshlrev_b64 v[6:7], 14, v[6:7]
	v_lshlrev_b32_e32 v0, 7, v12
	v_lshl_add_u64 v[6:7], s[82:83], 0, v[6:7]
	v_and_b32_e32 v0, 0x3f80, v0
	v_lshl_add_u64 v[6:7], v[6:7], 0, v[0:1]
	v_lshl_add_u64 v[10:11], v[6:7], 0, v[10:11]
	ds_read_b128 v[6:9], v14
	s_waitcnt lgkmcnt(0)
	global_store_dwordx4 v[10:11], v[6:9], off
	s_cbranch_scc1 .LBB0_468
; #define A256_LOADH(kt_, hf_) { a0 = la.ld1(kt_, (hf_) * 4 + 0, tid); a1 = la.ld1(kt_, (hf_) * 4 + 1, tid); a2 = la.ld1(kt_, (hf_) * 4 + 2, tid); a3 = la.ld1(kt_, (hf_) * 4 + 3, tid); }
; #define ZERO_ACC8(a) { _Pragma("unroll") for (int i_ = 0; i_ < 8; i_++) _Pragma("unroll") for (int r_ = 0; r_ < 16; r_++) a[i_][r_] = 0.f; }
; template <bool swap, class LA>
; DI void gemm256_ws(const LA& la, const bf16_t* Wt, const int KS, const int nk, bf16_t* smem, f32x16 (&acc)[8]) {
;     ...
;   A256_LOADH(0, 0) A256_STH(smem, 0)
;   A256_LOADH(0, 1) A256_STH(smem, 1)
;   W256_LD(0, 0, w00, w10) W256_LD(0, 1, w01, w11) W256_LD(0, 2, w02, w12) W256_LD(0, 3, w03, w13)
;   __syncthreads();
;   const int aoff = (tbk * 128 + l32) * LDT + h * 8;
; DI void ph_ple(const Params& P, int g, int layer, bf16_t* smem) {
;     ...
;     ZERO_ACC8(acc)
;     { LoadTile256 la{x1b + (size_t)(2 * mt) * 16 * 8192, 16 * 8192}; gemm256_ws<true>(la, Wg + (size_t)n0 * 1024, 64, 16, smem, acc); }
	s_lshl_b64 s[2:3], s[2:3], 18
	v_mov_b32_e32 v0, v234
	s_barrier
	s_add_u32 s2, s80, s2
	s_addc_u32 s3, s81, s3
	v_lshlrev_b32_e32 v2, 3, v0
	s_lshl_b64 s[10:11], s[8:9], 11
	v_readlane_b32 s12, v254, 7
	v_ashrrev_i32_e32 v3, 31, v2
	v_readlane_b32 s13, v254, 8
	s_add_u32 s12, s12, s10
	v_lshlrev_b64 v[174:175], 1, v[2:3]
	v_add_u32_e32 v6, 0x800, v2
	v_add_u32_e32 v8, 0x1000, v2
	v_add_u32_e32 v2, 0x1800, v2
	s_addc_u32 s13, s13, s11
	v_ashrrev_i32_e32 v7, 31, v6
	v_ashrrev_i32_e32 v9, 31, v8
	v_ashrrev_i32_e32 v3, 31, v2
	v_lshlrev_b64 v[176:177], 1, v[6:7]
	v_lshlrev_b64 v[178:179], 1, v[8:9]
	v_lshlrev_b64 v[180:181], 1, v[2:3]
	s_add_u32 s10, s2, 0x40000
	v_lshl_add_u64 v[4:5], s[2:3], 0, v[174:175]
	v_lshl_add_u64 v[6:7], s[2:3], 0, v[176:177]
	v_lshl_add_u64 v[16:17], s[2:3], 0, v[178:179]
	v_lshl_add_u64 v[2:3], s[2:3], 0, v[180:181]
	s_addc_u32 s11, s3, 0
	v_ashrrev_i32_e32 v40, 6, v0
	global_load_dwordx4 v[8:11], v[4:5], off
	global_load_dwordx4 v[12:15], v[6:7], off
	s_nop 0
	global_load_dwordx4 v[16:19], v[16:17], off
	s_nop 0
	global_load_dwordx4 v[20:23], v[2:3], off
	v_lshl_add_u64 v[2:3], s[10:11], 0, v[174:175]
	v_lshl_add_u64 v[6:7], s[10:11], 0, v[178:179]
	v_lshl_add_u64 v[36:37], s[10:11], 0, v[180:181]
	v_lshlrev_b32_e32 v41, 4, v0
	v_and_b32_e32 v40, -2, v40
	v_lshl_add_u64 v[4:5], s[10:11], 0, v[176:177]
	global_load_dwordx4 v[24:27], v[2:3], off
	global_load_dwordx4 v[28:31], v[4:5], off
	global_load_dwordx4 v[32:35], v[6:7], off
	s_nop 0
	global_load_dwordx4 v[36:39], v[36:37], off
	v_and_b32_e32 v7, 31, v0
	v_lshrrev_b32_e32 v43, 3, v0
	v_lshlrev_b32_e32 v44, 1, v0
	v_lshrrev_b32_e32 v45, 1, v0
	v_and_b32_e32 v0, 0x3f0, v41
	v_and_b32_e32 v42, 0x70, v41
	v_ashrrev_i32_e32 v41, 31, v40
	v_lshlrev_b64 v[40:41], 16, v[40:41]
	v_lshl_add_u64 v[40:41], s[12:13], 0, v[40:41]
	v_lshl_add_u64 v[184:185], v[40:41], 0, v[0:1]
	v_add_co_u32_e32 v40, vcc, s94, v184
	s_movk_i32 s36, 0x80
	s_nop 0
	v_addc_co_u32_e32 v41, vcc, 0, v185, vcc
	global_load_dwordx4 v[154:157], v[40:41], off
	global_load_dwordx4 v[158:161], v[184:185], off
	global_load_dwordx4 v[146:149], v[40:41], off offset:1024
	global_load_dwordx4 v[150:153], v[184:185], off offset:1024
	global_load_dwordx4 v[142:145], v[40:41], off offset:2048
	global_load_dwordx4 v[138:141], v[184:185], off offset:2048
	global_load_dwordx4 v[130:133], v[40:41], off offset:3072
	global_load_dwordx4 v[134:137], v[184:185], off offset:3072
	v_mov_b32_e32 v2, 0
	v_and_or_b32 v7, v44, s36, v7
	v_and_b32_e32 v44, 16, v45
	v_mad_u64_u32 v[182:183], s[36:37], v43, s0, v[42:43]
	s_mov_b64 s[12:13], 0x10000
	s_mov_b32 s29, 0
	v_mov_b32_e32 v3, v2
	v_mov_b32_e32 v4, v2
	v_mov_b32_e32 v5, v2
	v_mov_b32_e32 v6, v2
	v_mad_u32_u24 v183, v7, s0, v44
	v_lshl_add_u64 v[186:187], v[184:185], 0, s[12:13]
	v_mov_b32_e32 v7, v2
	v_mov_b32_e32 v40, v2
	v_mov_b32_e32 v41, v2
	v_mov_b32_e32 v42, v2
	v_mov_b32_e32 v43, v2
	v_mov_b32_e32 v44, v2
	v_mov_b32_e32 v45, v2
	v_mov_b32_e32 v46, v2
	v_mov_b32_e32 v47, v2
	v_mov_b32_e32 v48, v2
	v_mov_b32_e32 v49, v2
	v_mov_b32_e32 v66, v2
	v_mov_b32_e32 v67, v2
	v_mov_b32_e32 v68, v2
	v_mov_b32_e32 v69, v2
	v_mov_b32_e32 v70, v2
	v_mov_b32_e32 v71, v2
	v_mov_b32_e32 v72, v2
	v_mov_b32_e32 v73, v2
	s_waitcnt vmcnt(15)
	ds_write_b128 v182, v[8:11]
	s_waitcnt vmcnt(14)
	ds_write_b128 v182, v[12:15] offset:4608
	s_waitcnt vmcnt(13)
	ds_write_b128 v182, v[16:19] offset:9216
	s_waitcnt vmcnt(12)
	ds_write_b128 v182, v[20:23] offset:13824
	s_waitcnt vmcnt(11)
	ds_write_b128 v182, v[24:27] offset:18432
	s_waitcnt vmcnt(10)
	ds_write_b128 v182, v[28:31] offset:23040
	s_waitcnt vmcnt(9)
	ds_write_b128 v182, v[32:35] offset:27648
	s_waitcnt vmcnt(8)
	ds_write_b128 v182, v[36:39] offset:32256
	v_mov_b32_e32 v8, v2
	v_mov_b32_e32 v9, v2
	v_mov_b32_e32 v10, v2
	v_mov_b32_e32 v11, v2
	v_mov_b32_e32 v12, v2
	v_mov_b32_e32 v13, v2
	v_mov_b32_e32 v14, v2
	v_mov_b32_e32 v15, v2
	v_mov_b32_e32 v16, v2
	v_mov_b32_e32 v17, v2
	v_mov_b32_e32 v34, v2
	v_mov_b32_e32 v35, v2
	v_mov_b32_e32 v36, v2
	v_mov_b32_e32 v37, v2
	v_mov_b32_e32 v38, v2
	v_mov_b32_e32 v39, v2
	v_mov_b32_e32 v74, v2
	v_mov_b32_e32 v75, v2
	v_mov_b32_e32 v76, v2
	v_mov_b32_e32 v77, v2
	v_mov_b32_e32 v78, v2
	v_mov_b32_e32 v79, v2
	v_mov_b32_e32 v80, v2
	v_mov_b32_e32 v81, v2
	v_mov_b32_e32 v98, v2
	v_mov_b32_e32 v99, v2
	v_mov_b32_e32 v100, v2
	v_mov_b32_e32 v101, v2
	v_mov_b32_e32 v102, v2
	v_mov_b32_e32 v103, v2
	v_mov_b32_e32 v104, v2
	v_mov_b32_e32 v105, v2
	v_mov_b32_e32 v106, v2
	v_mov_b32_e32 v107, v2
	v_mov_b32_e32 v108, v2
	v_mov_b32_e32 v109, v2
	v_mov_b32_e32 v110, v2
	v_mov_b32_e32 v111, v2
	v_mov_b32_e32 v112, v2
	v_mov_b32_e32 v113, v2
	v_mov_b32_e32 v18, v2
	v_mov_b32_e32 v19, v2
	v_mov_b32_e32 v20, v2
	v_mov_b32_e32 v21, v2
	v_mov_b32_e32 v22, v2
	v_mov_b32_e32 v23, v2
	v_mov_b32_e32 v24, v2
	v_mov_b32_e32 v25, v2
	v_mov_b32_e32 v26, v2
	v_mov_b32_e32 v27, v2
	v_mov_b32_e32 v28, v2
	v_mov_b32_e32 v29, v2
	v_mov_b32_e32 v30, v2
	v_mov_b32_e32 v31, v2
	v_mov_b32_e32 v32, v2
	v_mov_b32_e32 v33, v2
	v_mov_b32_e32 v50, v2
	v_mov_b32_e32 v51, v2
	v_mov_b32_e32 v52, v2
	v_mov_b32_e32 v53, v2
	v_mov_b32_e32 v54, v2
	v_mov_b32_e32 v55, v2
	v_mov_b32_e32 v56, v2
	v_mov_b32_e32 v57, v2
	v_mov_b32_e32 v58, v2
	v_mov_b32_e32 v59, v2
	v_mov_b32_e32 v60, v2
	v_mov_b32_e32 v61, v2
	v_mov_b32_e32 v62, v2
	v_mov_b32_e32 v63, v2
	v_mov_b32_e32 v64, v2
	v_mov_b32_e32 v65, v2
	v_mov_b32_e32 v82, v2
	v_mov_b32_e32 v83, v2
	v_mov_b32_e32 v84, v2
	v_mov_b32_e32 v85, v2
	v_mov_b32_e32 v86, v2
	v_mov_b32_e32 v87, v2
	v_mov_b32_e32 v88, v2
	v_mov_b32_e32 v89, v2
	v_mov_b32_e32 v90, v2
	v_mov_b32_e32 v91, v2
	v_mov_b32_e32 v92, v2
	v_mov_b32_e32 v93, v2
	v_mov_b32_e32 v94, v2
	v_mov_b32_e32 v95, v2
	v_mov_b32_e32 v96, v2
	v_mov_b32_e32 v97, v2
	v_mov_b32_e32 v114, v2
	v_mov_b32_e32 v115, v2
	v_mov_b32_e32 v116, v2
	v_mov_b32_e32 v117, v2
	v_mov_b32_e32 v118, v2
	v_mov_b32_e32 v119, v2
	v_mov_b32_e32 v120, v2
	v_mov_b32_e32 v121, v2
	v_mov_b32_e32 v122, v2
	v_mov_b32_e32 v123, v2
	v_mov_b32_e32 v124, v2
	v_mov_b32_e32 v125, v2
	v_mov_b32_e32 v126, v2
	v_mov_b32_e32 v127, v2
	v_mov_b32_e32 v128, v2
	v_mov_b32_e32 v129, v2
	s_waitcnt lgkmcnt(0)
	s_barrier
; #define A256_LOADH(kt_, hf_) { a0 = la.ld1(kt_, (hf_) * 4 + 0, tid); a1 = la.ld1(kt_, (hf_) * 4 + 1, tid); a2 = la.ld1(kt_, (hf_) * 4 + 2, tid); a3 = la.ld1(kt_, (hf_) * 4 + 3, tid); }
; template <bool swap, class LA>
; DI void gemm256_ws(const LA& la, const bf16_t* Wt, const int KS, const int nk, bf16_t* smem, f32x16 (&acc)[8]) {
;     ...
;   for (int kt = 0; kt < nk; kt++) {
;     const int cur = kt & 1; const int kn = (kt + 1 < nk) ? kt + 1 : last;
;     const bf16_t* sp = smem + cur * ATILE_E + aoff;
;     bf16_t* nxt = smem + (cur ^ 1) * ATILE_E;
;     A256_LOADH(kn, 0)
;     MMA256(0, w00, w10) W256_LD(kn, 0, w00, w10)
;     MMA256(1, w01, w11) W256_LD(kn, 1, w01, w11)
;     A256_STH(nxt, 0)
;     A256_LOADH(kn, 1)
;     MMA256(2, w02, w12) W256_LD(kn, 2, w02, w12)
;     MMA256(3, w03, w13) W256_LD(kn, 3, w03, w13)
	s_lshl_b32 s37, 1, 14
	s_add_u32 s12, s2, s37
	s_addc_u32 s13, s3, 0
	v_lshl_add_u64 v[204:205], s[12:13], 0, v[174:175]
	s_add_u32 s12, s12, 0x1000
	s_addc_u32 s13, s13, 0
	v_lshl_add_u64 v[208:209], s[12:13], 0, v[174:175]
	s_add_u32 s12, s12, 0x1000
	s_addc_u32 s13, s13, 0
	v_lshl_add_u64 v[216:217], s[12:13], 0, v[174:175]
	s_add_u32 s12, s12, 0x1000
	s_addc_u32 s13, s13, 0
	v_lshl_add_u64 v[220:221], s[12:13], 0, v[174:175]
	global_load_dwordx4 v[204:207], v[204:205], off
	global_load_dwordx4 v[208:211], v[208:209], off
	global_load_dwordx4 v[216:219], v[216:217], off
	global_load_dwordx4 v[220:223], v[220:221], off
	s_add_u32 s12, s10, s37
	s_addc_u32 s13, s11, 0
	v_lshl_add_u64 v[224:225], s[12:13], 0, v[174:175]
	s_add_u32 s12, s12, 0x1000
	s_addc_u32 s13, s13, 0
	v_lshl_add_u64 v[228:229], s[12:13], 0, v[174:175]
	s_add_u32 s12, s12, 0x1000
	s_addc_u32 s13, s13, 0
	v_lshl_add_u64 v[246:247], s[12:13], 0, v[174:175]
	s_add_u32 s12, s12, 0x1000
	s_addc_u32 s13, s13, 0
	v_lshl_add_u64 v[176:177], s[12:13], 0, v[174:175]
	global_load_dwordx4 v[224:227], v[224:225], off
	global_load_dwordx4 v[228:231], v[228:229], off
	global_load_dwordx4 v[246:249], v[246:247], off
	global_load_dwordx4 v[176:179], v[176:177], off
	s_and_b32 s12, s29, 1
	s_mul_i32 s13, s12, 0x9000
	v_add_u32_e32 v0, s13, v183
.LBB0_470:
	ds_read_b128 v[192:195], v0
	ds_read_b128 v[196:199], v0 offset:4608
	ds_read_b128 v[200:203], v0 offset:9216
	s_and_b32 s12, s29, 1
	s_add_i32 s29, s29, 1
	s_min_u32 s36, s29, 15
	s_xor_b32 s12, s12, 1
	s_mul_i32 s13, s12, 0x9000
	v_add_u32_e32 v214, s13, v182
	s_lshl_b32 s90, s36, 12
	s_add_i32 s36, s29, 1
	s_min_u32 s36, s36, 15
	s_lshl_b32 s37, s36, 14
	s_waitcnt vmcnt(14) lgkmcnt(2)
	v_mfma_f32_32x32x16_bf16 v[98:113], v[154:157], v[192:195], v[98:113]
	v_mfma_f32_32x32x16_bf16 v[114:129], v[158:161], v[192:195], v[114:129]
	ds_read_b128 v[192:195], v0 offset:13824
	s_waitcnt lgkmcnt(2)
	v_mfma_f32_32x32x16_bf16 v[66:81], v[154:157], v[196:199], v[66:81]
	v_mfma_f32_32x32x16_bf16 v[82:97], v[158:161], v[196:199], v[82:97]
	ds_read_b128 v[196:199], v0 offset:32
	s_waitcnt lgkmcnt(2)
	v_mfma_f32_32x32x16_bf16 v[34:49], v[154:157], v[200:203], v[34:49]
	v_mfma_f32_32x32x16_bf16 v[50:65], v[158:161], v[200:203], v[50:65]
	ds_read_b128 v[200:203], v0 offset:4640
	s_waitcnt lgkmcnt(2)
	v_mfma_f32_32x32x16_bf16 v[2:17], v[154:157], v[192:195], v[2:17]
	v_mfma_f32_32x32x16_bf16 v[18:33], v[158:161], v[192:195], v[18:33]
	ds_read_b128 v[192:195], v0 offset:9248
	v_lshl_add_u64 v[154:155], v[186:187], 0, s[90:91]
	global_load_dwordx4 v[154:157], v[154:155], off
	v_lshl_add_u64 v[158:159], v[184:185], 0, s[90:91]
	global_load_dwordx4 v[158:161], v[158:159], off
	s_waitcnt vmcnt(14) lgkmcnt(2)
	v_mfma_f32_32x32x16_bf16 v[98:113], v[146:149], v[196:199], v[98:113]
	v_mfma_f32_32x32x16_bf16 v[114:129], v[150:153], v[196:199], v[114:129]
	ds_read_b128 v[196:199], v0 offset:13856
	s_waitcnt lgkmcnt(2)
	v_mfma_f32_32x32x16_bf16 v[66:81], v[146:149], v[200:203], v[66:81]
	v_mfma_f32_32x32x16_bf16 v[82:97], v[150:153], v[200:203], v[82:97]
	ds_read_b128 v[200:203], v0 offset:64
	s_waitcnt lgkmcnt(2)
	v_mfma_f32_32x32x16_bf16 v[34:49], v[146:149], v[192:195], v[34:49]
	v_mfma_f32_32x32x16_bf16 v[50:65], v[150:153], v[192:195], v[50:65]
	ds_read_b128 v[192:195], v0 offset:4672
	s_waitcnt lgkmcnt(2)
	v_mfma_f32_32x32x16_bf16 v[2:17], v[146:149], v[196:199], v[2:17]
	v_mfma_f32_32x32x16_bf16 v[18:33], v[150:153], v[196:199], v[18:33]
	ds_read_b128 v[196:199], v0 offset:9280
	v_lshl_add_u64 v[146:147], v[186:187], 0, s[90:91]
	global_load_dwordx4 v[146:149], v[146:147], off offset:1024
	v_lshl_add_u64 v[150:151], v[184:185], 0, s[90:91]
	global_load_dwordx4 v[150:153], v[150:151], off offset:1024
	s_waitcnt vmcnt(8)
	ds_write_b128 v214, v[204:207]
	ds_write_b128 v214, v[208:211] offset:4608
	ds_write_b128 v214, v[216:219] offset:9216
	ds_write_b128 v214, v[220:223] offset:13824
	s_add_u32 s12, s2, s37
	s_addc_u32 s13, s3, 0
	v_lshl_add_u64 v[204:205], s[12:13], 0, v[174:175]
	s_add_u32 s12, s12, 0x1000
	s_addc_u32 s13, s13, 0
	v_lshl_add_u64 v[208:209], s[12:13], 0, v[174:175]
	s_add_u32 s12, s12, 0x1000
	s_addc_u32 s13, s13, 0
	v_lshl_add_u64 v[216:217], s[12:13], 0, v[174:175]
	s_add_u32 s12, s12, 0x1000
	s_addc_u32 s13, s13, 0
	v_lshl_add_u64 v[220:221], s[12:13], 0, v[174:175]
	global_load_dwordx4 v[204:207], v[204:205], off
	global_load_dwordx4 v[208:211], v[208:209], off
	global_load_dwordx4 v[216:219], v[216:217], off
	global_load_dwordx4 v[220:223], v[220:221], off
	s_waitcnt lgkmcnt(6)
	v_mfma_f32_32x32x16_bf16 v[98:113], v[142:145], v[200:203], v[98:113]
	v_mfma_f32_32x32x16_bf16 v[114:129], v[138:141], v[200:203], v[114:129]
	ds_read_b128 v[200:203], v0 offset:13888
	s_waitcnt lgkmcnt(6)
	v_mfma_f32_32x32x16_bf16 v[66:81], v[142:145], v[192:195], v[66:81]
	v_mfma_f32_32x32x16_bf16 v[82:97], v[138:141], v[192:195], v[82:97]
	ds_read_b128 v[192:195], v0 offset:96
	s_waitcnt lgkmcnt(6)
	v_mfma_f32_32x32x16_bf16 v[34:49], v[142:145], v[196:199], v[34:49]
	v_mfma_f32_32x32x16_bf16 v[50:65], v[138:141], v[196:199], v[50:65]
	ds_read_b128 v[196:199], v0 offset:4704
	s_waitcnt lgkmcnt(2)
	v_mfma_f32_32x32x16_bf16 v[2:17], v[142:145], v[200:203], v[2:17]
	v_mfma_f32_32x32x16_bf16 v[18:33], v[138:141], v[200:203], v[18:33]
	ds_read_b128 v[200:203], v0 offset:9312
	v_lshl_add_u64 v[142:143], v[186:187], 0, s[90:91]
	global_load_dwordx4 v[142:145], v[142:143], off offset:2048
	v_lshl_add_u64 v[138:139], v[184:185], 0, s[90:91]
	global_load_dwordx4 v[138:141], v[138:139], off offset:2048
	s_waitcnt lgkmcnt(2)
; DI unsigned pk2(float a, float b) { f32v2 v = {a, b}; return __builtin_bit_cast(unsigned, __builtin_convertvector(v, bf16v2)); }
; DI float sigmoidf_(float v) { return 1.f / (1.f + __expf(-v)); }
; #define A256_LOADH(kt_, hf_) { a0 = la.ld1(kt_, (hf_) * 4 + 0, tid); a1 = la.ld1(kt_, (hf_) * 4 + 1, tid); a2 = la.ld1(kt_, (hf_) * 4 + 2, tid); a3 = la.ld1(kt_, (hf_) * 4 + 3, tid); }
; #define SW_FOR_TOK(j) _Pragma("unroll") for (int j = 0; j < 4; j++)
; #define SW_FOR_FEAT(i, rq) _Pragma("unroll") for (int i = 0; i < 2; i++) _Pragma("unroll") for (int rq = 0; rq < 4; rq++)
; template <bool swap, class LA>
; DI void gemm256_ws(const LA& la, const bf16_t* Wt, const int KS, const int nk, bf16_t* smem, f32x16 (&acc)[8]) {
;     ...
;     MMA256(1, w01, w11) W256_LD(kn, 1, w01, w11)
;     A256_STH(nxt, 0)
;     A256_LOADH(kn, 1)
;     MMA256(2, w02, w12) W256_LD(kn, 2, w02, w12)
;     MMA256(3, w03, w13) W256_LD(kn, 3, w03, w13)
;     A256_STH(nxt, 1)
;     __syncthreads();
; DI void ph_ple(const Params& P, int g, int layer, bf16_t* smem) {
;     ...
;     SW_FOR_TOK(j) { const int tl_ = wn * 128 + j * 32 + l32;
;       SW_FOR_FEAT(i, rq) { const int c_ = wm * 64 + i * 32 + 8 * rq + 4 * h;
;         *(uint2*)(smem + tl_ * EPLD + c_) = make_uint2(pk2(sigmoidf_(SWV(i, j, 4 * rq)), sigmoidf_(SWV(i, j, 4 * rq + 1))), pk2(sigmoidf_(SWV(i, j, 4 * rq + 2)), sigmoidf_(SWV(i, j, 4 * rq + 3)))); } }
	v_mfma_f32_32x32x16_bf16 v[98:113], v[130:133], v[192:195], v[98:113]
	v_mfma_f32_32x32x16_bf16 v[114:129], v[134:137], v[192:195], v[114:129]
	ds_read_b128 v[192:195], v0 offset:13920
	s_waitcnt lgkmcnt(2)
	v_mfma_f32_32x32x16_bf16 v[66:81], v[130:133], v[196:199], v[66:81]
	v_mfma_f32_32x32x16_bf16 v[82:97], v[134:137], v[196:199], v[82:97]
	s_waitcnt lgkmcnt(1)
	v_mfma_f32_32x32x16_bf16 v[34:49], v[130:133], v[200:203], v[34:49]
	v_mfma_f32_32x32x16_bf16 v[50:65], v[134:137], v[200:203], v[50:65]
	s_waitcnt lgkmcnt(0)
	v_mfma_f32_32x32x16_bf16 v[2:17], v[130:133], v[192:195], v[2:17]
	v_mfma_f32_32x32x16_bf16 v[18:33], v[134:137], v[192:195], v[18:33]
	v_lshl_add_u64 v[130:131], v[186:187], 0, s[90:91]
	global_load_dwordx4 v[130:133], v[130:131], off offset:3072
	v_lshl_add_u64 v[134:135], v[184:185], 0, s[90:91]
	global_load_dwordx4 v[134:137], v[134:135], off offset:3072
	s_waitcnt vmcnt(12)
	ds_write_b128 v214, v[224:227] offset:18432
	ds_write_b128 v214, v[228:231] offset:23040
	ds_write_b128 v214, v[246:249] offset:27648
	ds_write_b128 v214, v[176:179] offset:32256
	s_add_u32 s12, s10, s37
	s_addc_u32 s13, s11, 0
	v_lshl_add_u64 v[224:225], s[12:13], 0, v[174:175]
	s_add_u32 s12, s12, 0x1000
	s_addc_u32 s13, s13, 0
	v_lshl_add_u64 v[228:229], s[12:13], 0, v[174:175]
	s_add_u32 s12, s12, 0x1000
	s_addc_u32 s13, s13, 0
	v_lshl_add_u64 v[246:247], s[12:13], 0, v[174:175]
	s_add_u32 s12, s12, 0x1000
	s_addc_u32 s13, s13, 0
	v_lshl_add_u64 v[176:177], s[12:13], 0, v[174:175]
	global_load_dwordx4 v[224:227], v[224:225], off
	global_load_dwordx4 v[228:231], v[228:229], off
	global_load_dwordx4 v[246:249], v[246:247], off
	global_load_dwordx4 v[176:179], v[176:177], off
	s_and_b32 s12, s29, 1
	s_mul_i32 s12, s12, 0x9000
	v_add_u32_e32 v0, s12, v183
	s_cmp_lg_u32 s29, 16
	s_waitcnt lgkmcnt(0)
	s_barrier
	s_cbranch_scc1 .LBB0_470
	s_waitcnt vmcnt(0)
	v_mul_f32_e32 v0, 0xbfb8aa3b, v114
	v_exp_f32_e32 v114, v0
	v_mul_f32_e32 v0, 0xbfb8aa3b, v115
	v_exp_f32_e32 v115, v0
	s_nop 0
	v_pk_add_f32 v[114:115], v[114:115], 1.0 op_sel_hi:[1,0]
	s_nop 0
	v_div_scale_f32 v0, s[2:3], v115, v115, 1.0
	s_waitcnt vmcnt(0)
	v_rcp_f32_e32 v130, v0
	s_nop 0
	v_fma_f32 v131, -v0, v130, 1.0
	v_fmac_f32_e32 v130, v131, v130
	v_div_scale_f32 v131, vcc, 1.0, v115, 1.0
	v_mul_f32_e32 v132, v131, v130
	v_fma_f32 v133, -v0, v132, v131
	v_fmac_f32_e32 v132, v133, v130
	v_fma_f32 v0, -v0, v132, v131
	v_div_fmas_f32 v0, v0, v130, v132
	v_div_fixup_f32 v0, v0, v115, 1.0
	v_div_scale_f32 v115, s[2:3], v114, v114, 1.0
	v_rcp_f32_e32 v130, v115
	s_nop 0
	v_fma_f32 v131, -v115, v130, 1.0
	v_fmac_f32_e32 v130, v131, v130
	v_div_scale_f32 v131, vcc, 1.0, v114, 1.0
	v_mul_f32_e32 v132, v131, v130
	v_fma_f32 v133, -v115, v132, v131
	v_fmac_f32_e32 v132, v133, v130
	v_fma_f32 v115, -v115, v132, v131
	v_div_fmas_f32 v115, v115, v130, v132
	v_div_fixup_f32 v114, v115, v114, 1.0
	v_cvt_pk_bf16_f32 v114, v114, v0
	v_mul_f32_e32 v0, 0xbfb8aa3b, v116
	v_exp_f32_e32 v116, v0
	v_mul_f32_e32 v0, 0xbfb8aa3b, v117
	v_exp_f32_e32 v117, v0
	s_nop 0
	v_pk_add_f32 v[116:117], v[116:117], 1.0 op_sel_hi:[1,0]
	s_nop 0
	v_div_scale_f32 v0, s[2:3], v117, v117, 1.0
	v_rcp_f32_e32 v115, v0
	s_nop 0
	v_fma_f32 v130, -v0, v115, 1.0
	v_fmac_f32_e32 v115, v130, v115
	v_div_scale_f32 v130, vcc, 1.0, v117, 1.0
	v_mul_f32_e32 v131, v130, v115
	v_fma_f32 v132, -v0, v131, v130
	v_fmac_f32_e32 v131, v132, v115
	v_fma_f32 v0, -v0, v131, v130
	v_div_fmas_f32 v0, v0, v115, v131
	v_div_scale_f32 v115, s[2:3], v116, v116, 1.0
	v_div_fixup_f32 v0, v0, v117, 1.0
	v_rcp_f32_e32 v117, v115
	s_nop 0
	v_fma_f32 v130, -v115, v117, 1.0
	v_fmac_f32_e32 v117, v130, v117
	v_div_scale_f32 v130, vcc, 1.0, v116, 1.0
	v_mul_f32_e32 v131, v130, v117
	v_fma_f32 v132, -v115, v131, v130
	v_fmac_f32_e32 v131, v132, v117
	v_fma_f32 v115, -v115, v131, v130
	v_div_fmas_f32 v115, v115, v117, v131
	v_div_fixup_f32 v115, v115, v116, 1.0
	v_cvt_pk_bf16_f32 v115, v115, v0
	v_mul_f32_e32 v0, 0xbfb8aa3b, v118
	v_exp_f32_e32 v116, v0
	v_mul_f32_e32 v0, 0xbfb8aa3b, v119
	v_exp_f32_e32 v117, v0
	s_nop 0
	v_pk_add_f32 v[116:117], v[116:117], 1.0 op_sel_hi:[1,0]
	s_nop 0
	v_div_scale_f32 v0, s[2:3], v117, v117, 1.0
	v_rcp_f32_e32 v118, v0
	s_nop 0
	v_fma_f32 v119, -v0, v118, 1.0
	v_fmac_f32_e32 v118, v119, v118
	v_div_scale_f32 v119, vcc, 1.0, v117, 1.0
	v_mul_f32_e32 v130, v119, v118
	v_fma_f32 v131, -v0, v130, v119
	v_fmac_f32_e32 v130, v131, v118
	v_fma_f32 v0, -v0, v130, v119
	v_div_fmas_f32 v0, v0, v118, v130
	v_div_fixup_f32 v0, v0, v117, 1.0
	v_div_scale_f32 v117, s[2:3], v116, v116, 1.0
	v_rcp_f32_e32 v118, v117
	s_nop 0
	v_fma_f32 v119, -v117, v118, 1.0
	v_fmac_f32_e32 v118, v119, v118
	v_div_scale_f32 v119, vcc, 1.0, v116, 1.0
	v_mul_f32_e32 v130, v119, v118
	v_fma_f32 v131, -v117, v130, v119
	v_fmac_f32_e32 v130, v131, v118
	v_fma_f32 v117, -v117, v130, v119
	v_div_fmas_f32 v117, v117, v118, v130
	v_div_fixup_f32 v116, v117, v116, 1.0
	v_cvt_pk_bf16_f32 v116, v116, v0
	v_mul_f32_e32 v0, 0xbfb8aa3b, v120
	v_exp_f32_e32 v118, v0
	v_mul_f32_e32 v0, 0xbfb8aa3b, v121
	v_exp_f32_e32 v119, v0
	s_nop 0
	v_pk_add_f32 v[118:119], v[118:119], 1.0 op_sel_hi:[1,0]
	s_nop 0
	v_div_scale_f32 v0, s[2:3], v119, v119, 1.0
	v_rcp_f32_e32 v117, v0
	s_nop 0
	v_fma_f32 v120, -v0, v117, 1.0
	v_fmac_f32_e32 v117, v120, v117
	v_div_scale_f32 v120, vcc, 1.0, v119, 1.0
	v_mul_f32_e32 v121, v120, v117
	v_fma_f32 v130, -v0, v121, v120
	v_fmac_f32_e32 v121, v130, v117
	v_fma_f32 v0, -v0, v121, v120
	v_div_fmas_f32 v0, v0, v117, v121
	v_div_scale_f32 v117, s[2:3], v118, v118, 1.0
	v_div_fixup_f32 v0, v0, v119, 1.0
	v_rcp_f32_e32 v119, v117
	s_nop 0
; DI unsigned pk2(float a, float b) { f32v2 v = {a, b}; return __builtin_bit_cast(unsigned, __builtin_convertvector(v, bf16v2)); }
; DI float sigmoidf_(float v) { return 1.f / (1.f + __expf(-v)); }
; #define SW_FOR_TOK(j) _Pragma("unroll") for (int j = 0; j < 4; j++)
; #define SW_FOR_FEAT(i, rq) _Pragma("unroll") for (int i = 0; i < 2; i++) _Pragma("unroll") for (int rq = 0; rq < 4; rq++)
; DI void ph_ple(const Params& P, int g, int layer, bf16_t* smem) {
;     ...
;     SW_FOR_TOK(j) { const int tl_ = wn * 128 + j * 32 + l32;
;       SW_FOR_FEAT(i, rq) { const int c_ = wm * 64 + i * 32 + 8 * rq + 4 * h;
;         *(uint2*)(smem + tl_ * EPLD + c_) = make_uint2(pk2(sigmoidf_(SWV(i, j, 4 * rq)), sigmoidf_(SWV(i, j, 4 * rq + 1))), pk2(sigmoidf_(SWV(i, j, 4 * rq + 2)), sigmoidf_(SWV(i, j, 4 * rq + 3)))); } }
	v_fma_f32 v120, -v117, v119, 1.0
	v_fmac_f32_e32 v119, v120, v119
	v_div_scale_f32 v120, vcc, 1.0, v118, 1.0
	v_mul_f32_e32 v121, v120, v119
	v_fma_f32 v130, -v117, v121, v120
	v_fmac_f32_e32 v121, v130, v119
	v_fma_f32 v117, -v117, v121, v120
	v_div_fmas_f32 v117, v117, v119, v121
	v_div_fixup_f32 v117, v117, v118, 1.0
	v_cvt_pk_bf16_f32 v117, v117, v0
	v_mul_f32_e32 v0, 0xbfb8aa3b, v122
	ds_write2_b64 v165, v[114:115], v[116:117] offset1:2
	v_exp_f32_e32 v114, v0
	v_mul_f32_e32 v0, 0xbfb8aa3b, v123
	v_exp_f32_e32 v115, v0
	s_nop 0
	v_pk_add_f32 v[114:115], v[114:115], 1.0 op_sel_hi:[1,0]
	s_nop 0
	v_div_scale_f32 v0, s[2:3], v115, v115, 1.0
	v_rcp_f32_e32 v116, v0
	s_nop 0
	v_fma_f32 v117, -v0, v116, 1.0
	v_fmac_f32_e32 v116, v117, v116
	v_div_scale_f32 v117, vcc, 1.0, v115, 1.0
	v_mul_f32_e32 v118, v117, v116
	v_fma_f32 v119, -v0, v118, v117
	v_fmac_f32_e32 v118, v119, v116
	v_fma_f32 v0, -v0, v118, v117
	v_div_fmas_f32 v0, v0, v116, v118
	v_div_fixup_f32 v0, v0, v115, 1.0
	v_div_scale_f32 v115, s[2:3], v114, v114, 1.0
	v_rcp_f32_e32 v116, v115
	s_nop 0
	v_fma_f32 v117, -v115, v116, 1.0
	v_fmac_f32_e32 v116, v117, v116
	v_div_scale_f32 v117, vcc, 1.0, v114, 1.0
	v_mul_f32_e32 v118, v117, v116
	v_fma_f32 v119, -v115, v118, v117
	v_fmac_f32_e32 v118, v119, v116
	v_fma_f32 v115, -v115, v118, v117
	v_div_fmas_f32 v115, v115, v116, v118
	v_div_fixup_f32 v114, v115, v114, 1.0
	v_cvt_pk_bf16_f32 v114, v114, v0
	v_mul_f32_e32 v0, 0xbfb8aa3b, v124
	v_exp_f32_e32 v116, v0
	v_mul_f32_e32 v0, 0xbfb8aa3b, v125
	v_exp_f32_e32 v117, v0
	s_nop 0
	v_pk_add_f32 v[116:117], v[116:117], 1.0 op_sel_hi:[1,0]
	s_nop 0
	v_div_scale_f32 v0, s[2:3], v117, v117, 1.0
	v_rcp_f32_e32 v115, v0
	s_nop 0
	v_fma_f32 v118, -v0, v115, 1.0
	v_fmac_f32_e32 v115, v118, v115
	v_div_scale_f32 v118, vcc, 1.0, v117, 1.0
	v_mul_f32_e32 v119, v118, v115
	v_fma_f32 v120, -v0, v119, v118
	v_fmac_f32_e32 v119, v120, v115
	v_fma_f32 v0, -v0, v119, v118
	v_div_fmas_f32 v0, v0, v115, v119
	v_div_scale_f32 v115, s[2:3], v116, v116, 1.0
	v_div_fixup_f32 v0, v0, v117, 1.0
	v_rcp_f32_e32 v117, v115
	s_nop 0
	v_fma_f32 v118, -v115, v117, 1.0
	v_fmac_f32_e32 v117, v118, v117
	v_div_scale_f32 v118, vcc, 1.0, v116, 1.0
	v_mul_f32_e32 v119, v118, v117
	v_fma_f32 v120, -v115, v119, v118
	v_fmac_f32_e32 v119, v120, v117
	v_fma_f32 v115, -v115, v119, v118
	v_div_fmas_f32 v115, v115, v117, v119
	v_div_fixup_f32 v115, v115, v116, 1.0
	v_cvt_pk_bf16_f32 v115, v115, v0
	v_mul_f32_e32 v0, 0xbfb8aa3b, v126
	v_exp_f32_e32 v116, v0
	v_mul_f32_e32 v0, 0xbfb8aa3b, v127
	v_exp_f32_e32 v117, v0
	s_nop 0
	v_pk_add_f32 v[116:117], v[116:117], 1.0 op_sel_hi:[1,0]
	s_nop 0
	v_div_scale_f32 v0, s[2:3], v117, v117, 1.0
	v_rcp_f32_e32 v118, v0
	s_nop 0
	v_fma_f32 v119, -v0, v118, 1.0
	v_fmac_f32_e32 v118, v119, v118
	v_div_scale_f32 v119, vcc, 1.0, v117, 1.0
	v_mul_f32_e32 v120, v119, v118
	v_fma_f32 v121, -v0, v120, v119
	v_fmac_f32_e32 v120, v121, v118
	v_fma_f32 v0, -v0, v120, v119
	v_div_fmas_f32 v0, v0, v118, v120
	v_div_fixup_f32 v0, v0, v117, 1.0
	v_div_scale_f32 v117, s[2:3], v116, v116, 1.0
	v_rcp_f32_e32 v118, v117
	s_nop 0
	v_fma_f32 v119, -v117, v118, 1.0
	v_fmac_f32_e32 v118, v119, v118
	v_div_scale_f32 v119, vcc, 1.0, v116, 1.0
	v_mul_f32_e32 v120, v119, v118
	v_fma_f32 v121, -v117, v120, v119
	v_fmac_f32_e32 v120, v121, v118
	v_fma_f32 v117, -v117, v120, v119
	v_div_fmas_f32 v117, v117, v118, v120
	v_div_fixup_f32 v116, v117, v116, 1.0
	v_cvt_pk_bf16_f32 v116, v116, v0
	v_mul_f32_e32 v0, 0xbfb8aa3b, v128
	v_exp_f32_e32 v118, v0
	v_mul_f32_e32 v0, 0xbfb8aa3b, v129
	v_exp_f32_e32 v119, v0
	s_nop 0
	v_pk_add_f32 v[118:119], v[118:119], 1.0 op_sel_hi:[1,0]
	s_nop 0
	v_div_scale_f32 v0, s[2:3], v119, v119, 1.0
	v_rcp_f32_e32 v117, v0
	s_nop 0
	v_fma_f32 v120, -v0, v117, 1.0
	v_fmac_f32_e32 v117, v120, v117
	v_div_scale_f32 v120, vcc, 1.0, v119, 1.0
	v_mul_f32_e32 v121, v120, v117
	v_fma_f32 v122, -v0, v121, v120
	v_fmac_f32_e32 v121, v122, v117
	v_fma_f32 v0, -v0, v121, v120
	v_div_fmas_f32 v0, v0, v117, v121
	v_div_scale_f32 v117, s[2:3], v118, v118, 1.0
	v_div_fixup_f32 v0, v0, v119, 1.0
	v_rcp_f32_e32 v119, v117
	s_nop 0
	v_fma_f32 v120, -v117, v119, 1.0
	v_fmac_f32_e32 v119, v120, v119
	v_div_scale_f32 v120, vcc, 1.0, v118, 1.0
	v_mul_f32_e32 v121, v120, v119
	v_fma_f32 v122, -v117, v121, v120
	v_fmac_f32_e32 v121, v122, v119
	v_fma_f32 v117, -v117, v121, v120
	v_div_fmas_f32 v117, v117, v119, v121
	v_div_fixup_f32 v117, v117, v118, 1.0
	v_cvt_pk_bf16_f32 v117, v117, v0
	v_mul_f32_e32 v0, 0xbfb8aa3b, v98
	v_exp_f32_e32 v98, v0
	v_mul_f32_e32 v0, 0xbfb8aa3b, v99
	v_exp_f32_e32 v99, v0
	ds_write2_b64 v165, v[114:115], v[116:117] offset0:4 offset1:6
	v_pk_add_f32 v[98:99], v[98:99], 1.0 op_sel_hi:[1,0]
	s_nop 0
	v_div_scale_f32 v0, s[2:3], v99, v99, 1.0
	v_rcp_f32_e32 v114, v0
	s_nop 0
	v_fma_f32 v115, -v0, v114, 1.0
	v_fmac_f32_e32 v114, v115, v114
	v_div_scale_f32 v115, vcc, 1.0, v99, 1.0
	v_mul_f32_e32 v116, v115, v114
	v_fma_f32 v117, -v0, v116, v115
	v_fmac_f32_e32 v116, v117, v114
	v_fma_f32 v0, -v0, v116, v115
	v_div_fmas_f32 v0, v0, v114, v116
	v_div_fixup_f32 v0, v0, v99, 1.0
	v_div_scale_f32 v99, s[2:3], v98, v98, 1.0
	v_rcp_f32_e32 v114, v99
	s_nop 0
	v_fma_f32 v115, -v99, v114, 1.0
	v_fmac_f32_e32 v114, v115, v114
	v_div_scale_f32 v115, vcc, 1.0, v98, 1.0
	v_mul_f32_e32 v116, v115, v114
	v_fma_f32 v117, -v99, v116, v115
	v_fmac_f32_e32 v116, v117, v114
	v_fma_f32 v99, -v99, v116, v115
	v_div_fmas_f32 v99, v99, v114, v116
	v_div_fixup_f32 v98, v99, v98, 1.0
	v_cvt_pk_bf16_f32 v98, v98, v0
	v_mul_f32_e32 v0, 0xbfb8aa3b, v100
	v_exp_f32_e32 v100, v0
	v_mul_f32_e32 v0, 0xbfb8aa3b, v101
; DI unsigned pk2(float a, float b) { f32v2 v = {a, b}; return __builtin_bit_cast(unsigned, __builtin_convertvector(v, bf16v2)); }
; DI float sigmoidf_(float v) { return 1.f / (1.f + __expf(-v)); }
; #define SW_FOR_TOK(j) _Pragma("unroll") for (int j = 0; j < 4; j++)
; #define SW_FOR_FEAT(i, rq) _Pragma("unroll") for (int i = 0; i < 2; i++) _Pragma("unroll") for (int rq = 0; rq < 4; rq++)
; DI void ph_ple(const Params& P, int g, int layer, bf16_t* smem) {
;     ...
;     SW_FOR_TOK(j) { const int tl_ = wn * 128 + j * 32 + l32;
;       SW_FOR_FEAT(i, rq) { const int c_ = wm * 64 + i * 32 + 8 * rq + 4 * h;
;         *(uint2*)(smem + tl_ * EPLD + c_) = make_uint2(pk2(sigmoidf_(SWV(i, j, 4 * rq)), sigmoidf_(SWV(i, j, 4 * rq + 1))), pk2(sigmoidf_(SWV(i, j, 4 * rq + 2)), sigmoidf_(SWV(i, j, 4 * rq + 3)))); } }
	v_exp_f32_e32 v101, v0
	s_nop 0
	v_pk_add_f32 v[100:101], v[100:101], 1.0 op_sel_hi:[1,0]
	s_nop 0
	v_div_scale_f32 v0, s[2:3], v101, v101, 1.0
	v_rcp_f32_e32 v99, v0
	s_nop 0
	v_fma_f32 v114, -v0, v99, 1.0
	v_fmac_f32_e32 v99, v114, v99
	v_div_scale_f32 v114, vcc, 1.0, v101, 1.0
	v_mul_f32_e32 v115, v114, v99
	v_fma_f32 v116, -v0, v115, v114
	v_fmac_f32_e32 v115, v116, v99
	v_fma_f32 v0, -v0, v115, v114
	v_div_fmas_f32 v0, v0, v99, v115
	v_div_scale_f32 v99, s[2:3], v100, v100, 1.0
	v_div_fixup_f32 v0, v0, v101, 1.0
	v_rcp_f32_e32 v101, v99
	s_nop 0
	v_fma_f32 v114, -v99, v101, 1.0
	v_fmac_f32_e32 v101, v114, v101
	v_div_scale_f32 v114, vcc, 1.0, v100, 1.0
	v_mul_f32_e32 v115, v114, v101
	v_fma_f32 v116, -v99, v115, v114
	v_fmac_f32_e32 v115, v116, v101
	v_fma_f32 v99, -v99, v115, v114
	v_div_fmas_f32 v99, v99, v101, v115
	v_div_fixup_f32 v99, v99, v100, 1.0
	v_cvt_pk_bf16_f32 v99, v99, v0
	v_mul_f32_e32 v0, 0xbfb8aa3b, v102
	v_exp_f32_e32 v100, v0
	v_mul_f32_e32 v0, 0xbfb8aa3b, v103
	v_exp_f32_e32 v101, v0
	s_nop 0
	v_pk_add_f32 v[100:101], v[100:101], 1.0 op_sel_hi:[1,0]
	s_nop 0
	v_div_scale_f32 v0, s[2:3], v101, v101, 1.0
	v_rcp_f32_e32 v102, v0
	s_nop 0
	v_fma_f32 v103, -v0, v102, 1.0
	v_fmac_f32_e32 v102, v103, v102
	v_div_scale_f32 v103, vcc, 1.0, v101, 1.0
	v_mul_f32_e32 v114, v103, v102
	v_fma_f32 v115, -v0, v114, v103
	v_fmac_f32_e32 v114, v115, v102
	v_fma_f32 v0, -v0, v114, v103
	v_div_fmas_f32 v0, v0, v102, v114
	v_div_fixup_f32 v0, v0, v101, 1.0
	v_div_scale_f32 v101, s[2:3], v100, v100, 1.0
	v_rcp_f32_e32 v102, v101
	s_nop 0
	v_fma_f32 v103, -v101, v102, 1.0
	v_fmac_f32_e32 v102, v103, v102
	v_div_scale_f32 v103, vcc, 1.0, v100, 1.0
	v_mul_f32_e32 v114, v103, v102
	v_fma_f32 v115, -v101, v114, v103
	v_fmac_f32_e32 v114, v115, v102
	v_fma_f32 v101, -v101, v114, v103
	v_div_fmas_f32 v101, v101, v102, v114
	v_div_fixup_f32 v100, v101, v100, 1.0
	v_cvt_pk_bf16_f32 v100, v100, v0
	v_mul_f32_e32 v0, 0xbfb8aa3b, v104
	v_exp_f32_e32 v102, v0
	v_mul_f32_e32 v0, 0xbfb8aa3b, v105
	v_exp_f32_e32 v103, v0
	s_nop 0
	v_pk_add_f32 v[102:103], v[102:103], 1.0 op_sel_hi:[1,0]
	s_nop 0
	v_div_scale_f32 v0, s[2:3], v103, v103, 1.0
	v_rcp_f32_e32 v101, v0
	s_nop 0
	v_fma_f32 v104, -v0, v101, 1.0
	v_fmac_f32_e32 v101, v104, v101
	v_div_scale_f32 v104, vcc, 1.0, v103, 1.0
	v_mul_f32_e32 v105, v104, v101
	v_fma_f32 v114, -v0, v105, v104
	v_fmac_f32_e32 v105, v114, v101
	v_fma_f32 v0, -v0, v105, v104
	v_div_fmas_f32 v0, v0, v101, v105
	v_div_scale_f32 v101, s[2:3], v102, v102, 1.0
	v_div_fixup_f32 v0, v0, v103, 1.0
	v_rcp_f32_e32 v103, v101
	s_nop 0
	v_fma_f32 v104, -v101, v103, 1.0
	v_fmac_f32_e32 v103, v104, v103
	v_div_scale_f32 v104, vcc, 1.0, v102, 1.0
	v_mul_f32_e32 v105, v104, v103
	v_fma_f32 v114, -v101, v105, v104
	v_fmac_f32_e32 v105, v114, v103
	v_fma_f32 v101, -v101, v105, v104
	v_div_fmas_f32 v101, v101, v103, v105
	v_div_fixup_f32 v101, v101, v102, 1.0
	v_cvt_pk_bf16_f32 v101, v101, v0
	v_mul_f32_e32 v0, 0xbfb8aa3b, v106
	ds_write2_b64 v165, v[98:99], v[100:101] offset0:8 offset1:10
	v_exp_f32_e32 v98, v0
	v_mul_f32_e32 v0, 0xbfb8aa3b, v107
	v_exp_f32_e32 v99, v0
	s_nop 0
	v_pk_add_f32 v[98:99], v[98:99], 1.0 op_sel_hi:[1,0]
	s_nop 0
	v_div_scale_f32 v0, s[2:3], v99, v99, 1.0
	v_rcp_f32_e32 v100, v0
	s_nop 0
	v_fma_f32 v101, -v0, v100, 1.0
	v_fmac_f32_e32 v100, v101, v100
	v_div_scale_f32 v101, vcc, 1.0, v99, 1.0
	v_mul_f32_e32 v102, v101, v100
	v_fma_f32 v103, -v0, v102, v101
	v_fmac_f32_e32 v102, v103, v100
	v_fma_f32 v0, -v0, v102, v101
	v_div_fmas_f32 v0, v0, v100, v102
	v_div_fixup_f32 v0, v0, v99, 1.0
	v_div_scale_f32 v99, s[2:3], v98, v98, 1.0
	v_rcp_f32_e32 v100, v99
	s_nop 0
	v_fma_f32 v101, -v99, v100, 1.0
	v_fmac_f32_e32 v100, v101, v100
	v_div_scale_f32 v101, vcc, 1.0, v98, 1.0
	v_mul_f32_e32 v102, v101, v100
	v_fma_f32 v103, -v99, v102, v101
	v_fmac_f32_e32 v102, v103, v100
	v_fma_f32 v99, -v99, v102, v101
	v_div_fmas_f32 v99, v99, v100, v102
	v_div_fixup_f32 v98, v99, v98, 1.0
	v_cvt_pk_bf16_f32 v98, v98, v0
	v_mul_f32_e32 v0, 0xbfb8aa3b, v108
	v_exp_f32_e32 v100, v0
	v_mul_f32_e32 v0, 0xbfb8aa3b, v109
	v_exp_f32_e32 v101, v0
	s_nop 0
	v_pk_add_f32 v[100:101], v[100:101], 1.0 op_sel_hi:[1,0]
	s_nop 0
	v_div_scale_f32 v0, s[2:3], v101, v101, 1.0
	v_rcp_f32_e32 v99, v0
	s_nop 0
	v_fma_f32 v102, -v0, v99, 1.0
	v_fmac_f32_e32 v99, v102, v99
	v_div_scale_f32 v102, vcc, 1.0, v101, 1.0
	v_mul_f32_e32 v103, v102, v99
	v_fma_f32 v104, -v0, v103, v102
	v_fmac_f32_e32 v103, v104, v99
	v_fma_f32 v0, -v0, v103, v102
	v_div_fmas_f32 v0, v0, v99, v103
	v_div_scale_f32 v99, s[2:3], v100, v100, 1.0
	v_div_fixup_f32 v0, v0, v101, 1.0
	v_rcp_f32_e32 v101, v99
	s_nop 0
	v_fma_f32 v102, -v99, v101, 1.0
	v_fmac_f32_e32 v101, v102, v101
	v_div_scale_f32 v102, vcc, 1.0, v100, 1.0
	v_mul_f32_e32 v103, v102, v101
	v_fma_f32 v104, -v99, v103, v102
	v_fmac_f32_e32 v103, v104, v101
	v_fma_f32 v99, -v99, v103, v102
	v_div_fmas_f32 v99, v99, v101, v103
	v_div_fixup_f32 v99, v99, v100, 1.0
	v_cvt_pk_bf16_f32 v99, v99, v0
	v_mul_f32_e32 v0, 0xbfb8aa3b, v110
	v_exp_f32_e32 v100, v0
	v_mul_f32_e32 v0, 0xbfb8aa3b, v111
	v_exp_f32_e32 v101, v0
	s_nop 0
	v_pk_add_f32 v[100:101], v[100:101], 1.0 op_sel_hi:[1,0]
	s_nop 0
	v_div_scale_f32 v0, s[2:3], v101, v101, 1.0
	v_rcp_f32_e32 v102, v0
	s_nop 0
	v_fma_f32 v103, -v0, v102, 1.0
	v_fmac_f32_e32 v102, v103, v102
	v_div_scale_f32 v103, vcc, 1.0, v101, 1.0
	v_mul_f32_e32 v104, v103, v102
	v_fma_f32 v105, -v0, v104, v103
	v_fmac_f32_e32 v104, v105, v102
	v_fma_f32 v0, -v0, v104, v103
	v_div_fmas_f32 v0, v0, v102, v104
	v_div_fixup_f32 v0, v0, v101, 1.0
	v_div_scale_f32 v101, s[2:3], v100, v100, 1.0
; DI unsigned pk2(float a, float b) { f32v2 v = {a, b}; return __builtin_bit_cast(unsigned, __builtin_convertvector(v, bf16v2)); }
; DI float sigmoidf_(float v) { return 1.f / (1.f + __expf(-v)); }
; #define SW_FOR_TOK(j) _Pragma("unroll") for (int j = 0; j < 4; j++)
; #define SW_FOR_FEAT(i, rq) _Pragma("unroll") for (int i = 0; i < 2; i++) _Pragma("unroll") for (int rq = 0; rq < 4; rq++)
; DI void ph_ple(const Params& P, int g, int layer, bf16_t* smem) {
;     ...
;     SW_FOR_TOK(j) { const int tl_ = wn * 128 + j * 32 + l32;
;       SW_FOR_FEAT(i, rq) { const int c_ = wm * 64 + i * 32 + 8 * rq + 4 * h;
;         *(uint2*)(smem + tl_ * EPLD + c_) = make_uint2(pk2(sigmoidf_(SWV(i, j, 4 * rq)), sigmoidf_(SWV(i, j, 4 * rq + 1))), pk2(sigmoidf_(SWV(i, j, 4 * rq + 2)), sigmoidf_(SWV(i, j, 4 * rq + 3)))); } }
	v_rcp_f32_e32 v102, v101
	s_nop 0
	v_fma_f32 v103, -v101, v102, 1.0
	v_fmac_f32_e32 v102, v103, v102
	v_div_scale_f32 v103, vcc, 1.0, v100, 1.0
	v_mul_f32_e32 v104, v103, v102
	v_fma_f32 v105, -v101, v104, v103
	v_fmac_f32_e32 v104, v105, v102
	v_fma_f32 v101, -v101, v104, v103
	v_div_fmas_f32 v101, v101, v102, v104
	v_div_fixup_f32 v100, v101, v100, 1.0
	v_cvt_pk_bf16_f32 v100, v100, v0
	v_mul_f32_e32 v0, 0xbfb8aa3b, v112
	v_exp_f32_e32 v102, v0
	v_mul_f32_e32 v0, 0xbfb8aa3b, v113
	v_exp_f32_e32 v103, v0
	s_nop 0
	v_pk_add_f32 v[102:103], v[102:103], 1.0 op_sel_hi:[1,0]
	s_nop 0
	v_div_scale_f32 v0, s[2:3], v103, v103, 1.0
	v_rcp_f32_e32 v101, v0
	s_nop 0
	v_fma_f32 v104, -v0, v101, 1.0
	v_fmac_f32_e32 v101, v104, v101
	v_div_scale_f32 v104, vcc, 1.0, v103, 1.0
	v_mul_f32_e32 v105, v104, v101
	v_fma_f32 v106, -v0, v105, v104
	v_fmac_f32_e32 v105, v106, v101
	v_fma_f32 v0, -v0, v105, v104
	v_div_fmas_f32 v0, v0, v101, v105
	v_div_scale_f32 v101, s[2:3], v102, v102, 1.0
	v_div_fixup_f32 v0, v0, v103, 1.0
	v_rcp_f32_e32 v103, v101
	s_nop 0
	v_fma_f32 v104, -v101, v103, 1.0
	v_fmac_f32_e32 v103, v104, v103
	v_div_scale_f32 v104, vcc, 1.0, v102, 1.0
	v_mul_f32_e32 v105, v104, v103
	v_fma_f32 v106, -v101, v105, v104
	v_fmac_f32_e32 v105, v106, v103
	v_fma_f32 v101, -v101, v105, v104
	v_div_fmas_f32 v101, v101, v103, v105
	v_div_fixup_f32 v101, v101, v102, 1.0
	v_cvt_pk_bf16_f32 v101, v101, v0
	v_mul_f32_e32 v0, 0xbfb8aa3b, v82
	v_exp_f32_e32 v82, v0
	v_mul_f32_e32 v0, 0xbfb8aa3b, v83
	v_exp_f32_e32 v83, v0
	ds_write2_b64 v165, v[98:99], v[100:101] offset0:12 offset1:14
	v_pk_add_f32 v[82:83], v[82:83], 1.0 op_sel_hi:[1,0]
	s_nop 0
	v_div_scale_f32 v0, s[2:3], v83, v83, 1.0
	v_rcp_f32_e32 v98, v0
	s_nop 0
	v_fma_f32 v99, -v0, v98, 1.0
	v_fmac_f32_e32 v98, v99, v98
	v_div_scale_f32 v99, vcc, 1.0, v83, 1.0
	v_mul_f32_e32 v100, v99, v98
	v_fma_f32 v101, -v0, v100, v99
	v_fmac_f32_e32 v100, v101, v98
	v_fma_f32 v0, -v0, v100, v99
	v_div_fmas_f32 v0, v0, v98, v100
	v_div_fixup_f32 v0, v0, v83, 1.0
	v_div_scale_f32 v83, s[2:3], v82, v82, 1.0
	v_rcp_f32_e32 v98, v83
	s_nop 0
	v_fma_f32 v99, -v83, v98, 1.0
	v_fmac_f32_e32 v98, v99, v98
	v_div_scale_f32 v99, vcc, 1.0, v82, 1.0
	v_mul_f32_e32 v100, v99, v98
	v_fma_f32 v101, -v83, v100, v99
	v_fmac_f32_e32 v100, v101, v98
	v_fma_f32 v83, -v83, v100, v99
	v_div_fmas_f32 v83, v83, v98, v100
	v_div_fixup_f32 v82, v83, v82, 1.0
	v_cvt_pk_bf16_f32 v82, v82, v0
	v_mul_f32_e32 v0, 0xbfb8aa3b, v84
	v_exp_f32_e32 v84, v0
	v_mul_f32_e32 v0, 0xbfb8aa3b, v85
	v_exp_f32_e32 v85, v0
	s_nop 0
	v_pk_add_f32 v[84:85], v[84:85], 1.0 op_sel_hi:[1,0]
	s_nop 0
	v_div_scale_f32 v0, s[2:3], v85, v85, 1.0
	v_rcp_f32_e32 v83, v0
	s_nop 0
	v_fma_f32 v98, -v0, v83, 1.0
	v_fmac_f32_e32 v83, v98, v83
	v_div_scale_f32 v98, vcc, 1.0, v85, 1.0
	v_mul_f32_e32 v99, v98, v83
	v_fma_f32 v100, -v0, v99, v98
	v_fmac_f32_e32 v99, v100, v83
	v_fma_f32 v0, -v0, v99, v98
	v_div_fmas_f32 v0, v0, v83, v99
	v_div_scale_f32 v83, s[2:3], v84, v84, 1.0
	v_div_fixup_f32 v0, v0, v85, 1.0
	v_rcp_f32_e32 v85, v83
	s_nop 0
	v_fma_f32 v98, -v83, v85, 1.0
	v_fmac_f32_e32 v85, v98, v85
	v_div_scale_f32 v98, vcc, 1.0, v84, 1.0
	v_mul_f32_e32 v99, v98, v85
	v_fma_f32 v100, -v83, v99, v98
	v_fmac_f32_e32 v99, v100, v85
	v_fma_f32 v83, -v83, v99, v98
	v_div_fmas_f32 v83, v83, v85, v99
	v_div_fixup_f32 v83, v83, v84, 1.0
	v_cvt_pk_bf16_f32 v83, v83, v0
	v_mul_f32_e32 v0, 0xbfb8aa3b, v86
	v_exp_f32_e32 v84, v0
	v_mul_f32_e32 v0, 0xbfb8aa3b, v87
	v_exp_f32_e32 v85, v0
	s_nop 0
	v_pk_add_f32 v[84:85], v[84:85], 1.0 op_sel_hi:[1,0]
	s_nop 0
	v_div_scale_f32 v0, s[2:3], v85, v85, 1.0
	v_rcp_f32_e32 v86, v0
	s_nop 0
	v_fma_f32 v87, -v0, v86, 1.0
	v_fmac_f32_e32 v86, v87, v86
	v_div_scale_f32 v87, vcc, 1.0, v85, 1.0
	v_mul_f32_e32 v98, v87, v86
	v_fma_f32 v99, -v0, v98, v87
	v_fmac_f32_e32 v98, v99, v86
	v_fma_f32 v0, -v0, v98, v87
	v_div_fmas_f32 v0, v0, v86, v98
	v_div_fixup_f32 v0, v0, v85, 1.0
	v_div_scale_f32 v85, s[2:3], v84, v84, 1.0
	v_rcp_f32_e32 v86, v85
	s_nop 0
	v_fma_f32 v87, -v85, v86, 1.0
	v_fmac_f32_e32 v86, v87, v86
	v_div_scale_f32 v87, vcc, 1.0, v84, 1.0
	v_mul_f32_e32 v98, v87, v86
	v_fma_f32 v99, -v85, v98, v87
	v_fmac_f32_e32 v98, v99, v86
	v_fma_f32 v85, -v85, v98, v87
	v_div_fmas_f32 v85, v85, v86, v98
	v_div_fixup_f32 v84, v85, v84, 1.0
	v_cvt_pk_bf16_f32 v84, v84, v0
	v_mul_f32_e32 v0, 0xbfb8aa3b, v88
	v_exp_f32_e32 v86, v0
	v_mul_f32_e32 v0, 0xbfb8aa3b, v89
	v_exp_f32_e32 v87, v0
	s_nop 0
	v_pk_add_f32 v[86:87], v[86:87], 1.0 op_sel_hi:[1,0]
	s_nop 0
	v_div_scale_f32 v0, s[2:3], v87, v87, 1.0
	v_rcp_f32_e32 v85, v0
	s_nop 0
	v_fma_f32 v88, -v0, v85, 1.0
	v_fmac_f32_e32 v85, v88, v85
	v_div_scale_f32 v88, vcc, 1.0, v87, 1.0
	v_mul_f32_e32 v89, v88, v85
	v_fma_f32 v98, -v0, v89, v88
	v_fmac_f32_e32 v89, v98, v85
	v_fma_f32 v0, -v0, v89, v88
	v_div_fmas_f32 v0, v0, v85, v89
	v_div_scale_f32 v85, s[2:3], v86, v86, 1.0
	v_div_fixup_f32 v0, v0, v87, 1.0
	v_rcp_f32_e32 v87, v85
	s_nop 0
	v_fma_f32 v88, -v85, v87, 1.0
	v_fmac_f32_e32 v87, v88, v87
	v_div_scale_f32 v88, vcc, 1.0, v86, 1.0
	v_mul_f32_e32 v89, v88, v87
	v_fma_f32 v98, -v85, v89, v88
	v_fmac_f32_e32 v89, v98, v87
	v_fma_f32 v85, -v85, v89, v88
	v_div_fmas_f32 v85, v85, v87, v89
	v_div_fixup_f32 v85, v85, v86, 1.0
	v_cvt_pk_bf16_f32 v85, v85, v0
	v_mul_f32_e32 v0, 0xbfb8aa3b, v90
	ds_write2_b64 v191, v[82:83], v[84:85] offset0:64 offset1:66
	v_exp_f32_e32 v82, v0
	v_mul_f32_e32 v0, 0xbfb8aa3b, v91
	v_exp_f32_e32 v83, v0
	s_nop 0
	v_pk_add_f32 v[82:83], v[82:83], 1.0 op_sel_hi:[1,0]
	s_nop 0
	v_div_scale_f32 v0, s[2:3], v83, v83, 1.0
	v_rcp_f32_e32 v84, v0
	s_nop 0
	v_fma_f32 v85, -v0, v84, 1.0
; DI unsigned pk2(float a, float b) { f32v2 v = {a, b}; return __builtin_bit_cast(unsigned, __builtin_convertvector(v, bf16v2)); }
; DI float sigmoidf_(float v) { return 1.f / (1.f + __expf(-v)); }
; #define SW_FOR_TOK(j) _Pragma("unroll") for (int j = 0; j < 4; j++)
; #define SW_FOR_FEAT(i, rq) _Pragma("unroll") for (int i = 0; i < 2; i++) _Pragma("unroll") for (int rq = 0; rq < 4; rq++)
; DI void ph_ple(const Params& P, int g, int layer, bf16_t* smem) {
;     ...
;     SW_FOR_TOK(j) { const int tl_ = wn * 128 + j * 32 + l32;
;       SW_FOR_FEAT(i, rq) { const int c_ = wm * 64 + i * 32 + 8 * rq + 4 * h;
;         *(uint2*)(smem + tl_ * EPLD + c_) = make_uint2(pk2(sigmoidf_(SWV(i, j, 4 * rq)), sigmoidf_(SWV(i, j, 4 * rq + 1))), pk2(sigmoidf_(SWV(i, j, 4 * rq + 2)), sigmoidf_(SWV(i, j, 4 * rq + 3)))); } }
	v_fmac_f32_e32 v84, v85, v84
	v_div_scale_f32 v85, vcc, 1.0, v83, 1.0
	v_mul_f32_e32 v86, v85, v84
	v_fma_f32 v87, -v0, v86, v85
	v_fmac_f32_e32 v86, v87, v84
	v_fma_f32 v0, -v0, v86, v85
	v_div_fmas_f32 v0, v0, v84, v86
	v_div_fixup_f32 v0, v0, v83, 1.0
	v_div_scale_f32 v83, s[2:3], v82, v82, 1.0
	v_rcp_f32_e32 v84, v83
	s_nop 0
	v_fma_f32 v85, -v83, v84, 1.0
	v_fmac_f32_e32 v84, v85, v84
	v_div_scale_f32 v85, vcc, 1.0, v82, 1.0
	v_mul_f32_e32 v86, v85, v84
	v_fma_f32 v87, -v83, v86, v85
	v_fmac_f32_e32 v86, v87, v84
	v_fma_f32 v83, -v83, v86, v85
	v_div_fmas_f32 v83, v83, v84, v86
	v_div_fixup_f32 v82, v83, v82, 1.0
	v_cvt_pk_bf16_f32 v82, v82, v0
	v_mul_f32_e32 v0, 0xbfb8aa3b, v92
	v_exp_f32_e32 v84, v0
	v_mul_f32_e32 v0, 0xbfb8aa3b, v93
	v_exp_f32_e32 v85, v0
	s_nop 0
	v_pk_add_f32 v[84:85], v[84:85], 1.0 op_sel_hi:[1,0]
	s_nop 0
	v_div_scale_f32 v0, s[2:3], v85, v85, 1.0
	v_rcp_f32_e32 v83, v0
	s_nop 0
	v_fma_f32 v86, -v0, v83, 1.0
	v_fmac_f32_e32 v83, v86, v83
	v_div_scale_f32 v86, vcc, 1.0, v85, 1.0
	v_mul_f32_e32 v87, v86, v83
	v_fma_f32 v88, -v0, v87, v86
	v_fmac_f32_e32 v87, v88, v83
	v_fma_f32 v0, -v0, v87, v86
	v_div_fmas_f32 v0, v0, v83, v87
	v_div_scale_f32 v83, s[2:3], v84, v84, 1.0
	v_div_fixup_f32 v0, v0, v85, 1.0
	v_rcp_f32_e32 v85, v83
	s_nop 0
	v_fma_f32 v86, -v83, v85, 1.0
	v_fmac_f32_e32 v85, v86, v85
	v_div_scale_f32 v86, vcc, 1.0, v84, 1.0
	v_mul_f32_e32 v87, v86, v85
	v_fma_f32 v88, -v83, v87, v86
	v_fmac_f32_e32 v87, v88, v85
	v_fma_f32 v83, -v83, v87, v86
	v_div_fmas_f32 v83, v83, v85, v87
	v_div_fixup_f32 v83, v83, v84, 1.0
	v_cvt_pk_bf16_f32 v83, v83, v0
	v_mul_f32_e32 v0, 0xbfb8aa3b, v94
	v_exp_f32_e32 v84, v0
	v_mul_f32_e32 v0, 0xbfb8aa3b, v95
	v_exp_f32_e32 v85, v0
	s_nop 0
	v_pk_add_f32 v[84:85], v[84:85], 1.0 op_sel_hi:[1,0]
	s_nop 0
	v_div_scale_f32 v0, s[2:3], v85, v85, 1.0
	v_rcp_f32_e32 v86, v0
	s_nop 0
	v_fma_f32 v87, -v0, v86, 1.0
	v_fmac_f32_e32 v86, v87, v86
	v_div_scale_f32 v87, vcc, 1.0, v85, 1.0
	v_mul_f32_e32 v88, v87, v86
	v_fma_f32 v89, -v0, v88, v87
	v_fmac_f32_e32 v88, v89, v86
	v_fma_f32 v0, -v0, v88, v87
	v_div_fmas_f32 v0, v0, v86, v88
	v_div_fixup_f32 v0, v0, v85, 1.0
	v_div_scale_f32 v85, s[2:3], v84, v84, 1.0
	v_rcp_f32_e32 v86, v85
	s_nop 0
	v_fma_f32 v87, -v85, v86, 1.0
	v_fmac_f32_e32 v86, v87, v86
	v_div_scale_f32 v87, vcc, 1.0, v84, 1.0
	v_mul_f32_e32 v88, v87, v86
	v_fma_f32 v89, -v85, v88, v87
	v_fmac_f32_e32 v88, v89, v86
	v_fma_f32 v85, -v85, v88, v87
	v_div_fmas_f32 v85, v85, v86, v88
	v_div_fixup_f32 v84, v85, v84, 1.0
	v_cvt_pk_bf16_f32 v84, v84, v0
	v_mul_f32_e32 v0, 0xbfb8aa3b, v96
	v_exp_f32_e32 v86, v0
	v_mul_f32_e32 v0, 0xbfb8aa3b, v97
	v_exp_f32_e32 v87, v0
	s_nop 0
	v_pk_add_f32 v[86:87], v[86:87], 1.0 op_sel_hi:[1,0]
	s_nop 0
	v_div_scale_f32 v0, s[2:3], v87, v87, 1.0
	v_rcp_f32_e32 v85, v0
	s_nop 0
	v_fma_f32 v88, -v0, v85, 1.0
	v_fmac_f32_e32 v85, v88, v85
	v_div_scale_f32 v88, vcc, 1.0, v87, 1.0
	v_mul_f32_e32 v89, v88, v85
	v_fma_f32 v90, -v0, v89, v88
	v_fmac_f32_e32 v89, v90, v85
	v_fma_f32 v0, -v0, v89, v88
	v_div_fmas_f32 v0, v0, v85, v89
	v_div_scale_f32 v85, s[2:3], v86, v86, 1.0
	v_div_fixup_f32 v0, v0, v87, 1.0
	v_rcp_f32_e32 v87, v85
	s_nop 0
	v_fma_f32 v88, -v85, v87, 1.0
	v_fmac_f32_e32 v87, v88, v87
	v_div_scale_f32 v88, vcc, 1.0, v86, 1.0
	v_mul_f32_e32 v89, v88, v87
	v_fma_f32 v90, -v85, v89, v88
	v_fmac_f32_e32 v89, v90, v87
	v_fma_f32 v85, -v85, v89, v88
	v_div_fmas_f32 v85, v85, v87, v89
	v_div_fixup_f32 v85, v85, v86, 1.0
	v_cvt_pk_bf16_f32 v85, v85, v0
	v_mul_f32_e32 v0, 0xbfb8aa3b, v66
	v_exp_f32_e32 v66, v0
	v_mul_f32_e32 v0, 0xbfb8aa3b, v67
	v_exp_f32_e32 v67, v0
	ds_write2_b64 v191, v[82:83], v[84:85] offset0:68 offset1:70
	v_pk_add_f32 v[66:67], v[66:67], 1.0 op_sel_hi:[1,0]
	s_nop 0
	v_div_scale_f32 v0, s[2:3], v67, v67, 1.0
	v_rcp_f32_e32 v82, v0
	s_nop 0
	v_fma_f32 v83, -v0, v82, 1.0
	v_fmac_f32_e32 v82, v83, v82
	v_div_scale_f32 v83, vcc, 1.0, v67, 1.0
	v_mul_f32_e32 v84, v83, v82
	v_fma_f32 v85, -v0, v84, v83
	v_fmac_f32_e32 v84, v85, v82
	v_fma_f32 v0, -v0, v84, v83
	v_div_fmas_f32 v0, v0, v82, v84
	v_div_fixup_f32 v0, v0, v67, 1.0
	v_div_scale_f32 v67, s[2:3], v66, v66, 1.0
	v_rcp_f32_e32 v82, v67
	s_nop 0
	v_fma_f32 v83, -v67, v82, 1.0
	v_fmac_f32_e32 v82, v83, v82
	v_div_scale_f32 v83, vcc, 1.0, v66, 1.0
	v_mul_f32_e32 v84, v83, v82
	v_fma_f32 v85, -v67, v84, v83
	v_fmac_f32_e32 v84, v85, v82
	v_fma_f32 v67, -v67, v84, v83
	v_div_fmas_f32 v67, v67, v82, v84
	v_div_fixup_f32 v66, v67, v66, 1.0
	v_cvt_pk_bf16_f32 v66, v66, v0
	v_mul_f32_e32 v0, 0xbfb8aa3b, v68
	v_exp_f32_e32 v68, v0
	v_mul_f32_e32 v0, 0xbfb8aa3b, v69
	v_exp_f32_e32 v69, v0
	s_nop 0
	v_pk_add_f32 v[68:69], v[68:69], 1.0 op_sel_hi:[1,0]
	s_nop 0
	v_div_scale_f32 v0, s[2:3], v69, v69, 1.0
	v_rcp_f32_e32 v67, v0
	s_nop 0
	v_fma_f32 v82, -v0, v67, 1.0
	v_fmac_f32_e32 v67, v82, v67
	v_div_scale_f32 v82, vcc, 1.0, v69, 1.0
	v_mul_f32_e32 v83, v82, v67
	v_fma_f32 v84, -v0, v83, v82
	v_fmac_f32_e32 v83, v84, v67
	v_fma_f32 v0, -v0, v83, v82
	v_div_fmas_f32 v0, v0, v67, v83
	v_div_scale_f32 v67, s[2:3], v68, v68, 1.0
	v_div_fixup_f32 v0, v0, v69, 1.0
	v_rcp_f32_e32 v69, v67
	s_nop 0
	v_fma_f32 v82, -v67, v69, 1.0
	v_fmac_f32_e32 v69, v82, v69
	v_div_scale_f32 v82, vcc, 1.0, v68, 1.0
	v_mul_f32_e32 v83, v82, v69
	v_fma_f32 v84, -v67, v83, v82
	v_fmac_f32_e32 v83, v84, v69
	v_fma_f32 v67, -v67, v83, v82
	v_div_fmas_f32 v67, v67, v69, v83
	v_div_fixup_f32 v67, v67, v68, 1.0
	v_cvt_pk_bf16_f32 v67, v67, v0
	v_mul_f32_e32 v0, 0xbfb8aa3b, v70
	v_exp_f32_e32 v68, v0
	v_mul_f32_e32 v0, 0xbfb8aa3b, v71
	v_exp_f32_e32 v69, v0
	s_nop 0
	v_pk_add_f32 v[68:69], v[68:69], 1.0 op_sel_hi:[1,0]
; DI unsigned pk2(float a, float b) { f32v2 v = {a, b}; return __builtin_bit_cast(unsigned, __builtin_convertvector(v, bf16v2)); }
; DI float sigmoidf_(float v) { return 1.f / (1.f + __expf(-v)); }
; #define SW_FOR_TOK(j) _Pragma("unroll") for (int j = 0; j < 4; j++)
; #define SW_FOR_FEAT(i, rq) _Pragma("unroll") for (int i = 0; i < 2; i++) _Pragma("unroll") for (int rq = 0; rq < 4; rq++)
; DI void ph_ple(const Params& P, int g, int layer, bf16_t* smem) {
;     ...
;     SW_FOR_TOK(j) { const int tl_ = wn * 128 + j * 32 + l32;
;       SW_FOR_FEAT(i, rq) { const int c_ = wm * 64 + i * 32 + 8 * rq + 4 * h;
;         *(uint2*)(smem + tl_ * EPLD + c_) = make_uint2(pk2(sigmoidf_(SWV(i, j, 4 * rq)), sigmoidf_(SWV(i, j, 4 * rq + 1))), pk2(sigmoidf_(SWV(i, j, 4 * rq + 2)), sigmoidf_(SWV(i, j, 4 * rq + 3)))); } }
	s_nop 0
	v_div_scale_f32 v0, s[2:3], v69, v69, 1.0
	v_rcp_f32_e32 v70, v0
	s_nop 0
	v_fma_f32 v71, -v0, v70, 1.0
	v_fmac_f32_e32 v70, v71, v70
	v_div_scale_f32 v71, vcc, 1.0, v69, 1.0
	v_mul_f32_e32 v82, v71, v70
	v_fma_f32 v83, -v0, v82, v71
	v_fmac_f32_e32 v82, v83, v70
	v_fma_f32 v0, -v0, v82, v71
	v_div_fmas_f32 v0, v0, v70, v82
	v_div_fixup_f32 v0, v0, v69, 1.0
	v_div_scale_f32 v69, s[2:3], v68, v68, 1.0
	v_rcp_f32_e32 v70, v69
	s_nop 0
	v_fma_f32 v71, -v69, v70, 1.0
	v_fmac_f32_e32 v70, v71, v70
	v_div_scale_f32 v71, vcc, 1.0, v68, 1.0
	v_mul_f32_e32 v82, v71, v70
	v_fma_f32 v83, -v69, v82, v71
	v_fmac_f32_e32 v82, v83, v70
	v_fma_f32 v69, -v69, v82, v71
	v_div_fmas_f32 v69, v69, v70, v82
	v_div_fixup_f32 v68, v69, v68, 1.0
	v_cvt_pk_bf16_f32 v68, v68, v0
	v_mul_f32_e32 v0, 0xbfb8aa3b, v72
	v_exp_f32_e32 v70, v0
	v_mul_f32_e32 v0, 0xbfb8aa3b, v73
	v_exp_f32_e32 v71, v0
	s_nop 0
	v_pk_add_f32 v[70:71], v[70:71], 1.0 op_sel_hi:[1,0]
	s_nop 0
	v_div_scale_f32 v0, s[2:3], v71, v71, 1.0
	v_rcp_f32_e32 v69, v0
	s_nop 0
	v_fma_f32 v72, -v0, v69, 1.0
	v_fmac_f32_e32 v69, v72, v69
	v_div_scale_f32 v72, vcc, 1.0, v71, 1.0
	v_mul_f32_e32 v73, v72, v69
	v_fma_f32 v82, -v0, v73, v72
	v_fmac_f32_e32 v73, v82, v69
	v_fma_f32 v0, -v0, v73, v72
	v_div_fmas_f32 v0, v0, v69, v73
	v_div_scale_f32 v69, s[2:3], v70, v70, 1.0
	v_div_fixup_f32 v0, v0, v71, 1.0
	v_rcp_f32_e32 v71, v69
	s_nop 0
	v_fma_f32 v72, -v69, v71, 1.0
	v_fmac_f32_e32 v71, v72, v71
	v_div_scale_f32 v72, vcc, 1.0, v70, 1.0
	v_mul_f32_e32 v73, v72, v71
	v_fma_f32 v82, -v69, v73, v72
	v_fmac_f32_e32 v73, v82, v71
	v_fma_f32 v69, -v69, v73, v72
	v_div_fmas_f32 v69, v69, v71, v73
	v_div_fixup_f32 v69, v69, v70, 1.0
	v_cvt_pk_bf16_f32 v69, v69, v0
	v_mul_f32_e32 v0, 0xbfb8aa3b, v74
	ds_write2_b64 v191, v[66:67], v[68:69] offset0:72 offset1:74
	v_exp_f32_e32 v66, v0
	v_mul_f32_e32 v0, 0xbfb8aa3b, v75
	v_exp_f32_e32 v67, v0
	s_nop 0
	v_pk_add_f32 v[66:67], v[66:67], 1.0 op_sel_hi:[1,0]
	s_nop 0
	v_div_scale_f32 v0, s[2:3], v67, v67, 1.0
	v_rcp_f32_e32 v68, v0
	s_nop 0
	v_fma_f32 v69, -v0, v68, 1.0
	v_fmac_f32_e32 v68, v69, v68
	v_div_scale_f32 v69, vcc, 1.0, v67, 1.0
	v_mul_f32_e32 v70, v69, v68
	v_fma_f32 v71, -v0, v70, v69
	v_fmac_f32_e32 v70, v71, v68
	v_fma_f32 v0, -v0, v70, v69
	v_div_fmas_f32 v0, v0, v68, v70
	v_div_fixup_f32 v0, v0, v67, 1.0
	v_div_scale_f32 v67, s[2:3], v66, v66, 1.0
	v_rcp_f32_e32 v68, v67
	s_nop 0
	v_fma_f32 v69, -v67, v68, 1.0
	v_fmac_f32_e32 v68, v69, v68
	v_div_scale_f32 v69, vcc, 1.0, v66, 1.0
	v_mul_f32_e32 v70, v69, v68
	v_fma_f32 v71, -v67, v70, v69
	v_fmac_f32_e32 v70, v71, v68
	v_fma_f32 v67, -v67, v70, v69
	v_div_fmas_f32 v67, v67, v68, v70
	v_div_fixup_f32 v66, v67, v66, 1.0
	v_cvt_pk_bf16_f32 v66, v66, v0
	v_mul_f32_e32 v0, 0xbfb8aa3b, v76
	v_exp_f32_e32 v68, v0
	v_mul_f32_e32 v0, 0xbfb8aa3b, v77
	v_exp_f32_e32 v69, v0
	s_nop 0
	v_pk_add_f32 v[68:69], v[68:69], 1.0 op_sel_hi:[1,0]
	s_nop 0
	v_div_scale_f32 v0, s[2:3], v69, v69, 1.0
	v_rcp_f32_e32 v67, v0
	s_nop 0
	v_fma_f32 v70, -v0, v67, 1.0
	v_fmac_f32_e32 v67, v70, v67
	v_div_scale_f32 v70, vcc, 1.0, v69, 1.0
	v_mul_f32_e32 v71, v70, v67
	v_fma_f32 v72, -v0, v71, v70
	v_fmac_f32_e32 v71, v72, v67
	v_fma_f32 v0, -v0, v71, v70
	v_div_fmas_f32 v0, v0, v67, v71
	v_div_scale_f32 v67, s[2:3], v68, v68, 1.0
	v_div_fixup_f32 v0, v0, v69, 1.0
	v_rcp_f32_e32 v69, v67
	s_nop 0
	v_fma_f32 v70, -v67, v69, 1.0
	v_fmac_f32_e32 v69, v70, v69
	v_div_scale_f32 v70, vcc, 1.0, v68, 1.0
	v_mul_f32_e32 v71, v70, v69
	v_fma_f32 v72, -v67, v71, v70
	v_fmac_f32_e32 v71, v72, v69
	v_fma_f32 v67, -v67, v71, v70
	v_div_fmas_f32 v67, v67, v69, v71
	v_div_fixup_f32 v67, v67, v68, 1.0
	v_cvt_pk_bf16_f32 v67, v67, v0
	v_mul_f32_e32 v0, 0xbfb8aa3b, v78
	v_exp_f32_e32 v68, v0
	v_mul_f32_e32 v0, 0xbfb8aa3b, v79
	v_exp_f32_e32 v69, v0
	s_nop 0
	v_pk_add_f32 v[68:69], v[68:69], 1.0 op_sel_hi:[1,0]
	s_nop 0
	v_div_scale_f32 v0, s[2:3], v69, v69, 1.0
	v_rcp_f32_e32 v70, v0
	s_nop 0
	v_fma_f32 v71, -v0, v70, 1.0
	v_fmac_f32_e32 v70, v71, v70
	v_div_scale_f32 v71, vcc, 1.0, v69, 1.0
	v_mul_f32_e32 v72, v71, v70
	v_fma_f32 v73, -v0, v72, v71
	v_fmac_f32_e32 v72, v73, v70
	v_fma_f32 v0, -v0, v72, v71
	v_div_fmas_f32 v0, v0, v70, v72
	v_div_fixup_f32 v0, v0, v69, 1.0
	v_div_scale_f32 v69, s[2:3], v68, v68, 1.0
	v_rcp_f32_e32 v70, v69
	s_nop 0
	v_fma_f32 v71, -v69, v70, 1.0
	v_fmac_f32_e32 v70, v71, v70
	v_div_scale_f32 v71, vcc, 1.0, v68, 1.0
	v_mul_f32_e32 v72, v71, v70
	v_fma_f32 v73, -v69, v72, v71
	v_fmac_f32_e32 v72, v73, v70
	v_fma_f32 v69, -v69, v72, v71
	v_div_fmas_f32 v69, v69, v70, v72
	v_div_fixup_f32 v68, v69, v68, 1.0
	v_cvt_pk_bf16_f32 v68, v68, v0
	v_mul_f32_e32 v0, 0xbfb8aa3b, v80
	v_exp_f32_e32 v70, v0
	v_mul_f32_e32 v0, 0xbfb8aa3b, v81
	v_exp_f32_e32 v71, v0
	s_nop 0
	v_pk_add_f32 v[70:71], v[70:71], 1.0 op_sel_hi:[1,0]
	s_nop 0
	v_div_scale_f32 v0, s[2:3], v71, v71, 1.0
	v_rcp_f32_e32 v69, v0
	s_nop 0
	v_fma_f32 v72, -v0, v69, 1.0
	v_fmac_f32_e32 v69, v72, v69
	v_div_scale_f32 v72, vcc, 1.0, v71, 1.0
	v_mul_f32_e32 v73, v72, v69
	v_fma_f32 v74, -v0, v73, v72
	v_fmac_f32_e32 v73, v74, v69
	v_fma_f32 v0, -v0, v73, v72
	v_div_fmas_f32 v0, v0, v69, v73
	v_div_scale_f32 v69, s[2:3], v70, v70, 1.0
	v_div_fixup_f32 v0, v0, v71, 1.0
	v_rcp_f32_e32 v71, v69
	s_nop 0
	v_fma_f32 v72, -v69, v71, 1.0
	v_fmac_f32_e32 v71, v72, v71
	v_div_scale_f32 v72, vcc, 1.0, v70, 1.0
	v_mul_f32_e32 v73, v72, v71
	v_fma_f32 v74, -v69, v73, v72
	v_fmac_f32_e32 v73, v74, v71
	v_fma_f32 v69, -v69, v73, v72
	v_div_fmas_f32 v69, v69, v71, v73
	v_div_fixup_f32 v69, v69, v70, 1.0
	v_cvt_pk_bf16_f32 v69, v69, v0
	v_mul_f32_e32 v0, 0xbfb8aa3b, v50
; DI unsigned pk2(float a, float b) { f32v2 v = {a, b}; return __builtin_bit_cast(unsigned, __builtin_convertvector(v, bf16v2)); }
; DI float sigmoidf_(float v) { return 1.f / (1.f + __expf(-v)); }
; #define SW_FOR_TOK(j) _Pragma("unroll") for (int j = 0; j < 4; j++)
; #define SW_FOR_FEAT(i, rq) _Pragma("unroll") for (int i = 0; i < 2; i++) _Pragma("unroll") for (int rq = 0; rq < 4; rq++)
; DI void ph_ple(const Params& P, int g, int layer, bf16_t* smem) {
;     ...
;     SW_FOR_TOK(j) { const int tl_ = wn * 128 + j * 32 + l32;
;       SW_FOR_FEAT(i, rq) { const int c_ = wm * 64 + i * 32 + 8 * rq + 4 * h;
;         *(uint2*)(smem + tl_ * EPLD + c_) = make_uint2(pk2(sigmoidf_(SWV(i, j, 4 * rq)), sigmoidf_(SWV(i, j, 4 * rq + 1))), pk2(sigmoidf_(SWV(i, j, 4 * rq + 2)), sigmoidf_(SWV(i, j, 4 * rq + 3)))); } }
	v_exp_f32_e32 v50, v0
	v_mul_f32_e32 v0, 0xbfb8aa3b, v51
	v_exp_f32_e32 v51, v0
	ds_write2_b64 v191, v[66:67], v[68:69] offset0:76 offset1:78
	v_pk_add_f32 v[50:51], v[50:51], 1.0 op_sel_hi:[1,0]
	s_nop 0
	v_div_scale_f32 v0, s[2:3], v51, v51, 1.0
	v_rcp_f32_e32 v66, v0
	s_nop 0
	v_fma_f32 v67, -v0, v66, 1.0
	v_fmac_f32_e32 v66, v67, v66
	v_div_scale_f32 v67, vcc, 1.0, v51, 1.0
	v_mul_f32_e32 v68, v67, v66
	v_fma_f32 v69, -v0, v68, v67
	v_fmac_f32_e32 v68, v69, v66
	v_fma_f32 v0, -v0, v68, v67
	v_div_fmas_f32 v0, v0, v66, v68
	v_div_fixup_f32 v0, v0, v51, 1.0
	v_div_scale_f32 v51, s[2:3], v50, v50, 1.0
	v_rcp_f32_e32 v66, v51
	s_nop 0
	v_fma_f32 v67, -v51, v66, 1.0
	v_fmac_f32_e32 v66, v67, v66
	v_div_scale_f32 v67, vcc, 1.0, v50, 1.0
	v_mul_f32_e32 v68, v67, v66
	v_fma_f32 v69, -v51, v68, v67
	v_fmac_f32_e32 v68, v69, v66
	v_fma_f32 v51, -v51, v68, v67
	v_div_fmas_f32 v51, v51, v66, v68
	v_div_fixup_f32 v50, v51, v50, 1.0
	v_cvt_pk_bf16_f32 v50, v50, v0
	v_mul_f32_e32 v0, 0xbfb8aa3b, v52
	v_exp_f32_e32 v52, v0
	v_mul_f32_e32 v0, 0xbfb8aa3b, v53
	v_exp_f32_e32 v53, v0
	s_nop 0
	v_pk_add_f32 v[52:53], v[52:53], 1.0 op_sel_hi:[1,0]
	s_nop 0
	v_div_scale_f32 v0, s[2:3], v53, v53, 1.0
	v_rcp_f32_e32 v51, v0
	s_nop 0
	v_fma_f32 v66, -v0, v51, 1.0
	v_fmac_f32_e32 v51, v66, v51
	v_div_scale_f32 v66, vcc, 1.0, v53, 1.0
	v_mul_f32_e32 v67, v66, v51
	v_fma_f32 v68, -v0, v67, v66
	v_fmac_f32_e32 v67, v68, v51
	v_fma_f32 v0, -v0, v67, v66
	v_div_fmas_f32 v0, v0, v51, v67
	v_div_scale_f32 v51, s[2:3], v52, v52, 1.0
	v_div_fixup_f32 v0, v0, v53, 1.0
	v_rcp_f32_e32 v53, v51
	s_nop 0
	v_fma_f32 v66, -v51, v53, 1.0
	v_fmac_f32_e32 v53, v66, v53
	v_div_scale_f32 v66, vcc, 1.0, v52, 1.0
	v_mul_f32_e32 v67, v66, v53
	v_fma_f32 v68, -v51, v67, v66
	v_fmac_f32_e32 v67, v68, v53
	v_fma_f32 v51, -v51, v67, v66
	v_div_fmas_f32 v51, v51, v53, v67
	v_div_fixup_f32 v51, v51, v52, 1.0
	v_cvt_pk_bf16_f32 v51, v51, v0
	v_mul_f32_e32 v0, 0xbfb8aa3b, v54
	v_exp_f32_e32 v52, v0
	v_mul_f32_e32 v0, 0xbfb8aa3b, v55
	v_exp_f32_e32 v53, v0
	s_nop 0
	v_pk_add_f32 v[52:53], v[52:53], 1.0 op_sel_hi:[1,0]
	s_nop 0
	v_div_scale_f32 v0, s[2:3], v53, v53, 1.0
	v_rcp_f32_e32 v54, v0
	s_nop 0
	v_fma_f32 v55, -v0, v54, 1.0
	v_fmac_f32_e32 v54, v55, v54
	v_div_scale_f32 v55, vcc, 1.0, v53, 1.0
	v_mul_f32_e32 v66, v55, v54
	v_fma_f32 v67, -v0, v66, v55
	v_fmac_f32_e32 v66, v67, v54
	v_fma_f32 v0, -v0, v66, v55
	v_div_fmas_f32 v0, v0, v54, v66
	v_div_fixup_f32 v0, v0, v53, 1.0
	v_div_scale_f32 v53, s[2:3], v52, v52, 1.0
	v_rcp_f32_e32 v54, v53
	s_nop 0
	v_fma_f32 v55, -v53, v54, 1.0
	v_fmac_f32_e32 v54, v55, v54
	v_div_scale_f32 v55, vcc, 1.0, v52, 1.0
	v_mul_f32_e32 v66, v55, v54
	v_fma_f32 v67, -v53, v66, v55
	v_fmac_f32_e32 v66, v67, v54
	v_fma_f32 v53, -v53, v66, v55
	v_div_fmas_f32 v53, v53, v54, v66
	v_div_fixup_f32 v52, v53, v52, 1.0
	v_cvt_pk_bf16_f32 v52, v52, v0
	v_mul_f32_e32 v0, 0xbfb8aa3b, v56
	v_exp_f32_e32 v54, v0
	v_mul_f32_e32 v0, 0xbfb8aa3b, v57
	v_exp_f32_e32 v55, v0
	s_nop 0
	v_pk_add_f32 v[54:55], v[54:55], 1.0 op_sel_hi:[1,0]
	s_nop 0
	v_div_scale_f32 v0, s[2:3], v55, v55, 1.0
	v_rcp_f32_e32 v53, v0
	s_nop 0
	v_fma_f32 v56, -v0, v53, 1.0
	v_fmac_f32_e32 v53, v56, v53
	v_div_scale_f32 v56, vcc, 1.0, v55, 1.0
	v_mul_f32_e32 v57, v56, v53
	v_fma_f32 v66, -v0, v57, v56
	v_fmac_f32_e32 v57, v66, v53
	v_fma_f32 v0, -v0, v57, v56
	v_div_fmas_f32 v0, v0, v53, v57
	v_div_scale_f32 v53, s[2:3], v54, v54, 1.0
	v_div_fixup_f32 v0, v0, v55, 1.0
	v_rcp_f32_e32 v55, v53
	s_nop 0
	v_fma_f32 v56, -v53, v55, 1.0
	v_fmac_f32_e32 v55, v56, v55
	v_div_scale_f32 v56, vcc, 1.0, v54, 1.0
	v_mul_f32_e32 v57, v56, v55
	v_fma_f32 v66, -v53, v57, v56
	v_fmac_f32_e32 v57, v66, v55
	v_fma_f32 v53, -v53, v57, v56
	v_div_fmas_f32 v53, v53, v55, v57
	v_div_fixup_f32 v53, v53, v54, 1.0
	v_cvt_pk_bf16_f32 v53, v53, v0
	v_mul_f32_e32 v0, 0xbfb8aa3b, v58
	ds_write2_b64 v190, v[50:51], v[52:53] offset0:128 offset1:130
	v_exp_f32_e32 v50, v0
	v_mul_f32_e32 v0, 0xbfb8aa3b, v59
	v_exp_f32_e32 v51, v0
	s_nop 0
	v_pk_add_f32 v[50:51], v[50:51], 1.0 op_sel_hi:[1,0]
	s_nop 0
	v_div_scale_f32 v0, s[2:3], v51, v51, 1.0
	v_rcp_f32_e32 v52, v0
	s_nop 0
	v_fma_f32 v53, -v0, v52, 1.0
	v_fmac_f32_e32 v52, v53, v52
	v_div_scale_f32 v53, vcc, 1.0, v51, 1.0
	v_mul_f32_e32 v54, v53, v52
	v_fma_f32 v55, -v0, v54, v53
	v_fmac_f32_e32 v54, v55, v52
	v_fma_f32 v0, -v0, v54, v53
	v_div_fmas_f32 v0, v0, v52, v54
	v_div_fixup_f32 v0, v0, v51, 1.0
	v_div_scale_f32 v51, s[2:3], v50, v50, 1.0
	v_rcp_f32_e32 v52, v51
	s_nop 0
	v_fma_f32 v53, -v51, v52, 1.0
	v_fmac_f32_e32 v52, v53, v52
	v_div_scale_f32 v53, vcc, 1.0, v50, 1.0
	v_mul_f32_e32 v54, v53, v52
	v_fma_f32 v55, -v51, v54, v53
	v_fmac_f32_e32 v54, v55, v52
	v_fma_f32 v51, -v51, v54, v53
	v_div_fmas_f32 v51, v51, v52, v54
	v_div_fixup_f32 v50, v51, v50, 1.0
	v_cvt_pk_bf16_f32 v50, v50, v0
	v_mul_f32_e32 v0, 0xbfb8aa3b, v60
	v_exp_f32_e32 v52, v0
	v_mul_f32_e32 v0, 0xbfb8aa3b, v61
	v_exp_f32_e32 v53, v0
	s_nop 0
	v_pk_add_f32 v[52:53], v[52:53], 1.0 op_sel_hi:[1,0]
	s_nop 0
	v_div_scale_f32 v0, s[2:3], v53, v53, 1.0
	v_rcp_f32_e32 v51, v0
	s_nop 0
	v_fma_f32 v54, -v0, v51, 1.0
	v_fmac_f32_e32 v51, v54, v51
	v_div_scale_f32 v54, vcc, 1.0, v53, 1.0
	v_mul_f32_e32 v55, v54, v51
	v_fma_f32 v56, -v0, v55, v54
	v_fmac_f32_e32 v55, v56, v51
	v_fma_f32 v0, -v0, v55, v54
	v_div_fmas_f32 v0, v0, v51, v55
	v_div_scale_f32 v51, s[2:3], v52, v52, 1.0
	v_div_fixup_f32 v0, v0, v53, 1.0
	v_rcp_f32_e32 v53, v51
	s_nop 0
	v_fma_f32 v54, -v51, v53, 1.0
	v_fmac_f32_e32 v53, v54, v53
	v_div_scale_f32 v54, vcc, 1.0, v52, 1.0
	v_mul_f32_e32 v55, v54, v53
	v_fma_f32 v56, -v51, v55, v54
; DI unsigned pk2(float a, float b) { f32v2 v = {a, b}; return __builtin_bit_cast(unsigned, __builtin_convertvector(v, bf16v2)); }
; DI float sigmoidf_(float v) { return 1.f / (1.f + __expf(-v)); }
; #define SW_FOR_TOK(j) _Pragma("unroll") for (int j = 0; j < 4; j++)
; #define SW_FOR_FEAT(i, rq) _Pragma("unroll") for (int i = 0; i < 2; i++) _Pragma("unroll") for (int rq = 0; rq < 4; rq++)
; DI void ph_ple(const Params& P, int g, int layer, bf16_t* smem) {
;     ...
;     SW_FOR_TOK(j) { const int tl_ = wn * 128 + j * 32 + l32;
;       SW_FOR_FEAT(i, rq) { const int c_ = wm * 64 + i * 32 + 8 * rq + 4 * h;
;         *(uint2*)(smem + tl_ * EPLD + c_) = make_uint2(pk2(sigmoidf_(SWV(i, j, 4 * rq)), sigmoidf_(SWV(i, j, 4 * rq + 1))), pk2(sigmoidf_(SWV(i, j, 4 * rq + 2)), sigmoidf_(SWV(i, j, 4 * rq + 3)))); } }
	v_fmac_f32_e32 v55, v56, v53
	v_fma_f32 v51, -v51, v55, v54
	v_div_fmas_f32 v51, v51, v53, v55
	v_div_fixup_f32 v51, v51, v52, 1.0
	v_cvt_pk_bf16_f32 v51, v51, v0
	v_mul_f32_e32 v0, 0xbfb8aa3b, v62
	v_exp_f32_e32 v52, v0
	v_mul_f32_e32 v0, 0xbfb8aa3b, v63
	v_exp_f32_e32 v53, v0
	s_nop 0
	v_pk_add_f32 v[52:53], v[52:53], 1.0 op_sel_hi:[1,0]
	s_nop 0
	v_div_scale_f32 v0, s[2:3], v53, v53, 1.0
	v_rcp_f32_e32 v54, v0
	s_nop 0
	v_fma_f32 v55, -v0, v54, 1.0
	v_fmac_f32_e32 v54, v55, v54
	v_div_scale_f32 v55, vcc, 1.0, v53, 1.0
	v_mul_f32_e32 v56, v55, v54
	v_fma_f32 v57, -v0, v56, v55
	v_fmac_f32_e32 v56, v57, v54
	v_fma_f32 v0, -v0, v56, v55
	v_div_fmas_f32 v0, v0, v54, v56
	v_div_fixup_f32 v0, v0, v53, 1.0
	v_div_scale_f32 v53, s[2:3], v52, v52, 1.0
	v_rcp_f32_e32 v54, v53
	s_nop 0
	v_fma_f32 v55, -v53, v54, 1.0
	v_fmac_f32_e32 v54, v55, v54
	v_div_scale_f32 v55, vcc, 1.0, v52, 1.0
	v_mul_f32_e32 v56, v55, v54
	v_fma_f32 v57, -v53, v56, v55
	v_fmac_f32_e32 v56, v57, v54
	v_fma_f32 v53, -v53, v56, v55
	v_div_fmas_f32 v53, v53, v54, v56
	v_div_fixup_f32 v52, v53, v52, 1.0
	v_cvt_pk_bf16_f32 v52, v52, v0
	v_mul_f32_e32 v0, 0xbfb8aa3b, v64
	v_exp_f32_e32 v54, v0
	v_mul_f32_e32 v0, 0xbfb8aa3b, v65
	v_exp_f32_e32 v55, v0
	s_nop 0
	v_pk_add_f32 v[54:55], v[54:55], 1.0 op_sel_hi:[1,0]
	s_nop 0
	v_div_scale_f32 v0, s[2:3], v55, v55, 1.0
	v_rcp_f32_e32 v53, v0
	s_nop 0
	v_fma_f32 v56, -v0, v53, 1.0
	v_fmac_f32_e32 v53, v56, v53
	v_div_scale_f32 v56, vcc, 1.0, v55, 1.0
	v_mul_f32_e32 v57, v56, v53
	v_fma_f32 v58, -v0, v57, v56
	v_fmac_f32_e32 v57, v58, v53
	v_fma_f32 v0, -v0, v57, v56
	v_div_fmas_f32 v0, v0, v53, v57
	v_div_scale_f32 v53, s[2:3], v54, v54, 1.0
	v_div_fixup_f32 v0, v0, v55, 1.0
	v_rcp_f32_e32 v55, v53
	s_nop 0
	v_fma_f32 v56, -v53, v55, 1.0
	v_fmac_f32_e32 v55, v56, v55
	v_div_scale_f32 v56, vcc, 1.0, v54, 1.0
	v_mul_f32_e32 v57, v56, v55
	v_fma_f32 v58, -v53, v57, v56
	v_fmac_f32_e32 v57, v58, v55
	v_fma_f32 v53, -v53, v57, v56
	v_div_fmas_f32 v53, v53, v55, v57
	v_div_fixup_f32 v53, v53, v54, 1.0
	v_cvt_pk_bf16_f32 v53, v53, v0
	v_mul_f32_e32 v0, 0xbfb8aa3b, v34
	v_exp_f32_e32 v34, v0
	v_mul_f32_e32 v0, 0xbfb8aa3b, v35
	v_exp_f32_e32 v35, v0
	ds_write2_b64 v190, v[50:51], v[52:53] offset0:132 offset1:134
	v_pk_add_f32 v[34:35], v[34:35], 1.0 op_sel_hi:[1,0]
	s_nop 0
	v_div_scale_f32 v0, s[2:3], v35, v35, 1.0
	v_rcp_f32_e32 v50, v0
	s_nop 0
	v_fma_f32 v51, -v0, v50, 1.0
	v_fmac_f32_e32 v50, v51, v50
	v_div_scale_f32 v51, vcc, 1.0, v35, 1.0
	v_mul_f32_e32 v52, v51, v50
	v_fma_f32 v53, -v0, v52, v51
	v_fmac_f32_e32 v52, v53, v50
	v_fma_f32 v0, -v0, v52, v51
	v_div_fmas_f32 v0, v0, v50, v52
	v_div_fixup_f32 v0, v0, v35, 1.0
	v_div_scale_f32 v35, s[2:3], v34, v34, 1.0
	v_rcp_f32_e32 v50, v35
	s_nop 0
	v_fma_f32 v51, -v35, v50, 1.0
	v_fmac_f32_e32 v50, v51, v50
	v_div_scale_f32 v51, vcc, 1.0, v34, 1.0
	v_mul_f32_e32 v52, v51, v50
	v_fma_f32 v53, -v35, v52, v51
	v_fmac_f32_e32 v52, v53, v50
	v_fma_f32 v35, -v35, v52, v51
	v_div_fmas_f32 v35, v35, v50, v52
	v_div_fixup_f32 v34, v35, v34, 1.0
	v_cvt_pk_bf16_f32 v34, v34, v0
	v_mul_f32_e32 v0, 0xbfb8aa3b, v36
	v_exp_f32_e32 v36, v0
	v_mul_f32_e32 v0, 0xbfb8aa3b, v37
	v_exp_f32_e32 v37, v0
	s_nop 0
	v_pk_add_f32 v[36:37], v[36:37], 1.0 op_sel_hi:[1,0]
	s_nop 0
	v_div_scale_f32 v0, s[2:3], v37, v37, 1.0
	v_rcp_f32_e32 v35, v0
	s_nop 0
	v_fma_f32 v50, -v0, v35, 1.0
	v_fmac_f32_e32 v35, v50, v35
	v_div_scale_f32 v50, vcc, 1.0, v37, 1.0
	v_mul_f32_e32 v51, v50, v35
	v_fma_f32 v52, -v0, v51, v50
	v_fmac_f32_e32 v51, v52, v35
	v_fma_f32 v0, -v0, v51, v50
	v_div_fmas_f32 v0, v0, v35, v51
	v_div_scale_f32 v35, s[2:3], v36, v36, 1.0
	v_div_fixup_f32 v0, v0, v37, 1.0
	v_rcp_f32_e32 v37, v35
	s_nop 0
	v_fma_f32 v50, -v35, v37, 1.0
	v_fmac_f32_e32 v37, v50, v37
	v_div_scale_f32 v50, vcc, 1.0, v36, 1.0
	v_mul_f32_e32 v51, v50, v37
	v_fma_f32 v52, -v35, v51, v50
	v_fmac_f32_e32 v51, v52, v37
	v_fma_f32 v35, -v35, v51, v50
	v_div_fmas_f32 v35, v35, v37, v51
	v_div_fixup_f32 v35, v35, v36, 1.0
	v_cvt_pk_bf16_f32 v35, v35, v0
	v_mul_f32_e32 v0, 0xbfb8aa3b, v38
	v_exp_f32_e32 v36, v0
	v_mul_f32_e32 v0, 0xbfb8aa3b, v39
	v_exp_f32_e32 v37, v0
	s_nop 0
	v_pk_add_f32 v[36:37], v[36:37], 1.0 op_sel_hi:[1,0]
	s_nop 0
	v_div_scale_f32 v0, s[2:3], v37, v37, 1.0
	v_rcp_f32_e32 v38, v0
	s_nop 0
	v_fma_f32 v39, -v0, v38, 1.0
	v_fmac_f32_e32 v38, v39, v38
	v_div_scale_f32 v39, vcc, 1.0, v37, 1.0
	v_mul_f32_e32 v50, v39, v38
	v_fma_f32 v51, -v0, v50, v39
	v_fmac_f32_e32 v50, v51, v38
	v_fma_f32 v0, -v0, v50, v39
	v_div_fmas_f32 v0, v0, v38, v50
	v_div_fixup_f32 v0, v0, v37, 1.0
	v_div_scale_f32 v37, s[2:3], v36, v36, 1.0
	v_rcp_f32_e32 v38, v37
	s_nop 0
	v_fma_f32 v39, -v37, v38, 1.0
	v_fmac_f32_e32 v38, v39, v38
	v_div_scale_f32 v39, vcc, 1.0, v36, 1.0
	v_mul_f32_e32 v50, v39, v38
	v_fma_f32 v51, -v37, v50, v39
	v_fmac_f32_e32 v50, v51, v38
	v_fma_f32 v37, -v37, v50, v39
	v_div_fmas_f32 v37, v37, v38, v50
	v_div_fixup_f32 v36, v37, v36, 1.0
	v_cvt_pk_bf16_f32 v36, v36, v0
	v_mul_f32_e32 v0, 0xbfb8aa3b, v40
	v_exp_f32_e32 v38, v0
	v_mul_f32_e32 v0, 0xbfb8aa3b, v41
	v_exp_f32_e32 v39, v0
	s_nop 0
	v_pk_add_f32 v[38:39], v[38:39], 1.0 op_sel_hi:[1,0]
	s_nop 0
	v_div_scale_f32 v0, s[2:3], v39, v39, 1.0
	v_rcp_f32_e32 v37, v0
	s_nop 0
	v_fma_f32 v40, -v0, v37, 1.0
	v_fmac_f32_e32 v37, v40, v37
	v_div_scale_f32 v40, vcc, 1.0, v39, 1.0
	v_mul_f32_e32 v41, v40, v37
	v_fma_f32 v50, -v0, v41, v40
	v_fmac_f32_e32 v41, v50, v37
	v_fma_f32 v0, -v0, v41, v40
	v_div_fmas_f32 v0, v0, v37, v41
	v_div_scale_f32 v37, s[2:3], v38, v38, 1.0
	v_div_fixup_f32 v0, v0, v39, 1.0
	v_rcp_f32_e32 v39, v37
	s_nop 0
	v_fma_f32 v40, -v37, v39, 1.0
; DI unsigned pk2(float a, float b) { f32v2 v = {a, b}; return __builtin_bit_cast(unsigned, __builtin_convertvector(v, bf16v2)); }
; DI float sigmoidf_(float v) { return 1.f / (1.f + __expf(-v)); }
; #define SW_FOR_TOK(j) _Pragma("unroll") for (int j = 0; j < 4; j++)
; #define SW_FOR_FEAT(i, rq) _Pragma("unroll") for (int i = 0; i < 2; i++) _Pragma("unroll") for (int rq = 0; rq < 4; rq++)
; DI void ph_ple(const Params& P, int g, int layer, bf16_t* smem) {
;     ...
;     SW_FOR_TOK(j) { const int tl_ = wn * 128 + j * 32 + l32;
;       SW_FOR_FEAT(i, rq) { const int c_ = wm * 64 + i * 32 + 8 * rq + 4 * h;
;         *(uint2*)(smem + tl_ * EPLD + c_) = make_uint2(pk2(sigmoidf_(SWV(i, j, 4 * rq)), sigmoidf_(SWV(i, j, 4 * rq + 1))), pk2(sigmoidf_(SWV(i, j, 4 * rq + 2)), sigmoidf_(SWV(i, j, 4 * rq + 3)))); } }
	v_fmac_f32_e32 v39, v40, v39
	v_div_scale_f32 v40, vcc, 1.0, v38, 1.0
	v_mul_f32_e32 v41, v40, v39
	v_fma_f32 v50, -v37, v41, v40
	v_fmac_f32_e32 v41, v50, v39
	v_fma_f32 v37, -v37, v41, v40
	v_div_fmas_f32 v37, v37, v39, v41
	v_div_fixup_f32 v37, v37, v38, 1.0
	v_cvt_pk_bf16_f32 v37, v37, v0
	v_mul_f32_e32 v0, 0xbfb8aa3b, v42
	ds_write2_b64 v190, v[34:35], v[36:37] offset0:136 offset1:138
	v_exp_f32_e32 v34, v0
	v_mul_f32_e32 v0, 0xbfb8aa3b, v43
	v_exp_f32_e32 v35, v0
	s_nop 0
	v_pk_add_f32 v[34:35], v[34:35], 1.0 op_sel_hi:[1,0]
	s_nop 0
	v_div_scale_f32 v0, s[2:3], v35, v35, 1.0
	v_rcp_f32_e32 v36, v0
	s_nop 0
	v_fma_f32 v37, -v0, v36, 1.0
	v_fmac_f32_e32 v36, v37, v36
	v_div_scale_f32 v37, vcc, 1.0, v35, 1.0
	v_mul_f32_e32 v38, v37, v36
	v_fma_f32 v39, -v0, v38, v37
	v_fmac_f32_e32 v38, v39, v36
	v_fma_f32 v0, -v0, v38, v37
	v_div_fmas_f32 v0, v0, v36, v38
	v_div_fixup_f32 v0, v0, v35, 1.0
	v_div_scale_f32 v35, s[2:3], v34, v34, 1.0
	v_rcp_f32_e32 v36, v35
	s_nop 0
	v_fma_f32 v37, -v35, v36, 1.0
	v_fmac_f32_e32 v36, v37, v36
	v_div_scale_f32 v37, vcc, 1.0, v34, 1.0
	v_mul_f32_e32 v38, v37, v36
	v_fma_f32 v39, -v35, v38, v37
	v_fmac_f32_e32 v38, v39, v36
	v_fma_f32 v35, -v35, v38, v37
	v_div_fmas_f32 v35, v35, v36, v38
	v_div_fixup_f32 v34, v35, v34, 1.0
	v_cvt_pk_bf16_f32 v34, v34, v0
	v_mul_f32_e32 v0, 0xbfb8aa3b, v44
	v_exp_f32_e32 v36, v0
	v_mul_f32_e32 v0, 0xbfb8aa3b, v45
	v_exp_f32_e32 v37, v0
	s_nop 0
	v_pk_add_f32 v[36:37], v[36:37], 1.0 op_sel_hi:[1,0]
	s_nop 0
	v_div_scale_f32 v0, s[2:3], v37, v37, 1.0
	v_rcp_f32_e32 v35, v0
	s_nop 0
	v_fma_f32 v38, -v0, v35, 1.0
	v_fmac_f32_e32 v35, v38, v35
	v_div_scale_f32 v38, vcc, 1.0, v37, 1.0
	v_mul_f32_e32 v39, v38, v35
	v_fma_f32 v40, -v0, v39, v38
	v_fmac_f32_e32 v39, v40, v35
	v_fma_f32 v0, -v0, v39, v38
	v_div_fmas_f32 v0, v0, v35, v39
	v_div_scale_f32 v35, s[2:3], v36, v36, 1.0
	v_div_fixup_f32 v0, v0, v37, 1.0
	v_rcp_f32_e32 v37, v35
	s_nop 0
	v_fma_f32 v38, -v35, v37, 1.0
	v_fmac_f32_e32 v37, v38, v37
	v_div_scale_f32 v38, vcc, 1.0, v36, 1.0
	v_mul_f32_e32 v39, v38, v37
	v_fma_f32 v40, -v35, v39, v38
	v_fmac_f32_e32 v39, v40, v37
	v_fma_f32 v35, -v35, v39, v38
	v_div_fmas_f32 v35, v35, v37, v39
	v_div_fixup_f32 v35, v35, v36, 1.0
	v_cvt_pk_bf16_f32 v35, v35, v0
	v_mul_f32_e32 v0, 0xbfb8aa3b, v46
	v_exp_f32_e32 v36, v0
	v_mul_f32_e32 v0, 0xbfb8aa3b, v47
	v_exp_f32_e32 v37, v0
	s_nop 0
	v_pk_add_f32 v[36:37], v[36:37], 1.0 op_sel_hi:[1,0]
	s_nop 0
	v_div_scale_f32 v0, s[2:3], v37, v37, 1.0
	v_rcp_f32_e32 v38, v0
	s_nop 0
	v_fma_f32 v39, -v0, v38, 1.0
	v_fmac_f32_e32 v38, v39, v38
	v_div_scale_f32 v39, vcc, 1.0, v37, 1.0
	v_mul_f32_e32 v40, v39, v38
	v_fma_f32 v41, -v0, v40, v39
	v_fmac_f32_e32 v40, v41, v38
	v_fma_f32 v0, -v0, v40, v39
	v_div_fmas_f32 v0, v0, v38, v40
	v_div_fixup_f32 v0, v0, v37, 1.0
	v_div_scale_f32 v37, s[2:3], v36, v36, 1.0
	v_rcp_f32_e32 v38, v37
	s_nop 0
	v_fma_f32 v39, -v37, v38, 1.0
	v_fmac_f32_e32 v38, v39, v38
	v_div_scale_f32 v39, vcc, 1.0, v36, 1.0
	v_mul_f32_e32 v40, v39, v38
	v_fma_f32 v41, -v37, v40, v39
	v_fmac_f32_e32 v40, v41, v38
	v_fma_f32 v37, -v37, v40, v39
	v_div_fmas_f32 v37, v37, v38, v40
	v_div_fixup_f32 v36, v37, v36, 1.0
	v_cvt_pk_bf16_f32 v36, v36, v0
	v_mul_f32_e32 v0, 0xbfb8aa3b, v48
	v_exp_f32_e32 v38, v0
	v_mul_f32_e32 v0, 0xbfb8aa3b, v49
	v_exp_f32_e32 v39, v0
	s_nop 0
	v_pk_add_f32 v[38:39], v[38:39], 1.0 op_sel_hi:[1,0]
	s_nop 0
	v_div_scale_f32 v0, s[2:3], v39, v39, 1.0
	v_rcp_f32_e32 v37, v0
	s_nop 0
	v_fma_f32 v40, -v0, v37, 1.0
	v_fmac_f32_e32 v37, v40, v37
	v_div_scale_f32 v40, vcc, 1.0, v39, 1.0
	v_mul_f32_e32 v41, v40, v37
	v_fma_f32 v42, -v0, v41, v40
	v_fmac_f32_e32 v41, v42, v37
	v_fma_f32 v0, -v0, v41, v40
	v_div_fmas_f32 v0, v0, v37, v41
	v_div_scale_f32 v37, s[2:3], v38, v38, 1.0
	v_div_fixup_f32 v0, v0, v39, 1.0
	v_rcp_f32_e32 v39, v37
	s_nop 0
	v_fma_f32 v40, -v37, v39, 1.0
	v_fmac_f32_e32 v39, v40, v39
	v_div_scale_f32 v40, vcc, 1.0, v38, 1.0
	v_mul_f32_e32 v41, v40, v39
	v_fma_f32 v42, -v37, v41, v40
	v_fmac_f32_e32 v41, v42, v39
	v_fma_f32 v37, -v37, v41, v40
	v_div_fmas_f32 v37, v37, v39, v41
	v_div_fixup_f32 v37, v37, v38, 1.0
	v_cvt_pk_bf16_f32 v37, v37, v0
	v_mul_f32_e32 v0, 0xbfb8aa3b, v18
	v_exp_f32_e32 v18, v0
	v_mul_f32_e32 v0, 0xbfb8aa3b, v19
	v_exp_f32_e32 v19, v0
	ds_write2_b64 v190, v[34:35], v[36:37] offset0:140 offset1:142
	v_pk_add_f32 v[18:19], v[18:19], 1.0 op_sel_hi:[1,0]
	s_nop 0
	v_div_scale_f32 v0, s[2:3], v19, v19, 1.0
	v_rcp_f32_e32 v34, v0
	s_nop 0
	v_fma_f32 v35, -v0, v34, 1.0
	v_fmac_f32_e32 v34, v35, v34
	v_div_scale_f32 v35, vcc, 1.0, v19, 1.0
	v_mul_f32_e32 v36, v35, v34
	v_fma_f32 v37, -v0, v36, v35
	v_fmac_f32_e32 v36, v37, v34
	v_fma_f32 v0, -v0, v36, v35
	v_div_fmas_f32 v0, v0, v34, v36
	v_div_fixup_f32 v0, v0, v19, 1.0
	v_div_scale_f32 v19, s[2:3], v18, v18, 1.0
	v_rcp_f32_e32 v34, v19
	s_nop 0
	v_fma_f32 v35, -v19, v34, 1.0
	v_fmac_f32_e32 v34, v35, v34
	v_div_scale_f32 v35, vcc, 1.0, v18, 1.0
	v_mul_f32_e32 v36, v35, v34
	v_fma_f32 v37, -v19, v36, v35
	v_fmac_f32_e32 v36, v37, v34
	v_fma_f32 v19, -v19, v36, v35
	v_div_fmas_f32 v19, v19, v34, v36
	v_div_fixup_f32 v18, v19, v18, 1.0
	v_cvt_pk_bf16_f32 v18, v18, v0
	v_mul_f32_e32 v0, 0xbfb8aa3b, v20
	v_exp_f32_e32 v20, v0
	v_mul_f32_e32 v0, 0xbfb8aa3b, v21
	v_exp_f32_e32 v21, v0
	s_nop 0
	v_pk_add_f32 v[20:21], v[20:21], 1.0 op_sel_hi:[1,0]
	s_nop 0
	v_div_scale_f32 v0, s[2:3], v21, v21, 1.0
	v_rcp_f32_e32 v19, v0
	s_nop 0
	v_fma_f32 v34, -v0, v19, 1.0
	v_fmac_f32_e32 v19, v34, v19
	v_div_scale_f32 v34, vcc, 1.0, v21, 1.0
	v_mul_f32_e32 v35, v34, v19
	v_fma_f32 v36, -v0, v35, v34
	v_fmac_f32_e32 v35, v36, v19
; DI unsigned pk2(float a, float b) { f32v2 v = {a, b}; return __builtin_bit_cast(unsigned, __builtin_convertvector(v, bf16v2)); }
; DI float sigmoidf_(float v) { return 1.f / (1.f + __expf(-v)); }
; #define SW_FOR_TOK(j) _Pragma("unroll") for (int j = 0; j < 4; j++)
; #define SW_FOR_FEAT(i, rq) _Pragma("unroll") for (int i = 0; i < 2; i++) _Pragma("unroll") for (int rq = 0; rq < 4; rq++)
; DI void ph_ple(const Params& P, int g, int layer, bf16_t* smem) {
;     ...
;     SW_FOR_TOK(j) { const int tl_ = wn * 128 + j * 32 + l32;
;       SW_FOR_FEAT(i, rq) { const int c_ = wm * 64 + i * 32 + 8 * rq + 4 * h;
;         *(uint2*)(smem + tl_ * EPLD + c_) = make_uint2(pk2(sigmoidf_(SWV(i, j, 4 * rq)), sigmoidf_(SWV(i, j, 4 * rq + 1))), pk2(sigmoidf_(SWV(i, j, 4 * rq + 2)), sigmoidf_(SWV(i, j, 4 * rq + 3)))); } }
	v_fma_f32 v0, -v0, v35, v34
	v_div_fmas_f32 v0, v0, v19, v35
	v_div_scale_f32 v19, s[2:3], v20, v20, 1.0
	v_div_fixup_f32 v0, v0, v21, 1.0
	v_rcp_f32_e32 v21, v19
	s_nop 0
	v_fma_f32 v34, -v19, v21, 1.0
	v_fmac_f32_e32 v21, v34, v21
	v_div_scale_f32 v34, vcc, 1.0, v20, 1.0
	v_mul_f32_e32 v35, v34, v21
	v_fma_f32 v36, -v19, v35, v34
	v_fmac_f32_e32 v35, v36, v21
	v_fma_f32 v19, -v19, v35, v34
	v_div_fmas_f32 v19, v19, v21, v35
	v_div_fixup_f32 v19, v19, v20, 1.0
	v_cvt_pk_bf16_f32 v19, v19, v0
	v_mul_f32_e32 v0, 0xbfb8aa3b, v22
	v_exp_f32_e32 v20, v0
	v_mul_f32_e32 v0, 0xbfb8aa3b, v23
	v_exp_f32_e32 v21, v0
	s_nop 0
	v_pk_add_f32 v[20:21], v[20:21], 1.0 op_sel_hi:[1,0]
	s_nop 0
	v_div_scale_f32 v0, s[2:3], v21, v21, 1.0
	v_rcp_f32_e32 v22, v0
	s_nop 0
	v_fma_f32 v23, -v0, v22, 1.0
	v_fmac_f32_e32 v22, v23, v22
	v_div_scale_f32 v23, vcc, 1.0, v21, 1.0
	v_mul_f32_e32 v34, v23, v22
	v_fma_f32 v35, -v0, v34, v23
	v_fmac_f32_e32 v34, v35, v22
	v_fma_f32 v0, -v0, v34, v23
	v_div_fmas_f32 v0, v0, v22, v34
	v_div_fixup_f32 v0, v0, v21, 1.0
	v_div_scale_f32 v21, s[2:3], v20, v20, 1.0
	v_rcp_f32_e32 v22, v21
	s_nop 0
	v_fma_f32 v23, -v21, v22, 1.0
	v_fmac_f32_e32 v22, v23, v22
	v_div_scale_f32 v23, vcc, 1.0, v20, 1.0
	v_mul_f32_e32 v34, v23, v22
	v_fma_f32 v35, -v21, v34, v23
	v_fmac_f32_e32 v34, v35, v22
	v_fma_f32 v21, -v21, v34, v23
	v_div_fmas_f32 v21, v21, v22, v34
	v_div_fixup_f32 v20, v21, v20, 1.0
	v_cvt_pk_bf16_f32 v20, v20, v0
	v_mul_f32_e32 v0, 0xbfb8aa3b, v24
	v_exp_f32_e32 v22, v0
	v_mul_f32_e32 v0, 0xbfb8aa3b, v25
	v_exp_f32_e32 v23, v0
	s_nop 0
	v_pk_add_f32 v[22:23], v[22:23], 1.0 op_sel_hi:[1,0]
	s_nop 0
	v_div_scale_f32 v0, s[2:3], v23, v23, 1.0
	v_rcp_f32_e32 v21, v0
	s_nop 0
	v_fma_f32 v24, -v0, v21, 1.0
	v_fmac_f32_e32 v21, v24, v21
	v_div_scale_f32 v24, vcc, 1.0, v23, 1.0
	v_mul_f32_e32 v25, v24, v21
	v_fma_f32 v34, -v0, v25, v24
	v_fmac_f32_e32 v25, v34, v21
	v_fma_f32 v0, -v0, v25, v24
	v_div_fmas_f32 v0, v0, v21, v25
	v_div_scale_f32 v21, s[2:3], v22, v22, 1.0
	v_div_fixup_f32 v0, v0, v23, 1.0
	v_rcp_f32_e32 v23, v21
	s_nop 0
	v_fma_f32 v24, -v21, v23, 1.0
	v_fmac_f32_e32 v23, v24, v23
	v_div_scale_f32 v24, vcc, 1.0, v22, 1.0
	v_mul_f32_e32 v25, v24, v23
	v_fma_f32 v34, -v21, v25, v24
	v_fmac_f32_e32 v25, v34, v23
	v_fma_f32 v21, -v21, v25, v24
	v_div_fmas_f32 v21, v21, v23, v25
	v_div_fixup_f32 v21, v21, v22, 1.0
	v_cvt_pk_bf16_f32 v21, v21, v0
	v_mul_f32_e32 v0, 0xbfb8aa3b, v26
	ds_write2_b64 v189, v[18:19], v[20:21] offset0:192 offset1:194
	v_exp_f32_e32 v18, v0
	v_mul_f32_e32 v0, 0xbfb8aa3b, v27
	v_exp_f32_e32 v19, v0
	s_nop 0
	v_pk_add_f32 v[18:19], v[18:19], 1.0 op_sel_hi:[1,0]
	s_nop 0
	v_div_scale_f32 v0, s[2:3], v19, v19, 1.0
	v_rcp_f32_e32 v20, v0
	s_nop 0
	v_fma_f32 v21, -v0, v20, 1.0
	v_fmac_f32_e32 v20, v21, v20
	v_div_scale_f32 v21, vcc, 1.0, v19, 1.0
	v_mul_f32_e32 v22, v21, v20
	v_fma_f32 v23, -v0, v22, v21
	v_fmac_f32_e32 v22, v23, v20
	v_fma_f32 v0, -v0, v22, v21
	v_div_fmas_f32 v0, v0, v20, v22
	v_div_fixup_f32 v0, v0, v19, 1.0
	v_div_scale_f32 v19, s[2:3], v18, v18, 1.0
	v_rcp_f32_e32 v20, v19
	s_nop 0
	v_fma_f32 v21, -v19, v20, 1.0
	v_fmac_f32_e32 v20, v21, v20
	v_div_scale_f32 v21, vcc, 1.0, v18, 1.0
	v_mul_f32_e32 v22, v21, v20
	v_fma_f32 v23, -v19, v22, v21
	v_fmac_f32_e32 v22, v23, v20
	v_fma_f32 v19, -v19, v22, v21
	v_div_fmas_f32 v19, v19, v20, v22
	v_div_fixup_f32 v18, v19, v18, 1.0
	v_cvt_pk_bf16_f32 v18, v18, v0
	v_mul_f32_e32 v0, 0xbfb8aa3b, v28
	v_exp_f32_e32 v20, v0
	v_mul_f32_e32 v0, 0xbfb8aa3b, v29
	v_exp_f32_e32 v21, v0
	s_nop 0
	v_pk_add_f32 v[20:21], v[20:21], 1.0 op_sel_hi:[1,0]
	s_nop 0
	v_div_scale_f32 v0, s[2:3], v21, v21, 1.0
	v_rcp_f32_e32 v19, v0
	s_nop 0
	v_fma_f32 v22, -v0, v19, 1.0
	v_fmac_f32_e32 v19, v22, v19
	v_div_scale_f32 v22, vcc, 1.0, v21, 1.0
	v_mul_f32_e32 v23, v22, v19
	v_fma_f32 v24, -v0, v23, v22
	v_fmac_f32_e32 v23, v24, v19
	v_fma_f32 v0, -v0, v23, v22
	v_div_fmas_f32 v0, v0, v19, v23
	v_div_scale_f32 v19, s[2:3], v20, v20, 1.0
	v_div_fixup_f32 v0, v0, v21, 1.0
	v_rcp_f32_e32 v21, v19
	s_nop 0
	v_fma_f32 v22, -v19, v21, 1.0
	v_fmac_f32_e32 v21, v22, v21
	v_div_scale_f32 v22, vcc, 1.0, v20, 1.0
	v_mul_f32_e32 v23, v22, v21
	v_fma_f32 v24, -v19, v23, v22
	v_fmac_f32_e32 v23, v24, v21
	v_fma_f32 v19, -v19, v23, v22
	v_div_fmas_f32 v19, v19, v21, v23
	v_div_fixup_f32 v19, v19, v20, 1.0
	v_cvt_pk_bf16_f32 v19, v19, v0
	v_mul_f32_e32 v0, 0xbfb8aa3b, v30
	v_exp_f32_e32 v20, v0
	v_mul_f32_e32 v0, 0xbfb8aa3b, v31
	v_exp_f32_e32 v21, v0
	s_nop 0
	v_pk_add_f32 v[20:21], v[20:21], 1.0 op_sel_hi:[1,0]
	s_nop 0
	v_div_scale_f32 v0, s[2:3], v21, v21, 1.0
	v_rcp_f32_e32 v22, v0
	s_nop 0
	v_fma_f32 v23, -v0, v22, 1.0
	v_fmac_f32_e32 v22, v23, v22
	v_div_scale_f32 v23, vcc, 1.0, v21, 1.0
	v_mul_f32_e32 v24, v23, v22
	v_fma_f32 v25, -v0, v24, v23
	v_fmac_f32_e32 v24, v25, v22
	v_fma_f32 v0, -v0, v24, v23
	v_div_fmas_f32 v0, v0, v22, v24
	v_div_fixup_f32 v0, v0, v21, 1.0
	v_div_scale_f32 v21, s[2:3], v20, v20, 1.0
	v_rcp_f32_e32 v22, v21
	s_nop 0
	v_fma_f32 v23, -v21, v22, 1.0
	v_fmac_f32_e32 v22, v23, v22
	v_div_scale_f32 v23, vcc, 1.0, v20, 1.0
	v_mul_f32_e32 v24, v23, v22
	v_fma_f32 v25, -v21, v24, v23
	v_fmac_f32_e32 v24, v25, v22
	v_fma_f32 v21, -v21, v24, v23
	v_div_fmas_f32 v21, v21, v22, v24
	v_div_fixup_f32 v20, v21, v20, 1.0
	v_cvt_pk_bf16_f32 v20, v20, v0
	v_mul_f32_e32 v0, 0xbfb8aa3b, v32
	v_exp_f32_e32 v22, v0
	v_mul_f32_e32 v0, 0xbfb8aa3b, v33
	v_exp_f32_e32 v23, v0
	s_nop 0
	v_pk_add_f32 v[22:23], v[22:23], 1.0 op_sel_hi:[1,0]
	s_nop 0
	v_div_scale_f32 v0, s[2:3], v23, v23, 1.0
	v_rcp_f32_e32 v21, v0
	s_nop 0
	v_fma_f32 v24, -v0, v21, 1.0
	v_fmac_f32_e32 v21, v24, v21
; DI unsigned pk2(float a, float b) { f32v2 v = {a, b}; return __builtin_bit_cast(unsigned, __builtin_convertvector(v, bf16v2)); }
; DI float sigmoidf_(float v) { return 1.f / (1.f + __expf(-v)); }
; #define SW_FOR_TOK(j) _Pragma("unroll") for (int j = 0; j < 4; j++)
; #define SW_FOR_FEAT(i, rq) _Pragma("unroll") for (int i = 0; i < 2; i++) _Pragma("unroll") for (int rq = 0; rq < 4; rq++)
; DI void ph_ple(const Params& P, int g, int layer, bf16_t* smem) {
;     ...
;     SW_FOR_TOK(j) { const int tl_ = wn * 128 + j * 32 + l32;
;       SW_FOR_FEAT(i, rq) { const int c_ = wm * 64 + i * 32 + 8 * rq + 4 * h;
;         *(uint2*)(smem + tl_ * EPLD + c_) = make_uint2(pk2(sigmoidf_(SWV(i, j, 4 * rq)), sigmoidf_(SWV(i, j, 4 * rq + 1))), pk2(sigmoidf_(SWV(i, j, 4 * rq + 2)), sigmoidf_(SWV(i, j, 4 * rq + 3)))); } }
	v_div_scale_f32 v24, vcc, 1.0, v23, 1.0
	v_mul_f32_e32 v25, v24, v21
	v_fma_f32 v26, -v0, v25, v24
	v_fmac_f32_e32 v25, v26, v21
	v_fma_f32 v0, -v0, v25, v24
	v_div_fmas_f32 v0, v0, v21, v25
	v_div_scale_f32 v21, s[2:3], v22, v22, 1.0
	v_div_fixup_f32 v0, v0, v23, 1.0
	v_rcp_f32_e32 v23, v21
	s_nop 0
	v_fma_f32 v24, -v21, v23, 1.0
	v_fmac_f32_e32 v23, v24, v23
	v_div_scale_f32 v24, vcc, 1.0, v22, 1.0
	v_mul_f32_e32 v25, v24, v23
	v_fma_f32 v26, -v21, v25, v24
	v_fmac_f32_e32 v25, v26, v23
	v_fma_f32 v21, -v21, v25, v24
	v_div_fmas_f32 v21, v21, v23, v25
	v_div_fixup_f32 v21, v21, v22, 1.0
	v_cvt_pk_bf16_f32 v21, v21, v0
	v_mul_f32_e32 v0, 0xbfb8aa3b, v2
	v_exp_f32_e32 v2, v0
	v_mul_f32_e32 v0, 0xbfb8aa3b, v3
	v_exp_f32_e32 v3, v0
	ds_write2_b64 v189, v[18:19], v[20:21] offset0:196 offset1:198
	v_pk_add_f32 v[2:3], v[2:3], 1.0 op_sel_hi:[1,0]
	s_nop 0
	v_div_scale_f32 v0, s[2:3], v3, v3, 1.0
	v_rcp_f32_e32 v18, v0
	s_nop 0
	v_fma_f32 v19, -v0, v18, 1.0
	v_fmac_f32_e32 v18, v19, v18
	v_div_scale_f32 v19, vcc, 1.0, v3, 1.0
	v_mul_f32_e32 v20, v19, v18
	v_fma_f32 v21, -v0, v20, v19
	v_fmac_f32_e32 v20, v21, v18
	v_fma_f32 v0, -v0, v20, v19
	v_div_fmas_f32 v0, v0, v18, v20
	v_div_fixup_f32 v0, v0, v3, 1.0
	v_div_scale_f32 v3, s[2:3], v2, v2, 1.0
	v_rcp_f32_e32 v18, v3
	s_nop 0
	v_fma_f32 v19, -v3, v18, 1.0
	v_fmac_f32_e32 v18, v19, v18
	v_div_scale_f32 v19, vcc, 1.0, v2, 1.0
	v_mul_f32_e32 v20, v19, v18
	v_fma_f32 v21, -v3, v20, v19
	v_fmac_f32_e32 v20, v21, v18
	v_fma_f32 v3, -v3, v20, v19
	v_div_fmas_f32 v3, v3, v18, v20
	v_div_fixup_f32 v2, v3, v2, 1.0
	v_cvt_pk_bf16_f32 v2, v2, v0
	v_mul_f32_e32 v0, 0xbfb8aa3b, v4
	v_exp_f32_e32 v4, v0
	v_mul_f32_e32 v0, 0xbfb8aa3b, v5
	v_exp_f32_e32 v5, v0
	s_nop 0
	v_pk_add_f32 v[4:5], v[4:5], 1.0 op_sel_hi:[1,0]
	s_nop 0
	v_div_scale_f32 v0, s[2:3], v5, v5, 1.0
	v_rcp_f32_e32 v3, v0
	s_nop 0
	v_fma_f32 v18, -v0, v3, 1.0
	v_fmac_f32_e32 v3, v18, v3
	v_div_scale_f32 v18, vcc, 1.0, v5, 1.0
	v_mul_f32_e32 v19, v18, v3
	v_fma_f32 v20, -v0, v19, v18
	v_fmac_f32_e32 v19, v20, v3
	v_fma_f32 v0, -v0, v19, v18
	v_div_fmas_f32 v0, v0, v3, v19
	v_div_scale_f32 v3, s[2:3], v4, v4, 1.0
	v_div_fixup_f32 v0, v0, v5, 1.0
	v_rcp_f32_e32 v5, v3
	s_nop 0
	v_fma_f32 v18, -v3, v5, 1.0
	v_fmac_f32_e32 v5, v18, v5
	v_div_scale_f32 v18, vcc, 1.0, v4, 1.0
	v_mul_f32_e32 v19, v18, v5
	v_fma_f32 v20, -v3, v19, v18
	v_fmac_f32_e32 v19, v20, v5
	v_fma_f32 v3, -v3, v19, v18
	v_div_fmas_f32 v3, v3, v5, v19
	v_div_fixup_f32 v3, v3, v4, 1.0
	v_cvt_pk_bf16_f32 v3, v3, v0
	v_mul_f32_e32 v0, 0xbfb8aa3b, v6
	v_exp_f32_e32 v4, v0
	v_mul_f32_e32 v0, 0xbfb8aa3b, v7
	v_exp_f32_e32 v5, v0
	s_nop 0
	v_pk_add_f32 v[4:5], v[4:5], 1.0 op_sel_hi:[1,0]
	s_nop 0
	v_div_scale_f32 v0, s[2:3], v5, v5, 1.0
	v_rcp_f32_e32 v6, v0
	s_nop 0
	v_fma_f32 v7, -v0, v6, 1.0
	v_fmac_f32_e32 v6, v7, v6
	v_div_scale_f32 v7, vcc, 1.0, v5, 1.0
	v_mul_f32_e32 v18, v7, v6
	v_fma_f32 v19, -v0, v18, v7
	v_fmac_f32_e32 v18, v19, v6
	v_fma_f32 v0, -v0, v18, v7
	v_div_fmas_f32 v0, v0, v6, v18
	v_div_fixup_f32 v0, v0, v5, 1.0
	v_div_scale_f32 v5, s[2:3], v4, v4, 1.0
	v_rcp_f32_e32 v6, v5
	s_nop 0
	v_fma_f32 v7, -v5, v6, 1.0
	v_fmac_f32_e32 v6, v7, v6
	v_div_scale_f32 v7, vcc, 1.0, v4, 1.0
	v_mul_f32_e32 v18, v7, v6
	v_fma_f32 v19, -v5, v18, v7
	v_fmac_f32_e32 v18, v19, v6
	v_fma_f32 v5, -v5, v18, v7
	v_div_fmas_f32 v5, v5, v6, v18
	v_div_fixup_f32 v4, v5, v4, 1.0
	v_cvt_pk_bf16_f32 v4, v4, v0
	v_mul_f32_e32 v0, 0xbfb8aa3b, v8
	v_exp_f32_e32 v6, v0
	v_mul_f32_e32 v0, 0xbfb8aa3b, v9
	v_exp_f32_e32 v7, v0
	s_nop 0
	v_pk_add_f32 v[6:7], v[6:7], 1.0 op_sel_hi:[1,0]
	s_nop 0
	v_div_scale_f32 v0, s[2:3], v7, v7, 1.0
	v_rcp_f32_e32 v5, v0
	s_nop 0
	v_fma_f32 v8, -v0, v5, 1.0
	v_fmac_f32_e32 v5, v8, v5
	v_div_scale_f32 v8, vcc, 1.0, v7, 1.0
	v_mul_f32_e32 v9, v8, v5
	v_fma_f32 v18, -v0, v9, v8
	v_fmac_f32_e32 v9, v18, v5
	v_fma_f32 v0, -v0, v9, v8
	v_div_fmas_f32 v0, v0, v5, v9
	v_div_scale_f32 v5, s[2:3], v6, v6, 1.0
	v_div_fixup_f32 v0, v0, v7, 1.0
	v_rcp_f32_e32 v7, v5
	s_nop 0
	v_fma_f32 v8, -v5, v7, 1.0
	v_fmac_f32_e32 v7, v8, v7
	v_div_scale_f32 v8, vcc, 1.0, v6, 1.0
	v_mul_f32_e32 v9, v8, v7
; DI unsigned pk2(float a, float b) { f32v2 v = {a, b}; return __builtin_bit_cast(unsigned, __builtin_convertvector(v, bf16v2)); }
; DI float sigmoidf_(float v) { return 1.f / (1.f + __expf(-v)); }
; DI size_t tix(size_t t, int f, int KT) { return ((t >> 7) * KT + (f >> 6)) * 8192 + (t & 127) * 64 + (f & 63); }
; #define SW_FOR_TOK(j) _Pragma("unroll") for (int j = 0; j < 4; j++)
; #define SW_FOR_FEAT(i, rq) _Pragma("unroll") for (int i = 0; i < 2; i++) _Pragma("unroll") for (int rq = 0; rq < 4; rq++)
; DI void ph_ple(const Params& P, int g, int layer, bf16_t* smem) {
;     ...
;     SW_FOR_TOK(j) { const int tl_ = wn * 128 + j * 32 + l32;
;       SW_FOR_FEAT(i, rq) { const int c_ = wm * 64 + i * 32 + 8 * rq + 4 * h;
;         *(uint2*)(smem + tl_ * EPLD + c_) = make_uint2(pk2(sigmoidf_(SWV(i, j, 4 * rq)), sigmoidf_(SWV(i, j, 4 * rq + 1))), pk2(sigmoidf_(SWV(i, j, 4 * rq + 2)), sigmoidf_(SWV(i, j, 4 * rq + 3)))); } }
;     __syncthreads();
; #pragma unroll 8
;     for (int k = 0; k < 16; k++) {
;       const int c = tid + 256 * k; const int ch8 = c & 7, row = (c >> 3) & 255, fh = c >> 11;
;       const int f = fh * 64 + ch8 * 8; const size_t tg = (size_t)m0 + row;
;       const uint4 sg = *(const uint4*)(smem + row * EPLD + f);
;       bf16_t* ep = x2b + tix(tg, n0 + f, 16);
;       const uint4 eu = *(const uint4*)ep;
;       float* yp = y + tg * 1024 + n0 + f;
;       const uint4 xu = *(const uint4*)(x1b + tix(tg, n0 + f, 16));
	v_fma_f32 v18, -v5, v9, v8
	v_fmac_f32_e32 v9, v18, v7
	v_fma_f32 v5, -v5, v9, v8
	v_div_fmas_f32 v5, v5, v7, v9
	v_div_fixup_f32 v5, v5, v6, 1.0
	v_cvt_pk_bf16_f32 v5, v5, v0
	v_mul_f32_e32 v0, 0xbfb8aa3b, v10
	ds_write2_b64 v189, v[2:3], v[4:5] offset0:200 offset1:202
	v_exp_f32_e32 v2, v0
	v_mul_f32_e32 v0, 0xbfb8aa3b, v11
	v_exp_f32_e32 v3, v0
	s_nop 0
	v_pk_add_f32 v[2:3], v[2:3], 1.0 op_sel_hi:[1,0]
	s_nop 0
	v_div_scale_f32 v0, s[2:3], v3, v3, 1.0
	v_rcp_f32_e32 v4, v0
	s_nop 0
	v_fma_f32 v5, -v0, v4, 1.0
	v_fmac_f32_e32 v4, v5, v4
	v_div_scale_f32 v5, vcc, 1.0, v3, 1.0
	v_mul_f32_e32 v6, v5, v4
	v_fma_f32 v7, -v0, v6, v5
	v_fmac_f32_e32 v6, v7, v4
	v_fma_f32 v0, -v0, v6, v5
	v_div_fmas_f32 v0, v0, v4, v6
	v_div_fixup_f32 v0, v0, v3, 1.0
	v_div_scale_f32 v3, s[2:3], v2, v2, 1.0
	v_rcp_f32_e32 v4, v3
	s_nop 0
	v_fma_f32 v5, -v3, v4, 1.0
	v_fmac_f32_e32 v4, v5, v4
	v_div_scale_f32 v5, vcc, 1.0, v2, 1.0
	v_mul_f32_e32 v6, v5, v4
	v_fma_f32 v7, -v3, v6, v5
	v_fmac_f32_e32 v6, v7, v4
	v_fma_f32 v3, -v3, v6, v5
	v_div_fmas_f32 v3, v3, v4, v6
	v_div_fixup_f32 v2, v3, v2, 1.0
	v_cvt_pk_bf16_f32 v2, v2, v0
	v_mul_f32_e32 v0, 0xbfb8aa3b, v12
	v_exp_f32_e32 v4, v0
	v_mul_f32_e32 v0, 0xbfb8aa3b, v13
	v_exp_f32_e32 v5, v0
	s_nop 0
	v_pk_add_f32 v[4:5], v[4:5], 1.0 op_sel_hi:[1,0]
	s_nop 0
	v_div_scale_f32 v0, s[2:3], v5, v5, 1.0
	v_rcp_f32_e32 v3, v0
	s_nop 0
	v_fma_f32 v6, -v0, v3, 1.0
	v_fmac_f32_e32 v3, v6, v3
	v_div_scale_f32 v6, vcc, 1.0, v5, 1.0
	v_mul_f32_e32 v7, v6, v3
	v_fma_f32 v8, -v0, v7, v6
	v_fmac_f32_e32 v7, v8, v3
	v_fma_f32 v0, -v0, v7, v6
	v_div_fmas_f32 v0, v0, v3, v7
	v_div_scale_f32 v3, s[2:3], v4, v4, 1.0
	v_div_fixup_f32 v0, v0, v5, 1.0
	v_rcp_f32_e32 v5, v3
	s_nop 0
	v_fma_f32 v6, -v3, v5, 1.0
	v_fmac_f32_e32 v5, v6, v5
	v_div_scale_f32 v6, vcc, 1.0, v4, 1.0
	v_mul_f32_e32 v7, v6, v5
	v_fma_f32 v8, -v3, v7, v6
	v_fmac_f32_e32 v7, v8, v5
	v_fma_f32 v3, -v3, v7, v6
	v_div_fmas_f32 v3, v3, v5, v7
	v_div_fixup_f32 v3, v3, v4, 1.0
	v_cvt_pk_bf16_f32 v3, v3, v0
	v_mul_f32_e32 v0, 0xbfb8aa3b, v14
	v_exp_f32_e32 v4, v0
	v_mul_f32_e32 v0, 0xbfb8aa3b, v15
	v_exp_f32_e32 v5, v0
	s_nop 0
	v_pk_add_f32 v[4:5], v[4:5], 1.0 op_sel_hi:[1,0]
	s_nop 0
	v_div_scale_f32 v0, s[2:3], v5, v5, 1.0
	v_rcp_f32_e32 v6, v0
	s_nop 0
	v_fma_f32 v7, -v0, v6, 1.0
	v_fmac_f32_e32 v6, v7, v6
	v_div_scale_f32 v7, vcc, 1.0, v5, 1.0
	v_mul_f32_e32 v8, v7, v6
	v_fma_f32 v9, -v0, v8, v7
	v_fmac_f32_e32 v8, v9, v6
	v_fma_f32 v0, -v0, v8, v7
	v_div_fmas_f32 v0, v0, v6, v8
	v_div_fixup_f32 v0, v0, v5, 1.0
	v_div_scale_f32 v5, s[2:3], v4, v4, 1.0
	v_rcp_f32_e32 v6, v5
	s_nop 0
	v_fma_f32 v7, -v5, v6, 1.0
	v_fmac_f32_e32 v6, v7, v6
	v_div_scale_f32 v7, vcc, 1.0, v4, 1.0
	v_mul_f32_e32 v8, v7, v6
	v_fma_f32 v9, -v5, v8, v7
	v_fmac_f32_e32 v8, v9, v6
	v_fma_f32 v5, -v5, v8, v7
	v_div_fmas_f32 v5, v5, v6, v8
	v_div_fixup_f32 v4, v5, v4, 1.0
	v_cvt_pk_bf16_f32 v4, v4, v0
	v_mul_f32_e32 v0, 0xbfb8aa3b, v16
	v_exp_f32_e32 v6, v0
	v_mul_f32_e32 v0, 0xbfb8aa3b, v17
	v_exp_f32_e32 v7, v0
	s_nop 0
	v_pk_add_f32 v[6:7], v[6:7], 1.0 op_sel_hi:[1,0]
	s_nop 0
	v_div_scale_f32 v0, s[2:3], v7, v7, 1.0
	v_rcp_f32_e32 v5, v0
	s_nop 0
	v_fma_f32 v8, -v0, v5, 1.0
	v_fmac_f32_e32 v5, v8, v5
	v_div_scale_f32 v8, vcc, 1.0, v7, 1.0
	v_mul_f32_e32 v9, v8, v5
	v_fma_f32 v10, -v0, v9, v8
	v_fmac_f32_e32 v9, v10, v5
	v_fma_f32 v0, -v0, v9, v8
	v_div_fmas_f32 v0, v0, v5, v9
	v_div_scale_f32 v5, s[2:3], v6, v6, 1.0
	v_div_fixup_f32 v0, v0, v7, 1.0
	v_rcp_f32_e32 v7, v5
	s_lshl_b64 s[2:3], s[8:9], 2
	s_add_u32 s10, s6, s2
	s_addc_u32 s11, s7, s3
	v_fma_f32 v8, -v5, v7, 1.0
	v_fmac_f32_e32 v7, v8, v7
	v_div_scale_f32 v8, vcc, 1.0, v6, 1.0
	v_mul_f32_e32 v9, v8, v7
	v_fma_f32 v10, -v5, v9, v8
	v_fmac_f32_e32 v9, v10, v7
	v_fma_f32 v5, -v5, v9, v8
	v_div_fmas_f32 v5, v5, v7, v9
	v_div_fixup_f32 v5, v5, v6, 1.0
	v_cvt_pk_bf16_f32 v5, v5, v0
	ds_write2_b64 v189, v[2:3], v[4:5] offset0:204 offset1:206
	v_lshlrev_b64 v[2:3], 12, v[168:169]
	v_and_b32_e32 v7, 0x7ffff, v171
	v_and_b32_e32 v6, -16, v170
	v_or_b32_e32 v0, v172, v162
	v_lshl_add_u64 v[8:9], s[10:11], 0, v[2:3]
	s_mov_b32 s2, 0
	s_waitcnt lgkmcnt(0)
	s_barrier

; #define A256_LOADH(kt_, hf_) { a0 = la.ld1(kt_, (hf_) * 4 + 0, tid); a1 = la.ld1(kt_, (hf_) * 4 + 1, tid); a2 = la.ld1(kt_, (hf_) * 4 + 2, tid); a3 = la.ld1(kt_, (hf_) * 4 + 3, tid); }
; #define ZERO_ACC8(a) { _Pragma("unroll") for (int i_ = 0; i_ < 8; i_++) _Pragma("unroll") for (int r_ = 0; r_ < 16; r_++) a[i_][r_] = 0.f; }
; template <bool swap, class LA>
; DI void gemm256_ws(const LA& la, const bf16_t* Wt, const int KS, const int nk, bf16_t* smem, f32x16 (&acc)[8]) {
;     ...
;   A256_LOADH(0, 0) A256_STH(smem, 0)
;   A256_LOADH(0, 1) A256_STH(smem, 1)
;   W256_LD(0, 0, w00, w10) W256_LD(0, 1, w01, w11) W256_LD(0, 2, w02, w12) W256_LD(0, 3, w03, w13)
;   __syncthreads();
;   const int aoff = (tbk * 128 + l32) * LDT + h * 8;
; DI bool tile_sched256(int bid, int it, int NT, int PW, int& mt, int& nt) {
;   const int x = bid & 7, slot = bid >> 3, nslot = gridDim.x >> 3;
;   const int j = slot + it * nslot;
;   if (j >= 32 * NT) return false;
;   const int ppan = 32 * PW; const int panel = j / ppan, rem = j - panel * ppan;
;   const int ml = rem / PW; nt = panel * PW + (rem - ml * PW); mt = x * 32 + ml;
;   return true;
; }
; DI void ph_in_e(const Params& P, int g, bf16_t* smem, float* s_rs) {
;     ...
;   for (int it = 0;; it++) {
;     int mt, nt; if (!tile_sched256(bid, it, 28, 7, mt, nt)) break;
;     const int m0 = mt * 256, n0 = nt * 128; const int split = nt >> 2, cin = (nt & 3) * 128;
;     __syncthreads();
;     s_rs[tid] = rs_in[m0 + tid];
;     f32x16 acc[8]; ZERO_ACC8(acc)
;     LoadTile256 la{xb + (size_t)(2 * mt) * 16 * 8192, 16 * 8192};
;     const bool swap = (split != 2);
;     gemm256(la, W + (size_t)n0 * 1024, 64, 16, smem, acc, swap);
.LBB0_479:
	s_mul_hi_i32 s3, s2, 0x92492493
	s_add_i32 s3, s3, s2
	s_lshr_b32 s8, s3, 31
	s_ashr_i32 s3, s3, 7
	s_add_i32 s3, s3, s8
	s_mul_i32 s8, s3, 0xffffff20
	s_add_i32 s2, s8, s2
	s_mul_hi_i32 s8, s2, 0x92492493
	s_add_i32 s8, s8, s2
	s_lshr_b32 s9, s8, 31
	s_ashr_i32 s8, s8, 2
	s_add_i32 s9, s8, s9
	s_add_i32 s10, s9, s94
	s_lshl_b32 s8, s10, 8
	v_add_u32_e32 v2, s8, v163
	v_ashrrev_i32_e32 v3, 31, v2
	v_lshl_add_u64 v[2:3], v[2:3], 2, s[6:7]
	s_barrier
	global_load_dword v233, v[2:3], off
	s_sub_i32 s3, s3, s9
	s_mul_i32 s3, s3, 7
	s_lshl_b32 s12, s10, 1
	s_add_i32 s3, s3, s2
	s_ashr_i32 s13, s12, 31
	s_ashr_i32 s2, s3, 2
	s_lshl_b32 s10, s3, 7
	s_lshl_b64 s[16:17], s[12:13], 18
	s_add_u32 s14, s38, s16
	s_addc_u32 s15, s39, s17
	s_cmp_lg_u32 s2, 2
	s_cselect_b64 s[12:13], -1, 0
	s_ashr_i32 s11, s10, 31
	s_lshl_b64 s[86:87], s[10:11], 11
	s_add_u32 s92, s26, s86
	s_addc_u32 s93, s27, s87
	s_cmp_eq_u32 s2, 2
	s_mov_b64 s[18:19], -1
	s_cbranch_scc1 .LBB0_487
	v_mov_b32_e32 v0, v234
	v_readlane_b32 s18, v253, 2
	v_lshlrev_b32_e32 v2, 3, v0
	v_ashrrev_i32_e32 v3, 31, v2
	v_ashrrev_i32_e32 v48, 6, v0
	v_lshlrev_b64 v[170:171], 1, v[2:3]
	v_add_u32_e32 v6, 0x800, v2
	v_add_u32_e32 v8, 0x1000, v2
	v_add_u32_e32 v2, 0x1800, v2
	v_lshlrev_b32_e32 v49, 4, v0
	v_and_b32_e32 v48, -2, v48
	v_ashrrev_i32_e32 v3, 31, v2
	v_and_b32_e32 v15, 31, v0
	v_lshrrev_b32_e32 v51, 3, v0
	v_lshlrev_b32_e32 v52, 1, v0
	v_lshrrev_b32_e32 v53, 1, v0
	v_and_b32_e32 v0, 0x3f0, v49
	v_and_b32_e32 v50, 0x70, v49
	v_ashrrev_i32_e32 v49, 31, v48
	v_readlane_b32 s19, v253, 3
	v_ashrrev_i32_e32 v7, 31, v6
	v_ashrrev_i32_e32 v9, 31, v8
	v_lshlrev_b64 v[176:177], 1, v[2:3]
	s_add_u32 s18, s14, 0x40000
	v_lshlrev_b64 v[48:49], 16, v[48:49]
	v_lshl_add_u64 v[4:5], s[14:15], 0, v[170:171]
	v_lshlrev_b64 v[172:173], 1, v[6:7]
	v_lshlrev_b64 v[174:175], 1, v[8:9]
	v_lshl_add_u64 v[2:3], s[14:15], 0, v[176:177]
	s_addc_u32 s19, s15, 0
	v_lshl_add_u64 v[48:49], s[92:93], 0, v[48:49]
	v_lshl_add_u64 v[6:7], s[14:15], 0, v[172:173]
	v_lshl_add_u64 v[8:9], s[14:15], 0, v[174:175]
	global_load_dwordx4 v[16:19], v[4:5], off
	global_load_dwordx4 v[20:23], v[6:7], off
	global_load_dwordx4 v[24:27], v[8:9], off
	global_load_dwordx4 v[28:31], v[2:3], off
	v_lshl_add_u64 v[2:3], s[18:19], 0, v[170:171]
	v_lshl_add_u64 v[180:181], v[48:49], 0, v[0:1]
	global_load_dwordx4 v[32:35], v[2:3], off
	v_lshl_add_u64 v[2:3], s[18:19], 0, v[172:173]
	v_add_co_u32_e32 v48, vcc, s47, v180
	v_lshl_add_u64 v[4:5], s[18:19], 0, v[174:175]
	v_lshl_add_u64 v[6:7], s[18:19], 0, v[176:177]
	global_load_dwordx4 v[36:39], v[2:3], off
	global_load_dwordx4 v[40:43], v[4:5], off
	global_load_dwordx4 v[44:47], v[6:7], off
	v_addc_co_u32_e32 v49, vcc, 0, v181, vcc
	global_load_dwordx4 v[154:157], v[48:49], off
	global_load_dwordx4 v[158:161], v[180:181], off
	global_load_dwordx4 v[146:149], v[48:49], off offset:1024
	global_load_dwordx4 v[150:153], v[180:181], off offset:1024
	global_load_dwordx4 v[142:145], v[48:49], off offset:2048
	global_load_dwordx4 v[138:141], v[180:181], off offset:2048
	global_load_dwordx4 v[130:133], v[48:49], off offset:3072
	global_load_dwordx4 v[134:137], v[180:181], off offset:3072
	s_movk_i32 s9, 0x80
	v_mad_u64_u32 v[178:179], s[44:45], v51, s0, v[50:51]
	v_mov_b32_e32 v2, 0
	v_and_or_b32 v15, v52, s9, v15
	v_and_b32_e32 v52, 16, v53
	s_mov_b64 s[44:45], 0x10000
	s_mov_b32 s3, 0
	v_mov_b32_e32 v3, v2
	v_mov_b32_e32 v4, v2
	v_mov_b32_e32 v5, v2
	v_mov_b32_e32 v6, v2
	v_mov_b32_e32 v7, v2
	v_mov_b32_e32 v8, v2
	v_mov_b32_e32 v9, v2
	v_mov_b32_e32 v10, v2
	v_mov_b32_e32 v11, v2
	v_mov_b32_e32 v12, v2
	v_mov_b32_e32 v13, v2
	v_mov_b32_e32 v14, v2
	v_mad_u32_u24 v169, v15, s0, v52
	v_lshl_add_u64 v[182:183], v[180:181], 0, s[44:45]
	v_mov_b32_e32 v15, v2
	v_mov_b32_e32 v48, v2
	v_mov_b32_e32 v49, v2
	v_mov_b32_e32 v82, v2
	v_mov_b32_e32 v83, v2
	v_mov_b32_e32 v84, v2
	v_mov_b32_e32 v85, v2
	v_mov_b32_e32 v86, v2
	v_mov_b32_e32 v87, v2
	v_mov_b32_e32 v88, v2
	v_mov_b32_e32 v89, v2
	v_mov_b32_e32 v90, v2
	v_mov_b32_e32 v91, v2
	v_mov_b32_e32 v92, v2
	v_mov_b32_e32 v93, v2
	v_mov_b32_e32 v94, v2
	v_mov_b32_e32 v95, v2
	v_mov_b32_e32 v96, v2
	v_mov_b32_e32 v97, v2
	v_mov_b32_e32 v50, v2
	s_waitcnt vmcnt(15)
	ds_write_b32 v192, v233
	ds_write_b128 v178, v[16:19]
	s_waitcnt vmcnt(11)
	ds_write_b128 v178, v[32:35] offset:18432
	ds_write_b128 v178, v[20:23] offset:4608
	ds_write_b128 v178, v[24:27] offset:9216
	ds_write_b128 v178, v[28:31] offset:13824
	s_waitcnt vmcnt(10)
	ds_write_b128 v178, v[36:39] offset:23040
	s_waitcnt vmcnt(9)
	ds_write_b128 v178, v[40:43] offset:27648
	s_waitcnt vmcnt(8)
	ds_write_b128 v178, v[44:47] offset:32256
	v_mov_b32_e32 v16, v2
	v_mov_b32_e32 v17, v2
	v_mov_b32_e32 v34, v2
	v_mov_b32_e32 v35, v2
	v_mov_b32_e32 v36, v2
	v_mov_b32_e32 v37, v2
	v_mov_b32_e32 v38, v2
	v_mov_b32_e32 v39, v2
	v_mov_b32_e32 v40, v2
	v_mov_b32_e32 v41, v2
	v_mov_b32_e32 v42, v2
	v_mov_b32_e32 v43, v2
	v_mov_b32_e32 v44, v2
	v_mov_b32_e32 v45, v2
	v_mov_b32_e32 v46, v2
	v_mov_b32_e32 v47, v2
	v_mov_b32_e32 v18, v2
	v_mov_b32_e32 v19, v2
	v_mov_b32_e32 v20, v2
	v_mov_b32_e32 v21, v2
	v_mov_b32_e32 v22, v2
	v_mov_b32_e32 v23, v2
	v_mov_b32_e32 v24, v2
	v_mov_b32_e32 v25, v2
	v_mov_b32_e32 v26, v2
	v_mov_b32_e32 v27, v2
	v_mov_b32_e32 v28, v2
	v_mov_b32_e32 v29, v2
	v_mov_b32_e32 v30, v2
	v_mov_b32_e32 v31, v2
	v_mov_b32_e32 v32, v2
	v_mov_b32_e32 v33, v2
	v_mov_b32_e32 v51, v2
	v_mov_b32_e32 v52, v2
	v_mov_b32_e32 v53, v2
	v_mov_b32_e32 v54, v2
	v_mov_b32_e32 v55, v2
	v_mov_b32_e32 v56, v2
	v_mov_b32_e32 v57, v2
	v_mov_b32_e32 v58, v2
	v_mov_b32_e32 v59, v2
	v_mov_b32_e32 v60, v2
	v_mov_b32_e32 v61, v2
	v_mov_b32_e32 v62, v2
	v_mov_b32_e32 v63, v2
	v_mov_b32_e32 v64, v2
	v_mov_b32_e32 v65, v2
	v_mov_b32_e32 v98, v2
	v_mov_b32_e32 v99, v2
	v_mov_b32_e32 v100, v2
	v_mov_b32_e32 v101, v2
	v_mov_b32_e32 v102, v2
	v_mov_b32_e32 v103, v2
	v_mov_b32_e32 v104, v2
	v_mov_b32_e32 v105, v2
	v_mov_b32_e32 v106, v2
	v_mov_b32_e32 v107, v2
	v_mov_b32_e32 v108, v2
	v_mov_b32_e32 v109, v2
	v_mov_b32_e32 v110, v2
	v_mov_b32_e32 v111, v2
	v_mov_b32_e32 v112, v2
	v_mov_b32_e32 v113, v2
	v_mov_b32_e32 v66, v2
	v_mov_b32_e32 v67, v2
	v_mov_b32_e32 v68, v2
	v_mov_b32_e32 v69, v2
	v_mov_b32_e32 v70, v2
	v_mov_b32_e32 v71, v2
	v_mov_b32_e32 v72, v2
	v_mov_b32_e32 v73, v2
	v_mov_b32_e32 v74, v2
	v_mov_b32_e32 v75, v2
	v_mov_b32_e32 v76, v2
	v_mov_b32_e32 v77, v2
	v_mov_b32_e32 v78, v2
	v_mov_b32_e32 v79, v2
	v_mov_b32_e32 v80, v2
	v_mov_b32_e32 v81, v2
	v_mov_b32_e32 v114, v2
	v_mov_b32_e32 v115, v2
	v_mov_b32_e32 v116, v2
	v_mov_b32_e32 v117, v2
	v_mov_b32_e32 v118, v2
	v_mov_b32_e32 v119, v2
	v_mov_b32_e32 v120, v2
	v_mov_b32_e32 v121, v2
	v_mov_b32_e32 v122, v2
	v_mov_b32_e32 v123, v2
	v_mov_b32_e32 v124, v2
	v_mov_b32_e32 v125, v2
	v_mov_b32_e32 v126, v2
	v_mov_b32_e32 v127, v2
	v_mov_b32_e32 v128, v2
	v_mov_b32_e32 v129, v2
	s_waitcnt lgkmcnt(0)
	s_barrier
	s_and_b32 s9, s3, 1
	s_mul_i32 s11, s9, 0x9000
	v_add_u32_e32 v0, s11, v169
; #define A256_LOADH(kt_, hf_) { a0 = la.ld1(kt_, (hf_) * 4 + 0, tid); a1 = la.ld1(kt_, (hf_) * 4 + 1, tid); a2 = la.ld1(kt_, (hf_) * 4 + 2, tid); a3 = la.ld1(kt_, (hf_) * 4 + 3, tid); }
; template <bool swap, class LA>
; DI void gemm256_ws(const LA& la, const bf16_t* Wt, const int KS, const int nk, bf16_t* smem, f32x16 (&acc)[8]) {
;     ...
;   for (int kt = 0; kt < nk; kt++) {
;     const int cur = kt & 1; const int kn = (kt + 1 < nk) ? kt + 1 : last;
;     const bf16_t* sp = smem + cur * ATILE_E + aoff;
;     bf16_t* nxt = smem + (cur ^ 1) * ATILE_E;
;     A256_LOADH(kn, 0)
;     MMA256(0, w00, w10) W256_LD(kn, 0, w00, w10)
;     MMA256(1, w01, w11) W256_LD(kn, 1, w01, w11)
;     A256_STH(nxt, 0)
;     A256_LOADH(kn, 1)
;     MMA256(2, w02, w12) W256_LD(kn, 2, w02, w12)
;     MMA256(3, w03, w13) W256_LD(kn, 3, w03, w13)
;     A256_STH(nxt, 1)
;     __syncthreads();
;   }
.LBB0_481:
	ds_read_b128 v[184:187], v0
	ds_read_b128 v[188:191], v0 offset:4608
	ds_read_b128 v[196:199], v0 offset:9216
	ds_read_b128 v[200:203], v0 offset:13824
	s_and_b32 s9, s3, 1
	s_add_i32 s3, s3, 1
	s_min_u32 s11, s3, 15
	s_xor_b32 s9, s9, 1
	s_mul_i32 s9, s9, 0x9000
	v_add_u32_e32 v179, s9, v178
	s_lshl_b32 s43, s11, 14
	s_lshl_b32 s90, s11, 12
	s_add_u32 s44, s14, s43
	s_addc_u32 s45, s15, 0
	v_lshl_add_u64 v[204:205], s[44:45], 0, v[170:171]
	v_lshl_add_u64 v[220:221], s[44:45], 0, v[172:173]
	v_lshl_add_u64 v[224:225], s[44:45], 0, v[174:175]
	v_lshl_add_u64 v[228:229], s[44:45], 0, v[176:177]
	global_load_dwordx4 v[204:207], v[204:205], off
	global_load_dwordx4 v[220:223], v[220:221], off
	global_load_dwordx4 v[224:227], v[224:225], off
	global_load_dwordx4 v[228:231], v[228:229], off
	v_lshl_add_u64 v[208:209], v[182:183], 0, s[90:91]
	v_lshl_add_u64 v[232:233], v[180:181], 0, s[90:91]
	s_add_u32 s44, s18, s43
	s_addc_u32 s45, s19, 0
	s_waitcnt vmcnt(10) lgkmcnt(3)
	v_mfma_f32_32x32x16_bf16 v[82:97], v[154:157], v[184:187], v[82:97]
	v_mfma_f32_32x32x16_bf16 v[114:129], v[158:161], v[184:187], v[114:129]
	ds_read_b128 v[184:187], v0 offset:32
	s_waitcnt lgkmcnt(3)
	v_mfma_f32_32x32x16_bf16 v[18:33], v[154:157], v[188:191], v[18:33]
	v_mfma_f32_32x32x16_bf16 v[66:81], v[158:161], v[188:191], v[66:81]
	ds_read_b128 v[188:191], v0 offset:4640
	s_waitcnt lgkmcnt(3)
	v_mfma_f32_32x32x16_bf16 v[34:49], v[154:157], v[196:199], v[34:49]
	v_mfma_f32_32x32x16_bf16 v[98:113], v[158:161], v[196:199], v[98:113]
	ds_read_b128 v[196:199], v0 offset:9248
	s_waitcnt lgkmcnt(3)
	v_mfma_f32_32x32x16_bf16 v[2:17], v[154:157], v[200:203], v[2:17]
	v_mfma_f32_32x32x16_bf16 v[50:65], v[158:161], v[200:203], v[50:65]
	ds_read_b128 v[200:203], v0 offset:13856
	global_load_dwordx4 v[154:157], v[208:209], off
	global_load_dwordx4 v[158:161], v[232:233], off
	s_waitcnt vmcnt(10) lgkmcnt(3)
	v_mfma_f32_32x32x16_bf16 v[82:97], v[146:149], v[184:187], v[82:97]
	v_mfma_f32_32x32x16_bf16 v[114:129], v[150:153], v[184:187], v[114:129]
	ds_read_b128 v[184:187], v0 offset:64
	s_waitcnt lgkmcnt(3)
	v_mfma_f32_32x32x16_bf16 v[18:33], v[146:149], v[188:191], v[18:33]
	v_mfma_f32_32x32x16_bf16 v[66:81], v[150:153], v[188:191], v[66:81]
	ds_read_b128 v[188:191], v0 offset:4672
	s_waitcnt lgkmcnt(3)
	v_mfma_f32_32x32x16_bf16 v[34:49], v[146:149], v[196:199], v[34:49]
	v_mfma_f32_32x32x16_bf16 v[98:113], v[150:153], v[196:199], v[98:113]
	ds_read_b128 v[196:199], v0 offset:9280
	s_waitcnt lgkmcnt(3)
	v_mfma_f32_32x32x16_bf16 v[2:17], v[146:149], v[200:203], v[2:17]
	v_mfma_f32_32x32x16_bf16 v[50:65], v[150:153], v[200:203], v[50:65]
	ds_read_b128 v[200:203], v0 offset:13888
	global_load_dwordx4 v[146:149], v[208:209], off offset:1024
	global_load_dwordx4 v[150:153], v[232:233], off offset:1024
	s_waitcnt vmcnt(4)
	ds_write_b128 v179, v[204:207]
	ds_write_b128 v179, v[220:223] offset:4608
	ds_write_b128 v179, v[224:227] offset:9216
	ds_write_b128 v179, v[228:231] offset:13824
	v_lshl_add_u64 v[204:205], s[44:45], 0, v[170:171]
	v_lshl_add_u64 v[220:221], s[44:45], 0, v[172:173]
	v_lshl_add_u64 v[224:225], s[44:45], 0, v[174:175]
	v_lshl_add_u64 v[228:229], s[44:45], 0, v[176:177]
	global_load_dwordx4 v[204:207], v[204:205], off
	global_load_dwordx4 v[220:223], v[220:221], off
	global_load_dwordx4 v[224:227], v[224:225], off
	global_load_dwordx4 v[228:231], v[228:229], off
	s_waitcnt lgkmcnt(7)
	v_mfma_f32_32x32x16_bf16 v[82:97], v[142:145], v[184:187], v[82:97]
	v_mfma_f32_32x32x16_bf16 v[114:129], v[138:141], v[184:187], v[114:129]
	ds_read_b128 v[184:187], v0 offset:96
	s_waitcnt lgkmcnt(7)
	v_mfma_f32_32x32x16_bf16 v[18:33], v[142:145], v[188:191], v[18:33]
	v_mfma_f32_32x32x16_bf16 v[66:81], v[138:141], v[188:191], v[66:81]
	ds_read_b128 v[188:191], v0 offset:4704
	s_waitcnt lgkmcnt(7)
	v_mfma_f32_32x32x16_bf16 v[34:49], v[142:145], v[196:199], v[34:49]
	v_mfma_f32_32x32x16_bf16 v[98:113], v[138:141], v[196:199], v[98:113]
	ds_read_b128 v[196:199], v0 offset:9312
	s_waitcnt lgkmcnt(7)
	v_mfma_f32_32x32x16_bf16 v[2:17], v[142:145], v[200:203], v[2:17]
	v_mfma_f32_32x32x16_bf16 v[50:65], v[138:141], v[200:203], v[50:65]
	ds_read_b128 v[200:203], v0 offset:13920
	global_load_dwordx4 v[142:145], v[208:209], off offset:2048
	global_load_dwordx4 v[138:141], v[232:233], off offset:2048
	s_waitcnt lgkmcnt(3)
	v_mfma_f32_32x32x16_bf16 v[82:97], v[130:133], v[184:187], v[82:97]
	v_mfma_f32_32x32x16_bf16 v[114:129], v[134:137], v[184:187], v[114:129]
	s_waitcnt lgkmcnt(2)
	v_mfma_f32_32x32x16_bf16 v[18:33], v[130:133], v[188:191], v[18:33]
	v_mfma_f32_32x32x16_bf16 v[66:81], v[134:137], v[188:191], v[66:81]
	s_waitcnt lgkmcnt(1)
	v_mfma_f32_32x32x16_bf16 v[34:49], v[130:133], v[196:199], v[34:49]
	v_mfma_f32_32x32x16_bf16 v[98:113], v[134:137], v[196:199], v[98:113]
	s_waitcnt lgkmcnt(0)
	v_mfma_f32_32x32x16_bf16 v[2:17], v[130:133], v[200:203], v[2:17]
	v_mfma_f32_32x32x16_bf16 v[50:65], v[134:137], v[200:203], v[50:65]
	global_load_dwordx4 v[130:133], v[208:209], off offset:3072
	global_load_dwordx4 v[134:137], v[232:233], off offset:3072
	s_waitcnt vmcnt(4)
	ds_write_b128 v179, v[204:207] offset:18432
	ds_write_b128 v179, v[220:223] offset:23040
	ds_write_b128 v179, v[224:227] offset:27648
	ds_write_b128 v179, v[228:231] offset:32256
	s_and_b32 s9, s3, 1
	s_mul_i32 s9, s9, 0x9000
	v_add_u32_e32 v0, s9, v169
	s_cmp_eq_u32 s3, 16
	s_waitcnt lgkmcnt(0)
	s_barrier
	s_cbranch_scc0 .LBB0_481
	s_waitcnt vmcnt(0)
